# stack1i + one LDS-DMA moved from the 6-load SP2 segment to the following 2-load SP1 segment in every GEMM K-loop (vmcnt 8->7 at that SP2)
# baseline (speedup 1.0000x reference)
; #define PG8_STAGE(bufoff, gbase, voff) do { _Pragma("unroll") for (int _i = 0; _i < 2; ++_i) \
;         __builtin_amdgcn_global_load_lds((const unsigned*)((const char*)(gbase) + (voff)[_i]), (PG8_LAS unsigned*)(lds + (bufoff) + ldsw + _i * 8192), 16, 0, 0); } while (0)
; #define PG8_LDA(dst, b, h) do { _Pragma("unroll") for (int m = 0; m < 4; ++m) _Pragma("unroll") for (int k = 0; k < 2; ++k) dst[m][k] = *(const PG8_LAS bf16x8*)(lds + PG8_SA(b, h) + aoff + m * 2048 + k * 1024); } while (0)
; #define PG8_LDB(dst, b, h) do { _Pragma("unroll") for (int n = 0; n < 2; ++n) _Pragma("unroll") for (int k = 0; k < 2; ++k) dst[n][k] = *(const PG8_LAS bf16x8*)(lds + PG8_SB(b, h) + boff + n * 2048 + k * 1024); } while (0)
; #define PG8_MMA(ai, bj, At, Bt) do { __builtin_amdgcn_s_setprio(1); _Pragma("unroll") for (int m = 0; m < 4; ++m) _Pragma("unroll") for (int n = 0; n < 2; ++n) _Pragma("unroll") for (int k = 0; k < 2; ++k) \
;         acc[ai][bj][m][n] = __builtin_amdgcn_mfma_f32_16x16x32_bf16(Bt[n][k], At[m][k], acc[ai][bj][m][n], 0, 0, 0); __builtin_amdgcn_s_setprio(0); } while (0)
; #define PG8_WAIT_V(n) asm volatile("s_waitcnt vmcnt(" #n ")" ::: "memory")
; #define PG8_WAIT_L(n) asm volatile("s_waitcnt lgkmcnt(" #n ")" ::: "memory")
; template <class Epi, class Sched, bool ALIGN_EPI = false, bool SP2 = false>
; __device__ __forceinline__ void gemm_phase(PG8_LAS unsigned char* lds, const Gemm g, const Sched& S, const Epi& E) {
;     ...
;             const bool last = (t == nt - 2);
;             const char* a1 = cA + (size_t)(t + 1) * kstep;
;             const char* a2 = last ? nA : cA + (size_t)(t + 2) * kstep; const char* b2 = last ? nB : cB + (size_t)(t + 2) * kstep;
;             const char* a3 = a2 + kstep; const char* b3 = b2 + kstep;
;             if (last && has_next) S.a_ready(nxt);
;             if constexpr (SP2) {
;             PG8_LDB(B0, 0, 0); PG8_LDB(B1, 0, 1); PG8_SCHED; PG8_LDA(At, 0, 0); PG8_STAGE(PG8_SA(1, 1), a1 + hstep, voffA);
;             PG8_WAIT_V(8); PG8_WAIT_L(0); PG8_BAR; PG8_MMA(0, 0, At, B0); PG8_MMA(0, 1, At, B1); PG8_BAR; PG8_SCHED;
;             PG8_LDA(At, 0, 1); PG8_STAGE(PG8_SB(0, 0), b2, voffB); PG8_STAGE(PG8_SB(0, 1), b2 + hstep, voffB); PG8_STAGE(PG8_SA(0, 0), a2, voffA);
;             PG8_WAIT_V(8); PG8_WAIT_L(0); PG8_BAR; PG8_MMA(1, 0, At, B0); PG8_MMA(1, 1, At, B1); PG8_BAR; PG8_SCHED;
.LBB0_304:
	v_add_u32_e32 v166, s54, v169
	v_add_u32_e32 v168, s55, v169
	ds_read_b128 v[162:165], v166
	ds_read_b128 v[182:185], v166 offset:1024
	ds_read_b128 v[186:189], v166 offset:2048
	ds_read_b128 v[190:193], v166 offset:3072
	ds_read_b128 v[194:197], v168
	ds_read_b128 v[198:201], v168 offset:1024
	ds_read_b128 v[202:205], v168 offset:2048
	ds_read_b128 v[206:209], v168 offset:3072
	s_cmp_eq_u32 s53, s10
	v_lshl_add_u64 v[172:173], v[160:161], 0, s[22:23]
	s_cselect_b64 vcc, -1, 0
	s_add_i32 s10, s10, 2
	v_cndmask_b32_e32 v173, v173, v153, vcc
	v_cndmask_b32_e32 v172, v172, v152, vcc
	v_cndmask_b32_e32 v245, v159, v155, vcc
	v_cndmask_b32_e32 v244, v158, v154, vcc
	s_mov_b32 m0, s56
	v_lshl_add_u64 v[246:247], v[160:161], 0, v[148:149]
	ds_read_b128 v[210:213], v179
	ds_read_b128 v[216:219], v179 offset:1024
	ds_read_b128 v[220:223], v179 offset:2048
	ds_read_b128 v[224:227], v179 offset:3072
	ds_read_b128 v[228:231], v179 offset:4096
	ds_read_b128 v[232:235], v179 offset:5120
	ds_read_b128 v[236:239], v179 offset:6144
	ds_read_b128 v[240:243], v179 offset:7168
	global_load_lds_dwordx4 v[246:247], off
	s_mov_b32 m0, s57
	v_lshl_add_u64 v[246:247], v[160:161], 0, v[146:147]
	global_load_lds_dwordx4 v[246:247], off
	s_waitcnt vmcnt(8) lgkmcnt(0)
	s_setprio 1
	s_barrier
	v_mfma_f32_16x16x32_bf16 v[124:127], v[162:165], v[210:213], v[124:127]
	v_mfma_f32_16x16x32_bf16 v[116:119], v[186:189], v[210:213], v[116:119]
	v_mfma_f32_16x16x32_bf16 v[108:111], v[162:165], v[220:223], v[108:111]
	v_mfma_f32_16x16x32_bf16 v[100:103], v[186:189], v[220:223], v[100:103]
	v_mfma_f32_16x16x32_bf16 v[92:95], v[162:165], v[228:231], v[92:95]
	v_mfma_f32_16x16x32_bf16 v[84:87], v[186:189], v[228:231], v[84:87]
	v_mfma_f32_16x16x32_bf16 v[76:79], v[162:165], v[236:239], v[76:79]
	v_mfma_f32_16x16x32_bf16 v[68:71], v[186:189], v[236:239], v[68:71]
	v_mfma_f32_16x16x32_bf16 v[124:127], v[182:185], v[216:219], v[124:127]
	v_mfma_f32_16x16x32_bf16 v[116:119], v[190:193], v[216:219], v[116:119]
	v_mfma_f32_16x16x32_bf16 v[108:111], v[182:185], v[224:227], v[108:111]
	v_mfma_f32_16x16x32_bf16 v[100:103], v[190:193], v[224:227], v[100:103]
	v_mfma_f32_16x16x32_bf16 v[92:95], v[182:185], v[232:235], v[92:95]
	v_mfma_f32_16x16x32_bf16 v[84:87], v[190:193], v[232:235], v[84:87]
	v_mfma_f32_16x16x32_bf16 v[76:79], v[182:185], v[240:243], v[76:79]
	v_mfma_f32_16x16x32_bf16 v[68:71], v[190:193], v[240:243], v[68:71]
	v_mfma_f32_16x16x32_bf16 v[120:123], v[194:197], v[210:213], v[120:123]
	v_mfma_f32_16x16x32_bf16 v[112:115], v[202:205], v[210:213], v[112:115]
	v_mfma_f32_16x16x32_bf16 v[104:107], v[194:197], v[220:223], v[104:107]
	v_mfma_f32_16x16x32_bf16 v[96:99], v[202:205], v[220:223], v[96:99]
	v_mfma_f32_16x16x32_bf16 v[88:91], v[194:197], v[228:231], v[88:91]
	v_mfma_f32_16x16x32_bf16 v[80:83], v[202:205], v[228:231], v[80:83]
	v_mfma_f32_16x16x32_bf16 v[72:75], v[194:197], v[236:239], v[72:75]
	v_mfma_f32_16x16x32_bf16 v[64:67], v[202:205], v[236:239], v[64:67]
	v_mfma_f32_16x16x32_bf16 v[120:123], v[198:201], v[216:219], v[120:123]
	v_mfma_f32_16x16x32_bf16 v[112:115], v[206:209], v[216:219], v[112:115]
	v_mfma_f32_16x16x32_bf16 v[104:107], v[198:201], v[224:227], v[104:107]
	v_mfma_f32_16x16x32_bf16 v[96:99], v[206:209], v[224:227], v[96:99]
	v_mfma_f32_16x16x32_bf16 v[88:91], v[198:201], v[232:235], v[88:91]
	v_mfma_f32_16x16x32_bf16 v[80:83], v[206:209], v[232:235], v[80:83]
	v_mfma_f32_16x16x32_bf16 v[72:75], v[198:201], v[240:243], v[72:75]
	v_mfma_f32_16x16x32_bf16 v[64:67], v[206:209], v[240:243], v[64:67]
	s_setprio 0
	s_barrier
	s_mov_b32 m0, s60
	v_lshl_add_u64 v[246:247], v[244:245], 0, v[138:139]
	ds_read_b128 v[210:213], v179 offset:16384
	ds_read_b128 v[216:219], v179 offset:17408
	ds_read_b128 v[220:223], v179 offset:18432
	ds_read_b128 v[224:227], v179 offset:19456
	ds_read_b128 v[228:231], v179 offset:20480
	ds_read_b128 v[232:235], v179 offset:21504
	ds_read_b128 v[236:239], v179 offset:22528
	ds_read_b128 v[240:243], v179 offset:23552
	global_load_lds_dwordx4 v[246:247], off
	v_lshl_add_u64 v[248:249], v[244:245], 0, v[134:135]
	s_mov_b32 m0, s61
	v_lshl_add_u64 v[244:245], v[244:245], 0, s[14:15]
	global_load_lds_dwordx4 v[248:249], off
	v_lshl_add_u64 v[250:251], v[244:245], 0, v[138:139]
	s_mov_b32 m0, s62
	v_lshl_add_u64 v[244:245], v[244:245], 0, v[134:135]
	global_load_lds_dwordx4 v[250:251], off
	s_add_i32 m0, s62, 0x2000
	v_lshl_add_u64 v[252:253], v[172:173], 0, v[140:141]
	global_load_lds_dwordx4 v[244:245], off
	s_mov_b32 m0, s46
	v_lshl_add_u64 v[214:215], v[172:173], 0, v[136:137]
	global_load_lds_dwordx4 v[252:253], off
	s_nop 0
	s_waitcnt vmcnt(7) lgkmcnt(0)
	s_setprio 1
	s_barrier
; #define PG8_STAGE(bufoff, gbase, voff) do { _Pragma("unroll") for (int _i = 0; _i < 2; ++_i) \
;         __builtin_amdgcn_global_load_lds((const unsigned*)((const char*)(gbase) + (voff)[_i]), (PG8_LAS unsigned*)(lds + (bufoff) + ldsw + _i * 8192), 16, 0, 0); } while (0)
; #define PG8_LDA(dst, b, h) do { _Pragma("unroll") for (int m = 0; m < 4; ++m) _Pragma("unroll") for (int k = 0; k < 2; ++k) dst[m][k] = *(const PG8_LAS bf16x8*)(lds + PG8_SA(b, h) + aoff + m * 2048 + k * 1024); } while (0)
; #define PG8_LDB(dst, b, h) do { _Pragma("unroll") for (int n = 0; n < 2; ++n) _Pragma("unroll") for (int k = 0; k < 2; ++k) dst[n][k] = *(const PG8_LAS bf16x8*)(lds + PG8_SB(b, h) + boff + n * 2048 + k * 1024); } while (0)
; #define PG8_MMA(ai, bj, At, Bt) do { __builtin_amdgcn_s_setprio(1); _Pragma("unroll") for (int m = 0; m < 4; ++m) _Pragma("unroll") for (int n = 0; n < 2; ++n) _Pragma("unroll") for (int k = 0; k < 2; ++k) \
;         acc[ai][bj][m][n] = __builtin_amdgcn_mfma_f32_16x16x32_bf16(Bt[n][k], At[m][k], acc[ai][bj][m][n], 0, 0, 0); __builtin_amdgcn_s_setprio(0); } while (0)
; #define PG8_WAIT_V(n) asm volatile("s_waitcnt vmcnt(" #n ")" ::: "memory")
; #define PG8_WAIT_L(n) asm volatile("s_waitcnt lgkmcnt(" #n ")" ::: "memory")
; #define PG8_BAR __builtin_amdgcn_s_barrier()
; #define PG8_SCHED __builtin_amdgcn_sched_barrier(0)
; template <class Epi, class Sched, bool ALIGN_EPI = false, bool SP2 = false>
; __device__ __forceinline__ void gemm_phase(PG8_LAS unsigned char* lds, const Gemm g, const Sched& S, const Epi& E) {
;     ...
;             PG8_WAIT_V(8); PG8_WAIT_L(0); PG8_BAR; PG8_MMA(1, 0, At, B0); PG8_MMA(1, 1, At, B1); PG8_BAR; PG8_SCHED;
;             PG8_LDB(B0, 1, 0); PG8_LDB(B1, 1, 1); PG8_SCHED; PG8_LDA(At, 1, 0); PG8_STAGE(PG8_SA(0, 1), a2 + hstep, voffA);
;             PG8_WAIT_V(8); PG8_WAIT_L(0); PG8_BAR; PG8_MMA(0, 0, At, B0); PG8_MMA(0, 1, At, B1); PG8_BAR; PG8_SCHED;
	v_mfma_f32_16x16x32_bf16 v[60:63], v[162:165], v[210:213], v[60:63]
	v_mfma_f32_16x16x32_bf16 v[52:55], v[186:189], v[210:213], v[52:55]
	v_mfma_f32_16x16x32_bf16 v[44:47], v[162:165], v[220:223], v[44:47]
	v_mfma_f32_16x16x32_bf16 v[36:39], v[186:189], v[220:223], v[36:39]
	v_mfma_f32_16x16x32_bf16 v[28:31], v[162:165], v[228:231], v[28:31]
	v_mfma_f32_16x16x32_bf16 v[20:23], v[186:189], v[228:231], v[20:23]
	v_mfma_f32_16x16x32_bf16 v[12:15], v[162:165], v[236:239], v[12:15]
	v_mfma_f32_16x16x32_bf16 v[4:7], v[186:189], v[236:239], v[4:7]
	v_mfma_f32_16x16x32_bf16 v[60:63], v[182:185], v[216:219], v[60:63]
	v_mfma_f32_16x16x32_bf16 v[52:55], v[190:193], v[216:219], v[52:55]
	v_mfma_f32_16x16x32_bf16 v[44:47], v[182:185], v[224:227], v[44:47]
	v_mfma_f32_16x16x32_bf16 v[36:39], v[190:193], v[224:227], v[36:39]
	v_mfma_f32_16x16x32_bf16 v[28:31], v[182:185], v[232:235], v[28:31]
	v_mfma_f32_16x16x32_bf16 v[20:23], v[190:193], v[232:235], v[20:23]
	v_mfma_f32_16x16x32_bf16 v[12:15], v[182:185], v[240:243], v[12:15]
	v_mfma_f32_16x16x32_bf16 v[4:7], v[190:193], v[240:243], v[4:7]
	v_mfma_f32_16x16x32_bf16 v[56:59], v[194:197], v[210:213], v[56:59]
	v_mfma_f32_16x16x32_bf16 v[48:51], v[202:205], v[210:213], v[48:51]
	v_mfma_f32_16x16x32_bf16 v[40:43], v[194:197], v[220:223], v[40:43]
	v_mfma_f32_16x16x32_bf16 v[32:35], v[202:205], v[220:223], v[32:35]
	v_mfma_f32_16x16x32_bf16 v[24:27], v[194:197], v[228:231], v[24:27]
	v_mfma_f32_16x16x32_bf16 v[16:19], v[202:205], v[228:231], v[16:19]
	v_mfma_f32_16x16x32_bf16 v[8:11], v[194:197], v[236:239], v[8:11]
	v_mfma_f32_16x16x32_bf16 v[0:3], v[202:205], v[236:239], v[0:3]
	v_mfma_f32_16x16x32_bf16 v[56:59], v[198:201], v[216:219], v[56:59]
	v_mfma_f32_16x16x32_bf16 v[48:51], v[206:209], v[216:219], v[48:51]
	v_mfma_f32_16x16x32_bf16 v[40:43], v[198:201], v[224:227], v[40:43]
	v_mfma_f32_16x16x32_bf16 v[32:35], v[206:209], v[224:227], v[32:35]
	v_mfma_f32_16x16x32_bf16 v[24:27], v[198:201], v[232:235], v[24:27]
	v_mfma_f32_16x16x32_bf16 v[16:19], v[206:209], v[232:235], v[16:19]
	v_mfma_f32_16x16x32_bf16 v[8:11], v[198:201], v[240:243], v[8:11]
	v_mfma_f32_16x16x32_bf16 v[0:3], v[206:209], v[240:243], v[0:3]
	s_setprio 0
	s_barrier
	s_add_i32 s11, 0, 0x18000
	v_add_u32_e32 v166, s11, v169
	s_add_i32 s13, 0, 0x1c000
	s_mov_b32 m0, s47
	ds_read_b128 v[162:165], v166
	global_load_lds_dwordx4 v[214:215], off
	ds_read_b128 v[182:185], v166 offset:1024
	ds_read_b128 v[186:189], v166 offset:2048
	ds_read_b128 v[190:193], v166 offset:3072
	v_add_u32_e32 v166, s13, v169
	ds_read_b128 v[194:197], v166
	ds_read_b128 v[198:201], v166 offset:1024
	ds_read_b128 v[202:205], v166 offset:2048
	ds_read_b128 v[206:209], v166 offset:3072
	v_lshl_add_u64 v[172:173], v[172:173], 0, s[14:15]
	s_mov_b32 m0, s48
	v_lshl_add_u64 v[170:171], v[172:173], 0, v[140:141]
	ds_read_b128 v[210:213], v179 offset:32768
	ds_read_b128 v[216:219], v179 offset:33792
	ds_read_b128 v[220:223], v179 offset:34816
	ds_read_b128 v[224:227], v179 offset:35840
	ds_read_b128 v[228:231], v179 offset:36864
	ds_read_b128 v[232:235], v179 offset:37888
	ds_read_b128 v[236:239], v179 offset:38912
	ds_read_b128 v[240:243], v179 offset:39936
	global_load_lds_dwordx4 v[170:171], off
	s_mov_b32 m0, s49
	v_lshl_add_u64 v[170:171], v[172:173], 0, v[136:137]
	global_load_lds_dwordx4 v[170:171], off
	s_waitcnt vmcnt(8) lgkmcnt(0)
	s_setprio 1
	s_barrier
	v_mfma_f32_16x16x32_bf16 v[124:127], v[162:165], v[210:213], v[124:127]
	v_mfma_f32_16x16x32_bf16 v[116:119], v[186:189], v[210:213], v[116:119]
	v_mfma_f32_16x16x32_bf16 v[108:111], v[162:165], v[220:223], v[108:111]
	v_mfma_f32_16x16x32_bf16 v[100:103], v[186:189], v[220:223], v[100:103]
	v_mfma_f32_16x16x32_bf16 v[92:95], v[162:165], v[228:231], v[92:95]
	v_mfma_f32_16x16x32_bf16 v[84:87], v[186:189], v[228:231], v[84:87]
	v_mfma_f32_16x16x32_bf16 v[76:79], v[162:165], v[236:239], v[76:79]
	v_mfma_f32_16x16x32_bf16 v[68:71], v[186:189], v[236:239], v[68:71]
	v_mfma_f32_16x16x32_bf16 v[124:127], v[182:185], v[216:219], v[124:127]
	v_mfma_f32_16x16x32_bf16 v[116:119], v[190:193], v[216:219], v[116:119]
	v_mfma_f32_16x16x32_bf16 v[108:111], v[182:185], v[224:227], v[108:111]
	v_mfma_f32_16x16x32_bf16 v[100:103], v[190:193], v[224:227], v[100:103]
	v_mfma_f32_16x16x32_bf16 v[92:95], v[182:185], v[232:235], v[92:95]
	v_mfma_f32_16x16x32_bf16 v[84:87], v[190:193], v[232:235], v[84:87]
	v_mfma_f32_16x16x32_bf16 v[76:79], v[182:185], v[240:243], v[76:79]
	v_mfma_f32_16x16x32_bf16 v[68:71], v[190:193], v[240:243], v[68:71]
	v_mfma_f32_16x16x32_bf16 v[120:123], v[194:197], v[210:213], v[120:123]
	v_mfma_f32_16x16x32_bf16 v[112:115], v[202:205], v[210:213], v[112:115]
	v_mfma_f32_16x16x32_bf16 v[104:107], v[194:197], v[220:223], v[104:107]
	v_mfma_f32_16x16x32_bf16 v[96:99], v[202:205], v[220:223], v[96:99]
	v_mfma_f32_16x16x32_bf16 v[88:91], v[194:197], v[228:231], v[88:91]
	v_mfma_f32_16x16x32_bf16 v[80:83], v[202:205], v[228:231], v[80:83]
	v_mfma_f32_16x16x32_bf16 v[72:75], v[194:197], v[236:239], v[72:75]
	v_mfma_f32_16x16x32_bf16 v[64:67], v[202:205], v[236:239], v[64:67]
	v_mfma_f32_16x16x32_bf16 v[120:123], v[198:201], v[216:219], v[120:123]
	v_mfma_f32_16x16x32_bf16 v[112:115], v[206:209], v[216:219], v[112:115]
	v_mfma_f32_16x16x32_bf16 v[104:107], v[198:201], v[224:227], v[104:107]
	v_mfma_f32_16x16x32_bf16 v[96:99], v[206:209], v[224:227], v[96:99]
	v_mfma_f32_16x16x32_bf16 v[88:91], v[198:201], v[232:235], v[88:91]
	v_mfma_f32_16x16x32_bf16 v[80:83], v[206:209], v[232:235], v[80:83]
	v_mfma_f32_16x16x32_bf16 v[72:75], v[198:201], v[240:243], v[72:75]
	v_mfma_f32_16x16x32_bf16 v[64:67], v[206:209], v[240:243], v[64:67]
	s_setprio 0
	s_barrier
; #define PG8_STAGE(bufoff, gbase, voff) do { _Pragma("unroll") for (int _i = 0; _i < 2; ++_i) \
;         __builtin_amdgcn_global_load_lds((const unsigned*)((const char*)(gbase) + (voff)[_i]), (PG8_LAS unsigned*)(lds + (bufoff) + ldsw + _i * 8192), 16, 0, 0); } while (0)
; #define PG8_LDA(dst, b, h) do { _Pragma("unroll") for (int m = 0; m < 4; ++m) _Pragma("unroll") for (int k = 0; k < 2; ++k) dst[m][k] = *(const PG8_LAS bf16x8*)(lds + PG8_SA(b, h) + aoff + m * 2048 + k * 1024); } while (0)
; #define PG8_MMA(ai, bj, At, Bt) do { __builtin_amdgcn_s_setprio(1); _Pragma("unroll") for (int m = 0; m < 4; ++m) _Pragma("unroll") for (int n = 0; n < 2; ++n) _Pragma("unroll") for (int k = 0; k < 2; ++k) \
;         acc[ai][bj][m][n] = __builtin_amdgcn_mfma_f32_16x16x32_bf16(Bt[n][k], At[m][k], acc[ai][bj][m][n], 0, 0, 0); __builtin_amdgcn_s_setprio(0); } while (0)
; #define PG8_WAIT_V(n) asm volatile("s_waitcnt vmcnt(" #n ")" ::: "memory")
; #define PG8_WAIT_L(n) asm volatile("s_waitcnt lgkmcnt(" #n ")" ::: "memory")
; #define PG8_BAR __builtin_amdgcn_s_barrier()
; #define PG8_SCHED __builtin_amdgcn_sched_barrier(0)
; template <class Epi, class Sched, bool ALIGN_EPI = false, bool SP2 = false>
; __device__ __forceinline__ void gemm_phase(PG8_LAS unsigned char* lds, const Gemm g, const Sched& S, const Epi& E) {
;     ...
;             PG8_LDA(At, 1, 1); PG8_STAGE(PG8_SB(1, 0), b3, voffB); PG8_STAGE(PG8_SB(1, 1), b3 + hstep, voffB); PG8_STAGE(PG8_SA(1, 0), a3, voffA);
;             PG8_WAIT_V(8); PG8_WAIT_L(0); PG8_BAR; PG8_MMA(1, 0, At, B0); PG8_MMA(1, 1, At, B1); PG8_BAR; PG8_SCHED;
	s_add_i32 s11, s11, s29
	v_lshl_add_u64 v[170:171], v[246:247], 0, s[22:23]
	s_mov_b32 m0, s11
	ds_read_b128 v[210:213], v179 offset:49152
	ds_read_b128 v[216:219], v179 offset:50176
	ds_read_b128 v[220:223], v179 offset:51200
	ds_read_b128 v[224:227], v179 offset:52224
	ds_read_b128 v[228:231], v179 offset:53248
	ds_read_b128 v[232:235], v179 offset:54272
	ds_read_b128 v[236:239], v179 offset:55296
	ds_read_b128 v[240:243], v179 offset:56320
	global_load_lds_dwordx4 v[170:171], off
	v_lshl_add_u64 v[170:171], v[248:249], 0, s[22:23]
	s_add_i32 m0, s11, 0x2000
	s_add_i32 s11, s13, s29
	global_load_lds_dwordx4 v[170:171], off
	s_mov_b32 m0, s11
	v_lshl_add_u64 v[170:171], v[250:251], 0, s[22:23]
	global_load_lds_dwordx4 v[170:171], off
	s_add_i32 m0, s11, 0x2000
	v_lshl_add_u64 v[170:171], v[244:245], 0, s[22:23]
	global_load_lds_dwordx4 v[170:171], off
	s_mov_b32 m0, s50
	v_lshl_add_u64 v[170:171], v[252:253], 0, s[22:23]
	global_load_lds_dwordx4 v[170:171], off
	s_mov_b32 m0, s51
	v_lshl_add_u64 v[170:171], v[214:215], 0, s[22:23]
	global_load_lds_dwordx4 v[170:171], off
	s_waitcnt vmcnt(8) lgkmcnt(0)
	s_setprio 1
	s_barrier
	v_mfma_f32_16x16x32_bf16 v[60:63], v[162:165], v[210:213], v[60:63]
	v_mfma_f32_16x16x32_bf16 v[52:55], v[186:189], v[210:213], v[52:55]
	v_mfma_f32_16x16x32_bf16 v[44:47], v[162:165], v[220:223], v[44:47]
	v_mfma_f32_16x16x32_bf16 v[36:39], v[186:189], v[220:223], v[36:39]
	v_mfma_f32_16x16x32_bf16 v[28:31], v[162:165], v[228:231], v[28:31]
	v_mfma_f32_16x16x32_bf16 v[20:23], v[186:189], v[228:231], v[20:23]
	v_mfma_f32_16x16x32_bf16 v[12:15], v[162:165], v[236:239], v[12:15]
	v_mfma_f32_16x16x32_bf16 v[4:7], v[186:189], v[236:239], v[4:7]
	v_mfma_f32_16x16x32_bf16 v[60:63], v[182:185], v[216:219], v[60:63]
	v_mfma_f32_16x16x32_bf16 v[52:55], v[190:193], v[216:219], v[52:55]
	v_mfma_f32_16x16x32_bf16 v[44:47], v[182:185], v[224:227], v[44:47]
	v_mfma_f32_16x16x32_bf16 v[36:39], v[190:193], v[224:227], v[36:39]
	v_mfma_f32_16x16x32_bf16 v[28:31], v[182:185], v[232:235], v[28:31]
	v_mfma_f32_16x16x32_bf16 v[20:23], v[190:193], v[232:235], v[20:23]
	v_mfma_f32_16x16x32_bf16 v[12:15], v[182:185], v[240:243], v[12:15]
	v_mfma_f32_16x16x32_bf16 v[4:7], v[190:193], v[240:243], v[4:7]
	v_mfma_f32_16x16x32_bf16 v[56:59], v[194:197], v[210:213], v[56:59]
	v_mfma_f32_16x16x32_bf16 v[48:51], v[202:205], v[210:213], v[48:51]
	v_mfma_f32_16x16x32_bf16 v[40:43], v[194:197], v[220:223], v[40:43]
	v_mfma_f32_16x16x32_bf16 v[32:35], v[202:205], v[220:223], v[32:35]
	v_mfma_f32_16x16x32_bf16 v[24:27], v[194:197], v[228:231], v[24:27]
	v_mfma_f32_16x16x32_bf16 v[16:19], v[202:205], v[228:231], v[16:19]
	v_mfma_f32_16x16x32_bf16 v[8:11], v[194:197], v[236:239], v[8:11]
	v_mfma_f32_16x16x32_bf16 v[0:3], v[202:205], v[236:239], v[0:3]
	v_mfma_f32_16x16x32_bf16 v[56:59], v[198:201], v[216:219], v[56:59]
	v_mfma_f32_16x16x32_bf16 v[48:51], v[206:209], v[216:219], v[48:51]
	v_mfma_f32_16x16x32_bf16 v[40:43], v[198:201], v[224:227], v[40:43]
	v_mfma_f32_16x16x32_bf16 v[32:35], v[206:209], v[224:227], v[32:35]
	v_mfma_f32_16x16x32_bf16 v[24:27], v[198:201], v[232:235], v[24:27]
	v_mfma_f32_16x16x32_bf16 v[16:19], v[206:209], v[232:235], v[16:19]
	v_mfma_f32_16x16x32_bf16 v[8:11], v[198:201], v[240:243], v[8:11]
	v_mfma_f32_16x16x32_bf16 v[0:3], v[206:209], v[240:243], v[0:3]
	s_setprio 0
	s_barrier
	v_lshl_add_u64 v[158:159], v[158:159], 0, s[26:27]
	s_cmp_ge_i32 s10, s52
	v_lshl_add_u64 v[160:161], v[160:161], 0, s[26:27]
	s_cbranch_scc0 .LBB0_304

; #define PG8_STAGE(bufoff, gbase, voff) do { _Pragma("unroll") for (int _i = 0; _i < 2; ++_i) \
;         __builtin_amdgcn_global_load_lds((const unsigned*)((const char*)(gbase) + (voff)[_i]), (PG8_LAS unsigned*)(lds + (bufoff) + ldsw + _i * 8192), 16, 0, 0); } while (0)
; #define PG8_LDA(dst, b, h) do { _Pragma("unroll") for (int m = 0; m < 4; ++m) _Pragma("unroll") for (int k = 0; k < 2; ++k) dst[m][k] = *(const PG8_LAS bf16x8*)(lds + PG8_SA(b, h) + aoff + m * 2048 + k * 1024); } while (0)
; #define PG8_LDB(dst, b, h) do { _Pragma("unroll") for (int n = 0; n < 2; ++n) _Pragma("unroll") for (int k = 0; k < 2; ++k) dst[n][k] = *(const PG8_LAS bf16x8*)(lds + PG8_SB(b, h) + boff + n * 2048 + k * 1024); } while (0)
; #define PG8_MMA(ai, bj, At, Bt) do { __builtin_amdgcn_s_setprio(1); _Pragma("unroll") for (int m = 0; m < 4; ++m) _Pragma("unroll") for (int n = 0; n < 2; ++n) _Pragma("unroll") for (int k = 0; k < 2; ++k) \
;         acc[ai][bj][m][n] = __builtin_amdgcn_mfma_f32_16x16x32_bf16(Bt[n][k], At[m][k], acc[ai][bj][m][n], 0, 0, 0); __builtin_amdgcn_s_setprio(0); } while (0)
; #define PG8_WAIT_V(n) asm volatile("s_waitcnt vmcnt(" #n ")" ::: "memory")
; #define PG8_WAIT_L(n) asm volatile("s_waitcnt lgkmcnt(" #n ")" ::: "memory")
; template <class Epi, class Sched, bool ALIGN_EPI = false, bool SP2 = false>
; __device__ __forceinline__ void gemm_phase(PG8_LAS unsigned char* lds, const Gemm g, const Sched& S, const Epi& E) {
;     ...
;             const bool last = (t == nt - 2);
;             const char* a1 = cA + (size_t)(t + 1) * kstep;
;             const char* a2 = last ? nA : cA + (size_t)(t + 2) * kstep; const char* b2 = last ? nB : cB + (size_t)(t + 2) * kstep;
;             const char* a3 = a2 + kstep; const char* b3 = b2 + kstep;
;             if (last && has_next) S.a_ready(nxt);
;             if constexpr (SP2) {
;             PG8_LDB(B0, 0, 0); PG8_LDB(B1, 0, 1); PG8_SCHED; PG8_LDA(At, 0, 0); PG8_STAGE(PG8_SA(1, 1), a1 + hstep, voffA);
;             PG8_WAIT_V(8); PG8_WAIT_L(0); PG8_BAR; PG8_MMA(0, 0, At, B0); PG8_MMA(0, 1, At, B1); PG8_BAR; PG8_SCHED;
;             PG8_LDA(At, 0, 1); PG8_STAGE(PG8_SB(0, 0), b2, voffB); PG8_STAGE(PG8_SB(0, 1), b2 + hstep, voffB); PG8_STAGE(PG8_SA(0, 0), a2, voffA);
;             PG8_WAIT_V(8); PG8_WAIT_L(0); PG8_BAR; PG8_MMA(1, 0, At, B0); PG8_MMA(1, 1, At, B1); PG8_BAR; PG8_SCHED;
.LBB0_371:
	v_add_u32_e32 v148, s54, v201
	v_add_u32_e32 v190, s55, v201
	ds_read_b128 v[136:139], v148
	ds_read_b128 v[140:143], v148 offset:1024
	ds_read_b128 v[144:147], v148 offset:2048
	ds_read_b128 v[148:151], v148 offset:3072
	ds_read_b128 v[152:155], v190
	ds_read_b128 v[182:185], v190 offset:1024
	ds_read_b128 v[186:189], v190 offset:2048
	ds_read_b128 v[190:193], v190 offset:3072
	s_cmp_eq_u32 s48, s12
	v_lshl_add_u64 v[194:195], v[134:135], 0, s[22:23]
	s_cselect_b64 vcc, -1, 0
	s_add_i32 s12, s12, 2
	v_cndmask_b32_e32 v199, v195, v179, vcc
	v_cndmask_b32_e32 v198, v194, v178, vcc
	v_cndmask_b32_e32 v215, v133, v181, vcc
	v_cndmask_b32_e32 v214, v132, v180, vcc
	s_mov_b32 m0, s56
	v_lshl_add_u64 v[236:237], v[134:135], 0, v[174:175]
	ds_read_b128 v[194:197], v203
	ds_read_b128 v[206:209], v203 offset:1024
	ds_read_b128 v[210:213], v203 offset:2048
	ds_read_b128 v[216:219], v203 offset:3072
	ds_read_b128 v[220:223], v203 offset:4096
	ds_read_b128 v[224:227], v203 offset:5120
	ds_read_b128 v[228:231], v203 offset:6144
	ds_read_b128 v[232:235], v203 offset:7168
	global_load_lds_dwordx4 v[236:237], off
	s_mov_b32 m0, s57
	v_lshl_add_u64 v[236:237], v[134:135], 0, v[172:173]
	global_load_lds_dwordx4 v[236:237], off
	s_waitcnt vmcnt(8) lgkmcnt(0)
	s_setprio 1
	s_barrier
	v_mfma_f32_16x16x32_bf16 v[124:127], v[136:139], v[194:197], v[124:127]
	v_mfma_f32_16x16x32_bf16 v[128:131], v[144:147], v[194:197], v[128:131]
	v_mfma_f32_16x16x32_bf16 v[112:115], v[136:139], v[210:213], v[112:115]
	v_mfma_f32_16x16x32_bf16 v[108:111], v[144:147], v[210:213], v[108:111]
	v_mfma_f32_16x16x32_bf16 v[96:99], v[136:139], v[220:223], v[96:99]
	v_mfma_f32_16x16x32_bf16 v[92:95], v[144:147], v[220:223], v[92:95]
	v_mfma_f32_16x16x32_bf16 v[80:83], v[136:139], v[228:231], v[80:83]
	v_mfma_f32_16x16x32_bf16 v[76:79], v[144:147], v[228:231], v[76:79]
	v_mfma_f32_16x16x32_bf16 v[124:127], v[140:143], v[206:209], v[124:127]
	v_mfma_f32_16x16x32_bf16 v[128:131], v[148:151], v[206:209], v[128:131]
	v_mfma_f32_16x16x32_bf16 v[112:115], v[140:143], v[216:219], v[112:115]
	v_mfma_f32_16x16x32_bf16 v[108:111], v[148:151], v[216:219], v[108:111]
	v_mfma_f32_16x16x32_bf16 v[96:99], v[140:143], v[224:227], v[96:99]
	v_mfma_f32_16x16x32_bf16 v[92:95], v[148:151], v[224:227], v[92:95]
	v_mfma_f32_16x16x32_bf16 v[80:83], v[140:143], v[232:235], v[80:83]
	v_mfma_f32_16x16x32_bf16 v[76:79], v[148:151], v[232:235], v[76:79]
	v_mfma_f32_16x16x32_bf16 v[120:123], v[152:155], v[194:197], v[120:123]
	v_mfma_f32_16x16x32_bf16 v[116:119], v[186:189], v[194:197], v[116:119]
	v_mfma_f32_16x16x32_bf16 v[104:107], v[152:155], v[210:213], v[104:107]
	v_mfma_f32_16x16x32_bf16 v[100:103], v[186:189], v[210:213], v[100:103]
	v_mfma_f32_16x16x32_bf16 v[88:91], v[152:155], v[220:223], v[88:91]
	v_mfma_f32_16x16x32_bf16 v[84:87], v[186:189], v[220:223], v[84:87]
	v_mfma_f32_16x16x32_bf16 v[72:75], v[152:155], v[228:231], v[72:75]
	v_mfma_f32_16x16x32_bf16 v[68:71], v[186:189], v[228:231], v[68:71]
	v_mfma_f32_16x16x32_bf16 v[120:123], v[182:185], v[206:209], v[120:123]
	v_mfma_f32_16x16x32_bf16 v[116:119], v[190:193], v[206:209], v[116:119]
	v_mfma_f32_16x16x32_bf16 v[104:107], v[182:185], v[216:219], v[104:107]
	v_mfma_f32_16x16x32_bf16 v[100:103], v[190:193], v[216:219], v[100:103]
	v_mfma_f32_16x16x32_bf16 v[88:91], v[182:185], v[224:227], v[88:91]
	v_mfma_f32_16x16x32_bf16 v[84:87], v[190:193], v[224:227], v[84:87]
	v_mfma_f32_16x16x32_bf16 v[72:75], v[182:185], v[232:235], v[72:75]
	v_mfma_f32_16x16x32_bf16 v[68:71], v[190:193], v[232:235], v[68:71]
	s_setprio 0
	s_barrier
	s_mov_b32 m0, s58
	v_lshl_add_u64 v[236:237], v[214:215], 0, v[166:167]
	ds_read_b128 v[194:197], v203 offset:16384
	ds_read_b128 v[206:209], v203 offset:17408
	ds_read_b128 v[210:213], v203 offset:18432
	ds_read_b128 v[216:219], v203 offset:19456
	ds_read_b128 v[220:223], v203 offset:20480
	ds_read_b128 v[224:227], v203 offset:21504
	ds_read_b128 v[228:231], v203 offset:22528
	ds_read_b128 v[232:235], v203 offset:23552
	global_load_lds_dwordx4 v[236:237], off
	v_lshl_add_u64 v[238:239], v[214:215], 0, v[170:171]
	s_mov_b32 m0, s59
	v_lshl_add_u64 v[214:215], v[214:215], 0, s[14:15]
	s_add_i32 s13, s55, s30
	global_load_lds_dwordx4 v[238:239], off
	v_lshl_add_u64 v[240:241], v[214:215], 0, v[166:167]
	s_mov_b32 m0, s13
	v_lshl_add_u64 v[214:215], v[214:215], 0, v[170:171]
	global_load_lds_dwordx4 v[240:241], off
	s_add_i32 m0, s13, 0x2000
	v_lshl_add_u64 v[242:243], v[198:199], 0, v[164:165]
	global_load_lds_dwordx4 v[214:215], off
	s_mov_b32 m0, s31
	v_lshl_add_u64 v[244:245], v[198:199], 0, v[168:169]
	global_load_lds_dwordx4 v[242:243], off
	s_nop 0
	s_waitcnt vmcnt(7) lgkmcnt(0)
	s_setprio 1
	s_barrier
; #define PG8_STAGE(bufoff, gbase, voff) do { _Pragma("unroll") for (int _i = 0; _i < 2; ++_i) \
;         __builtin_amdgcn_global_load_lds((const unsigned*)((const char*)(gbase) + (voff)[_i]), (PG8_LAS unsigned*)(lds + (bufoff) + ldsw + _i * 8192), 16, 0, 0); } while (0)
; #define PG8_LDA(dst, b, h) do { _Pragma("unroll") for (int m = 0; m < 4; ++m) _Pragma("unroll") for (int k = 0; k < 2; ++k) dst[m][k] = *(const PG8_LAS bf16x8*)(lds + PG8_SA(b, h) + aoff + m * 2048 + k * 1024); } while (0)
; #define PG8_LDB(dst, b, h) do { _Pragma("unroll") for (int n = 0; n < 2; ++n) _Pragma("unroll") for (int k = 0; k < 2; ++k) dst[n][k] = *(const PG8_LAS bf16x8*)(lds + PG8_SB(b, h) + boff + n * 2048 + k * 1024); } while (0)
; #define PG8_MMA(ai, bj, At, Bt) do { __builtin_amdgcn_s_setprio(1); _Pragma("unroll") for (int m = 0; m < 4; ++m) _Pragma("unroll") for (int n = 0; n < 2; ++n) _Pragma("unroll") for (int k = 0; k < 2; ++k) \
;         acc[ai][bj][m][n] = __builtin_amdgcn_mfma_f32_16x16x32_bf16(Bt[n][k], At[m][k], acc[ai][bj][m][n], 0, 0, 0); __builtin_amdgcn_s_setprio(0); } while (0)
; #define PG8_WAIT_V(n) asm volatile("s_waitcnt vmcnt(" #n ")" ::: "memory")
; #define PG8_WAIT_L(n) asm volatile("s_waitcnt lgkmcnt(" #n ")" ::: "memory")
; #define PG8_BAR __builtin_amdgcn_s_barrier()
; #define PG8_SCHED __builtin_amdgcn_sched_barrier(0)
; template <class Epi, class Sched, bool ALIGN_EPI = false, bool SP2 = false>
; __device__ __forceinline__ void gemm_phase(PG8_LAS unsigned char* lds, const Gemm g, const Sched& S, const Epi& E) {
;     ...
;             PG8_WAIT_V(8); PG8_WAIT_L(0); PG8_BAR; PG8_MMA(1, 0, At, B0); PG8_MMA(1, 1, At, B1); PG8_BAR; PG8_SCHED;
;             PG8_LDB(B0, 1, 0); PG8_LDB(B1, 1, 1); PG8_SCHED; PG8_LDA(At, 1, 0); PG8_STAGE(PG8_SA(0, 1), a2 + hstep, voffA);
;             PG8_WAIT_V(8); PG8_WAIT_L(0); PG8_BAR; PG8_MMA(0, 0, At, B0); PG8_MMA(0, 1, At, B1); PG8_BAR; PG8_SCHED;
	v_mfma_f32_16x16x32_bf16 v[64:67], v[136:139], v[194:197], v[64:67]
	v_mfma_f32_16x16x32_bf16 v[60:63], v[144:147], v[194:197], v[60:63]
	v_mfma_f32_16x16x32_bf16 v[48:51], v[136:139], v[210:213], v[48:51]
	v_mfma_f32_16x16x32_bf16 v[44:47], v[144:147], v[210:213], v[44:47]
	v_mfma_f32_16x16x32_bf16 v[32:35], v[136:139], v[220:223], v[32:35]
	v_mfma_f32_16x16x32_bf16 v[28:31], v[144:147], v[220:223], v[28:31]
	v_mfma_f32_16x16x32_bf16 v[16:19], v[136:139], v[228:231], v[16:19]
	v_mfma_f32_16x16x32_bf16 v[12:15], v[144:147], v[228:231], v[12:15]
	v_mfma_f32_16x16x32_bf16 v[64:67], v[140:143], v[206:209], v[64:67]
	v_mfma_f32_16x16x32_bf16 v[60:63], v[148:151], v[206:209], v[60:63]
	v_mfma_f32_16x16x32_bf16 v[48:51], v[140:143], v[216:219], v[48:51]
	v_mfma_f32_16x16x32_bf16 v[44:47], v[148:151], v[216:219], v[44:47]
	v_mfma_f32_16x16x32_bf16 v[32:35], v[140:143], v[224:227], v[32:35]
	v_mfma_f32_16x16x32_bf16 v[28:31], v[148:151], v[224:227], v[28:31]
	v_mfma_f32_16x16x32_bf16 v[16:19], v[140:143], v[232:235], v[16:19]
	v_mfma_f32_16x16x32_bf16 v[12:15], v[148:151], v[232:235], v[12:15]
	v_mfma_f32_16x16x32_bf16 v[56:59], v[152:155], v[194:197], v[56:59]
	v_mfma_f32_16x16x32_bf16 v[52:55], v[186:189], v[194:197], v[52:55]
	v_mfma_f32_16x16x32_bf16 v[40:43], v[152:155], v[210:213], v[40:43]
	v_mfma_f32_16x16x32_bf16 v[36:39], v[186:189], v[210:213], v[36:39]
	v_mfma_f32_16x16x32_bf16 v[24:27], v[152:155], v[220:223], v[24:27]
	v_mfma_f32_16x16x32_bf16 v[20:23], v[186:189], v[220:223], v[20:23]
	v_mfma_f32_16x16x32_bf16 v[8:11], v[152:155], v[228:231], v[8:11]
	v_mfma_f32_16x16x32_bf16 v[4:7], v[186:189], v[228:231], v[4:7]
	v_mfma_f32_16x16x32_bf16 v[56:59], v[182:185], v[206:209], v[56:59]
	v_mfma_f32_16x16x32_bf16 v[52:55], v[190:193], v[206:209], v[52:55]
	v_mfma_f32_16x16x32_bf16 v[40:43], v[182:185], v[216:219], v[40:43]
	v_mfma_f32_16x16x32_bf16 v[36:39], v[190:193], v[216:219], v[36:39]
	v_mfma_f32_16x16x32_bf16 v[24:27], v[182:185], v[224:227], v[24:27]
	v_mfma_f32_16x16x32_bf16 v[20:23], v[190:193], v[224:227], v[20:23]
	v_mfma_f32_16x16x32_bf16 v[8:11], v[182:185], v[232:235], v[8:11]
	v_mfma_f32_16x16x32_bf16 v[4:7], v[190:193], v[232:235], v[4:7]
	s_setprio 0
	s_barrier
	s_add_i32 s13, 0, 0x18000
	s_add_i32 s29, 0, 0x1c000
	v_add_u32_e32 v148, s13, v201
	v_add_u32_e32 v190, s29, v201
	s_mov_b32 m0, s34
	ds_read_b128 v[136:139], v148
	global_load_lds_dwordx4 v[244:245], off
	ds_read_b128 v[140:143], v148 offset:1024
	ds_read_b128 v[144:147], v148 offset:2048
	ds_read_b128 v[148:151], v148 offset:3072
	ds_read_b128 v[152:155], v190
	ds_read_b128 v[182:185], v190 offset:1024
	ds_read_b128 v[186:189], v190 offset:2048
	ds_read_b128 v[190:193], v190 offset:3072
	v_lshl_add_u64 v[198:199], v[198:199], 0, s[14:15]
	s_mov_b32 m0, s35
	v_lshl_add_u64 v[246:247], v[198:199], 0, v[164:165]
	ds_read_b128 v[194:197], v203 offset:32768
	ds_read_b128 v[206:209], v203 offset:33792
	ds_read_b128 v[210:213], v203 offset:34816
	ds_read_b128 v[216:219], v203 offset:35840
	ds_read_b128 v[220:223], v203 offset:36864
	ds_read_b128 v[224:227], v203 offset:37888
	ds_read_b128 v[228:231], v203 offset:38912
	ds_read_b128 v[232:235], v203 offset:39936
	global_load_lds_dwordx4 v[246:247], off
	s_mov_b32 m0, s36
	v_lshl_add_u64 v[198:199], v[198:199], 0, v[168:169]
	global_load_lds_dwordx4 v[198:199], off
	s_waitcnt vmcnt(8) lgkmcnt(0)
	s_setprio 1
	s_barrier
	v_mfma_f32_16x16x32_bf16 v[124:127], v[136:139], v[194:197], v[124:127]
	v_mfma_f32_16x16x32_bf16 v[128:131], v[144:147], v[194:197], v[128:131]
	v_mfma_f32_16x16x32_bf16 v[112:115], v[136:139], v[210:213], v[112:115]
	v_mfma_f32_16x16x32_bf16 v[108:111], v[144:147], v[210:213], v[108:111]
	v_mfma_f32_16x16x32_bf16 v[96:99], v[136:139], v[220:223], v[96:99]
	v_mfma_f32_16x16x32_bf16 v[92:95], v[144:147], v[220:223], v[92:95]
	v_mfma_f32_16x16x32_bf16 v[80:83], v[136:139], v[228:231], v[80:83]
	v_mfma_f32_16x16x32_bf16 v[76:79], v[144:147], v[228:231], v[76:79]
	v_mfma_f32_16x16x32_bf16 v[124:127], v[140:143], v[206:209], v[124:127]
	v_mfma_f32_16x16x32_bf16 v[128:131], v[148:151], v[206:209], v[128:131]
	v_mfma_f32_16x16x32_bf16 v[112:115], v[140:143], v[216:219], v[112:115]
	v_mfma_f32_16x16x32_bf16 v[108:111], v[148:151], v[216:219], v[108:111]
	v_mfma_f32_16x16x32_bf16 v[96:99], v[140:143], v[224:227], v[96:99]
	v_mfma_f32_16x16x32_bf16 v[92:95], v[148:151], v[224:227], v[92:95]
	v_mfma_f32_16x16x32_bf16 v[80:83], v[140:143], v[232:235], v[80:83]
	v_mfma_f32_16x16x32_bf16 v[76:79], v[148:151], v[232:235], v[76:79]
	v_mfma_f32_16x16x32_bf16 v[120:123], v[152:155], v[194:197], v[120:123]
	v_mfma_f32_16x16x32_bf16 v[116:119], v[186:189], v[194:197], v[116:119]
	v_mfma_f32_16x16x32_bf16 v[104:107], v[152:155], v[210:213], v[104:107]
	v_mfma_f32_16x16x32_bf16 v[100:103], v[186:189], v[210:213], v[100:103]
	v_mfma_f32_16x16x32_bf16 v[88:91], v[152:155], v[220:223], v[88:91]
	v_mfma_f32_16x16x32_bf16 v[84:87], v[186:189], v[220:223], v[84:87]
	v_mfma_f32_16x16x32_bf16 v[72:75], v[152:155], v[228:231], v[72:75]
	v_mfma_f32_16x16x32_bf16 v[68:71], v[186:189], v[228:231], v[68:71]
	v_mfma_f32_16x16x32_bf16 v[120:123], v[182:185], v[206:209], v[120:123]
	v_mfma_f32_16x16x32_bf16 v[116:119], v[190:193], v[206:209], v[116:119]
	v_mfma_f32_16x16x32_bf16 v[104:107], v[182:185], v[216:219], v[104:107]
	v_mfma_f32_16x16x32_bf16 v[100:103], v[190:193], v[216:219], v[100:103]
	v_mfma_f32_16x16x32_bf16 v[88:91], v[182:185], v[224:227], v[88:91]
	v_mfma_f32_16x16x32_bf16 v[84:87], v[190:193], v[224:227], v[84:87]
	v_mfma_f32_16x16x32_bf16 v[72:75], v[182:185], v[232:235], v[72:75]
	v_mfma_f32_16x16x32_bf16 v[68:71], v[190:193], v[232:235], v[68:71]
	s_setprio 0
	s_barrier
; #define PG8_STAGE(bufoff, gbase, voff) do { _Pragma("unroll") for (int _i = 0; _i < 2; ++_i) \
;         __builtin_amdgcn_global_load_lds((const unsigned*)((const char*)(gbase) + (voff)[_i]), (PG8_LAS unsigned*)(lds + (bufoff) + ldsw + _i * 8192), 16, 0, 0); } while (0)
; #define PG8_LDA(dst, b, h) do { _Pragma("unroll") for (int m = 0; m < 4; ++m) _Pragma("unroll") for (int k = 0; k < 2; ++k) dst[m][k] = *(const PG8_LAS bf16x8*)(lds + PG8_SA(b, h) + aoff + m * 2048 + k * 1024); } while (0)
; #define PG8_MMA(ai, bj, At, Bt) do { __builtin_amdgcn_s_setprio(1); _Pragma("unroll") for (int m = 0; m < 4; ++m) _Pragma("unroll") for (int n = 0; n < 2; ++n) _Pragma("unroll") for (int k = 0; k < 2; ++k) \
;         acc[ai][bj][m][n] = __builtin_amdgcn_mfma_f32_16x16x32_bf16(Bt[n][k], At[m][k], acc[ai][bj][m][n], 0, 0, 0); __builtin_amdgcn_s_setprio(0); } while (0)
; #define PG8_WAIT_V(n) asm volatile("s_waitcnt vmcnt(" #n ")" ::: "memory")
; #define PG8_WAIT_L(n) asm volatile("s_waitcnt lgkmcnt(" #n ")" ::: "memory")
; #define PG8_BAR __builtin_amdgcn_s_barrier()
; #define PG8_SCHED __builtin_amdgcn_sched_barrier(0)
; template <class Epi, class Sched, bool ALIGN_EPI = false, bool SP2 = false>
; __device__ __forceinline__ void gemm_phase(PG8_LAS unsigned char* lds, const Gemm g, const Sched& S, const Epi& E) {
;     ...
;             PG8_LDA(At, 1, 1); PG8_STAGE(PG8_SB(1, 0), b3, voffB); PG8_STAGE(PG8_SB(1, 1), b3 + hstep, voffB); PG8_STAGE(PG8_SA(1, 0), a3, voffA);
;             PG8_WAIT_V(8); PG8_WAIT_L(0); PG8_BAR; PG8_MMA(1, 0, At, B0); PG8_MMA(1, 1, At, B1); PG8_BAR; PG8_SCHED;
	s_add_i32 s13, s13, s30
	v_lshl_add_u64 v[198:199], v[236:237], 0, s[22:23]
	s_mov_b32 m0, s13
	ds_read_b128 v[194:197], v203 offset:49152
	ds_read_b128 v[206:209], v203 offset:50176
	ds_read_b128 v[210:213], v203 offset:51200
	ds_read_b128 v[216:219], v203 offset:52224
	ds_read_b128 v[220:223], v203 offset:53248
	ds_read_b128 v[224:227], v203 offset:54272
	ds_read_b128 v[228:231], v203 offset:55296
	ds_read_b128 v[232:235], v203 offset:56320
	global_load_lds_dwordx4 v[198:199], off
	v_lshl_add_u64 v[198:199], v[238:239], 0, s[22:23]
	s_add_i32 m0, s13, 0x2000
	s_add_i32 s13, s29, s30
	global_load_lds_dwordx4 v[198:199], off
	s_mov_b32 m0, s13
	v_lshl_add_u64 v[198:199], v[240:241], 0, s[22:23]
	global_load_lds_dwordx4 v[198:199], off
	s_add_i32 m0, s13, 0x2000
	v_lshl_add_u64 v[198:199], v[214:215], 0, s[22:23]
	global_load_lds_dwordx4 v[198:199], off
	s_mov_b32 m0, s37
	v_lshl_add_u64 v[198:199], v[242:243], 0, s[22:23]
	global_load_lds_dwordx4 v[198:199], off
	s_mov_b32 m0, s41
	v_lshl_add_u64 v[198:199], v[244:245], 0, s[22:23]
	global_load_lds_dwordx4 v[198:199], off
	s_waitcnt vmcnt(8) lgkmcnt(0)
	s_setprio 1
	s_barrier
	v_mfma_f32_16x16x32_bf16 v[64:67], v[136:139], v[194:197], v[64:67]
	v_mfma_f32_16x16x32_bf16 v[60:63], v[144:147], v[194:197], v[60:63]
	v_mfma_f32_16x16x32_bf16 v[48:51], v[136:139], v[210:213], v[48:51]
	v_mfma_f32_16x16x32_bf16 v[44:47], v[144:147], v[210:213], v[44:47]
	v_mfma_f32_16x16x32_bf16 v[32:35], v[136:139], v[220:223], v[32:35]
	v_mfma_f32_16x16x32_bf16 v[28:31], v[144:147], v[220:223], v[28:31]
	v_mfma_f32_16x16x32_bf16 v[16:19], v[136:139], v[228:231], v[16:19]
	v_mfma_f32_16x16x32_bf16 v[12:15], v[144:147], v[228:231], v[12:15]
	v_mfma_f32_16x16x32_bf16 v[64:67], v[140:143], v[206:209], v[64:67]
	v_mfma_f32_16x16x32_bf16 v[60:63], v[148:151], v[206:209], v[60:63]
	v_mfma_f32_16x16x32_bf16 v[48:51], v[140:143], v[216:219], v[48:51]
	v_mfma_f32_16x16x32_bf16 v[44:47], v[148:151], v[216:219], v[44:47]
	v_mfma_f32_16x16x32_bf16 v[32:35], v[140:143], v[224:227], v[32:35]
	v_mfma_f32_16x16x32_bf16 v[28:31], v[148:151], v[224:227], v[28:31]
	v_mfma_f32_16x16x32_bf16 v[16:19], v[140:143], v[232:235], v[16:19]
	v_mfma_f32_16x16x32_bf16 v[12:15], v[148:151], v[232:235], v[12:15]
	v_mfma_f32_16x16x32_bf16 v[56:59], v[152:155], v[194:197], v[56:59]
	v_mfma_f32_16x16x32_bf16 v[52:55], v[186:189], v[194:197], v[52:55]
	v_mfma_f32_16x16x32_bf16 v[40:43], v[152:155], v[210:213], v[40:43]
	v_mfma_f32_16x16x32_bf16 v[36:39], v[186:189], v[210:213], v[36:39]
	v_mfma_f32_16x16x32_bf16 v[24:27], v[152:155], v[220:223], v[24:27]
	v_mfma_f32_16x16x32_bf16 v[20:23], v[186:189], v[220:223], v[20:23]
	v_mfma_f32_16x16x32_bf16 v[8:11], v[152:155], v[228:231], v[8:11]
	v_mfma_f32_16x16x32_bf16 v[4:7], v[186:189], v[228:231], v[4:7]
	v_mfma_f32_16x16x32_bf16 v[56:59], v[182:185], v[206:209], v[56:59]
	v_mfma_f32_16x16x32_bf16 v[52:55], v[190:193], v[206:209], v[52:55]
	v_mfma_f32_16x16x32_bf16 v[40:43], v[182:185], v[216:219], v[40:43]
	v_mfma_f32_16x16x32_bf16 v[36:39], v[190:193], v[216:219], v[36:39]
	v_mfma_f32_16x16x32_bf16 v[24:27], v[182:185], v[224:227], v[24:27]
	v_mfma_f32_16x16x32_bf16 v[20:23], v[190:193], v[224:227], v[20:23]
	v_mfma_f32_16x16x32_bf16 v[8:11], v[182:185], v[232:235], v[8:11]
	v_mfma_f32_16x16x32_bf16 v[4:7], v[190:193], v[232:235], v[4:7]
	s_setprio 0
	s_barrier
	v_lshl_add_u64 v[132:133], v[132:133], 0, s[26:27]
	s_cmp_ge_i32 s12, s47
	v_lshl_add_u64 v[134:135], v[134:135], 0, s[26:27]
	s_cbranch_scc0 .LBB0_371

; #define PG8_STAGE(bufoff, gbase, voff) do { _Pragma("unroll") for (int _i = 0; _i < 2; ++_i) \
;         __builtin_amdgcn_global_load_lds((const unsigned*)((const char*)(gbase) + (voff)[_i]), (PG8_LAS unsigned*)(lds + (bufoff) + ldsw + _i * 8192), 16, 0, 0); } while (0)
; #define PG8_LDA(dst, b, h) do { _Pragma("unroll") for (int m = 0; m < 4; ++m) _Pragma("unroll") for (int k = 0; k < 2; ++k) dst[m][k] = *(const PG8_LAS bf16x8*)(lds + PG8_SA(b, h) + aoff + m * 2048 + k * 1024); } while (0)
; #define PG8_LDB(dst, b, h) do { _Pragma("unroll") for (int n = 0; n < 2; ++n) _Pragma("unroll") for (int k = 0; k < 2; ++k) dst[n][k] = *(const PG8_LAS bf16x8*)(lds + PG8_SB(b, h) + boff + n * 2048 + k * 1024); } while (0)
; #define PG8_MMA(ai, bj, At, Bt) do { __builtin_amdgcn_s_setprio(1); _Pragma("unroll") for (int m = 0; m < 4; ++m) _Pragma("unroll") for (int n = 0; n < 2; ++n) _Pragma("unroll") for (int k = 0; k < 2; ++k) \
;         acc[ai][bj][m][n] = __builtin_amdgcn_mfma_f32_16x16x32_bf16(Bt[n][k], At[m][k], acc[ai][bj][m][n], 0, 0, 0); __builtin_amdgcn_s_setprio(0); } while (0)
; #define PG8_WAIT_V(n) asm volatile("s_waitcnt vmcnt(" #n ")" ::: "memory")
; #define PG8_WAIT_L(n) asm volatile("s_waitcnt lgkmcnt(" #n ")" ::: "memory")
; #define PG8_BAR __builtin_amdgcn_s_barrier()
; #define PG8_SCHED __builtin_amdgcn_sched_barrier(0)
; template <class Epi, class Sched, bool ALIGN_EPI = false, bool SP2 = false>
; __device__ __forceinline__ void gemm_phase(PG8_LAS unsigned char* lds, const Gemm g, const Sched& S, const Epi& E) {
;     ...
;             PG8_LDA(At, 0, 1); PG8_STAGE(PG8_SB(0, 0), b2, voffB); PG8_STAGE(PG8_SB(0, 1), b2 + hstep, voffB); PG8_STAGE(PG8_SA(0, 0), a2, voffA);
;             PG8_WAIT_V(8); PG8_WAIT_L(0); PG8_BAR; PG8_MMA(1, 0, At, B0); PG8_MMA(1, 1, At, B1); PG8_BAR; PG8_SCHED;
;             PG8_LDB(B0, 1, 0); PG8_LDB(B1, 1, 1); PG8_SCHED; PG8_LDA(At, 1, 0); PG8_STAGE(PG8_SA(0, 1), a2 + hstep, voffA);
;             PG8_WAIT_V(8); PG8_WAIT_L(0); PG8_BAR; PG8_MMA(0, 0, At, B0); PG8_MMA(0, 1, At, B1); PG8_BAR; PG8_SCHED;
.Lie_skipk0:
	s_setprio 0
	s_barrier
	s_add_i32 s13, s69, s37
	v_lshl_add_u64 v[214:215], v[212:213], 0, v[146:147]
	s_mov_b32 m0, s13
	ds_read_b128 v[200:203], v216 offset:16384
	ds_read_b128 v[204:207], v216 offset:17408
	ds_read_b128 v[218:221], v216 offset:18432
	ds_read_b128 v[222:225], v216 offset:19456
	ds_read_b128 v[226:229], v216 offset:20480
	ds_read_b128 v[230:233], v216 offset:21504
	ds_read_b128 v[234:237], v216 offset:22528
	ds_read_b128 v[238:241], v216 offset:23552
	global_load_lds_dwordx4 v[214:215], off
	v_lshl_add_u64 v[242:243], v[212:213], 0, v[150:151]
	s_add_i32 m0, s13, 0x2000
	v_lshl_add_u64 v[212:213], v[212:213], 0, s[16:17]
	s_add_i32 s13, s70, s37
	global_load_lds_dwordx4 v[242:243], off
	v_lshl_add_u64 v[244:245], v[212:213], 0, v[146:147]
	s_mov_b32 m0, s13
	v_lshl_add_u64 v[212:213], v[212:213], 0, v[150:151]
	global_load_lds_dwordx4 v[244:245], off
	s_add_i32 m0, s13, 0x2000
	v_lshl_add_u64 v[246:247], v[208:209], 0, v[144:145]
	global_load_lds_dwordx4 v[212:213], off
	s_mov_b32 m0, s41
	v_lshl_add_u64 v[248:249], v[208:209], 0, v[148:149]
	global_load_lds_dwordx4 v[246:247], off
	s_nop 0
	s_waitcnt vmcnt(7) lgkmcnt(0)
	s_setprio 1
	s_barrier
	v_mfma_f32_16x16x32_bf16 v[60:63], v[132:135], v[200:203], v[60:63]
	v_mfma_f32_16x16x32_bf16 v[56:59], v[176:179], v[200:203], v[56:59]
	v_mfma_f32_16x16x32_bf16 v[44:47], v[132:135], v[218:221], v[44:47]
	v_mfma_f32_16x16x32_bf16 v[40:43], v[176:179], v[218:221], v[40:43]
	v_mfma_f32_16x16x32_bf16 v[28:31], v[132:135], v[226:229], v[28:31]
	v_mfma_f32_16x16x32_bf16 v[24:27], v[176:179], v[226:229], v[24:27]
	v_mfma_f32_16x16x32_bf16 v[12:15], v[132:135], v[234:237], v[12:15]
	v_mfma_f32_16x16x32_bf16 v[8:11], v[176:179], v[234:237], v[8:11]
	v_mfma_f32_16x16x32_bf16 v[60:63], v[136:139], v[204:207], v[60:63]
	v_mfma_f32_16x16x32_bf16 v[56:59], v[180:183], v[204:207], v[56:59]
	v_mfma_f32_16x16x32_bf16 v[44:47], v[136:139], v[222:225], v[44:47]
	v_mfma_f32_16x16x32_bf16 v[40:43], v[180:183], v[222:225], v[40:43]
	v_mfma_f32_16x16x32_bf16 v[28:31], v[136:139], v[230:233], v[28:31]
	v_mfma_f32_16x16x32_bf16 v[24:27], v[180:183], v[230:233], v[24:27]
	v_mfma_f32_16x16x32_bf16 v[12:15], v[136:139], v[238:241], v[12:15]
	v_mfma_f32_16x16x32_bf16 v[8:11], v[180:183], v[238:241], v[8:11]
	s_cmp_gt_u32 s75, 3
	s_cbranch_scc1 .Lie_skipk1
	v_mfma_f32_16x16x32_bf16 v[52:55], v[184:187], v[200:203], v[52:55]
	v_mfma_f32_16x16x32_bf16 v[48:51], v[192:195], v[200:203], v[48:51]
	v_mfma_f32_16x16x32_bf16 v[36:39], v[184:187], v[218:221], v[36:39]
	v_mfma_f32_16x16x32_bf16 v[32:35], v[192:195], v[218:221], v[32:35]
	v_mfma_f32_16x16x32_bf16 v[20:23], v[184:187], v[226:229], v[20:23]
	v_mfma_f32_16x16x32_bf16 v[16:19], v[192:195], v[226:229], v[16:19]
	v_mfma_f32_16x16x32_bf16 v[4:7], v[184:187], v[234:237], v[4:7]
	v_mfma_f32_16x16x32_bf16 v[0:3], v[192:195], v[234:237], v[0:3]
	v_mfma_f32_16x16x32_bf16 v[52:55], v[188:191], v[204:207], v[52:55]
	v_mfma_f32_16x16x32_bf16 v[48:51], v[196:199], v[204:207], v[48:51]
	v_mfma_f32_16x16x32_bf16 v[36:39], v[188:191], v[222:225], v[36:39]
	v_mfma_f32_16x16x32_bf16 v[32:35], v[196:199], v[222:225], v[32:35]
	v_mfma_f32_16x16x32_bf16 v[20:23], v[188:191], v[230:233], v[20:23]
	v_mfma_f32_16x16x32_bf16 v[16:19], v[196:199], v[230:233], v[16:19]
	v_mfma_f32_16x16x32_bf16 v[4:7], v[188:191], v[238:241], v[4:7]
	v_mfma_f32_16x16x32_bf16 v[0:3], v[196:199], v[238:241], v[0:3]
.Lie_skipk1:
	s_setprio 0
	s_barrier
	s_add_i32 s13, 0, 0x18000
	v_add_u32_e32 v165, s13, v171
	s_add_i32 s15, 0, 0x1c000
	s_mov_b32 m0, s50
	ds_read_b128 v[132:135], v165
	global_load_lds_dwordx4 v[248:249], off
	ds_read_b128 v[136:139], v165 offset:1024
	ds_read_b128 v[176:179], v165 offset:2048
	ds_read_b128 v[180:183], v165 offset:3072
	v_add_u32_e32 v165, s15, v171
	ds_read_b128 v[184:187], v165
	ds_read_b128 v[188:191], v165 offset:1024
	ds_read_b128 v[192:195], v165 offset:2048
	ds_read_b128 v[196:199], v165 offset:3072
	v_lshl_add_u64 v[208:209], v[208:209], 0, s[16:17]
	s_mov_b32 m0, s52
	v_lshl_add_u64 v[250:251], v[208:209], 0, v[144:145]
	ds_read_b128 v[200:203], v216 offset:32768
	ds_read_b128 v[204:207], v216 offset:33792
	ds_read_b128 v[218:221], v216 offset:34816
	ds_read_b128 v[222:225], v216 offset:35840
	ds_read_b128 v[226:229], v216 offset:36864
	ds_read_b128 v[230:233], v216 offset:37888
	ds_read_b128 v[234:237], v216 offset:38912
	ds_read_b128 v[238:241], v216 offset:39936
	global_load_lds_dwordx4 v[250:251], off
	s_mov_b32 m0, s53
	v_lshl_add_u64 v[208:209], v[208:209], 0, v[148:149]
	global_load_lds_dwordx4 v[208:209], off
	s_waitcnt vmcnt(8) lgkmcnt(0)
	s_setprio 1
	s_barrier
	v_mfma_f32_16x16x32_bf16 v[124:127], v[132:135], v[200:203], v[124:127]
	v_mfma_f32_16x16x32_bf16 v[120:123], v[176:179], v[200:203], v[120:123]
	v_mfma_f32_16x16x32_bf16 v[108:111], v[132:135], v[218:221], v[108:111]
	v_mfma_f32_16x16x32_bf16 v[104:107], v[176:179], v[218:221], v[104:107]
	v_mfma_f32_16x16x32_bf16 v[92:95], v[132:135], v[226:229], v[92:95]
	v_mfma_f32_16x16x32_bf16 v[88:91], v[176:179], v[226:229], v[88:91]
	v_mfma_f32_16x16x32_bf16 v[76:79], v[132:135], v[234:237], v[76:79]
	v_mfma_f32_16x16x32_bf16 v[72:75], v[176:179], v[234:237], v[72:75]
	v_mfma_f32_16x16x32_bf16 v[124:127], v[136:139], v[204:207], v[124:127]
	v_mfma_f32_16x16x32_bf16 v[120:123], v[180:183], v[204:207], v[120:123]
	v_mfma_f32_16x16x32_bf16 v[108:111], v[136:139], v[222:225], v[108:111]
	v_mfma_f32_16x16x32_bf16 v[104:107], v[180:183], v[222:225], v[104:107]
	v_mfma_f32_16x16x32_bf16 v[92:95], v[136:139], v[230:233], v[92:95]
	v_mfma_f32_16x16x32_bf16 v[88:91], v[180:183], v[230:233], v[88:91]
	v_mfma_f32_16x16x32_bf16 v[76:79], v[136:139], v[238:241], v[76:79]
	v_mfma_f32_16x16x32_bf16 v[72:75], v[180:183], v[238:241], v[72:75]
	s_cmp_gt_u32 s75, 3
	s_cbranch_scc1 .Lie_skipk2
	v_mfma_f32_16x16x32_bf16 v[116:119], v[184:187], v[200:203], v[116:119]
	v_mfma_f32_16x16x32_bf16 v[112:115], v[192:195], v[200:203], v[112:115]
	v_mfma_f32_16x16x32_bf16 v[100:103], v[184:187], v[218:221], v[100:103]
	v_mfma_f32_16x16x32_bf16 v[96:99], v[192:195], v[218:221], v[96:99]
	v_mfma_f32_16x16x32_bf16 v[84:87], v[184:187], v[226:229], v[84:87]
	v_mfma_f32_16x16x32_bf16 v[80:83], v[192:195], v[226:229], v[80:83]
	v_mfma_f32_16x16x32_bf16 v[68:71], v[184:187], v[234:237], v[68:71]
	v_mfma_f32_16x16x32_bf16 v[64:67], v[192:195], v[234:237], v[64:67]
	v_mfma_f32_16x16x32_bf16 v[116:119], v[188:191], v[204:207], v[116:119]
	v_mfma_f32_16x16x32_bf16 v[112:115], v[196:199], v[204:207], v[112:115]
	v_mfma_f32_16x16x32_bf16 v[100:103], v[188:191], v[222:225], v[100:103]
	v_mfma_f32_16x16x32_bf16 v[96:99], v[196:199], v[222:225], v[96:99]
	v_mfma_f32_16x16x32_bf16 v[84:87], v[188:191], v[230:233], v[84:87]
	v_mfma_f32_16x16x32_bf16 v[80:83], v[196:199], v[230:233], v[80:83]
	v_mfma_f32_16x16x32_bf16 v[68:71], v[188:191], v[238:241], v[68:71]
	v_mfma_f32_16x16x32_bf16 v[64:67], v[196:199], v[238:241], v[64:67]

; #define PG8_STAGE(bufoff, gbase, voff) do { _Pragma("unroll") for (int _i = 0; _i < 2; ++_i) \
;         __builtin_amdgcn_global_load_lds((const unsigned*)((const char*)(gbase) + (voff)[_i]), (PG8_LAS unsigned*)(lds + (bufoff) + ldsw + _i * 8192), 16, 0, 0); } while (0)
; #define PG8_LDA(dst, b, h) do { _Pragma("unroll") for (int m = 0; m < 4; ++m) _Pragma("unroll") for (int k = 0; k < 2; ++k) dst[m][k] = *(const PG8_LAS bf16x8*)(lds + PG8_SA(b, h) + aoff + m * 2048 + k * 1024); } while (0)
; #define PG8_LDB(dst, b, h) do { _Pragma("unroll") for (int n = 0; n < 2; ++n) _Pragma("unroll") for (int k = 0; k < 2; ++k) dst[n][k] = *(const PG8_LAS bf16x8*)(lds + PG8_SB(b, h) + boff + n * 2048 + k * 1024); } while (0)
; #define PG8_MMA(ai, bj, At, Bt) do { __builtin_amdgcn_s_setprio(1); _Pragma("unroll") for (int m = 0; m < 4; ++m) _Pragma("unroll") for (int n = 0; n < 2; ++n) _Pragma("unroll") for (int k = 0; k < 2; ++k) \
;         acc[ai][bj][m][n] = __builtin_amdgcn_mfma_f32_16x16x32_bf16(Bt[n][k], At[m][k], acc[ai][bj][m][n], 0, 0, 0); __builtin_amdgcn_s_setprio(0); } while (0)
; #define PG8_WAIT_V(n) asm volatile("s_waitcnt vmcnt(" #n ")" ::: "memory")
; #define PG8_WAIT_L(n) asm volatile("s_waitcnt lgkmcnt(" #n ")" ::: "memory")
; template <class Epi, class Sched, bool ALIGN_EPI = false, bool SP2 = false>
; __device__ __forceinline__ void gemm_phase(PG8_LAS unsigned char* lds, const Gemm g, const Sched& S, const Epi& E) {
;     ...
;             const bool last = (t == nt - 2);
;             const char* a1 = cA + (size_t)(t + 1) * kstep;
;             const char* a2 = last ? nA : cA + (size_t)(t + 2) * kstep; const char* b2 = last ? nB : cB + (size_t)(t + 2) * kstep;
;             const char* a3 = a2 + kstep; const char* b3 = b2 + kstep;
;             if (last && has_next) S.a_ready(nxt);
;             if constexpr (SP2) {
;             PG8_LDB(B0, 0, 0); PG8_LDB(B1, 0, 1); PG8_SCHED; PG8_LDA(At, 0, 0); PG8_STAGE(PG8_SA(1, 1), a1 + hstep, voffA);
;             PG8_WAIT_V(8); PG8_WAIT_L(0); PG8_BAR; PG8_MMA(0, 0, At, B0); PG8_MMA(0, 1, At, B1); PG8_BAR; PG8_SCHED;
;             PG8_LDA(At, 0, 1); PG8_STAGE(PG8_SB(0, 0), b2, voffB); PG8_STAGE(PG8_SB(0, 1), b2 + hstep, voffB); PG8_STAGE(PG8_SA(0, 0), a2, voffA);
;             PG8_WAIT_V(8); PG8_WAIT_L(0); PG8_BAR; PG8_MMA(1, 0, At, B0); PG8_MMA(1, 1, At, B1); PG8_BAR; PG8_SCHED;
.LBB0_635:
	v_add_u32_e32 v144, s64, v209
	v_add_u32_e32 v194, s65, v209
	ds_read_b128 v[92:95], v144
	ds_read_b128 v[128:131], v144 offset:1024
	ds_read_b128 v[132:135], v144 offset:2048
	ds_read_b128 v[144:147], v144 offset:3072
	ds_read_b128 v[148:151], v194
	ds_read_b128 v[152:155], v194 offset:1024
	ds_read_b128 v[190:193], v194 offset:2048
	ds_read_b128 v[194:197], v194 offset:3072
	s_cmp_eq_u32 s58, s10
	v_lshl_add_u64 v[198:199], v[90:91], 0, s[24:25]
	s_cselect_b64 vcc, -1, 0
	s_add_i32 s10, s10, 2
	v_cndmask_b32_e32 v207, v199, v187, vcc
	v_cndmask_b32_e32 v206, v198, v186, vcc
	v_cndmask_b32_e32 v215, v89, v189, vcc
	v_cndmask_b32_e32 v214, v88, v188, vcc
	v_lshl_add_u64 v[238:239], v[90:91], 0, v[180:181]
	s_add_i32 m0, s41, 0xc000
	ds_read_b128 v[198:201], v216
	ds_read_b128 v[202:205], v216 offset:1024
	ds_read_b128 v[210:213], v216 offset:2048
	ds_read_b128 v[218:221], v216 offset:3072
	ds_read_b128 v[222:225], v216 offset:4096
	ds_read_b128 v[226:229], v216 offset:5120
	ds_read_b128 v[230:233], v216 offset:6144
	ds_read_b128 v[234:237], v216 offset:7168
	global_load_lds_dwordx4 v[238:239], off
	s_add_i32 m0, s41, 0xe000
	v_lshl_add_u64 v[238:239], v[90:91], 0, v[178:179]
	global_load_lds_dwordx4 v[238:239], off
	s_waitcnt vmcnt(8) lgkmcnt(0)
	s_setprio 1
	s_barrier
	v_mfma_f32_16x16x32_bf16 v[140:143], v[92:95], v[198:201], v[140:143]
	v_mfma_f32_16x16x32_bf16 v[136:139], v[132:135], v[198:201], v[136:139]
	v_mfma_f32_16x16x32_bf16 v[116:119], v[92:95], v[210:213], v[116:119]
	v_mfma_f32_16x16x32_bf16 v[112:115], v[132:135], v[210:213], v[112:115]
	v_mfma_f32_16x16x32_bf16 v[100:103], v[92:95], v[222:225], v[100:103]
	v_mfma_f32_16x16x32_bf16 v[96:99], v[132:135], v[222:225], v[96:99]
	v_mfma_f32_16x16x32_bf16 v[76:79], v[92:95], v[230:233], v[76:79]
	v_mfma_f32_16x16x32_bf16 v[72:75], v[132:135], v[230:233], v[72:75]
	v_mfma_f32_16x16x32_bf16 v[140:143], v[128:131], v[202:205], v[140:143]
	v_mfma_f32_16x16x32_bf16 v[136:139], v[144:147], v[202:205], v[136:139]
	v_mfma_f32_16x16x32_bf16 v[116:119], v[128:131], v[218:221], v[116:119]
	v_mfma_f32_16x16x32_bf16 v[112:115], v[144:147], v[218:221], v[112:115]
	v_mfma_f32_16x16x32_bf16 v[100:103], v[128:131], v[226:229], v[100:103]
	v_mfma_f32_16x16x32_bf16 v[96:99], v[144:147], v[226:229], v[96:99]
	v_mfma_f32_16x16x32_bf16 v[76:79], v[128:131], v[234:237], v[76:79]
	v_mfma_f32_16x16x32_bf16 v[72:75], v[144:147], v[234:237], v[72:75]
	v_mfma_f32_16x16x32_bf16 v[124:127], v[148:151], v[198:201], v[124:127]
	v_mfma_f32_16x16x32_bf16 v[120:123], v[190:193], v[198:201], v[120:123]
	v_mfma_f32_16x16x32_bf16 v[108:111], v[148:151], v[210:213], v[108:111]
	v_mfma_f32_16x16x32_bf16 v[104:107], v[190:193], v[210:213], v[104:107]
	v_mfma_f32_16x16x32_bf16 v[84:87], v[148:151], v[222:225], v[84:87]
	v_mfma_f32_16x16x32_bf16 v[80:83], v[190:193], v[222:225], v[80:83]
	v_mfma_f32_16x16x32_bf16 v[68:71], v[148:151], v[230:233], v[68:71]
	v_mfma_f32_16x16x32_bf16 v[64:67], v[190:193], v[230:233], v[64:67]
	v_mfma_f32_16x16x32_bf16 v[124:127], v[152:155], v[202:205], v[124:127]
	v_mfma_f32_16x16x32_bf16 v[120:123], v[194:197], v[202:205], v[120:123]
	v_mfma_f32_16x16x32_bf16 v[108:111], v[152:155], v[218:221], v[108:111]
	v_mfma_f32_16x16x32_bf16 v[104:107], v[194:197], v[218:221], v[104:107]
	v_mfma_f32_16x16x32_bf16 v[84:87], v[152:155], v[226:229], v[84:87]
	v_mfma_f32_16x16x32_bf16 v[80:83], v[194:197], v[226:229], v[80:83]
	v_mfma_f32_16x16x32_bf16 v[68:71], v[152:155], v[234:237], v[68:71]
	v_mfma_f32_16x16x32_bf16 v[64:67], v[194:197], v[234:237], v[64:67]
	s_setprio 0
	s_barrier
	s_add_i32 s11, s64, s35
	v_lshl_add_u64 v[238:239], v[214:215], 0, v[168:169]
	s_mov_b32 m0, s11
	ds_read_b128 v[198:201], v216 offset:16384
	ds_read_b128 v[202:205], v216 offset:17408
	ds_read_b128 v[210:213], v216 offset:18432
	ds_read_b128 v[218:221], v216 offset:19456
	ds_read_b128 v[222:225], v216 offset:20480
	ds_read_b128 v[226:229], v216 offset:21504
	ds_read_b128 v[230:233], v216 offset:22528
	ds_read_b128 v[234:237], v216 offset:23552
	global_load_lds_dwordx4 v[238:239], off
	v_lshl_add_u64 v[240:241], v[214:215], 0, v[172:173]
	s_add_i32 m0, s11, 0x2000
	v_lshl_add_u64 v[214:215], v[214:215], 0, s[18:19]
	s_add_i32 s11, s65, s35
	global_load_lds_dwordx4 v[240:241], off
	v_lshl_add_u64 v[242:243], v[214:215], 0, v[168:169]
	s_mov_b32 m0, s11
	v_lshl_add_u64 v[214:215], v[214:215], 0, v[172:173]
	global_load_lds_dwordx4 v[242:243], off
	s_add_i32 m0, s11, 0x2000
	v_lshl_add_u64 v[244:245], v[206:207], 0, v[166:167]
	global_load_lds_dwordx4 v[214:215], off
	s_mov_b32 m0, s41
	v_lshl_add_u64 v[246:247], v[206:207], 0, v[170:171]
	global_load_lds_dwordx4 v[244:245], off
	s_nop 0
	s_waitcnt vmcnt(7) lgkmcnt(0)
	s_setprio 1
	s_barrier
; #define PG8_STAGE(bufoff, gbase, voff) do { _Pragma("unroll") for (int _i = 0; _i < 2; ++_i) \
;         __builtin_amdgcn_global_load_lds((const unsigned*)((const char*)(gbase) + (voff)[_i]), (PG8_LAS unsigned*)(lds + (bufoff) + ldsw + _i * 8192), 16, 0, 0); } while (0)
; #define PG8_LDA(dst, b, h) do { _Pragma("unroll") for (int m = 0; m < 4; ++m) _Pragma("unroll") for (int k = 0; k < 2; ++k) dst[m][k] = *(const PG8_LAS bf16x8*)(lds + PG8_SA(b, h) + aoff + m * 2048 + k * 1024); } while (0)
; #define PG8_LDB(dst, b, h) do { _Pragma("unroll") for (int n = 0; n < 2; ++n) _Pragma("unroll") for (int k = 0; k < 2; ++k) dst[n][k] = *(const PG8_LAS bf16x8*)(lds + PG8_SB(b, h) + boff + n * 2048 + k * 1024); } while (0)
; #define PG8_MMA(ai, bj, At, Bt) do { __builtin_amdgcn_s_setprio(1); _Pragma("unroll") for (int m = 0; m < 4; ++m) _Pragma("unroll") for (int n = 0; n < 2; ++n) _Pragma("unroll") for (int k = 0; k < 2; ++k) \
;         acc[ai][bj][m][n] = __builtin_amdgcn_mfma_f32_16x16x32_bf16(Bt[n][k], At[m][k], acc[ai][bj][m][n], 0, 0, 0); __builtin_amdgcn_s_setprio(0); } while (0)
; #define PG8_WAIT_V(n) asm volatile("s_waitcnt vmcnt(" #n ")" ::: "memory")
; #define PG8_WAIT_L(n) asm volatile("s_waitcnt lgkmcnt(" #n ")" ::: "memory")
; #define PG8_BAR __builtin_amdgcn_s_barrier()
; #define PG8_SCHED __builtin_amdgcn_sched_barrier(0)
; template <class Epi, class Sched, bool ALIGN_EPI = false, bool SP2 = false>
; __device__ __forceinline__ void gemm_phase(PG8_LAS unsigned char* lds, const Gemm g, const Sched& S, const Epi& E) {
;     ...
;             PG8_WAIT_V(8); PG8_WAIT_L(0); PG8_BAR; PG8_MMA(1, 0, At, B0); PG8_MMA(1, 1, At, B1); PG8_BAR; PG8_SCHED;
;             PG8_LDB(B0, 1, 0); PG8_LDB(B1, 1, 1); PG8_SCHED; PG8_LDA(At, 1, 0); PG8_STAGE(PG8_SA(0, 1), a2 + hstep, voffA);
;             PG8_WAIT_V(8); PG8_WAIT_L(0); PG8_BAR; PG8_MMA(0, 0, At, B0); PG8_MMA(0, 1, At, B1); PG8_BAR; PG8_SCHED;
	v_mfma_f32_16x16x32_bf16 v[60:63], v[92:95], v[198:201], v[60:63]
	v_mfma_f32_16x16x32_bf16 v[56:59], v[132:135], v[198:201], v[56:59]
	v_mfma_f32_16x16x32_bf16 v[44:47], v[92:95], v[210:213], v[44:47]
	v_mfma_f32_16x16x32_bf16 v[40:43], v[132:135], v[210:213], v[40:43]
	v_mfma_f32_16x16x32_bf16 v[28:31], v[92:95], v[222:225], v[28:31]
	v_mfma_f32_16x16x32_bf16 v[24:27], v[132:135], v[222:225], v[24:27]
	v_mfma_f32_16x16x32_bf16 v[12:15], v[92:95], v[230:233], v[12:15]
	v_mfma_f32_16x16x32_bf16 v[8:11], v[132:135], v[230:233], v[8:11]
	v_mfma_f32_16x16x32_bf16 v[60:63], v[128:131], v[202:205], v[60:63]
	v_mfma_f32_16x16x32_bf16 v[56:59], v[144:147], v[202:205], v[56:59]
	v_mfma_f32_16x16x32_bf16 v[44:47], v[128:131], v[218:221], v[44:47]
	v_mfma_f32_16x16x32_bf16 v[40:43], v[144:147], v[218:221], v[40:43]
	v_mfma_f32_16x16x32_bf16 v[28:31], v[128:131], v[226:229], v[28:31]
	v_mfma_f32_16x16x32_bf16 v[24:27], v[144:147], v[226:229], v[24:27]
	v_mfma_f32_16x16x32_bf16 v[12:15], v[128:131], v[234:237], v[12:15]
	v_mfma_f32_16x16x32_bf16 v[8:11], v[144:147], v[234:237], v[8:11]
	v_mfma_f32_16x16x32_bf16 v[52:55], v[148:151], v[198:201], v[52:55]
	v_mfma_f32_16x16x32_bf16 v[48:51], v[190:193], v[198:201], v[48:51]
	v_mfma_f32_16x16x32_bf16 v[36:39], v[148:151], v[210:213], v[36:39]
	v_mfma_f32_16x16x32_bf16 v[32:35], v[190:193], v[210:213], v[32:35]
	v_mfma_f32_16x16x32_bf16 v[20:23], v[148:151], v[222:225], v[20:23]
	v_mfma_f32_16x16x32_bf16 v[16:19], v[190:193], v[222:225], v[16:19]
	v_mfma_f32_16x16x32_bf16 v[4:7], v[148:151], v[230:233], v[4:7]
	v_mfma_f32_16x16x32_bf16 v[0:3], v[190:193], v[230:233], v[0:3]
	v_mfma_f32_16x16x32_bf16 v[52:55], v[152:155], v[202:205], v[52:55]
	v_mfma_f32_16x16x32_bf16 v[48:51], v[194:197], v[202:205], v[48:51]
	v_mfma_f32_16x16x32_bf16 v[36:39], v[152:155], v[218:221], v[36:39]
	v_mfma_f32_16x16x32_bf16 v[32:35], v[194:197], v[218:221], v[32:35]
	v_mfma_f32_16x16x32_bf16 v[20:23], v[152:155], v[226:229], v[20:23]
	v_mfma_f32_16x16x32_bf16 v[16:19], v[194:197], v[226:229], v[16:19]
	v_mfma_f32_16x16x32_bf16 v[4:7], v[152:155], v[234:237], v[4:7]
	v_mfma_f32_16x16x32_bf16 v[0:3], v[194:197], v[234:237], v[0:3]
	s_setprio 0
	s_barrier
	s_add_i32 s11, 0, 0x18000
	s_add_i32 s14, 0, 0x1c000
	v_add_u32_e32 v144, s11, v209
	v_add_u32_e32 v194, s14, v209
	s_mov_b32 m0, s50
	ds_read_b128 v[92:95], v144
	global_load_lds_dwordx4 v[246:247], off
	ds_read_b128 v[128:131], v144 offset:1024
	ds_read_b128 v[132:135], v144 offset:2048
	ds_read_b128 v[144:147], v144 offset:3072
	ds_read_b128 v[148:151], v194
	ds_read_b128 v[152:155], v194 offset:1024
	ds_read_b128 v[190:193], v194 offset:2048
	ds_read_b128 v[194:197], v194 offset:3072
	v_lshl_add_u64 v[206:207], v[206:207], 0, s[18:19]
	s_mov_b32 m0, s51
	v_lshl_add_u64 v[248:249], v[206:207], 0, v[166:167]
	ds_read_b128 v[198:201], v216 offset:32768
	ds_read_b128 v[202:205], v216 offset:33792
	ds_read_b128 v[210:213], v216 offset:34816
	ds_read_b128 v[218:221], v216 offset:35840
	ds_read_b128 v[222:225], v216 offset:36864
	ds_read_b128 v[226:229], v216 offset:37888
	ds_read_b128 v[230:233], v216 offset:38912
	ds_read_b128 v[234:237], v216 offset:39936
	global_load_lds_dwordx4 v[248:249], off
	s_mov_b32 m0, s52
	v_lshl_add_u64 v[206:207], v[206:207], 0, v[170:171]
	global_load_lds_dwordx4 v[206:207], off
	s_waitcnt vmcnt(8) lgkmcnt(0)
	s_setprio 1
	s_barrier
	v_mfma_f32_16x16x32_bf16 v[140:143], v[92:95], v[198:201], v[140:143]
	v_mfma_f32_16x16x32_bf16 v[136:139], v[132:135], v[198:201], v[136:139]
	v_mfma_f32_16x16x32_bf16 v[116:119], v[92:95], v[210:213], v[116:119]
	v_mfma_f32_16x16x32_bf16 v[112:115], v[132:135], v[210:213], v[112:115]
	v_mfma_f32_16x16x32_bf16 v[100:103], v[92:95], v[222:225], v[100:103]
	v_mfma_f32_16x16x32_bf16 v[96:99], v[132:135], v[222:225], v[96:99]
	v_mfma_f32_16x16x32_bf16 v[76:79], v[92:95], v[230:233], v[76:79]
	v_mfma_f32_16x16x32_bf16 v[72:75], v[132:135], v[230:233], v[72:75]
	v_mfma_f32_16x16x32_bf16 v[140:143], v[128:131], v[202:205], v[140:143]
	v_mfma_f32_16x16x32_bf16 v[136:139], v[144:147], v[202:205], v[136:139]
	v_mfma_f32_16x16x32_bf16 v[116:119], v[128:131], v[218:221], v[116:119]
	v_mfma_f32_16x16x32_bf16 v[112:115], v[144:147], v[218:221], v[112:115]
	v_mfma_f32_16x16x32_bf16 v[100:103], v[128:131], v[226:229], v[100:103]
	v_mfma_f32_16x16x32_bf16 v[96:99], v[144:147], v[226:229], v[96:99]
	v_mfma_f32_16x16x32_bf16 v[76:79], v[128:131], v[234:237], v[76:79]
	v_mfma_f32_16x16x32_bf16 v[72:75], v[144:147], v[234:237], v[72:75]
	v_mfma_f32_16x16x32_bf16 v[124:127], v[148:151], v[198:201], v[124:127]
	v_mfma_f32_16x16x32_bf16 v[120:123], v[190:193], v[198:201], v[120:123]
	v_mfma_f32_16x16x32_bf16 v[108:111], v[148:151], v[210:213], v[108:111]
	v_mfma_f32_16x16x32_bf16 v[104:107], v[190:193], v[210:213], v[104:107]
	v_mfma_f32_16x16x32_bf16 v[84:87], v[148:151], v[222:225], v[84:87]
	v_mfma_f32_16x16x32_bf16 v[80:83], v[190:193], v[222:225], v[80:83]
	v_mfma_f32_16x16x32_bf16 v[68:71], v[148:151], v[230:233], v[68:71]
	v_mfma_f32_16x16x32_bf16 v[64:67], v[190:193], v[230:233], v[64:67]
	v_mfma_f32_16x16x32_bf16 v[124:127], v[152:155], v[202:205], v[124:127]
	v_mfma_f32_16x16x32_bf16 v[120:123], v[194:197], v[202:205], v[120:123]
	v_mfma_f32_16x16x32_bf16 v[108:111], v[152:155], v[218:221], v[108:111]
	v_mfma_f32_16x16x32_bf16 v[104:107], v[194:197], v[218:221], v[104:107]
	v_mfma_f32_16x16x32_bf16 v[84:87], v[152:155], v[226:229], v[84:87]
	v_mfma_f32_16x16x32_bf16 v[80:83], v[194:197], v[226:229], v[80:83]
	v_mfma_f32_16x16x32_bf16 v[68:71], v[152:155], v[234:237], v[68:71]
	v_mfma_f32_16x16x32_bf16 v[64:67], v[194:197], v[234:237], v[64:67]
	s_setprio 0
	s_barrier
; #define PG8_STAGE(bufoff, gbase, voff) do { _Pragma("unroll") for (int _i = 0; _i < 2; ++_i) \
;         __builtin_amdgcn_global_load_lds((const unsigned*)((const char*)(gbase) + (voff)[_i]), (PG8_LAS unsigned*)(lds + (bufoff) + ldsw + _i * 8192), 16, 0, 0); } while (0)
; #define PG8_LDA(dst, b, h) do { _Pragma("unroll") for (int m = 0; m < 4; ++m) _Pragma("unroll") for (int k = 0; k < 2; ++k) dst[m][k] = *(const PG8_LAS bf16x8*)(lds + PG8_SA(b, h) + aoff + m * 2048 + k * 1024); } while (0)
; #define PG8_MMA(ai, bj, At, Bt) do { __builtin_amdgcn_s_setprio(1); _Pragma("unroll") for (int m = 0; m < 4; ++m) _Pragma("unroll") for (int n = 0; n < 2; ++n) _Pragma("unroll") for (int k = 0; k < 2; ++k) \
;         acc[ai][bj][m][n] = __builtin_amdgcn_mfma_f32_16x16x32_bf16(Bt[n][k], At[m][k], acc[ai][bj][m][n], 0, 0, 0); __builtin_amdgcn_s_setprio(0); } while (0)
; #define PG8_WAIT_V(n) asm volatile("s_waitcnt vmcnt(" #n ")" ::: "memory")
; #define PG8_WAIT_L(n) asm volatile("s_waitcnt lgkmcnt(" #n ")" ::: "memory")
; #define PG8_BAR __builtin_amdgcn_s_barrier()
; #define PG8_SCHED __builtin_amdgcn_sched_barrier(0)
; template <class Epi, class Sched, bool ALIGN_EPI = false, bool SP2 = false>
; __device__ __forceinline__ void gemm_phase(PG8_LAS unsigned char* lds, const Gemm g, const Sched& S, const Epi& E) {
;     ...
;             PG8_LDA(At, 1, 1); PG8_STAGE(PG8_SB(1, 0), b3, voffB); PG8_STAGE(PG8_SB(1, 1), b3 + hstep, voffB); PG8_STAGE(PG8_SA(1, 0), a3, voffA);
;             PG8_WAIT_V(8); PG8_WAIT_L(0); PG8_BAR; PG8_MMA(1, 0, At, B0); PG8_MMA(1, 1, At, B1); PG8_BAR; PG8_SCHED;
	s_add_i32 s11, s11, s35
	v_lshl_add_u64 v[206:207], v[238:239], 0, s[24:25]
	s_mov_b32 m0, s11
	ds_read_b128 v[198:201], v216 offset:49152
	ds_read_b128 v[202:205], v216 offset:50176
	ds_read_b128 v[210:213], v216 offset:51200
	ds_read_b128 v[218:221], v216 offset:52224
	ds_read_b128 v[222:225], v216 offset:53248
	ds_read_b128 v[226:229], v216 offset:54272
	ds_read_b128 v[230:233], v216 offset:55296
	ds_read_b128 v[234:237], v216 offset:56320
	global_load_lds_dwordx4 v[206:207], off
	v_lshl_add_u64 v[206:207], v[240:241], 0, s[24:25]
	s_add_i32 m0, s11, 0x2000
	s_add_i32 s11, s14, s35
	global_load_lds_dwordx4 v[206:207], off
	s_mov_b32 m0, s11
	v_lshl_add_u64 v[206:207], v[242:243], 0, s[24:25]
	global_load_lds_dwordx4 v[206:207], off
	s_add_i32 m0, s11, 0x2000
	v_lshl_add_u64 v[206:207], v[214:215], 0, s[24:25]
	global_load_lds_dwordx4 v[206:207], off
	s_mov_b32 m0, s54
	v_lshl_add_u64 v[206:207], v[244:245], 0, s[24:25]
	global_load_lds_dwordx4 v[206:207], off
	s_mov_b32 m0, s55
	v_lshl_add_u64 v[206:207], v[246:247], 0, s[24:25]
	global_load_lds_dwordx4 v[206:207], off
	s_waitcnt vmcnt(8) lgkmcnt(0)
	s_setprio 1
	s_barrier
	v_mfma_f32_16x16x32_bf16 v[60:63], v[92:95], v[198:201], v[60:63]
	v_mfma_f32_16x16x32_bf16 v[56:59], v[132:135], v[198:201], v[56:59]
	v_mfma_f32_16x16x32_bf16 v[44:47], v[92:95], v[210:213], v[44:47]
	v_mfma_f32_16x16x32_bf16 v[40:43], v[132:135], v[210:213], v[40:43]
	v_mfma_f32_16x16x32_bf16 v[28:31], v[92:95], v[222:225], v[28:31]
	v_mfma_f32_16x16x32_bf16 v[24:27], v[132:135], v[222:225], v[24:27]
	v_mfma_f32_16x16x32_bf16 v[12:15], v[92:95], v[230:233], v[12:15]
	v_mfma_f32_16x16x32_bf16 v[8:11], v[132:135], v[230:233], v[8:11]
	v_mfma_f32_16x16x32_bf16 v[60:63], v[128:131], v[202:205], v[60:63]
	v_mfma_f32_16x16x32_bf16 v[56:59], v[144:147], v[202:205], v[56:59]
	v_mfma_f32_16x16x32_bf16 v[44:47], v[128:131], v[218:221], v[44:47]
	v_mfma_f32_16x16x32_bf16 v[40:43], v[144:147], v[218:221], v[40:43]
	v_mfma_f32_16x16x32_bf16 v[28:31], v[128:131], v[226:229], v[28:31]
	v_mfma_f32_16x16x32_bf16 v[24:27], v[144:147], v[226:229], v[24:27]
	v_mfma_f32_16x16x32_bf16 v[12:15], v[128:131], v[234:237], v[12:15]
	v_mfma_f32_16x16x32_bf16 v[8:11], v[144:147], v[234:237], v[8:11]
	v_mfma_f32_16x16x32_bf16 v[52:55], v[148:151], v[198:201], v[52:55]
	v_mfma_f32_16x16x32_bf16 v[48:51], v[190:193], v[198:201], v[48:51]
	v_mfma_f32_16x16x32_bf16 v[36:39], v[148:151], v[210:213], v[36:39]
	v_mfma_f32_16x16x32_bf16 v[32:35], v[190:193], v[210:213], v[32:35]
	v_mfma_f32_16x16x32_bf16 v[20:23], v[148:151], v[222:225], v[20:23]
	v_mfma_f32_16x16x32_bf16 v[16:19], v[190:193], v[222:225], v[16:19]
	v_mfma_f32_16x16x32_bf16 v[4:7], v[148:151], v[230:233], v[4:7]
	v_mfma_f32_16x16x32_bf16 v[0:3], v[190:193], v[230:233], v[0:3]
	v_mfma_f32_16x16x32_bf16 v[52:55], v[152:155], v[202:205], v[52:55]
	v_mfma_f32_16x16x32_bf16 v[48:51], v[194:197], v[202:205], v[48:51]
	v_mfma_f32_16x16x32_bf16 v[36:39], v[152:155], v[218:221], v[36:39]
	v_mfma_f32_16x16x32_bf16 v[32:35], v[194:197], v[218:221], v[32:35]
	v_mfma_f32_16x16x32_bf16 v[20:23], v[152:155], v[226:229], v[20:23]
	v_mfma_f32_16x16x32_bf16 v[16:19], v[194:197], v[226:229], v[16:19]
	v_mfma_f32_16x16x32_bf16 v[4:7], v[152:155], v[234:237], v[4:7]
	v_mfma_f32_16x16x32_bf16 v[0:3], v[194:197], v[234:237], v[0:3]
	s_setprio 0
	s_barrier
	v_lshl_add_u64 v[88:89], v[88:89], 0, s[30:31]
	s_cmp_ge_i32 s10, s57
	v_lshl_add_u64 v[90:91], v[90:91], 0, s[30:31]
	s_cbranch_scc0 .LBB0_635

; #define PG8_STAGE(bufoff, gbase, voff) do { _Pragma("unroll") for (int _i = 0; _i < 2; ++_i) \
;         __builtin_amdgcn_global_load_lds((const unsigned*)((const char*)(gbase) + (voff)[_i]), (PG8_LAS unsigned*)(lds + (bufoff) + ldsw + _i * 8192), 16, 0, 0); } while (0)
; #define PG8_LDA(dst, b, h) do { _Pragma("unroll") for (int m = 0; m < 4; ++m) _Pragma("unroll") for (int k = 0; k < 2; ++k) dst[m][k] = *(const PG8_LAS bf16x8*)(lds + PG8_SA(b, h) + aoff + m * 2048 + k * 1024); } while (0)
; #define PG8_LDB(dst, b, h) do { _Pragma("unroll") for (int n = 0; n < 2; ++n) _Pragma("unroll") for (int k = 0; k < 2; ++k) dst[n][k] = *(const PG8_LAS bf16x8*)(lds + PG8_SB(b, h) + boff + n * 2048 + k * 1024); } while (0)
; #define PG8_MMA(ai, bj, At, Bt) do { __builtin_amdgcn_s_setprio(1); _Pragma("unroll") for (int m = 0; m < 4; ++m) _Pragma("unroll") for (int n = 0; n < 2; ++n) _Pragma("unroll") for (int k = 0; k < 2; ++k) \
;         acc[ai][bj][m][n] = __builtin_amdgcn_mfma_f32_16x16x32_bf16(Bt[n][k], At[m][k], acc[ai][bj][m][n], 0, 0, 0); __builtin_amdgcn_s_setprio(0); } while (0)
; #define PG8_WAIT_V(n) asm volatile("s_waitcnt vmcnt(" #n ")" ::: "memory")
; #define PG8_WAIT_L(n) asm volatile("s_waitcnt lgkmcnt(" #n ")" ::: "memory")
; template <class Epi, class Sched, bool ALIGN_EPI = false, bool SP2 = false>
; __device__ __forceinline__ void gemm_phase(PG8_LAS unsigned char* lds, const Gemm g, const Sched& S, const Epi& E) {
;     ...
;             const bool last = (t == nt - 2);
;             const char* a1 = cA + (size_t)(t + 1) * kstep;
;             const char* a2 = last ? nA : cA + (size_t)(t + 2) * kstep; const char* b2 = last ? nB : cB + (size_t)(t + 2) * kstep;
;             const char* a3 = a2 + kstep; const char* b3 = b2 + kstep;
;             if (last && has_next) S.a_ready(nxt);
;             if constexpr (SP2) {
;             PG8_LDB(B0, 0, 0); PG8_LDB(B1, 0, 1); PG8_SCHED; PG8_LDA(At, 0, 0); PG8_STAGE(PG8_SA(1, 1), a1 + hstep, voffA);
;             PG8_WAIT_V(8); PG8_WAIT_L(0); PG8_BAR; PG8_MMA(0, 0, At, B0); PG8_MMA(0, 1, At, B1); PG8_BAR; PG8_SCHED;
;             PG8_LDA(At, 0, 1); PG8_STAGE(PG8_SB(0, 0), b2, voffB); PG8_STAGE(PG8_SB(0, 1), b2 + hstep, voffB); PG8_STAGE(PG8_SA(0, 0), a2, voffA);
;             PG8_WAIT_V(8); PG8_WAIT_L(0); PG8_BAR; PG8_MMA(1, 0, At, B0); PG8_MMA(1, 1, At, B1); PG8_BAR; PG8_SCHED;
.LBB0_722:
	v_add_u32_e32 v144, s59, v183
	v_add_u32_e32 v170, s60, v183
	ds_read_b128 v[116:119], v144
	ds_read_b128 v[136:139], v144 offset:1024
	ds_read_b128 v[140:143], v144 offset:2048
	ds_read_b128 v[144:147], v144 offset:3072
	ds_read_b128 v[148:151], v170
	ds_read_b128 v[188:191], v170 offset:1024
	ds_read_b128 v[192:195], v170 offset:2048
	ds_read_b128 v[198:201], v170 offset:3072
	s_cmp_eq_u32 s53, s8
	v_lshl_add_u64 v[204:205], v[114:115], 0, s[18:19]
	s_cselect_b64 vcc, -1, 0
	s_add_i32 s8, s8, 2
	v_cndmask_b32_e32 v213, v205, v185, vcc
	v_cndmask_b32_e32 v212, v204, v184, vcc
	v_cndmask_b32_e32 v215, v113, v187, vcc
	v_cndmask_b32_e32 v214, v112, v186, vcc
	v_lshl_add_u64 v[240:241], v[114:115], 0, v[178:179]
	s_add_i32 m0, s34, 0xc000
	ds_read_b128 v[204:207], v202
	ds_read_b128 v[208:211], v202 offset:1024
	ds_read_b128 v[216:219], v202 offset:2048
	ds_read_b128 v[220:223], v202 offset:3072
	ds_read_b128 v[224:227], v202 offset:4096
	ds_read_b128 v[228:231], v202 offset:5120
	ds_read_b128 v[232:235], v202 offset:6144
	ds_read_b128 v[236:239], v202 offset:7168
	global_load_lds_dwordx4 v[240:241], off
	s_add_i32 m0, s34, 0xe000
	v_lshl_add_u64 v[240:241], v[114:115], 0, v[176:177]
	global_load_lds_dwordx4 v[240:241], off
	s_waitcnt vmcnt(8) lgkmcnt(0)
	s_setprio 1
	s_barrier
	v_mfma_f32_16x16x32_bf16 v[132:135], v[116:119], v[204:207], v[132:135]
	v_mfma_f32_16x16x32_bf16 v[128:131], v[140:143], v[204:207], v[128:131]
	v_mfma_f32_16x16x32_bf16 v[108:111], v[116:119], v[216:219], v[108:111]
	v_mfma_f32_16x16x32_bf16 v[104:107], v[140:143], v[216:219], v[104:107]
	v_mfma_f32_16x16x32_bf16 v[92:95], v[116:119], v[224:227], v[92:95]
	v_mfma_f32_16x16x32_bf16 v[88:91], v[140:143], v[224:227], v[88:91]
	v_mfma_f32_16x16x32_bf16 v[76:79], v[116:119], v[232:235], v[76:79]
	v_mfma_f32_16x16x32_bf16 v[72:75], v[140:143], v[232:235], v[72:75]
	v_mfma_f32_16x16x32_bf16 v[132:135], v[136:139], v[208:211], v[132:135]
	v_mfma_f32_16x16x32_bf16 v[128:131], v[144:147], v[208:211], v[128:131]
	v_mfma_f32_16x16x32_bf16 v[108:111], v[136:139], v[220:223], v[108:111]
	v_mfma_f32_16x16x32_bf16 v[104:107], v[144:147], v[220:223], v[104:107]
	v_mfma_f32_16x16x32_bf16 v[92:95], v[136:139], v[228:231], v[92:95]
	v_mfma_f32_16x16x32_bf16 v[88:91], v[144:147], v[228:231], v[88:91]
	v_mfma_f32_16x16x32_bf16 v[76:79], v[136:139], v[236:239], v[76:79]
	v_mfma_f32_16x16x32_bf16 v[72:75], v[144:147], v[236:239], v[72:75]
	v_mfma_f32_16x16x32_bf16 v[124:127], v[148:151], v[204:207], v[124:127]
	v_mfma_f32_16x16x32_bf16 v[120:123], v[192:195], v[204:207], v[120:123]
	v_mfma_f32_16x16x32_bf16 v[100:103], v[148:151], v[216:219], v[100:103]
	v_mfma_f32_16x16x32_bf16 v[96:99], v[192:195], v[216:219], v[96:99]
	v_mfma_f32_16x16x32_bf16 v[84:87], v[148:151], v[224:227], v[84:87]
	v_mfma_f32_16x16x32_bf16 v[80:83], v[192:195], v[224:227], v[80:83]
	v_mfma_f32_16x16x32_bf16 v[68:71], v[148:151], v[232:235], v[68:71]
	v_mfma_f32_16x16x32_bf16 v[64:67], v[192:195], v[232:235], v[64:67]
	v_mfma_f32_16x16x32_bf16 v[124:127], v[188:191], v[208:211], v[124:127]
	v_mfma_f32_16x16x32_bf16 v[120:123], v[198:201], v[208:211], v[120:123]
	v_mfma_f32_16x16x32_bf16 v[100:103], v[188:191], v[220:223], v[100:103]
	v_mfma_f32_16x16x32_bf16 v[96:99], v[198:201], v[220:223], v[96:99]
	v_mfma_f32_16x16x32_bf16 v[84:87], v[188:191], v[228:231], v[84:87]
	v_mfma_f32_16x16x32_bf16 v[80:83], v[198:201], v[228:231], v[80:83]
	v_mfma_f32_16x16x32_bf16 v[68:71], v[188:191], v[236:239], v[68:71]
	v_mfma_f32_16x16x32_bf16 v[64:67], v[198:201], v[236:239], v[64:67]
	s_setprio 0
	s_barrier
	s_add_i32 s9, s59, s29
	v_lshl_add_u64 v[240:241], v[214:215], 0, v[164:165]
	s_mov_b32 m0, s9
	ds_read_b128 v[204:207], v202 offset:16384
	ds_read_b128 v[208:211], v202 offset:17408
	ds_read_b128 v[216:219], v202 offset:18432
	ds_read_b128 v[220:223], v202 offset:19456
	ds_read_b128 v[224:227], v202 offset:20480
	ds_read_b128 v[228:231], v202 offset:21504
	ds_read_b128 v[232:235], v202 offset:22528
	ds_read_b128 v[236:239], v202 offset:23552
	global_load_lds_dwordx4 v[240:241], off
	v_lshl_add_u64 v[242:243], v[214:215], 0, v[168:169]
	s_add_i32 m0, s9, 0x2000
	v_lshl_add_u64 v[214:215], v[214:215], 0, s[12:13]
	s_add_i32 s9, s60, s29
	global_load_lds_dwordx4 v[242:243], off
	v_lshl_add_u64 v[244:245], v[214:215], 0, v[164:165]
	s_mov_b32 m0, s9
	v_lshl_add_u64 v[214:215], v[214:215], 0, v[168:169]
	global_load_lds_dwordx4 v[244:245], off
	s_add_i32 m0, s9, 0x2000
	v_lshl_add_u64 v[246:247], v[212:213], 0, v[162:163]
	global_load_lds_dwordx4 v[214:215], off
	s_mov_b32 m0, s34
	v_lshl_add_u64 v[248:249], v[212:213], 0, v[166:167]
	global_load_lds_dwordx4 v[246:247], off
	s_nop 0
	s_waitcnt vmcnt(7) lgkmcnt(0)
	s_setprio 1
	s_barrier
; #define PG8_STAGE(bufoff, gbase, voff) do { _Pragma("unroll") for (int _i = 0; _i < 2; ++_i) \
;         __builtin_amdgcn_global_load_lds((const unsigned*)((const char*)(gbase) + (voff)[_i]), (PG8_LAS unsigned*)(lds + (bufoff) + ldsw + _i * 8192), 16, 0, 0); } while (0)
; #define PG8_LDA(dst, b, h) do { _Pragma("unroll") for (int m = 0; m < 4; ++m) _Pragma("unroll") for (int k = 0; k < 2; ++k) dst[m][k] = *(const PG8_LAS bf16x8*)(lds + PG8_SA(b, h) + aoff + m * 2048 + k * 1024); } while (0)
; #define PG8_LDB(dst, b, h) do { _Pragma("unroll") for (int n = 0; n < 2; ++n) _Pragma("unroll") for (int k = 0; k < 2; ++k) dst[n][k] = *(const PG8_LAS bf16x8*)(lds + PG8_SB(b, h) + boff + n * 2048 + k * 1024); } while (0)
; #define PG8_MMA(ai, bj, At, Bt) do { __builtin_amdgcn_s_setprio(1); _Pragma("unroll") for (int m = 0; m < 4; ++m) _Pragma("unroll") for (int n = 0; n < 2; ++n) _Pragma("unroll") for (int k = 0; k < 2; ++k) \
;         acc[ai][bj][m][n] = __builtin_amdgcn_mfma_f32_16x16x32_bf16(Bt[n][k], At[m][k], acc[ai][bj][m][n], 0, 0, 0); __builtin_amdgcn_s_setprio(0); } while (0)
; #define PG8_WAIT_V(n) asm volatile("s_waitcnt vmcnt(" #n ")" ::: "memory")
; #define PG8_WAIT_L(n) asm volatile("s_waitcnt lgkmcnt(" #n ")" ::: "memory")
; #define PG8_BAR __builtin_amdgcn_s_barrier()
; #define PG8_SCHED __builtin_amdgcn_sched_barrier(0)
; template <class Epi, class Sched, bool ALIGN_EPI = false, bool SP2 = false>
; __device__ __forceinline__ void gemm_phase(PG8_LAS unsigned char* lds, const Gemm g, const Sched& S, const Epi& E) {
;     ...
;             PG8_WAIT_V(8); PG8_WAIT_L(0); PG8_BAR; PG8_MMA(1, 0, At, B0); PG8_MMA(1, 1, At, B1); PG8_BAR; PG8_SCHED;
;             PG8_LDB(B0, 1, 0); PG8_LDB(B1, 1, 1); PG8_SCHED; PG8_LDA(At, 1, 0); PG8_STAGE(PG8_SA(0, 1), a2 + hstep, voffA);
;             PG8_WAIT_V(8); PG8_WAIT_L(0); PG8_BAR; PG8_MMA(0, 0, At, B0); PG8_MMA(0, 1, At, B1); PG8_BAR; PG8_SCHED;
	v_mfma_f32_16x16x32_bf16 v[60:63], v[116:119], v[204:207], v[60:63]
	v_mfma_f32_16x16x32_bf16 v[56:59], v[140:143], v[204:207], v[56:59]
	v_mfma_f32_16x16x32_bf16 v[44:47], v[116:119], v[216:219], v[44:47]
	v_mfma_f32_16x16x32_bf16 v[40:43], v[140:143], v[216:219], v[40:43]
	v_mfma_f32_16x16x32_bf16 v[28:31], v[116:119], v[224:227], v[28:31]
	v_mfma_f32_16x16x32_bf16 v[24:27], v[140:143], v[224:227], v[24:27]
	v_mfma_f32_16x16x32_bf16 v[12:15], v[116:119], v[232:235], v[12:15]
	v_mfma_f32_16x16x32_bf16 v[8:11], v[140:143], v[232:235], v[8:11]
	v_mfma_f32_16x16x32_bf16 v[60:63], v[136:139], v[208:211], v[60:63]
	v_mfma_f32_16x16x32_bf16 v[56:59], v[144:147], v[208:211], v[56:59]
	v_mfma_f32_16x16x32_bf16 v[44:47], v[136:139], v[220:223], v[44:47]
	v_mfma_f32_16x16x32_bf16 v[40:43], v[144:147], v[220:223], v[40:43]
	v_mfma_f32_16x16x32_bf16 v[28:31], v[136:139], v[228:231], v[28:31]
	v_mfma_f32_16x16x32_bf16 v[24:27], v[144:147], v[228:231], v[24:27]
	v_mfma_f32_16x16x32_bf16 v[12:15], v[136:139], v[236:239], v[12:15]
	v_mfma_f32_16x16x32_bf16 v[8:11], v[144:147], v[236:239], v[8:11]
	v_mfma_f32_16x16x32_bf16 v[52:55], v[148:151], v[204:207], v[52:55]
	v_mfma_f32_16x16x32_bf16 v[48:51], v[192:195], v[204:207], v[48:51]
	v_mfma_f32_16x16x32_bf16 v[36:39], v[148:151], v[216:219], v[36:39]
	v_mfma_f32_16x16x32_bf16 v[32:35], v[192:195], v[216:219], v[32:35]
	v_mfma_f32_16x16x32_bf16 v[20:23], v[148:151], v[224:227], v[20:23]
	v_mfma_f32_16x16x32_bf16 v[16:19], v[192:195], v[224:227], v[16:19]
	v_mfma_f32_16x16x32_bf16 v[4:7], v[148:151], v[232:235], v[4:7]
	v_mfma_f32_16x16x32_bf16 v[0:3], v[192:195], v[232:235], v[0:3]
	v_mfma_f32_16x16x32_bf16 v[52:55], v[188:191], v[208:211], v[52:55]
	v_mfma_f32_16x16x32_bf16 v[48:51], v[198:201], v[208:211], v[48:51]
	v_mfma_f32_16x16x32_bf16 v[36:39], v[188:191], v[220:223], v[36:39]
	v_mfma_f32_16x16x32_bf16 v[32:35], v[198:201], v[220:223], v[32:35]
	v_mfma_f32_16x16x32_bf16 v[20:23], v[188:191], v[228:231], v[20:23]
	v_mfma_f32_16x16x32_bf16 v[16:19], v[198:201], v[228:231], v[16:19]
	v_mfma_f32_16x16x32_bf16 v[4:7], v[188:191], v[236:239], v[4:7]
	v_mfma_f32_16x16x32_bf16 v[0:3], v[198:201], v[236:239], v[0:3]
	s_setprio 0
	s_barrier
	s_add_i32 s9, 0, 0x18000
	s_add_i32 s10, 0, 0x1c000
	v_add_u32_e32 v144, s9, v183
	v_add_u32_e32 v170, s10, v183
	s_mov_b32 m0, s36
	ds_read_b128 v[116:119], v144
	global_load_lds_dwordx4 v[248:249], off
	ds_read_b128 v[136:139], v144 offset:1024
	ds_read_b128 v[140:143], v144 offset:2048
	ds_read_b128 v[144:147], v144 offset:3072
	ds_read_b128 v[148:151], v170
	ds_read_b128 v[188:191], v170 offset:1024
	ds_read_b128 v[192:195], v170 offset:2048
	ds_read_b128 v[198:201], v170 offset:3072
	v_lshl_add_u64 v[212:213], v[212:213], 0, s[12:13]
	s_mov_b32 m0, s37
	v_lshl_add_u64 v[250:251], v[212:213], 0, v[162:163]
	ds_read_b128 v[204:207], v202 offset:32768
	ds_read_b128 v[208:211], v202 offset:33792
	ds_read_b128 v[216:219], v202 offset:34816
	ds_read_b128 v[220:223], v202 offset:35840
	ds_read_b128 v[224:227], v202 offset:36864
	ds_read_b128 v[228:231], v202 offset:37888
	ds_read_b128 v[232:235], v202 offset:38912
	ds_read_b128 v[236:239], v202 offset:39936
	global_load_lds_dwordx4 v[250:251], off
	s_mov_b32 m0, s41
	v_lshl_add_u64 v[212:213], v[212:213], 0, v[166:167]
	global_load_lds_dwordx4 v[212:213], off
	s_waitcnt vmcnt(8) lgkmcnt(0)
	s_setprio 1
	s_barrier
	v_mfma_f32_16x16x32_bf16 v[132:135], v[116:119], v[204:207], v[132:135]
	v_mfma_f32_16x16x32_bf16 v[128:131], v[140:143], v[204:207], v[128:131]
	v_mfma_f32_16x16x32_bf16 v[108:111], v[116:119], v[216:219], v[108:111]
	v_mfma_f32_16x16x32_bf16 v[104:107], v[140:143], v[216:219], v[104:107]
	v_mfma_f32_16x16x32_bf16 v[92:95], v[116:119], v[224:227], v[92:95]
	v_mfma_f32_16x16x32_bf16 v[88:91], v[140:143], v[224:227], v[88:91]
	v_mfma_f32_16x16x32_bf16 v[76:79], v[116:119], v[232:235], v[76:79]
	v_mfma_f32_16x16x32_bf16 v[72:75], v[140:143], v[232:235], v[72:75]
	v_mfma_f32_16x16x32_bf16 v[132:135], v[136:139], v[208:211], v[132:135]
	v_mfma_f32_16x16x32_bf16 v[128:131], v[144:147], v[208:211], v[128:131]
	v_mfma_f32_16x16x32_bf16 v[108:111], v[136:139], v[220:223], v[108:111]
	v_mfma_f32_16x16x32_bf16 v[104:107], v[144:147], v[220:223], v[104:107]
	v_mfma_f32_16x16x32_bf16 v[92:95], v[136:139], v[228:231], v[92:95]
	v_mfma_f32_16x16x32_bf16 v[88:91], v[144:147], v[228:231], v[88:91]
	v_mfma_f32_16x16x32_bf16 v[76:79], v[136:139], v[236:239], v[76:79]
	v_mfma_f32_16x16x32_bf16 v[72:75], v[144:147], v[236:239], v[72:75]
	v_mfma_f32_16x16x32_bf16 v[124:127], v[148:151], v[204:207], v[124:127]
	v_mfma_f32_16x16x32_bf16 v[120:123], v[192:195], v[204:207], v[120:123]
	v_mfma_f32_16x16x32_bf16 v[100:103], v[148:151], v[216:219], v[100:103]
	v_mfma_f32_16x16x32_bf16 v[96:99], v[192:195], v[216:219], v[96:99]
	v_mfma_f32_16x16x32_bf16 v[84:87], v[148:151], v[224:227], v[84:87]
	v_mfma_f32_16x16x32_bf16 v[80:83], v[192:195], v[224:227], v[80:83]
	v_mfma_f32_16x16x32_bf16 v[68:71], v[148:151], v[232:235], v[68:71]
	v_mfma_f32_16x16x32_bf16 v[64:67], v[192:195], v[232:235], v[64:67]
	v_mfma_f32_16x16x32_bf16 v[124:127], v[188:191], v[208:211], v[124:127]
	v_mfma_f32_16x16x32_bf16 v[120:123], v[198:201], v[208:211], v[120:123]
	v_mfma_f32_16x16x32_bf16 v[100:103], v[188:191], v[220:223], v[100:103]
	v_mfma_f32_16x16x32_bf16 v[96:99], v[198:201], v[220:223], v[96:99]
	v_mfma_f32_16x16x32_bf16 v[84:87], v[188:191], v[228:231], v[84:87]
	v_mfma_f32_16x16x32_bf16 v[80:83], v[198:201], v[228:231], v[80:83]
	v_mfma_f32_16x16x32_bf16 v[68:71], v[188:191], v[236:239], v[68:71]
	v_mfma_f32_16x16x32_bf16 v[64:67], v[198:201], v[236:239], v[64:67]
	s_setprio 0
	s_barrier
; #define PG8_STAGE(bufoff, gbase, voff) do { _Pragma("unroll") for (int _i = 0; _i < 2; ++_i) \
;         __builtin_amdgcn_global_load_lds((const unsigned*)((const char*)(gbase) + (voff)[_i]), (PG8_LAS unsigned*)(lds + (bufoff) + ldsw + _i * 8192), 16, 0, 0); } while (0)
; #define PG8_LDA(dst, b, h) do { _Pragma("unroll") for (int m = 0; m < 4; ++m) _Pragma("unroll") for (int k = 0; k < 2; ++k) dst[m][k] = *(const PG8_LAS bf16x8*)(lds + PG8_SA(b, h) + aoff + m * 2048 + k * 1024); } while (0)
; #define PG8_MMA(ai, bj, At, Bt) do { __builtin_amdgcn_s_setprio(1); _Pragma("unroll") for (int m = 0; m < 4; ++m) _Pragma("unroll") for (int n = 0; n < 2; ++n) _Pragma("unroll") for (int k = 0; k < 2; ++k) \
;         acc[ai][bj][m][n] = __builtin_amdgcn_mfma_f32_16x16x32_bf16(Bt[n][k], At[m][k], acc[ai][bj][m][n], 0, 0, 0); __builtin_amdgcn_s_setprio(0); } while (0)
; #define PG8_WAIT_V(n) asm volatile("s_waitcnt vmcnt(" #n ")" ::: "memory")
; #define PG8_WAIT_L(n) asm volatile("s_waitcnt lgkmcnt(" #n ")" ::: "memory")
; #define PG8_BAR __builtin_amdgcn_s_barrier()
; #define PG8_SCHED __builtin_amdgcn_sched_barrier(0)
; template <class Epi, class Sched, bool ALIGN_EPI = false, bool SP2 = false>
; __device__ __forceinline__ void gemm_phase(PG8_LAS unsigned char* lds, const Gemm g, const Sched& S, const Epi& E) {
;     ...
;             PG8_LDA(At, 1, 1); PG8_STAGE(PG8_SB(1, 0), b3, voffB); PG8_STAGE(PG8_SB(1, 1), b3 + hstep, voffB); PG8_STAGE(PG8_SA(1, 0), a3, voffA);
;             PG8_WAIT_V(8); PG8_WAIT_L(0); PG8_BAR; PG8_MMA(1, 0, At, B0); PG8_MMA(1, 1, At, B1); PG8_BAR; PG8_SCHED;
	s_add_i32 s9, s9, s29
	v_lshl_add_u64 v[212:213], v[240:241], 0, s[18:19]
	s_mov_b32 m0, s9
	ds_read_b128 v[204:207], v202 offset:49152
	ds_read_b128 v[208:211], v202 offset:50176
	ds_read_b128 v[216:219], v202 offset:51200
	ds_read_b128 v[220:223], v202 offset:52224
	ds_read_b128 v[224:227], v202 offset:53248
	ds_read_b128 v[228:231], v202 offset:54272
	ds_read_b128 v[232:235], v202 offset:55296
	ds_read_b128 v[236:239], v202 offset:56320
	global_load_lds_dwordx4 v[212:213], off
	v_lshl_add_u64 v[212:213], v[242:243], 0, s[18:19]
	s_add_i32 m0, s9, 0x2000
	s_add_i32 s9, s10, s29
	global_load_lds_dwordx4 v[212:213], off
	s_mov_b32 m0, s9
	v_lshl_add_u64 v[212:213], v[244:245], 0, s[18:19]
	global_load_lds_dwordx4 v[212:213], off
	s_add_i32 m0, s9, 0x2000
	v_lshl_add_u64 v[212:213], v[214:215], 0, s[18:19]
	global_load_lds_dwordx4 v[212:213], off
	s_mov_b32 m0, s49
	v_lshl_add_u64 v[212:213], v[246:247], 0, s[18:19]
	global_load_lds_dwordx4 v[212:213], off
	s_mov_b32 m0, s50
	v_lshl_add_u64 v[212:213], v[248:249], 0, s[18:19]
	global_load_lds_dwordx4 v[212:213], off
	s_waitcnt vmcnt(8) lgkmcnt(0)
	s_setprio 1
	s_barrier
	v_mfma_f32_16x16x32_bf16 v[60:63], v[116:119], v[204:207], v[60:63]
	v_mfma_f32_16x16x32_bf16 v[56:59], v[140:143], v[204:207], v[56:59]
	v_mfma_f32_16x16x32_bf16 v[44:47], v[116:119], v[216:219], v[44:47]
	v_mfma_f32_16x16x32_bf16 v[40:43], v[140:143], v[216:219], v[40:43]
	v_mfma_f32_16x16x32_bf16 v[28:31], v[116:119], v[224:227], v[28:31]
	v_mfma_f32_16x16x32_bf16 v[24:27], v[140:143], v[224:227], v[24:27]
	v_mfma_f32_16x16x32_bf16 v[12:15], v[116:119], v[232:235], v[12:15]
	v_mfma_f32_16x16x32_bf16 v[8:11], v[140:143], v[232:235], v[8:11]
	v_mfma_f32_16x16x32_bf16 v[60:63], v[136:139], v[208:211], v[60:63]
	v_mfma_f32_16x16x32_bf16 v[56:59], v[144:147], v[208:211], v[56:59]
	v_mfma_f32_16x16x32_bf16 v[44:47], v[136:139], v[220:223], v[44:47]
	v_mfma_f32_16x16x32_bf16 v[40:43], v[144:147], v[220:223], v[40:43]
	v_mfma_f32_16x16x32_bf16 v[28:31], v[136:139], v[228:231], v[28:31]
	v_mfma_f32_16x16x32_bf16 v[24:27], v[144:147], v[228:231], v[24:27]
	v_mfma_f32_16x16x32_bf16 v[12:15], v[136:139], v[236:239], v[12:15]
	v_mfma_f32_16x16x32_bf16 v[8:11], v[144:147], v[236:239], v[8:11]
	v_mfma_f32_16x16x32_bf16 v[52:55], v[148:151], v[204:207], v[52:55]
	v_mfma_f32_16x16x32_bf16 v[48:51], v[192:195], v[204:207], v[48:51]
	v_mfma_f32_16x16x32_bf16 v[36:39], v[148:151], v[216:219], v[36:39]
	v_mfma_f32_16x16x32_bf16 v[32:35], v[192:195], v[216:219], v[32:35]
	v_mfma_f32_16x16x32_bf16 v[20:23], v[148:151], v[224:227], v[20:23]
	v_mfma_f32_16x16x32_bf16 v[16:19], v[192:195], v[224:227], v[16:19]
	v_mfma_f32_16x16x32_bf16 v[4:7], v[148:151], v[232:235], v[4:7]
	v_mfma_f32_16x16x32_bf16 v[0:3], v[192:195], v[232:235], v[0:3]
	v_mfma_f32_16x16x32_bf16 v[52:55], v[188:191], v[208:211], v[52:55]
	v_mfma_f32_16x16x32_bf16 v[48:51], v[198:201], v[208:211], v[48:51]
	v_mfma_f32_16x16x32_bf16 v[36:39], v[188:191], v[220:223], v[36:39]
	v_mfma_f32_16x16x32_bf16 v[32:35], v[198:201], v[220:223], v[32:35]
	v_mfma_f32_16x16x32_bf16 v[20:23], v[188:191], v[228:231], v[20:23]
	v_mfma_f32_16x16x32_bf16 v[16:19], v[198:201], v[228:231], v[16:19]
	v_mfma_f32_16x16x32_bf16 v[4:7], v[188:191], v[236:239], v[4:7]
	v_mfma_f32_16x16x32_bf16 v[0:3], v[198:201], v[236:239], v[0:3]
	s_setprio 0
	s_barrier
	v_lshl_add_u64 v[112:113], v[112:113], 0, s[26:27]
	s_cmp_ge_i32 s8, s51
	v_lshl_add_u64 v[114:115], v[114:115], 0, s[26:27]
	s_cbranch_scc0 .LBB0_722

; #define PG8_STAGE(bufoff, gbase, voff) do { _Pragma("unroll") for (int _i = 0; _i < 2; ++_i) \
;         __builtin_amdgcn_global_load_lds((const unsigned*)((const char*)(gbase) + (voff)[_i]), (PG8_LAS unsigned*)(lds + (bufoff) + ldsw + _i * 8192), 16, 0, 0); } while (0)
; #define PG8_LDA(dst, b, h) do { _Pragma("unroll") for (int m = 0; m < 4; ++m) _Pragma("unroll") for (int k = 0; k < 2; ++k) dst[m][k] = *(const PG8_LAS bf16x8*)(lds + PG8_SA(b, h) + aoff + m * 2048 + k * 1024); } while (0)
; #define PG8_LDB(dst, b, h) do { _Pragma("unroll") for (int n = 0; n < 2; ++n) _Pragma("unroll") for (int k = 0; k < 2; ++k) dst[n][k] = *(const PG8_LAS bf16x8*)(lds + PG8_SB(b, h) + boff + n * 2048 + k * 1024); } while (0)
; #define PG8_MMA(ai, bj, At, Bt) do { __builtin_amdgcn_s_setprio(1); _Pragma("unroll") for (int m = 0; m < 4; ++m) _Pragma("unroll") for (int n = 0; n < 2; ++n) _Pragma("unroll") for (int k = 0; k < 2; ++k) \
;         acc[ai][bj][m][n] = __builtin_amdgcn_mfma_f32_16x16x32_bf16(Bt[n][k], At[m][k], acc[ai][bj][m][n], 0, 0, 0); __builtin_amdgcn_s_setprio(0); } while (0)
; #define PG8_WAIT_V(n) asm volatile("s_waitcnt vmcnt(" #n ")" ::: "memory")
; #define PG8_WAIT_L(n) asm volatile("s_waitcnt lgkmcnt(" #n ")" ::: "memory")
; template <class Epi, class Sched, bool ALIGN_EPI = false, bool SP2 = false>
; __device__ __forceinline__ void gemm_phase(PG8_LAS unsigned char* lds, const Gemm g, const Sched& S, const Epi& E) {
;     ...
;             const bool last = (t == nt - 2);
;             const char* a1 = cA + (size_t)(t + 1) * kstep;
;             const char* a2 = last ? nA : cA + (size_t)(t + 2) * kstep; const char* b2 = last ? nB : cB + (size_t)(t + 2) * kstep;
;             const char* a3 = a2 + kstep; const char* b3 = b2 + kstep;
;             if (last && has_next) S.a_ready(nxt);
;             if constexpr (SP2) {
;             PG8_LDB(B0, 0, 0); PG8_LDB(B1, 0, 1); PG8_SCHED; PG8_LDA(At, 0, 0); PG8_STAGE(PG8_SA(1, 1), a1 + hstep, voffA);
;             PG8_WAIT_V(8); PG8_WAIT_L(0); PG8_BAR; PG8_MMA(0, 0, At, B0); PG8_MMA(0, 1, At, B1); PG8_BAR; PG8_SCHED;
;             PG8_LDA(At, 0, 1); PG8_STAGE(PG8_SB(0, 0), b2, voffB); PG8_STAGE(PG8_SB(0, 1), b2 + hstep, voffB); PG8_STAGE(PG8_SA(0, 0), a2, voffA);
;             PG8_WAIT_V(8); PG8_WAIT_L(0); PG8_BAR; PG8_MMA(1, 0, At, B0); PG8_MMA(1, 1, At, B1); PG8_BAR; PG8_SCHED;
.LBB0_940:
	v_add_u32_e32 v188, s55, v199
	ds_read_b128 v[132:135], v201
	ds_read_b128 v[136:139], v201 offset:1024
	ds_read_b128 v[140:143], v201 offset:2048
	ds_read_b128 v[144:147], v201 offset:3072
	ds_read_b128 v[148:151], v188
	ds_read_b128 v[180:183], v188 offset:1024
	ds_read_b128 v[184:187], v188 offset:2048
	ds_read_b128 v[188:191], v188 offset:3072
	s_cmp_eq_u32 s48, s12
	v_lshl_add_u64 v[192:193], v[130:131], 0, s[22:23]
	s_cselect_b64 vcc, -1, 0
	s_add_i32 s12, s12, 2
	v_cndmask_b32_e32 v197, v193, v177, vcc
	v_cndmask_b32_e32 v196, v192, v176, vcc
	v_cndmask_b32_e32 v213, v129, v179, vcc
	v_cndmask_b32_e32 v212, v128, v178, vcc
	s_mov_b32 m0, s56
	v_lshl_add_u64 v[214:215], v[130:131], 0, v[172:173]
	ds_read_b128 v[192:195], v202
	ds_read_b128 v[204:207], v202 offset:1024
	ds_read_b128 v[208:211], v202 offset:2048
	ds_read_b128 v[216:219], v202 offset:3072
	ds_read_b128 v[220:223], v202 offset:4096
	ds_read_b128 v[224:227], v202 offset:5120
	ds_read_b128 v[228:231], v202 offset:6144
	ds_read_b128 v[232:235], v202 offset:7168
	global_load_lds_dwordx4 v[214:215], off
	s_mov_b32 m0, s57
	v_lshl_add_u64 v[214:215], v[130:131], 0, v[170:171]
	global_load_lds_dwordx4 v[214:215], off
	s_waitcnt vmcnt(8) lgkmcnt(0)
	s_setprio 1
	s_barrier
	v_mfma_f32_16x16x32_bf16 v[120:123], v[132:135], v[192:195], v[120:123]
	v_mfma_f32_16x16x32_bf16 v[124:127], v[140:143], v[192:195], v[124:127]
	v_mfma_f32_16x16x32_bf16 v[108:111], v[132:135], v[208:211], v[108:111]
	v_mfma_f32_16x16x32_bf16 v[104:107], v[140:143], v[208:211], v[104:107]
	v_mfma_f32_16x16x32_bf16 v[92:95], v[132:135], v[220:223], v[92:95]
	v_mfma_f32_16x16x32_bf16 v[88:91], v[140:143], v[220:223], v[88:91]
	v_mfma_f32_16x16x32_bf16 v[76:79], v[132:135], v[228:231], v[76:79]
	v_mfma_f32_16x16x32_bf16 v[72:75], v[140:143], v[228:231], v[72:75]
	v_mfma_f32_16x16x32_bf16 v[120:123], v[136:139], v[204:207], v[120:123]
	v_mfma_f32_16x16x32_bf16 v[124:127], v[144:147], v[204:207], v[124:127]
	v_mfma_f32_16x16x32_bf16 v[108:111], v[136:139], v[216:219], v[108:111]
	v_mfma_f32_16x16x32_bf16 v[104:107], v[144:147], v[216:219], v[104:107]
	v_mfma_f32_16x16x32_bf16 v[92:95], v[136:139], v[224:227], v[92:95]
	v_mfma_f32_16x16x32_bf16 v[88:91], v[144:147], v[224:227], v[88:91]
	v_mfma_f32_16x16x32_bf16 v[76:79], v[136:139], v[232:235], v[76:79]
	v_mfma_f32_16x16x32_bf16 v[72:75], v[144:147], v[232:235], v[72:75]
	v_mfma_f32_16x16x32_bf16 v[116:119], v[148:151], v[192:195], v[116:119]
	v_mfma_f32_16x16x32_bf16 v[112:115], v[184:187], v[192:195], v[112:115]
	v_mfma_f32_16x16x32_bf16 v[100:103], v[148:151], v[208:211], v[100:103]
	v_mfma_f32_16x16x32_bf16 v[96:99], v[184:187], v[208:211], v[96:99]
	v_mfma_f32_16x16x32_bf16 v[84:87], v[148:151], v[220:223], v[84:87]
	v_mfma_f32_16x16x32_bf16 v[80:83], v[184:187], v[220:223], v[80:83]
	v_mfma_f32_16x16x32_bf16 v[68:71], v[148:151], v[228:231], v[68:71]
	v_mfma_f32_16x16x32_bf16 v[64:67], v[184:187], v[228:231], v[64:67]
	v_mfma_f32_16x16x32_bf16 v[116:119], v[180:183], v[204:207], v[116:119]
	v_mfma_f32_16x16x32_bf16 v[112:115], v[188:191], v[204:207], v[112:115]
	v_mfma_f32_16x16x32_bf16 v[100:103], v[180:183], v[216:219], v[100:103]
	v_mfma_f32_16x16x32_bf16 v[96:99], v[188:191], v[216:219], v[96:99]
	v_mfma_f32_16x16x32_bf16 v[84:87], v[180:183], v[224:227], v[84:87]
	v_mfma_f32_16x16x32_bf16 v[80:83], v[188:191], v[224:227], v[80:83]
	v_mfma_f32_16x16x32_bf16 v[68:71], v[180:183], v[232:235], v[68:71]
	v_mfma_f32_16x16x32_bf16 v[64:67], v[188:191], v[232:235], v[64:67]
	s_setprio 0
	s_barrier
	s_mov_b32 m0, s58
	v_lshl_add_u64 v[214:215], v[212:213], 0, v[164:165]
	ds_read_b128 v[192:195], v202 offset:16384
	ds_read_b128 v[204:207], v202 offset:17408
	ds_read_b128 v[208:211], v202 offset:18432
	ds_read_b128 v[216:219], v202 offset:19456
	ds_read_b128 v[220:223], v202 offset:20480
	ds_read_b128 v[224:227], v202 offset:21504
	ds_read_b128 v[228:231], v202 offset:22528
	ds_read_b128 v[232:235], v202 offset:23552
	global_load_lds_dwordx4 v[214:215], off
	v_lshl_add_u64 v[236:237], v[212:213], 0, v[168:169]
	s_mov_b32 m0, s59
	v_lshl_add_u64 v[212:213], v[212:213], 0, s[14:15]
	s_add_i32 s13, s55, s30
	global_load_lds_dwordx4 v[236:237], off
	v_lshl_add_u64 v[238:239], v[212:213], 0, v[164:165]
	s_mov_b32 m0, s13
	v_lshl_add_u64 v[212:213], v[212:213], 0, v[168:169]
	global_load_lds_dwordx4 v[238:239], off
	s_add_i32 m0, s13, 0x2000
	v_lshl_add_u64 v[240:241], v[196:197], 0, v[162:163]
	global_load_lds_dwordx4 v[212:213], off
	s_mov_b32 m0, s31
	v_lshl_add_u64 v[242:243], v[196:197], 0, v[166:167]
	global_load_lds_dwordx4 v[240:241], off
	s_nop 0
	s_waitcnt vmcnt(7) lgkmcnt(0)
	s_setprio 1
	s_barrier
; #define PG8_STAGE(bufoff, gbase, voff) do { _Pragma("unroll") for (int _i = 0; _i < 2; ++_i) \
;         __builtin_amdgcn_global_load_lds((const unsigned*)((const char*)(gbase) + (voff)[_i]), (PG8_LAS unsigned*)(lds + (bufoff) + ldsw + _i * 8192), 16, 0, 0); } while (0)
; #define PG8_LDA(dst, b, h) do { _Pragma("unroll") for (int m = 0; m < 4; ++m) _Pragma("unroll") for (int k = 0; k < 2; ++k) dst[m][k] = *(const PG8_LAS bf16x8*)(lds + PG8_SA(b, h) + aoff + m * 2048 + k * 1024); } while (0)
; #define PG8_LDB(dst, b, h) do { _Pragma("unroll") for (int n = 0; n < 2; ++n) _Pragma("unroll") for (int k = 0; k < 2; ++k) dst[n][k] = *(const PG8_LAS bf16x8*)(lds + PG8_SB(b, h) + boff + n * 2048 + k * 1024); } while (0)
; #define PG8_MMA(ai, bj, At, Bt) do { __builtin_amdgcn_s_setprio(1); _Pragma("unroll") for (int m = 0; m < 4; ++m) _Pragma("unroll") for (int n = 0; n < 2; ++n) _Pragma("unroll") for (int k = 0; k < 2; ++k) \
;         acc[ai][bj][m][n] = __builtin_amdgcn_mfma_f32_16x16x32_bf16(Bt[n][k], At[m][k], acc[ai][bj][m][n], 0, 0, 0); __builtin_amdgcn_s_setprio(0); } while (0)
; #define PG8_WAIT_V(n) asm volatile("s_waitcnt vmcnt(" #n ")" ::: "memory")
; #define PG8_WAIT_L(n) asm volatile("s_waitcnt lgkmcnt(" #n ")" ::: "memory")
; #define PG8_BAR __builtin_amdgcn_s_barrier()
; #define PG8_SCHED __builtin_amdgcn_sched_barrier(0)
; template <class Epi, class Sched, bool ALIGN_EPI = false, bool SP2 = false>
; __device__ __forceinline__ void gemm_phase(PG8_LAS unsigned char* lds, const Gemm g, const Sched& S, const Epi& E) {
;     ...
;             PG8_WAIT_V(8); PG8_WAIT_L(0); PG8_BAR; PG8_MMA(1, 0, At, B0); PG8_MMA(1, 1, At, B1); PG8_BAR; PG8_SCHED;
;             PG8_LDB(B0, 1, 0); PG8_LDB(B1, 1, 1); PG8_SCHED; PG8_LDA(At, 1, 0); PG8_STAGE(PG8_SA(0, 1), a2 + hstep, voffA);
;             PG8_WAIT_V(8); PG8_WAIT_L(0); PG8_BAR; PG8_MMA(0, 0, At, B0); PG8_MMA(0, 1, At, B1); PG8_BAR; PG8_SCHED;
	v_mfma_f32_16x16x32_bf16 v[60:63], v[132:135], v[192:195], v[60:63]
	v_mfma_f32_16x16x32_bf16 v[56:59], v[140:143], v[192:195], v[56:59]
	v_mfma_f32_16x16x32_bf16 v[44:47], v[132:135], v[208:211], v[44:47]
	v_mfma_f32_16x16x32_bf16 v[40:43], v[140:143], v[208:211], v[40:43]
	v_mfma_f32_16x16x32_bf16 v[28:31], v[132:135], v[220:223], v[28:31]
	v_mfma_f32_16x16x32_bf16 v[24:27], v[140:143], v[220:223], v[24:27]
	v_mfma_f32_16x16x32_bf16 v[12:15], v[132:135], v[228:231], v[12:15]
	v_mfma_f32_16x16x32_bf16 v[8:11], v[140:143], v[228:231], v[8:11]
	v_mfma_f32_16x16x32_bf16 v[60:63], v[136:139], v[204:207], v[60:63]
	v_mfma_f32_16x16x32_bf16 v[56:59], v[144:147], v[204:207], v[56:59]
	v_mfma_f32_16x16x32_bf16 v[44:47], v[136:139], v[216:219], v[44:47]
	v_mfma_f32_16x16x32_bf16 v[40:43], v[144:147], v[216:219], v[40:43]
	v_mfma_f32_16x16x32_bf16 v[28:31], v[136:139], v[224:227], v[28:31]
	v_mfma_f32_16x16x32_bf16 v[24:27], v[144:147], v[224:227], v[24:27]
	v_mfma_f32_16x16x32_bf16 v[12:15], v[136:139], v[232:235], v[12:15]
	v_mfma_f32_16x16x32_bf16 v[8:11], v[144:147], v[232:235], v[8:11]
	v_mfma_f32_16x16x32_bf16 v[52:55], v[148:151], v[192:195], v[52:55]
	v_mfma_f32_16x16x32_bf16 v[48:51], v[184:187], v[192:195], v[48:51]
	v_mfma_f32_16x16x32_bf16 v[36:39], v[148:151], v[208:211], v[36:39]
	v_mfma_f32_16x16x32_bf16 v[32:35], v[184:187], v[208:211], v[32:35]
	v_mfma_f32_16x16x32_bf16 v[20:23], v[148:151], v[220:223], v[20:23]
	v_mfma_f32_16x16x32_bf16 v[16:19], v[184:187], v[220:223], v[16:19]
	v_mfma_f32_16x16x32_bf16 v[4:7], v[148:151], v[228:231], v[4:7]
	v_mfma_f32_16x16x32_bf16 v[0:3], v[184:187], v[228:231], v[0:3]
	v_mfma_f32_16x16x32_bf16 v[52:55], v[180:183], v[204:207], v[52:55]
	v_mfma_f32_16x16x32_bf16 v[48:51], v[188:191], v[204:207], v[48:51]
	v_mfma_f32_16x16x32_bf16 v[36:39], v[180:183], v[216:219], v[36:39]
	v_mfma_f32_16x16x32_bf16 v[32:35], v[188:191], v[216:219], v[32:35]
	v_mfma_f32_16x16x32_bf16 v[20:23], v[180:183], v[224:227], v[20:23]
	v_mfma_f32_16x16x32_bf16 v[16:19], v[188:191], v[224:227], v[16:19]
	v_mfma_f32_16x16x32_bf16 v[4:7], v[180:183], v[232:235], v[4:7]
	v_mfma_f32_16x16x32_bf16 v[0:3], v[188:191], v[232:235], v[0:3]
	s_setprio 0
	s_barrier
	s_add_i32 s13, 0, 0x18000
	s_add_i32 s29, 0, 0x1c000
	v_add_u32_e32 v144, s13, v199
	v_add_u32_e32 v188, s29, v199
	s_mov_b32 m0, s34
	ds_read_b128 v[132:135], v144
	global_load_lds_dwordx4 v[242:243], off
	ds_read_b128 v[136:139], v144 offset:1024
	ds_read_b128 v[140:143], v144 offset:2048
	ds_read_b128 v[144:147], v144 offset:3072
	ds_read_b128 v[148:151], v188
	ds_read_b128 v[180:183], v188 offset:1024
	ds_read_b128 v[184:187], v188 offset:2048
	ds_read_b128 v[188:191], v188 offset:3072
	v_lshl_add_u64 v[196:197], v[196:197], 0, s[14:15]
	s_mov_b32 m0, s35
	v_lshl_add_u64 v[244:245], v[196:197], 0, v[162:163]
	ds_read_b128 v[192:195], v202 offset:32768
	ds_read_b128 v[204:207], v202 offset:33792
	ds_read_b128 v[208:211], v202 offset:34816
	ds_read_b128 v[216:219], v202 offset:35840
	ds_read_b128 v[220:223], v202 offset:36864
	ds_read_b128 v[224:227], v202 offset:37888
	ds_read_b128 v[228:231], v202 offset:38912
	ds_read_b128 v[232:235], v202 offset:39936
	global_load_lds_dwordx4 v[244:245], off
	s_mov_b32 m0, s36
	v_lshl_add_u64 v[196:197], v[196:197], 0, v[166:167]
	global_load_lds_dwordx4 v[196:197], off
	s_waitcnt vmcnt(8) lgkmcnt(0)
	s_setprio 1
	s_barrier
	v_mfma_f32_16x16x32_bf16 v[120:123], v[132:135], v[192:195], v[120:123]
	v_mfma_f32_16x16x32_bf16 v[124:127], v[140:143], v[192:195], v[124:127]
	v_mfma_f32_16x16x32_bf16 v[108:111], v[132:135], v[208:211], v[108:111]
	v_mfma_f32_16x16x32_bf16 v[104:107], v[140:143], v[208:211], v[104:107]
	v_mfma_f32_16x16x32_bf16 v[92:95], v[132:135], v[220:223], v[92:95]
	v_mfma_f32_16x16x32_bf16 v[88:91], v[140:143], v[220:223], v[88:91]
	v_mfma_f32_16x16x32_bf16 v[76:79], v[132:135], v[228:231], v[76:79]
	v_mfma_f32_16x16x32_bf16 v[72:75], v[140:143], v[228:231], v[72:75]
	v_mfma_f32_16x16x32_bf16 v[120:123], v[136:139], v[204:207], v[120:123]
	v_mfma_f32_16x16x32_bf16 v[124:127], v[144:147], v[204:207], v[124:127]
	v_mfma_f32_16x16x32_bf16 v[108:111], v[136:139], v[216:219], v[108:111]
	v_mfma_f32_16x16x32_bf16 v[104:107], v[144:147], v[216:219], v[104:107]
	v_mfma_f32_16x16x32_bf16 v[92:95], v[136:139], v[224:227], v[92:95]
	v_mfma_f32_16x16x32_bf16 v[88:91], v[144:147], v[224:227], v[88:91]
	v_mfma_f32_16x16x32_bf16 v[76:79], v[136:139], v[232:235], v[76:79]
	v_mfma_f32_16x16x32_bf16 v[72:75], v[144:147], v[232:235], v[72:75]
	v_mfma_f32_16x16x32_bf16 v[116:119], v[148:151], v[192:195], v[116:119]
	v_mfma_f32_16x16x32_bf16 v[112:115], v[184:187], v[192:195], v[112:115]
	v_mfma_f32_16x16x32_bf16 v[100:103], v[148:151], v[208:211], v[100:103]
	v_mfma_f32_16x16x32_bf16 v[96:99], v[184:187], v[208:211], v[96:99]
	v_mfma_f32_16x16x32_bf16 v[84:87], v[148:151], v[220:223], v[84:87]
	v_mfma_f32_16x16x32_bf16 v[80:83], v[184:187], v[220:223], v[80:83]
	v_mfma_f32_16x16x32_bf16 v[68:71], v[148:151], v[228:231], v[68:71]
	v_mfma_f32_16x16x32_bf16 v[64:67], v[184:187], v[228:231], v[64:67]
	v_mfma_f32_16x16x32_bf16 v[116:119], v[180:183], v[204:207], v[116:119]
	v_mfma_f32_16x16x32_bf16 v[112:115], v[188:191], v[204:207], v[112:115]
	v_mfma_f32_16x16x32_bf16 v[100:103], v[180:183], v[216:219], v[100:103]
	v_mfma_f32_16x16x32_bf16 v[96:99], v[188:191], v[216:219], v[96:99]
	v_mfma_f32_16x16x32_bf16 v[84:87], v[180:183], v[224:227], v[84:87]
	v_mfma_f32_16x16x32_bf16 v[80:83], v[188:191], v[224:227], v[80:83]
	v_mfma_f32_16x16x32_bf16 v[68:71], v[180:183], v[232:235], v[68:71]
	v_mfma_f32_16x16x32_bf16 v[64:67], v[188:191], v[232:235], v[64:67]
	s_setprio 0
	s_barrier
; #define PG8_STAGE(bufoff, gbase, voff) do { _Pragma("unroll") for (int _i = 0; _i < 2; ++_i) \
;         __builtin_amdgcn_global_load_lds((const unsigned*)((const char*)(gbase) + (voff)[_i]), (PG8_LAS unsigned*)(lds + (bufoff) + ldsw + _i * 8192), 16, 0, 0); } while (0)
; #define PG8_LDA(dst, b, h) do { _Pragma("unroll") for (int m = 0; m < 4; ++m) _Pragma("unroll") for (int k = 0; k < 2; ++k) dst[m][k] = *(const PG8_LAS bf16x8*)(lds + PG8_SA(b, h) + aoff + m * 2048 + k * 1024); } while (0)
; #define PG8_MMA(ai, bj, At, Bt) do { __builtin_amdgcn_s_setprio(1); _Pragma("unroll") for (int m = 0; m < 4; ++m) _Pragma("unroll") for (int n = 0; n < 2; ++n) _Pragma("unroll") for (int k = 0; k < 2; ++k) \
;         acc[ai][bj][m][n] = __builtin_amdgcn_mfma_f32_16x16x32_bf16(Bt[n][k], At[m][k], acc[ai][bj][m][n], 0, 0, 0); __builtin_amdgcn_s_setprio(0); } while (0)
; #define PG8_WAIT_V(n) asm volatile("s_waitcnt vmcnt(" #n ")" ::: "memory")
; #define PG8_WAIT_L(n) asm volatile("s_waitcnt lgkmcnt(" #n ")" ::: "memory")
; #define PG8_BAR __builtin_amdgcn_s_barrier()
; #define PG8_SCHED __builtin_amdgcn_sched_barrier(0)
; template <class Epi, class Sched, bool ALIGN_EPI = false, bool SP2 = false>
; __device__ __forceinline__ void gemm_phase(PG8_LAS unsigned char* lds, const Gemm g, const Sched& S, const Epi& E) {
;     ...
;             PG8_LDA(At, 1, 1); PG8_STAGE(PG8_SB(1, 0), b3, voffB); PG8_STAGE(PG8_SB(1, 1), b3 + hstep, voffB); PG8_STAGE(PG8_SA(1, 0), a3, voffA);
;             PG8_WAIT_V(8); PG8_WAIT_L(0); PG8_BAR; PG8_MMA(1, 0, At, B0); PG8_MMA(1, 1, At, B1); PG8_BAR; PG8_SCHED;
	s_add_i32 s13, s13, s30
	v_lshl_add_u64 v[196:197], v[214:215], 0, s[22:23]
	s_mov_b32 m0, s13
	ds_read_b128 v[192:195], v202 offset:49152
	ds_read_b128 v[204:207], v202 offset:50176
	ds_read_b128 v[208:211], v202 offset:51200
	ds_read_b128 v[216:219], v202 offset:52224
	ds_read_b128 v[220:223], v202 offset:53248
	ds_read_b128 v[224:227], v202 offset:54272
	ds_read_b128 v[228:231], v202 offset:55296
	ds_read_b128 v[232:235], v202 offset:56320
	global_load_lds_dwordx4 v[196:197], off
	v_lshl_add_u64 v[196:197], v[236:237], 0, s[22:23]
	s_add_i32 m0, s13, 0x2000
	s_add_i32 s13, s29, s30
	global_load_lds_dwordx4 v[196:197], off
	s_mov_b32 m0, s13
	v_lshl_add_u64 v[196:197], v[238:239], 0, s[22:23]
	global_load_lds_dwordx4 v[196:197], off
	s_add_i32 m0, s13, 0x2000
	v_lshl_add_u64 v[196:197], v[212:213], 0, s[22:23]
	global_load_lds_dwordx4 v[196:197], off
	s_mov_b32 m0, s37
	v_lshl_add_u64 v[196:197], v[240:241], 0, s[22:23]
	global_load_lds_dwordx4 v[196:197], off
	s_mov_b32 m0, s41
	v_lshl_add_u64 v[196:197], v[242:243], 0, s[22:23]
	global_load_lds_dwordx4 v[196:197], off
	s_waitcnt vmcnt(8) lgkmcnt(0)
	s_setprio 1
	s_barrier
	v_mfma_f32_16x16x32_bf16 v[60:63], v[132:135], v[192:195], v[60:63]
	v_mfma_f32_16x16x32_bf16 v[56:59], v[140:143], v[192:195], v[56:59]
	v_mfma_f32_16x16x32_bf16 v[44:47], v[132:135], v[208:211], v[44:47]
	v_mfma_f32_16x16x32_bf16 v[40:43], v[140:143], v[208:211], v[40:43]
	v_mfma_f32_16x16x32_bf16 v[28:31], v[132:135], v[220:223], v[28:31]
	v_mfma_f32_16x16x32_bf16 v[24:27], v[140:143], v[220:223], v[24:27]
	v_mfma_f32_16x16x32_bf16 v[12:15], v[132:135], v[228:231], v[12:15]
	v_mfma_f32_16x16x32_bf16 v[8:11], v[140:143], v[228:231], v[8:11]
	v_mfma_f32_16x16x32_bf16 v[60:63], v[136:139], v[204:207], v[60:63]
	v_mfma_f32_16x16x32_bf16 v[56:59], v[144:147], v[204:207], v[56:59]
	v_mfma_f32_16x16x32_bf16 v[44:47], v[136:139], v[216:219], v[44:47]
	v_mfma_f32_16x16x32_bf16 v[40:43], v[144:147], v[216:219], v[40:43]
	v_mfma_f32_16x16x32_bf16 v[28:31], v[136:139], v[224:227], v[28:31]
	v_mfma_f32_16x16x32_bf16 v[24:27], v[144:147], v[224:227], v[24:27]
	v_mfma_f32_16x16x32_bf16 v[12:15], v[136:139], v[232:235], v[12:15]
	v_mfma_f32_16x16x32_bf16 v[8:11], v[144:147], v[232:235], v[8:11]
	v_mfma_f32_16x16x32_bf16 v[52:55], v[148:151], v[192:195], v[52:55]
	v_mfma_f32_16x16x32_bf16 v[48:51], v[184:187], v[192:195], v[48:51]
	v_mfma_f32_16x16x32_bf16 v[36:39], v[148:151], v[208:211], v[36:39]
	v_mfma_f32_16x16x32_bf16 v[32:35], v[184:187], v[208:211], v[32:35]
	v_mfma_f32_16x16x32_bf16 v[20:23], v[148:151], v[220:223], v[20:23]
	v_mfma_f32_16x16x32_bf16 v[16:19], v[184:187], v[220:223], v[16:19]
	v_mfma_f32_16x16x32_bf16 v[4:7], v[148:151], v[228:231], v[4:7]
	v_mfma_f32_16x16x32_bf16 v[0:3], v[184:187], v[228:231], v[0:3]
	v_mfma_f32_16x16x32_bf16 v[52:55], v[180:183], v[204:207], v[52:55]
	v_mfma_f32_16x16x32_bf16 v[48:51], v[188:191], v[204:207], v[48:51]
	v_mfma_f32_16x16x32_bf16 v[36:39], v[180:183], v[216:219], v[36:39]
	v_mfma_f32_16x16x32_bf16 v[32:35], v[188:191], v[216:219], v[32:35]
	v_mfma_f32_16x16x32_bf16 v[20:23], v[180:183], v[224:227], v[20:23]
	v_mfma_f32_16x16x32_bf16 v[16:19], v[188:191], v[224:227], v[16:19]
	v_mfma_f32_16x16x32_bf16 v[4:7], v[180:183], v[232:235], v[4:7]
	v_mfma_f32_16x16x32_bf16 v[0:3], v[188:191], v[232:235], v[0:3]
	s_setprio 0
	s_barrier
	v_lshl_add_u64 v[128:129], v[128:129], 0, s[26:27]
	s_cmp_ge_i32 s12, s47
	v_lshl_add_u64 v[130:131], v[130:131], 0, s[26:27]
	s_cbranch_scc0 .LBB0_940

; #define PG8_STAGE(bufoff, gbase, voff) do { _Pragma("unroll") for (int _i = 0; _i < 2; ++_i) \
;         __builtin_amdgcn_global_load_lds((const unsigned*)((const char*)(gbase) + (voff)[_i]), (PG8_LAS unsigned*)(lds + (bufoff) + ldsw + _i * 8192), 16, 0, 0); } while (0)
; #define PG8_LDA(dst, b, h) do { _Pragma("unroll") for (int m = 0; m < 4; ++m) _Pragma("unroll") for (int k = 0; k < 2; ++k) dst[m][k] = *(const PG8_LAS bf16x8*)(lds + PG8_SA(b, h) + aoff + m * 2048 + k * 1024); } while (0)
; #define PG8_LDB(dst, b, h) do { _Pragma("unroll") for (int n = 0; n < 2; ++n) _Pragma("unroll") for (int k = 0; k < 2; ++k) dst[n][k] = *(const PG8_LAS bf16x8*)(lds + PG8_SB(b, h) + boff + n * 2048 + k * 1024); } while (0)
; #define PG8_MMA(ai, bj, At, Bt) do { __builtin_amdgcn_s_setprio(1); _Pragma("unroll") for (int m = 0; m < 4; ++m) _Pragma("unroll") for (int n = 0; n < 2; ++n) _Pragma("unroll") for (int k = 0; k < 2; ++k) \
;         acc[ai][bj][m][n] = __builtin_amdgcn_mfma_f32_16x16x32_bf16(Bt[n][k], At[m][k], acc[ai][bj][m][n], 0, 0, 0); __builtin_amdgcn_s_setprio(0); } while (0)
; #define PG8_WAIT_V(n) asm volatile("s_waitcnt vmcnt(" #n ")" ::: "memory")
; #define PG8_WAIT_L(n) asm volatile("s_waitcnt lgkmcnt(" #n ")" ::: "memory")
; template <class Epi, class Sched, bool ALIGN_EPI = false, bool SP2 = false>
; __device__ __forceinline__ void gemm_phase(PG8_LAS unsigned char* lds, const Gemm g, const Sched& S, const Epi& E) {
;     ...
;             const bool last = (t == nt - 2);
;             const char* a1 = cA + (size_t)(t + 1) * kstep;
;             const char* a2 = last ? nA : cA + (size_t)(t + 2) * kstep; const char* b2 = last ? nB : cB + (size_t)(t + 2) * kstep;
;             const char* a3 = a2 + kstep; const char* b3 = b2 + kstep;
;             if (last && has_next) S.a_ready(nxt);
;             if constexpr (SP2) {
;             PG8_LDB(B0, 0, 0); PG8_LDB(B1, 0, 1); PG8_SCHED; PG8_LDA(At, 0, 0); PG8_STAGE(PG8_SA(1, 1), a1 + hstep, voffA);
;             PG8_WAIT_V(8); PG8_WAIT_L(0); PG8_BAR; PG8_MMA(0, 0, At, B0); PG8_MMA(0, 1, At, B1); PG8_BAR; PG8_SCHED;
;             PG8_LDA(At, 0, 1); PG8_STAGE(PG8_SB(0, 0), b2, voffB); PG8_STAGE(PG8_SB(0, 1), b2 + hstep, voffB); PG8_STAGE(PG8_SA(0, 0), a2, voffA);
;             PG8_WAIT_V(8); PG8_WAIT_L(0); PG8_BAR; PG8_MMA(1, 0, At, B0); PG8_MMA(1, 1, At, B1); PG8_BAR; PG8_SCHED;
.LBB0_1021:
	v_add_u32_e32 v166, s55, v169
	v_add_u32_e32 v168, s56, v169
	ds_read_b128 v[162:165], v166
	ds_read_b128 v[182:185], v166 offset:1024
	ds_read_b128 v[186:189], v166 offset:2048
	ds_read_b128 v[190:193], v166 offset:3072
	ds_read_b128 v[194:197], v168
	ds_read_b128 v[198:201], v168 offset:1024
	ds_read_b128 v[202:205], v168 offset:2048
	ds_read_b128 v[206:209], v168 offset:3072
	s_cmp_eq_u32 s54, s10
	v_lshl_add_u64 v[172:173], v[160:161], 0, s[22:23]
	s_cselect_b64 vcc, -1, 0
	s_add_i32 s10, s10, 2
	v_cndmask_b32_e32 v173, v173, v153, vcc
	v_cndmask_b32_e32 v172, v172, v152, vcc
	v_cndmask_b32_e32 v215, v159, v155, vcc
	v_cndmask_b32_e32 v214, v158, v154, vcc
	s_mov_b32 m0, s57
	v_lshl_add_u64 v[244:245], v[160:161], 0, v[148:149]
	ds_read_b128 v[210:213], v179
	ds_read_b128 v[216:219], v179 offset:1024
	ds_read_b128 v[220:223], v179 offset:2048
	ds_read_b128 v[224:227], v179 offset:3072
	ds_read_b128 v[228:231], v179 offset:4096
	ds_read_b128 v[232:235], v179 offset:5120
	ds_read_b128 v[236:239], v179 offset:6144
	ds_read_b128 v[240:243], v179 offset:7168
	global_load_lds_dwordx4 v[244:245], off
	s_mov_b32 m0, s58
	v_lshl_add_u64 v[244:245], v[160:161], 0, v[146:147]
	global_load_lds_dwordx4 v[244:245], off
	s_waitcnt vmcnt(8) lgkmcnt(0)
	s_setprio 1
	s_barrier
	v_mfma_f32_16x16x32_bf16 v[124:127], v[162:165], v[210:213], v[124:127]
	v_mfma_f32_16x16x32_bf16 v[116:119], v[186:189], v[210:213], v[116:119]
	v_mfma_f32_16x16x32_bf16 v[108:111], v[162:165], v[220:223], v[108:111]
	v_mfma_f32_16x16x32_bf16 v[100:103], v[186:189], v[220:223], v[100:103]
	v_mfma_f32_16x16x32_bf16 v[92:95], v[162:165], v[228:231], v[92:95]
	v_mfma_f32_16x16x32_bf16 v[84:87], v[186:189], v[228:231], v[84:87]
	v_mfma_f32_16x16x32_bf16 v[76:79], v[162:165], v[236:239], v[76:79]
	v_mfma_f32_16x16x32_bf16 v[68:71], v[186:189], v[236:239], v[68:71]
	v_mfma_f32_16x16x32_bf16 v[124:127], v[182:185], v[216:219], v[124:127]
	v_mfma_f32_16x16x32_bf16 v[116:119], v[190:193], v[216:219], v[116:119]
	v_mfma_f32_16x16x32_bf16 v[108:111], v[182:185], v[224:227], v[108:111]
	v_mfma_f32_16x16x32_bf16 v[100:103], v[190:193], v[224:227], v[100:103]
	v_mfma_f32_16x16x32_bf16 v[92:95], v[182:185], v[232:235], v[92:95]
	v_mfma_f32_16x16x32_bf16 v[84:87], v[190:193], v[232:235], v[84:87]
	v_mfma_f32_16x16x32_bf16 v[76:79], v[182:185], v[240:243], v[76:79]
	v_mfma_f32_16x16x32_bf16 v[68:71], v[190:193], v[240:243], v[68:71]
	v_mfma_f32_16x16x32_bf16 v[120:123], v[194:197], v[210:213], v[120:123]
	v_mfma_f32_16x16x32_bf16 v[112:115], v[202:205], v[210:213], v[112:115]
	v_mfma_f32_16x16x32_bf16 v[104:107], v[194:197], v[220:223], v[104:107]
	v_mfma_f32_16x16x32_bf16 v[96:99], v[202:205], v[220:223], v[96:99]
	v_mfma_f32_16x16x32_bf16 v[88:91], v[194:197], v[228:231], v[88:91]
	v_mfma_f32_16x16x32_bf16 v[80:83], v[202:205], v[228:231], v[80:83]
	v_mfma_f32_16x16x32_bf16 v[72:75], v[194:197], v[236:239], v[72:75]
	v_mfma_f32_16x16x32_bf16 v[64:67], v[202:205], v[236:239], v[64:67]
	v_mfma_f32_16x16x32_bf16 v[120:123], v[198:201], v[216:219], v[120:123]
	v_mfma_f32_16x16x32_bf16 v[112:115], v[206:209], v[216:219], v[112:115]
	v_mfma_f32_16x16x32_bf16 v[104:107], v[198:201], v[224:227], v[104:107]
	v_mfma_f32_16x16x32_bf16 v[96:99], v[206:209], v[224:227], v[96:99]
	v_mfma_f32_16x16x32_bf16 v[88:91], v[198:201], v[232:235], v[88:91]
	v_mfma_f32_16x16x32_bf16 v[80:83], v[206:209], v[232:235], v[80:83]
	v_mfma_f32_16x16x32_bf16 v[72:75], v[198:201], v[240:243], v[72:75]
	v_mfma_f32_16x16x32_bf16 v[64:67], v[206:209], v[240:243], v[64:67]
	s_setprio 0
	s_barrier
	s_mov_b32 m0, s61
	v_lshl_add_u64 v[244:245], v[214:215], 0, v[138:139]
	ds_read_b128 v[210:213], v179 offset:16384
	ds_read_b128 v[216:219], v179 offset:17408
	ds_read_b128 v[220:223], v179 offset:18432
	ds_read_b128 v[224:227], v179 offset:19456
	ds_read_b128 v[228:231], v179 offset:20480
	ds_read_b128 v[232:235], v179 offset:21504
	ds_read_b128 v[236:239], v179 offset:22528
	ds_read_b128 v[240:243], v179 offset:23552
	global_load_lds_dwordx4 v[244:245], off
	v_lshl_add_u64 v[246:247], v[214:215], 0, v[134:135]
	s_mov_b32 m0, s62
	v_lshl_add_u64 v[214:215], v[214:215], 0, s[14:15]
	global_load_lds_dwordx4 v[246:247], off
	v_lshl_add_u64 v[248:249], v[214:215], 0, v[138:139]
	s_mov_b32 m0, s63
	v_lshl_add_u64 v[214:215], v[214:215], 0, v[134:135]
	global_load_lds_dwordx4 v[248:249], off
	s_add_i32 m0, s63, 0x2000
	v_lshl_add_u64 v[250:251], v[172:173], 0, v[140:141]
	global_load_lds_dwordx4 v[214:215], off
	s_mov_b32 m0, s46
	v_lshl_add_u64 v[252:253], v[172:173], 0, v[136:137]
	global_load_lds_dwordx4 v[250:251], off
	s_nop 0
	s_waitcnt vmcnt(7) lgkmcnt(0)
	s_setprio 1
	s_barrier
; #define PG8_STAGE(bufoff, gbase, voff) do { _Pragma("unroll") for (int _i = 0; _i < 2; ++_i) \
;         __builtin_amdgcn_global_load_lds((const unsigned*)((const char*)(gbase) + (voff)[_i]), (PG8_LAS unsigned*)(lds + (bufoff) + ldsw + _i * 8192), 16, 0, 0); } while (0)
; #define PG8_LDA(dst, b, h) do { _Pragma("unroll") for (int m = 0; m < 4; ++m) _Pragma("unroll") for (int k = 0; k < 2; ++k) dst[m][k] = *(const PG8_LAS bf16x8*)(lds + PG8_SA(b, h) + aoff + m * 2048 + k * 1024); } while (0)
; #define PG8_LDB(dst, b, h) do { _Pragma("unroll") for (int n = 0; n < 2; ++n) _Pragma("unroll") for (int k = 0; k < 2; ++k) dst[n][k] = *(const PG8_LAS bf16x8*)(lds + PG8_SB(b, h) + boff + n * 2048 + k * 1024); } while (0)
; #define PG8_MMA(ai, bj, At, Bt) do { __builtin_amdgcn_s_setprio(1); _Pragma("unroll") for (int m = 0; m < 4; ++m) _Pragma("unroll") for (int n = 0; n < 2; ++n) _Pragma("unroll") for (int k = 0; k < 2; ++k) \
;         acc[ai][bj][m][n] = __builtin_amdgcn_mfma_f32_16x16x32_bf16(Bt[n][k], At[m][k], acc[ai][bj][m][n], 0, 0, 0); __builtin_amdgcn_s_setprio(0); } while (0)
; #define PG8_WAIT_V(n) asm volatile("s_waitcnt vmcnt(" #n ")" ::: "memory")
; #define PG8_WAIT_L(n) asm volatile("s_waitcnt lgkmcnt(" #n ")" ::: "memory")
; #define PG8_BAR __builtin_amdgcn_s_barrier()
; #define PG8_SCHED __builtin_amdgcn_sched_barrier(0)
; template <class Epi, class Sched, bool ALIGN_EPI = false, bool SP2 = false>
; __device__ __forceinline__ void gemm_phase(PG8_LAS unsigned char* lds, const Gemm g, const Sched& S, const Epi& E) {
;     ...
;             PG8_WAIT_V(8); PG8_WAIT_L(0); PG8_BAR; PG8_MMA(1, 0, At, B0); PG8_MMA(1, 1, At, B1); PG8_BAR; PG8_SCHED;
;             PG8_LDB(B0, 1, 0); PG8_LDB(B1, 1, 1); PG8_SCHED; PG8_LDA(At, 1, 0); PG8_STAGE(PG8_SA(0, 1), a2 + hstep, voffA);
;             PG8_WAIT_V(8); PG8_WAIT_L(0); PG8_BAR; PG8_MMA(0, 0, At, B0); PG8_MMA(0, 1, At, B1); PG8_BAR; PG8_SCHED;
	v_mfma_f32_16x16x32_bf16 v[60:63], v[162:165], v[210:213], v[60:63]
	v_mfma_f32_16x16x32_bf16 v[52:55], v[186:189], v[210:213], v[52:55]
	v_mfma_f32_16x16x32_bf16 v[44:47], v[162:165], v[220:223], v[44:47]
	v_mfma_f32_16x16x32_bf16 v[36:39], v[186:189], v[220:223], v[36:39]
	v_mfma_f32_16x16x32_bf16 v[28:31], v[162:165], v[228:231], v[28:31]
	v_mfma_f32_16x16x32_bf16 v[20:23], v[186:189], v[228:231], v[20:23]
	v_mfma_f32_16x16x32_bf16 v[12:15], v[162:165], v[236:239], v[12:15]
	v_mfma_f32_16x16x32_bf16 v[4:7], v[186:189], v[236:239], v[4:7]
	v_mfma_f32_16x16x32_bf16 v[60:63], v[182:185], v[216:219], v[60:63]
	v_mfma_f32_16x16x32_bf16 v[52:55], v[190:193], v[216:219], v[52:55]
	v_mfma_f32_16x16x32_bf16 v[44:47], v[182:185], v[224:227], v[44:47]
	v_mfma_f32_16x16x32_bf16 v[36:39], v[190:193], v[224:227], v[36:39]
	v_mfma_f32_16x16x32_bf16 v[28:31], v[182:185], v[232:235], v[28:31]
	v_mfma_f32_16x16x32_bf16 v[20:23], v[190:193], v[232:235], v[20:23]
	v_mfma_f32_16x16x32_bf16 v[12:15], v[182:185], v[240:243], v[12:15]
	v_mfma_f32_16x16x32_bf16 v[4:7], v[190:193], v[240:243], v[4:7]
	v_mfma_f32_16x16x32_bf16 v[56:59], v[194:197], v[210:213], v[56:59]
	v_mfma_f32_16x16x32_bf16 v[48:51], v[202:205], v[210:213], v[48:51]
	v_mfma_f32_16x16x32_bf16 v[40:43], v[194:197], v[220:223], v[40:43]
	v_mfma_f32_16x16x32_bf16 v[32:35], v[202:205], v[220:223], v[32:35]
	v_mfma_f32_16x16x32_bf16 v[24:27], v[194:197], v[228:231], v[24:27]
	v_mfma_f32_16x16x32_bf16 v[16:19], v[202:205], v[228:231], v[16:19]
	v_mfma_f32_16x16x32_bf16 v[8:11], v[194:197], v[236:239], v[8:11]
	v_mfma_f32_16x16x32_bf16 v[0:3], v[202:205], v[236:239], v[0:3]
	v_mfma_f32_16x16x32_bf16 v[56:59], v[198:201], v[216:219], v[56:59]
	v_mfma_f32_16x16x32_bf16 v[48:51], v[206:209], v[216:219], v[48:51]
	v_mfma_f32_16x16x32_bf16 v[40:43], v[198:201], v[224:227], v[40:43]
	v_mfma_f32_16x16x32_bf16 v[32:35], v[206:209], v[224:227], v[32:35]
	v_mfma_f32_16x16x32_bf16 v[24:27], v[198:201], v[232:235], v[24:27]
	v_mfma_f32_16x16x32_bf16 v[16:19], v[206:209], v[232:235], v[16:19]
	v_mfma_f32_16x16x32_bf16 v[8:11], v[198:201], v[240:243], v[8:11]
	v_mfma_f32_16x16x32_bf16 v[0:3], v[206:209], v[240:243], v[0:3]
	s_setprio 0
	s_barrier
	s_add_i32 s11, 0, 0x18000
	v_add_u32_e32 v166, s11, v169
	s_add_i32 s13, 0, 0x1c000
	s_mov_b32 m0, s47
	ds_read_b128 v[162:165], v166
	global_load_lds_dwordx4 v[252:253], off
	ds_read_b128 v[182:185], v166 offset:1024
	ds_read_b128 v[186:189], v166 offset:2048
	ds_read_b128 v[190:193], v166 offset:3072
	v_add_u32_e32 v166, s13, v169
	ds_read_b128 v[194:197], v166
	ds_read_b128 v[198:201], v166 offset:1024
	ds_read_b128 v[202:205], v166 offset:2048
	ds_read_b128 v[206:209], v166 offset:3072
	v_lshl_add_u64 v[172:173], v[172:173], 0, s[14:15]
	s_mov_b32 m0, s48
	v_lshl_add_u64 v[170:171], v[172:173], 0, v[140:141]
	ds_read_b128 v[210:213], v179 offset:32768
	ds_read_b128 v[216:219], v179 offset:33792
	ds_read_b128 v[220:223], v179 offset:34816
	ds_read_b128 v[224:227], v179 offset:35840
	ds_read_b128 v[228:231], v179 offset:36864
	ds_read_b128 v[232:235], v179 offset:37888
	ds_read_b128 v[236:239], v179 offset:38912
	ds_read_b128 v[240:243], v179 offset:39936
	global_load_lds_dwordx4 v[170:171], off
	s_mov_b32 m0, s49
	v_lshl_add_u64 v[170:171], v[172:173], 0, v[136:137]
	global_load_lds_dwordx4 v[170:171], off
	s_waitcnt vmcnt(8) lgkmcnt(0)
	s_setprio 1
	s_barrier
	v_mfma_f32_16x16x32_bf16 v[124:127], v[162:165], v[210:213], v[124:127]
	v_mfma_f32_16x16x32_bf16 v[116:119], v[186:189], v[210:213], v[116:119]
	v_mfma_f32_16x16x32_bf16 v[108:111], v[162:165], v[220:223], v[108:111]
	v_mfma_f32_16x16x32_bf16 v[100:103], v[186:189], v[220:223], v[100:103]
	v_mfma_f32_16x16x32_bf16 v[92:95], v[162:165], v[228:231], v[92:95]
	v_mfma_f32_16x16x32_bf16 v[84:87], v[186:189], v[228:231], v[84:87]
	v_mfma_f32_16x16x32_bf16 v[76:79], v[162:165], v[236:239], v[76:79]
	v_mfma_f32_16x16x32_bf16 v[68:71], v[186:189], v[236:239], v[68:71]
	v_mfma_f32_16x16x32_bf16 v[124:127], v[182:185], v[216:219], v[124:127]
	v_mfma_f32_16x16x32_bf16 v[116:119], v[190:193], v[216:219], v[116:119]
	v_mfma_f32_16x16x32_bf16 v[108:111], v[182:185], v[224:227], v[108:111]
	v_mfma_f32_16x16x32_bf16 v[100:103], v[190:193], v[224:227], v[100:103]
	v_mfma_f32_16x16x32_bf16 v[92:95], v[182:185], v[232:235], v[92:95]
	v_mfma_f32_16x16x32_bf16 v[84:87], v[190:193], v[232:235], v[84:87]
	v_mfma_f32_16x16x32_bf16 v[76:79], v[182:185], v[240:243], v[76:79]
	v_mfma_f32_16x16x32_bf16 v[68:71], v[190:193], v[240:243], v[68:71]
	v_mfma_f32_16x16x32_bf16 v[120:123], v[194:197], v[210:213], v[120:123]
	v_mfma_f32_16x16x32_bf16 v[112:115], v[202:205], v[210:213], v[112:115]
	v_mfma_f32_16x16x32_bf16 v[104:107], v[194:197], v[220:223], v[104:107]
	v_mfma_f32_16x16x32_bf16 v[96:99], v[202:205], v[220:223], v[96:99]
	v_mfma_f32_16x16x32_bf16 v[88:91], v[194:197], v[228:231], v[88:91]
	v_mfma_f32_16x16x32_bf16 v[80:83], v[202:205], v[228:231], v[80:83]
	v_mfma_f32_16x16x32_bf16 v[72:75], v[194:197], v[236:239], v[72:75]
	v_mfma_f32_16x16x32_bf16 v[64:67], v[202:205], v[236:239], v[64:67]
	v_mfma_f32_16x16x32_bf16 v[120:123], v[198:201], v[216:219], v[120:123]
	v_mfma_f32_16x16x32_bf16 v[112:115], v[206:209], v[216:219], v[112:115]
	v_mfma_f32_16x16x32_bf16 v[104:107], v[198:201], v[224:227], v[104:107]
	v_mfma_f32_16x16x32_bf16 v[96:99], v[206:209], v[224:227], v[96:99]
	v_mfma_f32_16x16x32_bf16 v[88:91], v[198:201], v[232:235], v[88:91]
	v_mfma_f32_16x16x32_bf16 v[80:83], v[206:209], v[232:235], v[80:83]
	v_mfma_f32_16x16x32_bf16 v[72:75], v[198:201], v[240:243], v[72:75]
	v_mfma_f32_16x16x32_bf16 v[64:67], v[206:209], v[240:243], v[64:67]
	s_setprio 0
	s_barrier
; #define PG8_STAGE(bufoff, gbase, voff) do { _Pragma("unroll") for (int _i = 0; _i < 2; ++_i) \
;         __builtin_amdgcn_global_load_lds((const unsigned*)((const char*)(gbase) + (voff)[_i]), (PG8_LAS unsigned*)(lds + (bufoff) + ldsw + _i * 8192), 16, 0, 0); } while (0)
; #define PG8_LDA(dst, b, h) do { _Pragma("unroll") for (int m = 0; m < 4; ++m) _Pragma("unroll") for (int k = 0; k < 2; ++k) dst[m][k] = *(const PG8_LAS bf16x8*)(lds + PG8_SA(b, h) + aoff + m * 2048 + k * 1024); } while (0)
; #define PG8_MMA(ai, bj, At, Bt) do { __builtin_amdgcn_s_setprio(1); _Pragma("unroll") for (int m = 0; m < 4; ++m) _Pragma("unroll") for (int n = 0; n < 2; ++n) _Pragma("unroll") for (int k = 0; k < 2; ++k) \
;         acc[ai][bj][m][n] = __builtin_amdgcn_mfma_f32_16x16x32_bf16(Bt[n][k], At[m][k], acc[ai][bj][m][n], 0, 0, 0); __builtin_amdgcn_s_setprio(0); } while (0)
; #define PG8_WAIT_V(n) asm volatile("s_waitcnt vmcnt(" #n ")" ::: "memory")
; #define PG8_WAIT_L(n) asm volatile("s_waitcnt lgkmcnt(" #n ")" ::: "memory")
; #define PG8_BAR __builtin_amdgcn_s_barrier()
; #define PG8_SCHED __builtin_amdgcn_sched_barrier(0)
; template <class Epi, class Sched, bool ALIGN_EPI = false, bool SP2 = false>
; __device__ __forceinline__ void gemm_phase(PG8_LAS unsigned char* lds, const Gemm g, const Sched& S, const Epi& E) {
;     ...
;             PG8_LDA(At, 1, 1); PG8_STAGE(PG8_SB(1, 0), b3, voffB); PG8_STAGE(PG8_SB(1, 1), b3 + hstep, voffB); PG8_STAGE(PG8_SA(1, 0), a3, voffA);
;             PG8_WAIT_V(8); PG8_WAIT_L(0); PG8_BAR; PG8_MMA(1, 0, At, B0); PG8_MMA(1, 1, At, B1); PG8_BAR; PG8_SCHED;
	s_add_i32 s11, s11, s29
	v_lshl_add_u64 v[170:171], v[244:245], 0, s[22:23]
	s_mov_b32 m0, s11
	ds_read_b128 v[210:213], v179 offset:49152
	ds_read_b128 v[216:219], v179 offset:50176
	ds_read_b128 v[220:223], v179 offset:51200
	ds_read_b128 v[224:227], v179 offset:52224
	ds_read_b128 v[228:231], v179 offset:53248
	ds_read_b128 v[232:235], v179 offset:54272
	ds_read_b128 v[236:239], v179 offset:55296
	ds_read_b128 v[240:243], v179 offset:56320
	global_load_lds_dwordx4 v[170:171], off
	v_lshl_add_u64 v[170:171], v[246:247], 0, s[22:23]
	s_add_i32 m0, s11, 0x2000
	s_add_i32 s11, s13, s29
	global_load_lds_dwordx4 v[170:171], off
	s_mov_b32 m0, s11
	v_lshl_add_u64 v[170:171], v[248:249], 0, s[22:23]
	global_load_lds_dwordx4 v[170:171], off
	s_add_i32 m0, s11, 0x2000
	v_lshl_add_u64 v[170:171], v[214:215], 0, s[22:23]
	global_load_lds_dwordx4 v[170:171], off
	s_mov_b32 m0, s50
	v_lshl_add_u64 v[170:171], v[250:251], 0, s[22:23]
	global_load_lds_dwordx4 v[170:171], off
	s_mov_b32 m0, s51
	v_lshl_add_u64 v[170:171], v[252:253], 0, s[22:23]
	global_load_lds_dwordx4 v[170:171], off
	s_waitcnt vmcnt(8) lgkmcnt(0)
	s_setprio 1
	s_barrier
	v_mfma_f32_16x16x32_bf16 v[60:63], v[162:165], v[210:213], v[60:63]
	v_mfma_f32_16x16x32_bf16 v[52:55], v[186:189], v[210:213], v[52:55]
	v_mfma_f32_16x16x32_bf16 v[44:47], v[162:165], v[220:223], v[44:47]
	v_mfma_f32_16x16x32_bf16 v[36:39], v[186:189], v[220:223], v[36:39]
	v_mfma_f32_16x16x32_bf16 v[28:31], v[162:165], v[228:231], v[28:31]
	v_mfma_f32_16x16x32_bf16 v[20:23], v[186:189], v[228:231], v[20:23]
	v_mfma_f32_16x16x32_bf16 v[12:15], v[162:165], v[236:239], v[12:15]
	v_mfma_f32_16x16x32_bf16 v[4:7], v[186:189], v[236:239], v[4:7]
	v_mfma_f32_16x16x32_bf16 v[60:63], v[182:185], v[216:219], v[60:63]
	v_mfma_f32_16x16x32_bf16 v[52:55], v[190:193], v[216:219], v[52:55]
	v_mfma_f32_16x16x32_bf16 v[44:47], v[182:185], v[224:227], v[44:47]
	v_mfma_f32_16x16x32_bf16 v[36:39], v[190:193], v[224:227], v[36:39]
	v_mfma_f32_16x16x32_bf16 v[28:31], v[182:185], v[232:235], v[28:31]
	v_mfma_f32_16x16x32_bf16 v[20:23], v[190:193], v[232:235], v[20:23]
	v_mfma_f32_16x16x32_bf16 v[12:15], v[182:185], v[240:243], v[12:15]
	v_mfma_f32_16x16x32_bf16 v[4:7], v[190:193], v[240:243], v[4:7]
	v_mfma_f32_16x16x32_bf16 v[56:59], v[194:197], v[210:213], v[56:59]
	v_mfma_f32_16x16x32_bf16 v[48:51], v[202:205], v[210:213], v[48:51]
	v_mfma_f32_16x16x32_bf16 v[40:43], v[194:197], v[220:223], v[40:43]
	v_mfma_f32_16x16x32_bf16 v[32:35], v[202:205], v[220:223], v[32:35]
	v_mfma_f32_16x16x32_bf16 v[24:27], v[194:197], v[228:231], v[24:27]
	v_mfma_f32_16x16x32_bf16 v[16:19], v[202:205], v[228:231], v[16:19]
	v_mfma_f32_16x16x32_bf16 v[8:11], v[194:197], v[236:239], v[8:11]
	v_mfma_f32_16x16x32_bf16 v[0:3], v[202:205], v[236:239], v[0:3]
	v_mfma_f32_16x16x32_bf16 v[56:59], v[198:201], v[216:219], v[56:59]
	v_mfma_f32_16x16x32_bf16 v[48:51], v[206:209], v[216:219], v[48:51]
	v_mfma_f32_16x16x32_bf16 v[40:43], v[198:201], v[224:227], v[40:43]
	v_mfma_f32_16x16x32_bf16 v[32:35], v[206:209], v[224:227], v[32:35]
	v_mfma_f32_16x16x32_bf16 v[24:27], v[198:201], v[232:235], v[24:27]
	v_mfma_f32_16x16x32_bf16 v[16:19], v[206:209], v[232:235], v[16:19]
	v_mfma_f32_16x16x32_bf16 v[8:11], v[198:201], v[240:243], v[8:11]
	v_mfma_f32_16x16x32_bf16 v[0:3], v[206:209], v[240:243], v[0:3]
	s_setprio 0
	s_barrier
	v_lshl_add_u64 v[158:159], v[158:159], 0, s[26:27]
	s_cmp_ge_i32 s10, s52
	v_lshl_add_u64 v[160:161], v[160:161], 0, s[26:27]
	s_cbranch_scc0 .LBB0_1021

; #define PG8_STAGE(bufoff, gbase, voff) do { _Pragma("unroll") for (int _i = 0; _i < 2; ++_i) \
;         __builtin_amdgcn_global_load_lds((const unsigned*)((const char*)(gbase) + (voff)[_i]), (PG8_LAS unsigned*)(lds + (bufoff) + ldsw + _i * 8192), 16, 0, 0); } while (0)
; #define PG8_LDA(dst, b, h) do { _Pragma("unroll") for (int m = 0; m < 4; ++m) _Pragma("unroll") for (int k = 0; k < 2; ++k) dst[m][k] = *(const PG8_LAS bf16x8*)(lds + PG8_SA(b, h) + aoff + m * 2048 + k * 1024); } while (0)
; #define PG8_LDB(dst, b, h) do { _Pragma("unroll") for (int n = 0; n < 2; ++n) _Pragma("unroll") for (int k = 0; k < 2; ++k) dst[n][k] = *(const PG8_LAS bf16x8*)(lds + PG8_SB(b, h) + boff + n * 2048 + k * 1024); } while (0)
; #define PG8_MMA(ai, bj, At, Bt) do { __builtin_amdgcn_s_setprio(1); _Pragma("unroll") for (int m = 0; m < 4; ++m) _Pragma("unroll") for (int n = 0; n < 2; ++n) _Pragma("unroll") for (int k = 0; k < 2; ++k) \
;         acc[ai][bj][m][n] = __builtin_amdgcn_mfma_f32_16x16x32_bf16(Bt[n][k], At[m][k], acc[ai][bj][m][n], 0, 0, 0); __builtin_amdgcn_s_setprio(0); } while (0)
; #define PG8_WAIT_V(n) asm volatile("s_waitcnt vmcnt(" #n ")" ::: "memory")
; #define PG8_BAR __builtin_amdgcn_s_barrier()
; template <class Epi, class Sched, bool ALIGN_EPI = false, bool SP2 = false>
; __device__ __forceinline__ void gemm_phase(PG8_LAS unsigned char* lds, const Gemm g, const Sched& S, const Epi& E) {
;     ...
;         for (int t = 0; t < nt; t += 2) {
;             const bool last = (t == nt - 2);
;             const char* a1 = cA + (size_t)(t + 1) * kstep;
;             const char* a2 = last ? nA : cA + (size_t)(t + 2) * kstep; const char* b2 = last ? nB : cB + (size_t)(t + 2) * kstep;
;             const char* a3 = a2 + kstep; const char* b3 = b2 + kstep;
;             if (last && has_next) S.a_ready(nxt);
;             if constexpr (SP2) {
;             PG8_LDB(B0, 0, 0); PG8_LDB(B1, 0, 1); PG8_SCHED; PG8_LDA(At, 0, 0); PG8_STAGE(PG8_SA(1, 1), a1 + hstep, voffA);
;             PG8_WAIT_V(8); PG8_WAIT_L(0); PG8_BAR; PG8_MMA(0, 0, At, B0); PG8_MMA(0, 1, At, B1); PG8_BAR; PG8_SCHED;
;             PG8_LDA(At, 0, 1); PG8_STAGE(PG8_SB(0, 0), b2, voffB); PG8_STAGE(PG8_SB(0, 1), b2 + hstep, voffB); PG8_STAGE(PG8_SA(0, 0), a2, voffA);
;             PG8_WAIT_V(8); PG8_WAIT_L(0); PG8_BAR; PG8_MMA(1, 0, At, B0); PG8_MMA(1, 1, At, B1); PG8_BAR; PG8_SCHED;
.LBB0_1169:
	v_add_u32_e32 v192, s52, v161
	ds_read_b128 v[164:167], v162
	ds_read_b128 v[168:171], v162 offset:1024
	ds_read_b128 v[172:175], v162 offset:2048
	ds_read_b128 v[176:179], v162 offset:3072
	ds_read_b128 v[180:183], v192
	ds_read_b128 v[184:187], v192 offset:1024
	ds_read_b128 v[188:191], v192 offset:2048
	ds_read_b128 v[192:195], v192 offset:3072
	s_cmp_eq_u32 s51, s10
	v_lshl_add_u64 v[196:197], v[158:159], 0, s[24:25]
	s_cselect_b64 vcc, -1, 0
	s_add_i32 s10, s10, 2
	v_cndmask_b32_e32 v213, v197, v151, vcc
	v_cndmask_b32_e32 v212, v196, v150, vcc
	v_cndmask_b32_e32 v215, v155, v153, vcc
	v_cndmask_b32_e32 v214, v154, v152, vcc
	s_mov_b32 m0, s54
	v_lshl_add_u64 v[232:233], v[158:159], 0, v[146:147]
	ds_read_b128 v[196:199], v163
	ds_read_b128 v[200:203], v163 offset:1024
	ds_read_b128 v[204:207], v163 offset:2048
	ds_read_b128 v[208:211], v163 offset:3072
	ds_read_b128 v[216:219], v163 offset:4096
	ds_read_b128 v[220:223], v163 offset:5120
	ds_read_b128 v[224:227], v163 offset:6144
	ds_read_b128 v[228:231], v163 offset:7168
	global_load_lds_dwordx4 v[232:233], off
	s_mov_b32 m0, s55
	v_lshl_add_u64 v[232:233], v[158:159], 0, v[144:145]
	global_load_lds_dwordx4 v[232:233], off
	s_waitcnt vmcnt(8) lgkmcnt(0)
	s_setprio 1
	s_barrier
	v_mfma_f32_16x16x32_bf16 v[124:127], v[164:167], v[196:199], v[124:127]
	v_mfma_f32_16x16x32_bf16 v[120:123], v[172:175], v[196:199], v[120:123]
	v_mfma_f32_16x16x32_bf16 v[108:111], v[164:167], v[204:207], v[108:111]
	v_mfma_f32_16x16x32_bf16 v[104:107], v[172:175], v[204:207], v[104:107]
	v_mfma_f32_16x16x32_bf16 v[92:95], v[164:167], v[216:219], v[92:95]
	v_mfma_f32_16x16x32_bf16 v[88:91], v[172:175], v[216:219], v[88:91]
	v_mfma_f32_16x16x32_bf16 v[76:79], v[164:167], v[224:227], v[76:79]
	v_mfma_f32_16x16x32_bf16 v[72:75], v[172:175], v[224:227], v[72:75]
	v_mfma_f32_16x16x32_bf16 v[124:127], v[168:171], v[200:203], v[124:127]
	v_mfma_f32_16x16x32_bf16 v[120:123], v[176:179], v[200:203], v[120:123]
	v_mfma_f32_16x16x32_bf16 v[108:111], v[168:171], v[208:211], v[108:111]
	v_mfma_f32_16x16x32_bf16 v[104:107], v[176:179], v[208:211], v[104:107]
	v_mfma_f32_16x16x32_bf16 v[92:95], v[168:171], v[220:223], v[92:95]
	v_mfma_f32_16x16x32_bf16 v[88:91], v[176:179], v[220:223], v[88:91]
	v_mfma_f32_16x16x32_bf16 v[76:79], v[168:171], v[228:231], v[76:79]
	v_mfma_f32_16x16x32_bf16 v[72:75], v[176:179], v[228:231], v[72:75]
	v_mfma_f32_16x16x32_bf16 v[116:119], v[180:183], v[196:199], v[116:119]
	v_mfma_f32_16x16x32_bf16 v[112:115], v[188:191], v[196:199], v[112:115]
	v_mfma_f32_16x16x32_bf16 v[100:103], v[180:183], v[204:207], v[100:103]
	v_mfma_f32_16x16x32_bf16 v[96:99], v[188:191], v[204:207], v[96:99]
	v_mfma_f32_16x16x32_bf16 v[84:87], v[180:183], v[216:219], v[84:87]
	v_mfma_f32_16x16x32_bf16 v[80:83], v[188:191], v[216:219], v[80:83]
	v_mfma_f32_16x16x32_bf16 v[68:71], v[180:183], v[224:227], v[68:71]
	v_mfma_f32_16x16x32_bf16 v[64:67], v[188:191], v[224:227], v[64:67]
	v_mfma_f32_16x16x32_bf16 v[116:119], v[184:187], v[200:203], v[116:119]
	v_mfma_f32_16x16x32_bf16 v[112:115], v[192:195], v[200:203], v[112:115]
	v_mfma_f32_16x16x32_bf16 v[100:103], v[184:187], v[208:211], v[100:103]
	v_mfma_f32_16x16x32_bf16 v[96:99], v[192:195], v[208:211], v[96:99]
	v_mfma_f32_16x16x32_bf16 v[84:87], v[184:187], v[220:223], v[84:87]
	v_mfma_f32_16x16x32_bf16 v[80:83], v[192:195], v[220:223], v[80:83]
	v_mfma_f32_16x16x32_bf16 v[68:71], v[184:187], v[228:231], v[68:71]
	v_mfma_f32_16x16x32_bf16 v[64:67], v[192:195], v[228:231], v[64:67]
	s_setprio 0
	s_barrier
	s_mov_b32 m0, s56
	v_lshl_add_u64 v[232:233], v[214:215], 0, v[138:139]
	ds_read_b128 v[196:199], v163 offset:16384
	ds_read_b128 v[200:203], v163 offset:17408
	ds_read_b128 v[204:207], v163 offset:18432
	ds_read_b128 v[208:211], v163 offset:19456
	ds_read_b128 v[216:219], v163 offset:20480
	ds_read_b128 v[220:223], v163 offset:21504
	ds_read_b128 v[224:227], v163 offset:22528
	ds_read_b128 v[228:231], v163 offset:23552
	global_load_lds_dwordx4 v[232:233], off
	v_lshl_add_u64 v[234:235], v[214:215], 0, v[134:135]
	s_mov_b32 m0, s57
	v_lshl_add_u64 v[214:215], v[214:215], 0, s[14:15]
	global_load_lds_dwordx4 v[234:235], off
	v_lshl_add_u64 v[236:237], v[214:215], 0, v[138:139]
	s_mov_b32 m0, s58
	v_lshl_add_u64 v[214:215], v[214:215], 0, v[134:135]
	global_load_lds_dwordx4 v[236:237], off
	s_mov_b32 m0, s59
	v_lshl_add_u64 v[238:239], v[212:213], 0, v[140:141]
	global_load_lds_dwordx4 v[214:215], off
	s_mov_b32 m0, s37
	v_lshl_add_u64 v[240:241], v[212:213], 0, v[136:137]
	global_load_lds_dwordx4 v[238:239], off
	s_nop 0
	s_waitcnt vmcnt(7) lgkmcnt(0)
	s_setprio 1
	s_barrier
; #define PG8_STAGE(bufoff, gbase, voff) do { _Pragma("unroll") for (int _i = 0; _i < 2; ++_i) \
;         __builtin_amdgcn_global_load_lds((const unsigned*)((const char*)(gbase) + (voff)[_i]), (PG8_LAS unsigned*)(lds + (bufoff) + ldsw + _i * 8192), 16, 0, 0); } while (0)
; #define PG8_LDA(dst, b, h) do { _Pragma("unroll") for (int m = 0; m < 4; ++m) _Pragma("unroll") for (int k = 0; k < 2; ++k) dst[m][k] = *(const PG8_LAS bf16x8*)(lds + PG8_SA(b, h) + aoff + m * 2048 + k * 1024); } while (0)
; #define PG8_LDB(dst, b, h) do { _Pragma("unroll") for (int n = 0; n < 2; ++n) _Pragma("unroll") for (int k = 0; k < 2; ++k) dst[n][k] = *(const PG8_LAS bf16x8*)(lds + PG8_SB(b, h) + boff + n * 2048 + k * 1024); } while (0)
; #define PG8_MMA(ai, bj, At, Bt) do { __builtin_amdgcn_s_setprio(1); _Pragma("unroll") for (int m = 0; m < 4; ++m) _Pragma("unroll") for (int n = 0; n < 2; ++n) _Pragma("unroll") for (int k = 0; k < 2; ++k) \
;         acc[ai][bj][m][n] = __builtin_amdgcn_mfma_f32_16x16x32_bf16(Bt[n][k], At[m][k], acc[ai][bj][m][n], 0, 0, 0); __builtin_amdgcn_s_setprio(0); } while (0)
; #define PG8_WAIT_V(n) asm volatile("s_waitcnt vmcnt(" #n ")" ::: "memory")
; #define PG8_WAIT_L(n) asm volatile("s_waitcnt lgkmcnt(" #n ")" ::: "memory")
; #define PG8_BAR __builtin_amdgcn_s_barrier()
; #define PG8_SCHED __builtin_amdgcn_sched_barrier(0)
; template <class Epi, class Sched, bool ALIGN_EPI = false, bool SP2 = false>
; __device__ __forceinline__ void gemm_phase(PG8_LAS unsigned char* lds, const Gemm g, const Sched& S, const Epi& E) {
;     ...
;             PG8_WAIT_V(8); PG8_WAIT_L(0); PG8_BAR; PG8_MMA(1, 0, At, B0); PG8_MMA(1, 1, At, B1); PG8_BAR; PG8_SCHED;
;             PG8_LDB(B0, 1, 0); PG8_LDB(B1, 1, 1); PG8_SCHED; PG8_LDA(At, 1, 0); PG8_STAGE(PG8_SA(0, 1), a2 + hstep, voffA);
;             PG8_WAIT_V(8); PG8_WAIT_L(0); PG8_BAR; PG8_MMA(0, 0, At, B0); PG8_MMA(0, 1, At, B1); PG8_BAR; PG8_SCHED;
	v_mfma_f32_16x16x32_bf16 v[60:63], v[164:167], v[196:199], v[60:63]
	v_mfma_f32_16x16x32_bf16 v[56:59], v[172:175], v[196:199], v[56:59]
	v_mfma_f32_16x16x32_bf16 v[44:47], v[164:167], v[204:207], v[44:47]
	v_mfma_f32_16x16x32_bf16 v[40:43], v[172:175], v[204:207], v[40:43]
	v_mfma_f32_16x16x32_bf16 v[28:31], v[164:167], v[216:219], v[28:31]
	v_mfma_f32_16x16x32_bf16 v[24:27], v[172:175], v[216:219], v[24:27]
	v_mfma_f32_16x16x32_bf16 v[12:15], v[164:167], v[224:227], v[12:15]
	v_mfma_f32_16x16x32_bf16 v[8:11], v[172:175], v[224:227], v[8:11]
	v_mfma_f32_16x16x32_bf16 v[60:63], v[168:171], v[200:203], v[60:63]
	v_mfma_f32_16x16x32_bf16 v[56:59], v[176:179], v[200:203], v[56:59]
	v_mfma_f32_16x16x32_bf16 v[44:47], v[168:171], v[208:211], v[44:47]
	v_mfma_f32_16x16x32_bf16 v[40:43], v[176:179], v[208:211], v[40:43]
	v_mfma_f32_16x16x32_bf16 v[28:31], v[168:171], v[220:223], v[28:31]
	v_mfma_f32_16x16x32_bf16 v[24:27], v[176:179], v[220:223], v[24:27]
	v_mfma_f32_16x16x32_bf16 v[12:15], v[168:171], v[228:231], v[12:15]
	v_mfma_f32_16x16x32_bf16 v[8:11], v[176:179], v[228:231], v[8:11]
	v_mfma_f32_16x16x32_bf16 v[52:55], v[180:183], v[196:199], v[52:55]
	v_mfma_f32_16x16x32_bf16 v[48:51], v[188:191], v[196:199], v[48:51]
	v_mfma_f32_16x16x32_bf16 v[36:39], v[180:183], v[204:207], v[36:39]
	v_mfma_f32_16x16x32_bf16 v[32:35], v[188:191], v[204:207], v[32:35]
	v_mfma_f32_16x16x32_bf16 v[20:23], v[180:183], v[216:219], v[20:23]
	v_mfma_f32_16x16x32_bf16 v[16:19], v[188:191], v[216:219], v[16:19]
	v_mfma_f32_16x16x32_bf16 v[4:7], v[180:183], v[224:227], v[4:7]
	v_mfma_f32_16x16x32_bf16 v[0:3], v[188:191], v[224:227], v[0:3]
	v_mfma_f32_16x16x32_bf16 v[52:55], v[184:187], v[200:203], v[52:55]
	v_mfma_f32_16x16x32_bf16 v[48:51], v[192:195], v[200:203], v[48:51]
	v_mfma_f32_16x16x32_bf16 v[36:39], v[184:187], v[208:211], v[36:39]
	v_mfma_f32_16x16x32_bf16 v[32:35], v[192:195], v[208:211], v[32:35]
	v_mfma_f32_16x16x32_bf16 v[20:23], v[184:187], v[220:223], v[20:23]
	v_mfma_f32_16x16x32_bf16 v[16:19], v[192:195], v[220:223], v[16:19]
	v_mfma_f32_16x16x32_bf16 v[4:7], v[184:187], v[228:231], v[4:7]
	v_mfma_f32_16x16x32_bf16 v[0:3], v[192:195], v[228:231], v[0:3]
	s_setprio 0
	s_barrier
	v_add_u32_e32 v176, s60, v161
	v_add_u32_e32 v192, s61, v161
	s_mov_b32 m0, s41
	ds_read_b128 v[164:167], v176
	global_load_lds_dwordx4 v[240:241], off
	ds_read_b128 v[168:171], v176 offset:1024
	ds_read_b128 v[172:175], v176 offset:2048
	ds_read_b128 v[176:179], v176 offset:3072
	ds_read_b128 v[180:183], v192
	ds_read_b128 v[184:187], v192 offset:1024
	ds_read_b128 v[188:191], v192 offset:2048
	ds_read_b128 v[192:195], v192 offset:3072
	v_lshl_add_u64 v[212:213], v[212:213], 0, s[14:15]
	s_mov_b32 m0, s46
	v_lshl_add_u64 v[242:243], v[212:213], 0, v[140:141]
	ds_read_b128 v[196:199], v163 offset:32768
	ds_read_b128 v[200:203], v163 offset:33792
	ds_read_b128 v[204:207], v163 offset:34816
	ds_read_b128 v[208:211], v163 offset:35840
	ds_read_b128 v[216:219], v163 offset:36864
	ds_read_b128 v[220:223], v163 offset:37888
	ds_read_b128 v[224:227], v163 offset:38912
	ds_read_b128 v[228:231], v163 offset:39936
	global_load_lds_dwordx4 v[242:243], off
	s_mov_b32 m0, s47
	v_lshl_add_u64 v[212:213], v[212:213], 0, v[136:137]
	global_load_lds_dwordx4 v[212:213], off
	s_waitcnt vmcnt(8) lgkmcnt(0)
	s_setprio 1
	s_barrier
	v_mfma_f32_16x16x32_bf16 v[124:127], v[164:167], v[196:199], v[124:127]
	v_mfma_f32_16x16x32_bf16 v[120:123], v[172:175], v[196:199], v[120:123]
	v_mfma_f32_16x16x32_bf16 v[108:111], v[164:167], v[204:207], v[108:111]
	v_mfma_f32_16x16x32_bf16 v[104:107], v[172:175], v[204:207], v[104:107]
	v_mfma_f32_16x16x32_bf16 v[92:95], v[164:167], v[216:219], v[92:95]
	v_mfma_f32_16x16x32_bf16 v[88:91], v[172:175], v[216:219], v[88:91]
	v_mfma_f32_16x16x32_bf16 v[76:79], v[164:167], v[224:227], v[76:79]
	v_mfma_f32_16x16x32_bf16 v[72:75], v[172:175], v[224:227], v[72:75]
	v_mfma_f32_16x16x32_bf16 v[124:127], v[168:171], v[200:203], v[124:127]
	v_mfma_f32_16x16x32_bf16 v[120:123], v[176:179], v[200:203], v[120:123]
	v_mfma_f32_16x16x32_bf16 v[108:111], v[168:171], v[208:211], v[108:111]
	v_mfma_f32_16x16x32_bf16 v[104:107], v[176:179], v[208:211], v[104:107]
	v_mfma_f32_16x16x32_bf16 v[92:95], v[168:171], v[220:223], v[92:95]
	v_mfma_f32_16x16x32_bf16 v[88:91], v[176:179], v[220:223], v[88:91]
	v_mfma_f32_16x16x32_bf16 v[76:79], v[168:171], v[228:231], v[76:79]
	v_mfma_f32_16x16x32_bf16 v[72:75], v[176:179], v[228:231], v[72:75]
	v_mfma_f32_16x16x32_bf16 v[116:119], v[180:183], v[196:199], v[116:119]
	v_mfma_f32_16x16x32_bf16 v[112:115], v[188:191], v[196:199], v[112:115]
	v_mfma_f32_16x16x32_bf16 v[100:103], v[180:183], v[204:207], v[100:103]
	v_mfma_f32_16x16x32_bf16 v[96:99], v[188:191], v[204:207], v[96:99]
	v_mfma_f32_16x16x32_bf16 v[84:87], v[180:183], v[216:219], v[84:87]
	v_mfma_f32_16x16x32_bf16 v[80:83], v[188:191], v[216:219], v[80:83]
	v_mfma_f32_16x16x32_bf16 v[68:71], v[180:183], v[224:227], v[68:71]
	v_mfma_f32_16x16x32_bf16 v[64:67], v[188:191], v[224:227], v[64:67]
	v_mfma_f32_16x16x32_bf16 v[116:119], v[184:187], v[200:203], v[116:119]
	v_mfma_f32_16x16x32_bf16 v[112:115], v[192:195], v[200:203], v[112:115]
	v_mfma_f32_16x16x32_bf16 v[100:103], v[184:187], v[208:211], v[100:103]
	v_mfma_f32_16x16x32_bf16 v[96:99], v[192:195], v[208:211], v[96:99]
	v_mfma_f32_16x16x32_bf16 v[84:87], v[184:187], v[220:223], v[84:87]
	v_mfma_f32_16x16x32_bf16 v[80:83], v[192:195], v[220:223], v[80:83]
	v_mfma_f32_16x16x32_bf16 v[68:71], v[184:187], v[228:231], v[68:71]
	v_mfma_f32_16x16x32_bf16 v[64:67], v[192:195], v[228:231], v[64:67]
	s_setprio 0
	s_barrier
; #define PG8_STAGE(bufoff, gbase, voff) do { _Pragma("unroll") for (int _i = 0; _i < 2; ++_i) \
;         __builtin_amdgcn_global_load_lds((const unsigned*)((const char*)(gbase) + (voff)[_i]), (PG8_LAS unsigned*)(lds + (bufoff) + ldsw + _i * 8192), 16, 0, 0); } while (0)
; #define PG8_LDA(dst, b, h) do { _Pragma("unroll") for (int m = 0; m < 4; ++m) _Pragma("unroll") for (int k = 0; k < 2; ++k) dst[m][k] = *(const PG8_LAS bf16x8*)(lds + PG8_SA(b, h) + aoff + m * 2048 + k * 1024); } while (0)
; #define PG8_MMA(ai, bj, At, Bt) do { __builtin_amdgcn_s_setprio(1); _Pragma("unroll") for (int m = 0; m < 4; ++m) _Pragma("unroll") for (int n = 0; n < 2; ++n) _Pragma("unroll") for (int k = 0; k < 2; ++k) \
;         acc[ai][bj][m][n] = __builtin_amdgcn_mfma_f32_16x16x32_bf16(Bt[n][k], At[m][k], acc[ai][bj][m][n], 0, 0, 0); __builtin_amdgcn_s_setprio(0); } while (0)
; #define PG8_WAIT_V(n) asm volatile("s_waitcnt vmcnt(" #n ")" ::: "memory")
; #define PG8_WAIT_L(n) asm volatile("s_waitcnt lgkmcnt(" #n ")" ::: "memory")
; #define PG8_BAR __builtin_amdgcn_s_barrier()
; #define PG8_SCHED __builtin_amdgcn_sched_barrier(0)
; template <class Epi, class Sched, bool ALIGN_EPI = false, bool SP2 = false>
; __device__ __forceinline__ void gemm_phase(PG8_LAS unsigned char* lds, const Gemm g, const Sched& S, const Epi& E) {
;     ...
;             PG8_LDA(At, 1, 1); PG8_STAGE(PG8_SB(1, 0), b3, voffB); PG8_STAGE(PG8_SB(1, 1), b3 + hstep, voffB); PG8_STAGE(PG8_SA(1, 0), a3, voffA);
;             PG8_WAIT_V(8); PG8_WAIT_L(0); PG8_BAR; PG8_MMA(1, 0, At, B0); PG8_MMA(1, 1, At, B1); PG8_BAR; PG8_SCHED;
	s_mov_b32 m0, s62
	v_lshl_add_u64 v[212:213], v[232:233], 0, s[24:25]
	ds_read_b128 v[196:199], v163 offset:49152
	ds_read_b128 v[200:203], v163 offset:50176
	ds_read_b128 v[204:207], v163 offset:51200
	ds_read_b128 v[208:211], v163 offset:52224
	ds_read_b128 v[216:219], v163 offset:53248
	ds_read_b128 v[220:223], v163 offset:54272
	ds_read_b128 v[224:227], v163 offset:55296
	ds_read_b128 v[228:231], v163 offset:56320
	global_load_lds_dwordx4 v[212:213], off
	s_mov_b32 m0, s63
	v_lshl_add_u64 v[212:213], v[234:235], 0, s[24:25]
	global_load_lds_dwordx4 v[212:213], off
	s_mov_b32 m0, s64
	v_lshl_add_u64 v[212:213], v[236:237], 0, s[24:25]
	global_load_lds_dwordx4 v[212:213], off
	s_mov_b32 m0, s65
	v_lshl_add_u64 v[212:213], v[214:215], 0, s[24:25]
	global_load_lds_dwordx4 v[212:213], off
	s_mov_b32 m0, s48
	v_lshl_add_u64 v[212:213], v[238:239], 0, s[24:25]
	global_load_lds_dwordx4 v[212:213], off
	s_mov_b32 m0, s49
	v_lshl_add_u64 v[212:213], v[240:241], 0, s[24:25]
	global_load_lds_dwordx4 v[212:213], off
	s_waitcnt vmcnt(8) lgkmcnt(0)
	s_setprio 1
	s_barrier
	v_mfma_f32_16x16x32_bf16 v[60:63], v[164:167], v[196:199], v[60:63]
	v_mfma_f32_16x16x32_bf16 v[56:59], v[172:175], v[196:199], v[56:59]
	v_mfma_f32_16x16x32_bf16 v[44:47], v[164:167], v[204:207], v[44:47]
	v_mfma_f32_16x16x32_bf16 v[40:43], v[172:175], v[204:207], v[40:43]
	v_mfma_f32_16x16x32_bf16 v[28:31], v[164:167], v[216:219], v[28:31]
	v_mfma_f32_16x16x32_bf16 v[24:27], v[172:175], v[216:219], v[24:27]
	v_mfma_f32_16x16x32_bf16 v[12:15], v[164:167], v[224:227], v[12:15]
	v_mfma_f32_16x16x32_bf16 v[8:11], v[172:175], v[224:227], v[8:11]
	v_mfma_f32_16x16x32_bf16 v[60:63], v[168:171], v[200:203], v[60:63]
	v_mfma_f32_16x16x32_bf16 v[56:59], v[176:179], v[200:203], v[56:59]
	v_mfma_f32_16x16x32_bf16 v[44:47], v[168:171], v[208:211], v[44:47]
	v_mfma_f32_16x16x32_bf16 v[40:43], v[176:179], v[208:211], v[40:43]
	v_mfma_f32_16x16x32_bf16 v[28:31], v[168:171], v[220:223], v[28:31]
	v_mfma_f32_16x16x32_bf16 v[24:27], v[176:179], v[220:223], v[24:27]
	v_mfma_f32_16x16x32_bf16 v[12:15], v[168:171], v[228:231], v[12:15]
	v_mfma_f32_16x16x32_bf16 v[8:11], v[176:179], v[228:231], v[8:11]
	v_mfma_f32_16x16x32_bf16 v[52:55], v[180:183], v[196:199], v[52:55]
	v_mfma_f32_16x16x32_bf16 v[48:51], v[188:191], v[196:199], v[48:51]
	v_mfma_f32_16x16x32_bf16 v[36:39], v[180:183], v[204:207], v[36:39]
	v_mfma_f32_16x16x32_bf16 v[32:35], v[188:191], v[204:207], v[32:35]
	v_mfma_f32_16x16x32_bf16 v[20:23], v[180:183], v[216:219], v[20:23]
	v_mfma_f32_16x16x32_bf16 v[16:19], v[188:191], v[216:219], v[16:19]
	v_mfma_f32_16x16x32_bf16 v[4:7], v[180:183], v[224:227], v[4:7]
	v_mfma_f32_16x16x32_bf16 v[0:3], v[188:191], v[224:227], v[0:3]
	v_mfma_f32_16x16x32_bf16 v[52:55], v[184:187], v[200:203], v[52:55]
	v_mfma_f32_16x16x32_bf16 v[48:51], v[192:195], v[200:203], v[48:51]
	v_mfma_f32_16x16x32_bf16 v[36:39], v[184:187], v[208:211], v[36:39]
	v_mfma_f32_16x16x32_bf16 v[32:35], v[192:195], v[208:211], v[32:35]
	v_mfma_f32_16x16x32_bf16 v[20:23], v[184:187], v[220:223], v[20:23]
	v_mfma_f32_16x16x32_bf16 v[16:19], v[192:195], v[220:223], v[16:19]
	v_mfma_f32_16x16x32_bf16 v[4:7], v[184:187], v[228:231], v[4:7]
	v_mfma_f32_16x16x32_bf16 v[0:3], v[192:195], v[228:231], v[0:3]
	s_setprio 0
	s_barrier
	v_lshl_add_u64 v[154:155], v[154:155], 0, s[28:29]
	s_cmp_ge_i32 s10, s50
	v_lshl_add_u64 v[158:159], v[158:159], 0, s[28:29]
	s_cbranch_scc0 .LBB0_1169

; #define PG8_STAGE(bufoff, gbase, voff) do { _Pragma("unroll") for (int _i = 0; _i < 2; ++_i) \
;         __builtin_amdgcn_global_load_lds((const unsigned*)((const char*)(gbase) + (voff)[_i]), (PG8_LAS unsigned*)(lds + (bufoff) + ldsw + _i * 8192), 16, 0, 0); } while (0)
; #define PG8_LDA(dst, b, h) do { _Pragma("unroll") for (int m = 0; m < 4; ++m) _Pragma("unroll") for (int k = 0; k < 2; ++k) dst[m][k] = *(const PG8_LAS bf16x8*)(lds + PG8_SA(b, h) + aoff + m * 2048 + k * 1024); } while (0)
; #define PG8_LDB(dst, b, h) do { _Pragma("unroll") for (int n = 0; n < 2; ++n) _Pragma("unroll") for (int k = 0; k < 2; ++k) dst[n][k] = *(const PG8_LAS bf16x8*)(lds + PG8_SB(b, h) + boff + n * 2048 + k * 1024); } while (0)
; #define PG8_MMA(ai, bj, At, Bt) do { __builtin_amdgcn_s_setprio(1); _Pragma("unroll") for (int m = 0; m < 4; ++m) _Pragma("unroll") for (int n = 0; n < 2; ++n) _Pragma("unroll") for (int k = 0; k < 2; ++k) \
;         acc[ai][bj][m][n] = __builtin_amdgcn_mfma_f32_16x16x32_bf16(Bt[n][k], At[m][k], acc[ai][bj][m][n], 0, 0, 0); __builtin_amdgcn_s_setprio(0); } while (0)
; #define PG8_WAIT_V(n) asm volatile("s_waitcnt vmcnt(" #n ")" ::: "memory")
; #define PG8_BAR __builtin_amdgcn_s_barrier()
; template <class Epi, class Sched, bool ALIGN_EPI = false, bool SP2 = false>
; __device__ __forceinline__ void gemm_phase(PG8_LAS unsigned char* lds, const Gemm g, const Sched& S, const Epi& E) {
;     ...
;         for (int t = 0; t < nt; t += 2) {
;             const bool last = (t == nt - 2);
;             const char* a1 = cA + (size_t)(t + 1) * kstep;
;             const char* a2 = last ? nA : cA + (size_t)(t + 2) * kstep; const char* b2 = last ? nB : cB + (size_t)(t + 2) * kstep;
;             const char* a3 = a2 + kstep; const char* b3 = b2 + kstep;
;             if (last && has_next) S.a_ready(nxt);
;             if constexpr (SP2) {
;             PG8_LDB(B0, 0, 0); PG8_LDB(B1, 0, 1); PG8_SCHED; PG8_LDA(At, 0, 0); PG8_STAGE(PG8_SA(1, 1), a1 + hstep, voffA);
;             PG8_WAIT_V(8); PG8_WAIT_L(0); PG8_BAR; PG8_MMA(0, 0, At, B0); PG8_MMA(0, 1, At, B1); PG8_BAR; PG8_SCHED;
;             PG8_LDA(At, 0, 1); PG8_STAGE(PG8_SB(0, 0), b2, voffB); PG8_STAGE(PG8_SB(0, 1), b2 + hstep, voffB); PG8_STAGE(PG8_SA(0, 0), a2, voffA);
;             PG8_WAIT_V(8); PG8_WAIT_L(0); PG8_BAR; PG8_MMA(1, 0, At, B0); PG8_MMA(1, 1, At, B1); PG8_BAR; PG8_SCHED;
.LBB0_1192:
	v_add_u32_e32 v178, s56, v216
	v_add_u32_e32 v194, s57, v216
	ds_read_b128 v[138:141], v178
	ds_read_b128 v[142:145], v178 offset:1024
	ds_read_b128 v[146:149], v178 offset:2048
	ds_read_b128 v[178:181], v178 offset:3072
	ds_read_b128 v[182:185], v194
	ds_read_b128 v[186:189], v194 offset:1024
	ds_read_b128 v[190:193], v194 offset:2048
	ds_read_b128 v[194:197], v194 offset:3072
	s_cmp_eq_u32 s49, s10
	v_lshl_add_u64 v[198:199], v[136:137], 0, s[20:21]
	s_cselect_b64 vcc, -1, 0
	s_add_i32 s10, s10, 2
	v_cndmask_b32_e32 v215, v199, v175, vcc
	v_cndmask_b32_e32 v214, v198, v174, vcc
	v_cndmask_b32_e32 v237, v135, v177, vcc
	v_cndmask_b32_e32 v236, v134, v176, vcc
	v_lshl_add_u64 v[238:239], v[136:137], 0, v[168:169]
	s_add_i32 m0, s34, 0xc000
	ds_read_b128 v[198:201], v218
	ds_read_b128 v[202:205], v218 offset:1024
	ds_read_b128 v[206:209], v218 offset:2048
	ds_read_b128 v[210:213], v218 offset:3072
	ds_read_b128 v[220:223], v218 offset:4096
	ds_read_b128 v[224:227], v218 offset:5120
	ds_read_b128 v[228:231], v218 offset:6144
	ds_read_b128 v[232:235], v218 offset:7168
	global_load_lds_dwordx4 v[238:239], off
	s_add_i32 m0, s34, 0xe000
	v_lshl_add_u64 v[238:239], v[136:137], 0, v[166:167]
	global_load_lds_dwordx4 v[238:239], off
	s_waitcnt vmcnt(8) lgkmcnt(0)
	s_setprio 1
	s_barrier
	v_mfma_f32_16x16x32_bf16 v[130:133], v[138:141], v[198:201], v[130:133]
	v_mfma_f32_16x16x32_bf16 v[126:129], v[146:149], v[198:201], v[126:129]
	v_mfma_f32_16x16x32_bf16 v[114:117], v[138:141], v[206:209], v[114:117]
	v_mfma_f32_16x16x32_bf16 v[110:113], v[146:149], v[206:209], v[110:113]
	v_mfma_f32_16x16x32_bf16 v[98:101], v[138:141], v[220:223], v[98:101]
	v_mfma_f32_16x16x32_bf16 v[94:97], v[146:149], v[220:223], v[94:97]
	v_mfma_f32_16x16x32_bf16 v[82:85], v[138:141], v[228:231], v[82:85]
	v_mfma_f32_16x16x32_bf16 v[78:81], v[146:149], v[228:231], v[78:81]
	v_mfma_f32_16x16x32_bf16 v[130:133], v[142:145], v[202:205], v[130:133]
	v_mfma_f32_16x16x32_bf16 v[126:129], v[178:181], v[202:205], v[126:129]
	v_mfma_f32_16x16x32_bf16 v[114:117], v[142:145], v[210:213], v[114:117]
	v_mfma_f32_16x16x32_bf16 v[110:113], v[178:181], v[210:213], v[110:113]
	v_mfma_f32_16x16x32_bf16 v[98:101], v[142:145], v[224:227], v[98:101]
	v_mfma_f32_16x16x32_bf16 v[94:97], v[178:181], v[224:227], v[94:97]
	v_mfma_f32_16x16x32_bf16 v[82:85], v[142:145], v[232:235], v[82:85]
	v_mfma_f32_16x16x32_bf16 v[78:81], v[178:181], v[232:235], v[78:81]
	v_mfma_f32_16x16x32_bf16 v[122:125], v[182:185], v[198:201], v[122:125]
	v_mfma_f32_16x16x32_bf16 v[118:121], v[190:193], v[198:201], v[118:121]
	v_mfma_f32_16x16x32_bf16 v[106:109], v[182:185], v[206:209], v[106:109]
	v_mfma_f32_16x16x32_bf16 v[102:105], v[190:193], v[206:209], v[102:105]
	v_mfma_f32_16x16x32_bf16 v[90:93], v[182:185], v[220:223], v[90:93]
	v_mfma_f32_16x16x32_bf16 v[86:89], v[190:193], v[220:223], v[86:89]
	v_mfma_f32_16x16x32_bf16 v[74:77], v[182:185], v[228:231], v[74:77]
	v_mfma_f32_16x16x32_bf16 v[70:73], v[190:193], v[228:231], v[70:73]
	v_mfma_f32_16x16x32_bf16 v[122:125], v[186:189], v[202:205], v[122:125]
	v_mfma_f32_16x16x32_bf16 v[118:121], v[194:197], v[202:205], v[118:121]
	v_mfma_f32_16x16x32_bf16 v[106:109], v[186:189], v[210:213], v[106:109]
	v_mfma_f32_16x16x32_bf16 v[102:105], v[194:197], v[210:213], v[102:105]
	v_mfma_f32_16x16x32_bf16 v[90:93], v[186:189], v[224:227], v[90:93]
	v_mfma_f32_16x16x32_bf16 v[86:89], v[194:197], v[224:227], v[86:89]
	v_mfma_f32_16x16x32_bf16 v[74:77], v[186:189], v[232:235], v[74:77]
	v_mfma_f32_16x16x32_bf16 v[70:73], v[194:197], v[232:235], v[70:73]
	s_setprio 0
	s_barrier
	s_add_i32 s11, s56, s29
	v_lshl_add_u64 v[238:239], v[236:237], 0, v[158:159]
	s_mov_b32 m0, s11
	ds_read_b128 v[198:201], v218 offset:16384
	ds_read_b128 v[202:205], v218 offset:17408
	ds_read_b128 v[206:209], v218 offset:18432
	ds_read_b128 v[210:213], v218 offset:19456
	ds_read_b128 v[220:223], v218 offset:20480
	ds_read_b128 v[224:227], v218 offset:21504
	ds_read_b128 v[228:231], v218 offset:22528
	ds_read_b128 v[232:235], v218 offset:23552
	global_load_lds_dwordx4 v[238:239], off
	v_lshl_add_u64 v[240:241], v[236:237], 0, v[162:163]
	s_add_i32 m0, s11, 0x2000
	v_lshl_add_u64 v[236:237], v[236:237], 0, s[12:13]
	s_add_i32 s11, s57, s29
	global_load_lds_dwordx4 v[240:241], off
	v_lshl_add_u64 v[242:243], v[236:237], 0, v[158:159]
	s_mov_b32 m0, s11
	v_lshl_add_u64 v[236:237], v[236:237], 0, v[162:163]
	global_load_lds_dwordx4 v[242:243], off
	s_add_i32 m0, s11, 0x2000
	v_lshl_add_u64 v[244:245], v[214:215], 0, v[154:155]
	global_load_lds_dwordx4 v[236:237], off
	s_mov_b32 m0, s34
	v_lshl_add_u64 v[246:247], v[214:215], 0, v[160:161]
	global_load_lds_dwordx4 v[244:245], off
	s_nop 0
	s_waitcnt vmcnt(7) lgkmcnt(0)
	s_setprio 1
	s_barrier
; #define PG8_STAGE(bufoff, gbase, voff) do { _Pragma("unroll") for (int _i = 0; _i < 2; ++_i) \
;         __builtin_amdgcn_global_load_lds((const unsigned*)((const char*)(gbase) + (voff)[_i]), (PG8_LAS unsigned*)(lds + (bufoff) + ldsw + _i * 8192), 16, 0, 0); } while (0)
; #define PG8_LDA(dst, b, h) do { _Pragma("unroll") for (int m = 0; m < 4; ++m) _Pragma("unroll") for (int k = 0; k < 2; ++k) dst[m][k] = *(const PG8_LAS bf16x8*)(lds + PG8_SA(b, h) + aoff + m * 2048 + k * 1024); } while (0)
; #define PG8_LDB(dst, b, h) do { _Pragma("unroll") for (int n = 0; n < 2; ++n) _Pragma("unroll") for (int k = 0; k < 2; ++k) dst[n][k] = *(const PG8_LAS bf16x8*)(lds + PG8_SB(b, h) + boff + n * 2048 + k * 1024); } while (0)
; #define PG8_MMA(ai, bj, At, Bt) do { __builtin_amdgcn_s_setprio(1); _Pragma("unroll") for (int m = 0; m < 4; ++m) _Pragma("unroll") for (int n = 0; n < 2; ++n) _Pragma("unroll") for (int k = 0; k < 2; ++k) \
;         acc[ai][bj][m][n] = __builtin_amdgcn_mfma_f32_16x16x32_bf16(Bt[n][k], At[m][k], acc[ai][bj][m][n], 0, 0, 0); __builtin_amdgcn_s_setprio(0); } while (0)
; #define PG8_WAIT_V(n) asm volatile("s_waitcnt vmcnt(" #n ")" ::: "memory")
; #define PG8_WAIT_L(n) asm volatile("s_waitcnt lgkmcnt(" #n ")" ::: "memory")
; #define PG8_BAR __builtin_amdgcn_s_barrier()
; #define PG8_SCHED __builtin_amdgcn_sched_barrier(0)
; template <class Epi, class Sched, bool ALIGN_EPI = false, bool SP2 = false>
; __device__ __forceinline__ void gemm_phase(PG8_LAS unsigned char* lds, const Gemm g, const Sched& S, const Epi& E) {
;     ...
;             PG8_WAIT_V(8); PG8_WAIT_L(0); PG8_BAR; PG8_MMA(1, 0, At, B0); PG8_MMA(1, 1, At, B1); PG8_BAR; PG8_SCHED;
;             PG8_LDB(B0, 1, 0); PG8_LDB(B1, 1, 1); PG8_SCHED; PG8_LDA(At, 1, 0); PG8_STAGE(PG8_SA(0, 1), a2 + hstep, voffA);
;             PG8_WAIT_V(8); PG8_WAIT_L(0); PG8_BAR; PG8_MMA(0, 0, At, B0); PG8_MMA(0, 1, At, B1); PG8_BAR; PG8_SCHED;
	v_mfma_f32_16x16x32_bf16 v[66:69], v[138:141], v[198:201], v[66:69]
	v_mfma_f32_16x16x32_bf16 v[62:65], v[146:149], v[198:201], v[62:65]
	v_mfma_f32_16x16x32_bf16 v[50:53], v[138:141], v[206:209], v[50:53]
	v_mfma_f32_16x16x32_bf16 v[46:49], v[146:149], v[206:209], v[46:49]
	v_mfma_f32_16x16x32_bf16 v[34:37], v[138:141], v[220:223], v[34:37]
	v_mfma_f32_16x16x32_bf16 v[30:33], v[146:149], v[220:223], v[30:33]
	v_mfma_f32_16x16x32_bf16 v[18:21], v[138:141], v[228:231], v[18:21]
	v_mfma_f32_16x16x32_bf16 v[14:17], v[146:149], v[228:231], v[14:17]
	v_mfma_f32_16x16x32_bf16 v[66:69], v[142:145], v[202:205], v[66:69]
	v_mfma_f32_16x16x32_bf16 v[62:65], v[178:181], v[202:205], v[62:65]
	v_mfma_f32_16x16x32_bf16 v[50:53], v[142:145], v[210:213], v[50:53]
	v_mfma_f32_16x16x32_bf16 v[46:49], v[178:181], v[210:213], v[46:49]
	v_mfma_f32_16x16x32_bf16 v[34:37], v[142:145], v[224:227], v[34:37]
	v_mfma_f32_16x16x32_bf16 v[30:33], v[178:181], v[224:227], v[30:33]
	v_mfma_f32_16x16x32_bf16 v[18:21], v[142:145], v[232:235], v[18:21]
	v_mfma_f32_16x16x32_bf16 v[14:17], v[178:181], v[232:235], v[14:17]
	v_mfma_f32_16x16x32_bf16 v[58:61], v[182:185], v[198:201], v[58:61]
	v_mfma_f32_16x16x32_bf16 v[54:57], v[190:193], v[198:201], v[54:57]
	v_mfma_f32_16x16x32_bf16 v[42:45], v[182:185], v[206:209], v[42:45]
	v_mfma_f32_16x16x32_bf16 v[38:41], v[190:193], v[206:209], v[38:41]
	v_mfma_f32_16x16x32_bf16 v[26:29], v[182:185], v[220:223], v[26:29]
	v_mfma_f32_16x16x32_bf16 v[22:25], v[190:193], v[220:223], v[22:25]
	v_mfma_f32_16x16x32_bf16 v[10:13], v[182:185], v[228:231], v[10:13]
	v_mfma_f32_16x16x32_bf16 v[6:9], v[190:193], v[228:231], v[6:9]
	v_mfma_f32_16x16x32_bf16 v[58:61], v[186:189], v[202:205], v[58:61]
	v_mfma_f32_16x16x32_bf16 v[54:57], v[194:197], v[202:205], v[54:57]
	v_mfma_f32_16x16x32_bf16 v[42:45], v[186:189], v[210:213], v[42:45]
	v_mfma_f32_16x16x32_bf16 v[38:41], v[194:197], v[210:213], v[38:41]
	v_mfma_f32_16x16x32_bf16 v[26:29], v[186:189], v[224:227], v[26:29]
	v_mfma_f32_16x16x32_bf16 v[22:25], v[194:197], v[224:227], v[22:25]
	v_mfma_f32_16x16x32_bf16 v[10:13], v[186:189], v[232:235], v[10:13]
	v_mfma_f32_16x16x32_bf16 v[6:9], v[194:197], v[232:235], v[6:9]
	s_setprio 0
	s_barrier
	s_add_i32 s11, 0, 0x18000
	s_add_i32 s31, 0, 0x1c000
	v_add_u32_e32 v178, s11, v216
	v_add_u32_e32 v194, s31, v216
	s_mov_b32 m0, s35
	ds_read_b128 v[138:141], v178
	global_load_lds_dwordx4 v[246:247], off
	ds_read_b128 v[142:145], v178 offset:1024
	ds_read_b128 v[146:149], v178 offset:2048
	ds_read_b128 v[178:181], v178 offset:3072
	ds_read_b128 v[182:185], v194
	ds_read_b128 v[186:189], v194 offset:1024
	ds_read_b128 v[190:193], v194 offset:2048
	ds_read_b128 v[194:197], v194 offset:3072
	v_lshl_add_u64 v[214:215], v[214:215], 0, s[12:13]
	s_mov_b32 m0, s36
	v_lshl_add_u64 v[248:249], v[214:215], 0, v[154:155]
	ds_read_b128 v[198:201], v218 offset:32768
	ds_read_b128 v[202:205], v218 offset:33792
	ds_read_b128 v[206:209], v218 offset:34816
	ds_read_b128 v[210:213], v218 offset:35840
	ds_read_b128 v[220:223], v218 offset:36864
	ds_read_b128 v[224:227], v218 offset:37888
	ds_read_b128 v[228:231], v218 offset:38912
	ds_read_b128 v[232:235], v218 offset:39936
	global_load_lds_dwordx4 v[248:249], off
	s_mov_b32 m0, s37
	v_lshl_add_u64 v[214:215], v[214:215], 0, v[160:161]
	global_load_lds_dwordx4 v[214:215], off
	s_waitcnt vmcnt(8) lgkmcnt(0)
	s_setprio 1
	s_barrier
	v_mfma_f32_16x16x32_bf16 v[130:133], v[138:141], v[198:201], v[130:133]
	v_mfma_f32_16x16x32_bf16 v[126:129], v[146:149], v[198:201], v[126:129]
	v_mfma_f32_16x16x32_bf16 v[114:117], v[138:141], v[206:209], v[114:117]
	v_mfma_f32_16x16x32_bf16 v[110:113], v[146:149], v[206:209], v[110:113]
	v_mfma_f32_16x16x32_bf16 v[98:101], v[138:141], v[220:223], v[98:101]
	v_mfma_f32_16x16x32_bf16 v[94:97], v[146:149], v[220:223], v[94:97]
	v_mfma_f32_16x16x32_bf16 v[82:85], v[138:141], v[228:231], v[82:85]
	v_mfma_f32_16x16x32_bf16 v[78:81], v[146:149], v[228:231], v[78:81]
	v_mfma_f32_16x16x32_bf16 v[130:133], v[142:145], v[202:205], v[130:133]
	v_mfma_f32_16x16x32_bf16 v[126:129], v[178:181], v[202:205], v[126:129]
	v_mfma_f32_16x16x32_bf16 v[114:117], v[142:145], v[210:213], v[114:117]
	v_mfma_f32_16x16x32_bf16 v[110:113], v[178:181], v[210:213], v[110:113]
	v_mfma_f32_16x16x32_bf16 v[98:101], v[142:145], v[224:227], v[98:101]
	v_mfma_f32_16x16x32_bf16 v[94:97], v[178:181], v[224:227], v[94:97]
	v_mfma_f32_16x16x32_bf16 v[82:85], v[142:145], v[232:235], v[82:85]
	v_mfma_f32_16x16x32_bf16 v[78:81], v[178:181], v[232:235], v[78:81]
	v_mfma_f32_16x16x32_bf16 v[122:125], v[182:185], v[198:201], v[122:125]
	v_mfma_f32_16x16x32_bf16 v[118:121], v[190:193], v[198:201], v[118:121]
	v_mfma_f32_16x16x32_bf16 v[106:109], v[182:185], v[206:209], v[106:109]
	v_mfma_f32_16x16x32_bf16 v[102:105], v[190:193], v[206:209], v[102:105]
	v_mfma_f32_16x16x32_bf16 v[90:93], v[182:185], v[220:223], v[90:93]
	v_mfma_f32_16x16x32_bf16 v[86:89], v[190:193], v[220:223], v[86:89]
	v_mfma_f32_16x16x32_bf16 v[74:77], v[182:185], v[228:231], v[74:77]
	v_mfma_f32_16x16x32_bf16 v[70:73], v[190:193], v[228:231], v[70:73]
	v_mfma_f32_16x16x32_bf16 v[122:125], v[186:189], v[202:205], v[122:125]
	v_mfma_f32_16x16x32_bf16 v[118:121], v[194:197], v[202:205], v[118:121]
	v_mfma_f32_16x16x32_bf16 v[106:109], v[186:189], v[210:213], v[106:109]
	v_mfma_f32_16x16x32_bf16 v[102:105], v[194:197], v[210:213], v[102:105]
	v_mfma_f32_16x16x32_bf16 v[90:93], v[186:189], v[224:227], v[90:93]
	v_mfma_f32_16x16x32_bf16 v[86:89], v[194:197], v[224:227], v[86:89]
	v_mfma_f32_16x16x32_bf16 v[74:77], v[186:189], v[232:235], v[74:77]
	v_mfma_f32_16x16x32_bf16 v[70:73], v[194:197], v[232:235], v[70:73]
	s_setprio 0
	s_barrier
; #define PG8_STAGE(bufoff, gbase, voff) do { _Pragma("unroll") for (int _i = 0; _i < 2; ++_i) \
;         __builtin_amdgcn_global_load_lds((const unsigned*)((const char*)(gbase) + (voff)[_i]), (PG8_LAS unsigned*)(lds + (bufoff) + ldsw + _i * 8192), 16, 0, 0); } while (0)
; #define PG8_LDA(dst, b, h) do { _Pragma("unroll") for (int m = 0; m < 4; ++m) _Pragma("unroll") for (int k = 0; k < 2; ++k) dst[m][k] = *(const PG8_LAS bf16x8*)(lds + PG8_SA(b, h) + aoff + m * 2048 + k * 1024); } while (0)
; #define PG8_MMA(ai, bj, At, Bt) do { __builtin_amdgcn_s_setprio(1); _Pragma("unroll") for (int m = 0; m < 4; ++m) _Pragma("unroll") for (int n = 0; n < 2; ++n) _Pragma("unroll") for (int k = 0; k < 2; ++k) \
;         acc[ai][bj][m][n] = __builtin_amdgcn_mfma_f32_16x16x32_bf16(Bt[n][k], At[m][k], acc[ai][bj][m][n], 0, 0, 0); __builtin_amdgcn_s_setprio(0); } while (0)
; #define PG8_WAIT_V(n) asm volatile("s_waitcnt vmcnt(" #n ")" ::: "memory")
; #define PG8_WAIT_L(n) asm volatile("s_waitcnt lgkmcnt(" #n ")" ::: "memory")
; #define PG8_BAR __builtin_amdgcn_s_barrier()
; #define PG8_SCHED __builtin_amdgcn_sched_barrier(0)
; template <class Epi, class Sched, bool ALIGN_EPI = false, bool SP2 = false>
; __device__ __forceinline__ void gemm_phase(PG8_LAS unsigned char* lds, const Gemm g, const Sched& S, const Epi& E) {
;     ...
;             PG8_LDA(At, 1, 1); PG8_STAGE(PG8_SB(1, 0), b3, voffB); PG8_STAGE(PG8_SB(1, 1), b3 + hstep, voffB); PG8_STAGE(PG8_SA(1, 0), a3, voffA);
;             PG8_WAIT_V(8); PG8_WAIT_L(0); PG8_BAR; PG8_MMA(1, 0, At, B0); PG8_MMA(1, 1, At, B1); PG8_BAR; PG8_SCHED;
	s_add_i32 s11, s11, s29
	v_lshl_add_u64 v[214:215], v[238:239], 0, s[20:21]
	s_mov_b32 m0, s11
	ds_read_b128 v[198:201], v218 offset:49152
	ds_read_b128 v[202:205], v218 offset:50176
	ds_read_b128 v[206:209], v218 offset:51200
	ds_read_b128 v[210:213], v218 offset:52224
	ds_read_b128 v[220:223], v218 offset:53248
	ds_read_b128 v[224:227], v218 offset:54272
	ds_read_b128 v[228:231], v218 offset:55296
	ds_read_b128 v[232:235], v218 offset:56320
	global_load_lds_dwordx4 v[214:215], off
	v_lshl_add_u64 v[214:215], v[240:241], 0, s[20:21]
	s_add_i32 m0, s11, 0x2000
	s_add_i32 s11, s31, s29
	global_load_lds_dwordx4 v[214:215], off
	s_mov_b32 m0, s11
	v_lshl_add_u64 v[214:215], v[242:243], 0, s[20:21]
	global_load_lds_dwordx4 v[214:215], off
	s_add_i32 m0, s11, 0x2000
	v_lshl_add_u64 v[214:215], v[236:237], 0, s[20:21]
	global_load_lds_dwordx4 v[214:215], off
	s_mov_b32 m0, s41
	v_lshl_add_u64 v[214:215], v[244:245], 0, s[20:21]
	global_load_lds_dwordx4 v[214:215], off
	s_mov_b32 m0, s46
	v_lshl_add_u64 v[214:215], v[246:247], 0, s[20:21]
	global_load_lds_dwordx4 v[214:215], off
	s_waitcnt vmcnt(8) lgkmcnt(0)
	s_setprio 1
	s_barrier
	v_mfma_f32_16x16x32_bf16 v[66:69], v[138:141], v[198:201], v[66:69]
	v_mfma_f32_16x16x32_bf16 v[62:65], v[146:149], v[198:201], v[62:65]
	v_mfma_f32_16x16x32_bf16 v[50:53], v[138:141], v[206:209], v[50:53]
	v_mfma_f32_16x16x32_bf16 v[46:49], v[146:149], v[206:209], v[46:49]
	v_mfma_f32_16x16x32_bf16 v[34:37], v[138:141], v[220:223], v[34:37]
	v_mfma_f32_16x16x32_bf16 v[30:33], v[146:149], v[220:223], v[30:33]
	v_mfma_f32_16x16x32_bf16 v[18:21], v[138:141], v[228:231], v[18:21]
	v_mfma_f32_16x16x32_bf16 v[14:17], v[146:149], v[228:231], v[14:17]
	v_mfma_f32_16x16x32_bf16 v[66:69], v[142:145], v[202:205], v[66:69]
	v_mfma_f32_16x16x32_bf16 v[62:65], v[178:181], v[202:205], v[62:65]
	v_mfma_f32_16x16x32_bf16 v[50:53], v[142:145], v[210:213], v[50:53]
	v_mfma_f32_16x16x32_bf16 v[46:49], v[178:181], v[210:213], v[46:49]
	v_mfma_f32_16x16x32_bf16 v[34:37], v[142:145], v[224:227], v[34:37]
	v_mfma_f32_16x16x32_bf16 v[30:33], v[178:181], v[224:227], v[30:33]
	v_mfma_f32_16x16x32_bf16 v[18:21], v[142:145], v[232:235], v[18:21]
	v_mfma_f32_16x16x32_bf16 v[14:17], v[178:181], v[232:235], v[14:17]
	v_mfma_f32_16x16x32_bf16 v[58:61], v[182:185], v[198:201], v[58:61]
	v_mfma_f32_16x16x32_bf16 v[54:57], v[190:193], v[198:201], v[54:57]
	v_mfma_f32_16x16x32_bf16 v[42:45], v[182:185], v[206:209], v[42:45]
	v_mfma_f32_16x16x32_bf16 v[38:41], v[190:193], v[206:209], v[38:41]
	v_mfma_f32_16x16x32_bf16 v[26:29], v[182:185], v[220:223], v[26:29]
	v_mfma_f32_16x16x32_bf16 v[22:25], v[190:193], v[220:223], v[22:25]
	v_mfma_f32_16x16x32_bf16 v[10:13], v[182:185], v[228:231], v[10:13]
	v_mfma_f32_16x16x32_bf16 v[6:9], v[190:193], v[228:231], v[6:9]
	v_mfma_f32_16x16x32_bf16 v[58:61], v[186:189], v[202:205], v[58:61]
	v_mfma_f32_16x16x32_bf16 v[54:57], v[194:197], v[202:205], v[54:57]
	v_mfma_f32_16x16x32_bf16 v[42:45], v[186:189], v[210:213], v[42:45]
	v_mfma_f32_16x16x32_bf16 v[38:41], v[194:197], v[210:213], v[38:41]
	v_mfma_f32_16x16x32_bf16 v[26:29], v[186:189], v[224:227], v[26:29]
	v_mfma_f32_16x16x32_bf16 v[22:25], v[194:197], v[224:227], v[22:25]
	v_mfma_f32_16x16x32_bf16 v[10:13], v[186:189], v[232:235], v[10:13]
	v_mfma_f32_16x16x32_bf16 v[6:9], v[194:197], v[232:235], v[6:9]
	s_setprio 0
	s_barrier
	v_lshl_add_u64 v[134:135], v[134:135], 0, s[26:27]
	s_cmp_ge_i32 s10, s48
	v_lshl_add_u64 v[136:137], v[136:137], 0, s[26:27]
	s_cbranch_scc0 .LBB0_1192

; #define PG8_STAGE(bufoff, gbase, voff) do { _Pragma("unroll") for (int _i = 0; _i < 2; ++_i) \
;         __builtin_amdgcn_global_load_lds((const unsigned*)((const char*)(gbase) + (voff)[_i]), (PG8_LAS unsigned*)(lds + (bufoff) + ldsw + _i * 8192), 16, 0, 0); } while (0)
; #define PG8_LDA(dst, b, h) do { _Pragma("unroll") for (int m = 0; m < 4; ++m) _Pragma("unroll") for (int k = 0; k < 2; ++k) dst[m][k] = *(const PG8_LAS bf16x8*)(lds + PG8_SA(b, h) + aoff + m * 2048 + k * 1024); } while (0)
; #define PG8_LDB(dst, b, h) do { _Pragma("unroll") for (int n = 0; n < 2; ++n) _Pragma("unroll") for (int k = 0; k < 2; ++k) dst[n][k] = *(const PG8_LAS bf16x8*)(lds + PG8_SB(b, h) + boff + n * 2048 + k * 1024); } while (0)
; #define PG8_MMA(ai, bj, At, Bt) do { __builtin_amdgcn_s_setprio(1); _Pragma("unroll") for (int m = 0; m < 4; ++m) _Pragma("unroll") for (int n = 0; n < 2; ++n) _Pragma("unroll") for (int k = 0; k < 2; ++k) \
;         acc[ai][bj][m][n] = __builtin_amdgcn_mfma_f32_16x16x32_bf16(Bt[n][k], At[m][k], acc[ai][bj][m][n], 0, 0, 0); __builtin_amdgcn_s_setprio(0); } while (0)
; #define PG8_WAIT_V(n) asm volatile("s_waitcnt vmcnt(" #n ")" ::: "memory")
; #define PG8_BAR __builtin_amdgcn_s_barrier()
; template <class Epi, class Sched, bool ALIGN_EPI = false, bool SP2 = false>
; __device__ __forceinline__ void gemm_phase(PG8_LAS unsigned char* lds, const Gemm g, const Sched& S, const Epi& E) {
;     ...
;         for (int t = 0; t < nt; t += 2) {
;             const bool last = (t == nt - 2);
;             const char* a1 = cA + (size_t)(t + 1) * kstep;
;             const char* a2 = last ? nA : cA + (size_t)(t + 2) * kstep; const char* b2 = last ? nB : cB + (size_t)(t + 2) * kstep;
;             const char* a3 = a2 + kstep; const char* b3 = b2 + kstep;
;             if (last && has_next) S.a_ready(nxt);
;             if constexpr (SP2) {
;             PG8_LDB(B0, 0, 0); PG8_LDB(B1, 0, 1); PG8_SCHED; PG8_LDA(At, 0, 0); PG8_STAGE(PG8_SA(1, 1), a1 + hstep, voffA);
;             PG8_WAIT_V(8); PG8_WAIT_L(0); PG8_BAR; PG8_MMA(0, 0, At, B0); PG8_MMA(0, 1, At, B1); PG8_BAR; PG8_SCHED;
;             PG8_LDA(At, 0, 1); PG8_STAGE(PG8_SB(0, 0), b2, voffB); PG8_STAGE(PG8_SB(0, 1), b2 + hstep, voffB); PG8_STAGE(PG8_SA(0, 0), a2, voffA);
;             PG8_WAIT_V(8); PG8_WAIT_L(0); PG8_BAR; PG8_MMA(1, 0, At, B0); PG8_MMA(1, 1, At, B1); PG8_BAR; PG8_SCHED;
.LBB0_1340:
	v_add_u32_e32 v148, s55, v201
	v_add_u32_e32 v190, s56, v201
	ds_read_b128 v[136:139], v148
	ds_read_b128 v[140:143], v148 offset:1024
	ds_read_b128 v[144:147], v148 offset:2048
	ds_read_b128 v[148:151], v148 offset:3072
	ds_read_b128 v[152:155], v190
	ds_read_b128 v[182:185], v190 offset:1024
	ds_read_b128 v[186:189], v190 offset:2048
	ds_read_b128 v[190:193], v190 offset:3072
	s_cmp_eq_u32 s48, s12
	v_lshl_add_u64 v[194:195], v[134:135], 0, s[22:23]
	s_cselect_b64 vcc, -1, 0
	s_add_i32 s12, s12, 2
	v_cndmask_b32_e32 v199, v195, v179, vcc
	v_cndmask_b32_e32 v198, v194, v178, vcc
	v_cndmask_b32_e32 v215, v133, v181, vcc
	v_cndmask_b32_e32 v214, v132, v180, vcc
	s_mov_b32 m0, s57
	v_lshl_add_u64 v[236:237], v[134:135], 0, v[174:175]
	ds_read_b128 v[194:197], v203
	ds_read_b128 v[206:209], v203 offset:1024
	ds_read_b128 v[210:213], v203 offset:2048
	ds_read_b128 v[216:219], v203 offset:3072
	ds_read_b128 v[220:223], v203 offset:4096
	ds_read_b128 v[224:227], v203 offset:5120
	ds_read_b128 v[228:231], v203 offset:6144
	ds_read_b128 v[232:235], v203 offset:7168
	global_load_lds_dwordx4 v[236:237], off
	s_mov_b32 m0, s58
	v_lshl_add_u64 v[236:237], v[134:135], 0, v[172:173]
	global_load_lds_dwordx4 v[236:237], off
	s_waitcnt vmcnt(8) lgkmcnt(0)
	s_setprio 1
	s_barrier
	v_mfma_f32_16x16x32_bf16 v[124:127], v[136:139], v[194:197], v[124:127]
	v_mfma_f32_16x16x32_bf16 v[128:131], v[144:147], v[194:197], v[128:131]
	v_mfma_f32_16x16x32_bf16 v[112:115], v[136:139], v[210:213], v[112:115]
	v_mfma_f32_16x16x32_bf16 v[108:111], v[144:147], v[210:213], v[108:111]
	v_mfma_f32_16x16x32_bf16 v[96:99], v[136:139], v[220:223], v[96:99]
	v_mfma_f32_16x16x32_bf16 v[92:95], v[144:147], v[220:223], v[92:95]
	v_mfma_f32_16x16x32_bf16 v[80:83], v[136:139], v[228:231], v[80:83]
	v_mfma_f32_16x16x32_bf16 v[76:79], v[144:147], v[228:231], v[76:79]
	v_mfma_f32_16x16x32_bf16 v[124:127], v[140:143], v[206:209], v[124:127]
	v_mfma_f32_16x16x32_bf16 v[128:131], v[148:151], v[206:209], v[128:131]
	v_mfma_f32_16x16x32_bf16 v[112:115], v[140:143], v[216:219], v[112:115]
	v_mfma_f32_16x16x32_bf16 v[108:111], v[148:151], v[216:219], v[108:111]
	v_mfma_f32_16x16x32_bf16 v[96:99], v[140:143], v[224:227], v[96:99]
	v_mfma_f32_16x16x32_bf16 v[92:95], v[148:151], v[224:227], v[92:95]
	v_mfma_f32_16x16x32_bf16 v[80:83], v[140:143], v[232:235], v[80:83]
	v_mfma_f32_16x16x32_bf16 v[76:79], v[148:151], v[232:235], v[76:79]
	v_mfma_f32_16x16x32_bf16 v[120:123], v[152:155], v[194:197], v[120:123]
	v_mfma_f32_16x16x32_bf16 v[116:119], v[186:189], v[194:197], v[116:119]
	v_mfma_f32_16x16x32_bf16 v[104:107], v[152:155], v[210:213], v[104:107]
	v_mfma_f32_16x16x32_bf16 v[100:103], v[186:189], v[210:213], v[100:103]
	v_mfma_f32_16x16x32_bf16 v[88:91], v[152:155], v[220:223], v[88:91]
	v_mfma_f32_16x16x32_bf16 v[84:87], v[186:189], v[220:223], v[84:87]
	v_mfma_f32_16x16x32_bf16 v[72:75], v[152:155], v[228:231], v[72:75]
	v_mfma_f32_16x16x32_bf16 v[68:71], v[186:189], v[228:231], v[68:71]
	v_mfma_f32_16x16x32_bf16 v[120:123], v[182:185], v[206:209], v[120:123]
	v_mfma_f32_16x16x32_bf16 v[116:119], v[190:193], v[206:209], v[116:119]
	v_mfma_f32_16x16x32_bf16 v[104:107], v[182:185], v[216:219], v[104:107]
	v_mfma_f32_16x16x32_bf16 v[100:103], v[190:193], v[216:219], v[100:103]
	v_mfma_f32_16x16x32_bf16 v[88:91], v[182:185], v[224:227], v[88:91]
	v_mfma_f32_16x16x32_bf16 v[84:87], v[190:193], v[224:227], v[84:87]
	v_mfma_f32_16x16x32_bf16 v[72:75], v[182:185], v[232:235], v[72:75]
	v_mfma_f32_16x16x32_bf16 v[68:71], v[190:193], v[232:235], v[68:71]
	s_setprio 0
	s_barrier
	s_mov_b32 m0, s59
	v_lshl_add_u64 v[236:237], v[214:215], 0, v[166:167]
	ds_read_b128 v[194:197], v203 offset:16384
	ds_read_b128 v[206:209], v203 offset:17408
	ds_read_b128 v[210:213], v203 offset:18432
	ds_read_b128 v[216:219], v203 offset:19456
	ds_read_b128 v[220:223], v203 offset:20480
	ds_read_b128 v[224:227], v203 offset:21504
	ds_read_b128 v[228:231], v203 offset:22528
	ds_read_b128 v[232:235], v203 offset:23552
	global_load_lds_dwordx4 v[236:237], off
	v_lshl_add_u64 v[238:239], v[214:215], 0, v[170:171]
	s_mov_b32 m0, s60
	v_lshl_add_u64 v[214:215], v[214:215], 0, s[14:15]
	s_add_i32 s13, s56, s30
	global_load_lds_dwordx4 v[238:239], off
	v_lshl_add_u64 v[240:241], v[214:215], 0, v[166:167]
	s_mov_b32 m0, s13
	v_lshl_add_u64 v[214:215], v[214:215], 0, v[170:171]
	global_load_lds_dwordx4 v[240:241], off
	s_add_i32 m0, s13, 0x2000
	v_lshl_add_u64 v[242:243], v[198:199], 0, v[164:165]
	global_load_lds_dwordx4 v[214:215], off
	s_mov_b32 m0, s31
	v_lshl_add_u64 v[244:245], v[198:199], 0, v[168:169]
	global_load_lds_dwordx4 v[242:243], off
	s_nop 0
	s_waitcnt vmcnt(7) lgkmcnt(0)
	s_setprio 1
	s_barrier
; #define PG8_STAGE(bufoff, gbase, voff) do { _Pragma("unroll") for (int _i = 0; _i < 2; ++_i) \
;         __builtin_amdgcn_global_load_lds((const unsigned*)((const char*)(gbase) + (voff)[_i]), (PG8_LAS unsigned*)(lds + (bufoff) + ldsw + _i * 8192), 16, 0, 0); } while (0)
; #define PG8_LDA(dst, b, h) do { _Pragma("unroll") for (int m = 0; m < 4; ++m) _Pragma("unroll") for (int k = 0; k < 2; ++k) dst[m][k] = *(const PG8_LAS bf16x8*)(lds + PG8_SA(b, h) + aoff + m * 2048 + k * 1024); } while (0)
; #define PG8_LDB(dst, b, h) do { _Pragma("unroll") for (int n = 0; n < 2; ++n) _Pragma("unroll") for (int k = 0; k < 2; ++k) dst[n][k] = *(const PG8_LAS bf16x8*)(lds + PG8_SB(b, h) + boff + n * 2048 + k * 1024); } while (0)
; #define PG8_MMA(ai, bj, At, Bt) do { __builtin_amdgcn_s_setprio(1); _Pragma("unroll") for (int m = 0; m < 4; ++m) _Pragma("unroll") for (int n = 0; n < 2; ++n) _Pragma("unroll") for (int k = 0; k < 2; ++k) \
;         acc[ai][bj][m][n] = __builtin_amdgcn_mfma_f32_16x16x32_bf16(Bt[n][k], At[m][k], acc[ai][bj][m][n], 0, 0, 0); __builtin_amdgcn_s_setprio(0); } while (0)
; #define PG8_WAIT_V(n) asm volatile("s_waitcnt vmcnt(" #n ")" ::: "memory")
; #define PG8_WAIT_L(n) asm volatile("s_waitcnt lgkmcnt(" #n ")" ::: "memory")
; #define PG8_BAR __builtin_amdgcn_s_barrier()
; #define PG8_SCHED __builtin_amdgcn_sched_barrier(0)
; template <class Epi, class Sched, bool ALIGN_EPI = false, bool SP2 = false>
; __device__ __forceinline__ void gemm_phase(PG8_LAS unsigned char* lds, const Gemm g, const Sched& S, const Epi& E) {
;     ...
;             PG8_WAIT_V(8); PG8_WAIT_L(0); PG8_BAR; PG8_MMA(1, 0, At, B0); PG8_MMA(1, 1, At, B1); PG8_BAR; PG8_SCHED;
;             PG8_LDB(B0, 1, 0); PG8_LDB(B1, 1, 1); PG8_SCHED; PG8_LDA(At, 1, 0); PG8_STAGE(PG8_SA(0, 1), a2 + hstep, voffA);
;             PG8_WAIT_V(8); PG8_WAIT_L(0); PG8_BAR; PG8_MMA(0, 0, At, B0); PG8_MMA(0, 1, At, B1); PG8_BAR; PG8_SCHED;
	v_mfma_f32_16x16x32_bf16 v[64:67], v[136:139], v[194:197], v[64:67]
	v_mfma_f32_16x16x32_bf16 v[60:63], v[144:147], v[194:197], v[60:63]
	v_mfma_f32_16x16x32_bf16 v[48:51], v[136:139], v[210:213], v[48:51]
	v_mfma_f32_16x16x32_bf16 v[44:47], v[144:147], v[210:213], v[44:47]
	v_mfma_f32_16x16x32_bf16 v[32:35], v[136:139], v[220:223], v[32:35]
	v_mfma_f32_16x16x32_bf16 v[28:31], v[144:147], v[220:223], v[28:31]
	v_mfma_f32_16x16x32_bf16 v[16:19], v[136:139], v[228:231], v[16:19]
	v_mfma_f32_16x16x32_bf16 v[12:15], v[144:147], v[228:231], v[12:15]
	v_mfma_f32_16x16x32_bf16 v[64:67], v[140:143], v[206:209], v[64:67]
	v_mfma_f32_16x16x32_bf16 v[60:63], v[148:151], v[206:209], v[60:63]
	v_mfma_f32_16x16x32_bf16 v[48:51], v[140:143], v[216:219], v[48:51]
	v_mfma_f32_16x16x32_bf16 v[44:47], v[148:151], v[216:219], v[44:47]
	v_mfma_f32_16x16x32_bf16 v[32:35], v[140:143], v[224:227], v[32:35]
	v_mfma_f32_16x16x32_bf16 v[28:31], v[148:151], v[224:227], v[28:31]
	v_mfma_f32_16x16x32_bf16 v[16:19], v[140:143], v[232:235], v[16:19]
	v_mfma_f32_16x16x32_bf16 v[12:15], v[148:151], v[232:235], v[12:15]
	v_mfma_f32_16x16x32_bf16 v[56:59], v[152:155], v[194:197], v[56:59]
	v_mfma_f32_16x16x32_bf16 v[52:55], v[186:189], v[194:197], v[52:55]
	v_mfma_f32_16x16x32_bf16 v[40:43], v[152:155], v[210:213], v[40:43]
	v_mfma_f32_16x16x32_bf16 v[36:39], v[186:189], v[210:213], v[36:39]
	v_mfma_f32_16x16x32_bf16 v[24:27], v[152:155], v[220:223], v[24:27]
	v_mfma_f32_16x16x32_bf16 v[20:23], v[186:189], v[220:223], v[20:23]
	v_mfma_f32_16x16x32_bf16 v[8:11], v[152:155], v[228:231], v[8:11]
	v_mfma_f32_16x16x32_bf16 v[4:7], v[186:189], v[228:231], v[4:7]
	v_mfma_f32_16x16x32_bf16 v[56:59], v[182:185], v[206:209], v[56:59]
	v_mfma_f32_16x16x32_bf16 v[52:55], v[190:193], v[206:209], v[52:55]
	v_mfma_f32_16x16x32_bf16 v[40:43], v[182:185], v[216:219], v[40:43]
	v_mfma_f32_16x16x32_bf16 v[36:39], v[190:193], v[216:219], v[36:39]
	v_mfma_f32_16x16x32_bf16 v[24:27], v[182:185], v[224:227], v[24:27]
	v_mfma_f32_16x16x32_bf16 v[20:23], v[190:193], v[224:227], v[20:23]
	v_mfma_f32_16x16x32_bf16 v[8:11], v[182:185], v[232:235], v[8:11]
	v_mfma_f32_16x16x32_bf16 v[4:7], v[190:193], v[232:235], v[4:7]
	s_setprio 0
	s_barrier
	s_add_i32 s13, 0, 0x18000
	s_add_i32 s29, 0, 0x1c000
	v_add_u32_e32 v148, s13, v201
	v_add_u32_e32 v190, s29, v201
	s_mov_b32 m0, s34
	ds_read_b128 v[136:139], v148
	global_load_lds_dwordx4 v[244:245], off
	ds_read_b128 v[140:143], v148 offset:1024
	ds_read_b128 v[144:147], v148 offset:2048
	ds_read_b128 v[148:151], v148 offset:3072
	ds_read_b128 v[152:155], v190
	ds_read_b128 v[182:185], v190 offset:1024
	ds_read_b128 v[186:189], v190 offset:2048
	ds_read_b128 v[190:193], v190 offset:3072
	v_lshl_add_u64 v[198:199], v[198:199], 0, s[14:15]
	s_mov_b32 m0, s35
	v_lshl_add_u64 v[246:247], v[198:199], 0, v[164:165]
	ds_read_b128 v[194:197], v203 offset:32768
	ds_read_b128 v[206:209], v203 offset:33792
	ds_read_b128 v[210:213], v203 offset:34816
	ds_read_b128 v[216:219], v203 offset:35840
	ds_read_b128 v[220:223], v203 offset:36864
	ds_read_b128 v[224:227], v203 offset:37888
	ds_read_b128 v[228:231], v203 offset:38912
	ds_read_b128 v[232:235], v203 offset:39936
	global_load_lds_dwordx4 v[246:247], off
	s_mov_b32 m0, s36
	v_lshl_add_u64 v[198:199], v[198:199], 0, v[168:169]
	global_load_lds_dwordx4 v[198:199], off
	s_waitcnt vmcnt(8) lgkmcnt(0)
	s_setprio 1
	s_barrier
	v_mfma_f32_16x16x32_bf16 v[124:127], v[136:139], v[194:197], v[124:127]
	v_mfma_f32_16x16x32_bf16 v[128:131], v[144:147], v[194:197], v[128:131]
	v_mfma_f32_16x16x32_bf16 v[112:115], v[136:139], v[210:213], v[112:115]
	v_mfma_f32_16x16x32_bf16 v[108:111], v[144:147], v[210:213], v[108:111]
	v_mfma_f32_16x16x32_bf16 v[96:99], v[136:139], v[220:223], v[96:99]
	v_mfma_f32_16x16x32_bf16 v[92:95], v[144:147], v[220:223], v[92:95]
	v_mfma_f32_16x16x32_bf16 v[80:83], v[136:139], v[228:231], v[80:83]
	v_mfma_f32_16x16x32_bf16 v[76:79], v[144:147], v[228:231], v[76:79]
	v_mfma_f32_16x16x32_bf16 v[124:127], v[140:143], v[206:209], v[124:127]
	v_mfma_f32_16x16x32_bf16 v[128:131], v[148:151], v[206:209], v[128:131]
	v_mfma_f32_16x16x32_bf16 v[112:115], v[140:143], v[216:219], v[112:115]
	v_mfma_f32_16x16x32_bf16 v[108:111], v[148:151], v[216:219], v[108:111]
	v_mfma_f32_16x16x32_bf16 v[96:99], v[140:143], v[224:227], v[96:99]
	v_mfma_f32_16x16x32_bf16 v[92:95], v[148:151], v[224:227], v[92:95]
	v_mfma_f32_16x16x32_bf16 v[80:83], v[140:143], v[232:235], v[80:83]
	v_mfma_f32_16x16x32_bf16 v[76:79], v[148:151], v[232:235], v[76:79]
	v_mfma_f32_16x16x32_bf16 v[120:123], v[152:155], v[194:197], v[120:123]
	v_mfma_f32_16x16x32_bf16 v[116:119], v[186:189], v[194:197], v[116:119]
	v_mfma_f32_16x16x32_bf16 v[104:107], v[152:155], v[210:213], v[104:107]
	v_mfma_f32_16x16x32_bf16 v[100:103], v[186:189], v[210:213], v[100:103]
	v_mfma_f32_16x16x32_bf16 v[88:91], v[152:155], v[220:223], v[88:91]
	v_mfma_f32_16x16x32_bf16 v[84:87], v[186:189], v[220:223], v[84:87]
	v_mfma_f32_16x16x32_bf16 v[72:75], v[152:155], v[228:231], v[72:75]
	v_mfma_f32_16x16x32_bf16 v[68:71], v[186:189], v[228:231], v[68:71]
	v_mfma_f32_16x16x32_bf16 v[120:123], v[182:185], v[206:209], v[120:123]
	v_mfma_f32_16x16x32_bf16 v[116:119], v[190:193], v[206:209], v[116:119]
	v_mfma_f32_16x16x32_bf16 v[104:107], v[182:185], v[216:219], v[104:107]
	v_mfma_f32_16x16x32_bf16 v[100:103], v[190:193], v[216:219], v[100:103]
	v_mfma_f32_16x16x32_bf16 v[88:91], v[182:185], v[224:227], v[88:91]
	v_mfma_f32_16x16x32_bf16 v[84:87], v[190:193], v[224:227], v[84:87]
	v_mfma_f32_16x16x32_bf16 v[72:75], v[182:185], v[232:235], v[72:75]
	v_mfma_f32_16x16x32_bf16 v[68:71], v[190:193], v[232:235], v[68:71]
	s_setprio 0
	s_barrier
; #define PG8_STAGE(bufoff, gbase, voff) do { _Pragma("unroll") for (int _i = 0; _i < 2; ++_i) \
;         __builtin_amdgcn_global_load_lds((const unsigned*)((const char*)(gbase) + (voff)[_i]), (PG8_LAS unsigned*)(lds + (bufoff) + ldsw + _i * 8192), 16, 0, 0); } while (0)
; #define PG8_LDA(dst, b, h) do { _Pragma("unroll") for (int m = 0; m < 4; ++m) _Pragma("unroll") for (int k = 0; k < 2; ++k) dst[m][k] = *(const PG8_LAS bf16x8*)(lds + PG8_SA(b, h) + aoff + m * 2048 + k * 1024); } while (0)
; #define PG8_MMA(ai, bj, At, Bt) do { __builtin_amdgcn_s_setprio(1); _Pragma("unroll") for (int m = 0; m < 4; ++m) _Pragma("unroll") for (int n = 0; n < 2; ++n) _Pragma("unroll") for (int k = 0; k < 2; ++k) \
;         acc[ai][bj][m][n] = __builtin_amdgcn_mfma_f32_16x16x32_bf16(Bt[n][k], At[m][k], acc[ai][bj][m][n], 0, 0, 0); __builtin_amdgcn_s_setprio(0); } while (0)
; #define PG8_WAIT_V(n) asm volatile("s_waitcnt vmcnt(" #n ")" ::: "memory")
; #define PG8_WAIT_L(n) asm volatile("s_waitcnt lgkmcnt(" #n ")" ::: "memory")
; #define PG8_BAR __builtin_amdgcn_s_barrier()
; #define PG8_SCHED __builtin_amdgcn_sched_barrier(0)
; template <class Epi, class Sched, bool ALIGN_EPI = false, bool SP2 = false>
; __device__ __forceinline__ void gemm_phase(PG8_LAS unsigned char* lds, const Gemm g, const Sched& S, const Epi& E) {
;     ...
;             PG8_LDA(At, 1, 1); PG8_STAGE(PG8_SB(1, 0), b3, voffB); PG8_STAGE(PG8_SB(1, 1), b3 + hstep, voffB); PG8_STAGE(PG8_SA(1, 0), a3, voffA);
;             PG8_WAIT_V(8); PG8_WAIT_L(0); PG8_BAR; PG8_MMA(1, 0, At, B0); PG8_MMA(1, 1, At, B1); PG8_BAR; PG8_SCHED;
	s_add_i32 s13, s13, s30
	v_lshl_add_u64 v[198:199], v[236:237], 0, s[22:23]
	s_mov_b32 m0, s13
	ds_read_b128 v[194:197], v203 offset:49152
	ds_read_b128 v[206:209], v203 offset:50176
	ds_read_b128 v[210:213], v203 offset:51200
	ds_read_b128 v[216:219], v203 offset:52224
	ds_read_b128 v[220:223], v203 offset:53248
	ds_read_b128 v[224:227], v203 offset:54272
	ds_read_b128 v[228:231], v203 offset:55296
	ds_read_b128 v[232:235], v203 offset:56320
	global_load_lds_dwordx4 v[198:199], off
	v_lshl_add_u64 v[198:199], v[238:239], 0, s[22:23]
	s_add_i32 m0, s13, 0x2000
	s_add_i32 s13, s29, s30
	global_load_lds_dwordx4 v[198:199], off
	s_mov_b32 m0, s13
	v_lshl_add_u64 v[198:199], v[240:241], 0, s[22:23]
	global_load_lds_dwordx4 v[198:199], off
	s_add_i32 m0, s13, 0x2000
	v_lshl_add_u64 v[198:199], v[214:215], 0, s[22:23]
	global_load_lds_dwordx4 v[198:199], off
	s_mov_b32 m0, s37
	v_lshl_add_u64 v[198:199], v[242:243], 0, s[22:23]
	global_load_lds_dwordx4 v[198:199], off
	s_mov_b32 m0, s41
	v_lshl_add_u64 v[198:199], v[244:245], 0, s[22:23]
	global_load_lds_dwordx4 v[198:199], off
	s_waitcnt vmcnt(8) lgkmcnt(0)
	s_setprio 1
	s_barrier
	v_mfma_f32_16x16x32_bf16 v[64:67], v[136:139], v[194:197], v[64:67]
	v_mfma_f32_16x16x32_bf16 v[60:63], v[144:147], v[194:197], v[60:63]
	v_mfma_f32_16x16x32_bf16 v[48:51], v[136:139], v[210:213], v[48:51]
	v_mfma_f32_16x16x32_bf16 v[44:47], v[144:147], v[210:213], v[44:47]
	v_mfma_f32_16x16x32_bf16 v[32:35], v[136:139], v[220:223], v[32:35]
	v_mfma_f32_16x16x32_bf16 v[28:31], v[144:147], v[220:223], v[28:31]
	v_mfma_f32_16x16x32_bf16 v[16:19], v[136:139], v[228:231], v[16:19]
	v_mfma_f32_16x16x32_bf16 v[12:15], v[144:147], v[228:231], v[12:15]
	v_mfma_f32_16x16x32_bf16 v[64:67], v[140:143], v[206:209], v[64:67]
	v_mfma_f32_16x16x32_bf16 v[60:63], v[148:151], v[206:209], v[60:63]
	v_mfma_f32_16x16x32_bf16 v[48:51], v[140:143], v[216:219], v[48:51]
	v_mfma_f32_16x16x32_bf16 v[44:47], v[148:151], v[216:219], v[44:47]
	v_mfma_f32_16x16x32_bf16 v[32:35], v[140:143], v[224:227], v[32:35]
	v_mfma_f32_16x16x32_bf16 v[28:31], v[148:151], v[224:227], v[28:31]
	v_mfma_f32_16x16x32_bf16 v[16:19], v[140:143], v[232:235], v[16:19]
	v_mfma_f32_16x16x32_bf16 v[12:15], v[148:151], v[232:235], v[12:15]
	v_mfma_f32_16x16x32_bf16 v[56:59], v[152:155], v[194:197], v[56:59]
	v_mfma_f32_16x16x32_bf16 v[52:55], v[186:189], v[194:197], v[52:55]
	v_mfma_f32_16x16x32_bf16 v[40:43], v[152:155], v[210:213], v[40:43]
	v_mfma_f32_16x16x32_bf16 v[36:39], v[186:189], v[210:213], v[36:39]
	v_mfma_f32_16x16x32_bf16 v[24:27], v[152:155], v[220:223], v[24:27]
	v_mfma_f32_16x16x32_bf16 v[20:23], v[186:189], v[220:223], v[20:23]
	v_mfma_f32_16x16x32_bf16 v[8:11], v[152:155], v[228:231], v[8:11]
	v_mfma_f32_16x16x32_bf16 v[4:7], v[186:189], v[228:231], v[4:7]
	v_mfma_f32_16x16x32_bf16 v[56:59], v[182:185], v[206:209], v[56:59]
	v_mfma_f32_16x16x32_bf16 v[52:55], v[190:193], v[206:209], v[52:55]
	v_mfma_f32_16x16x32_bf16 v[40:43], v[182:185], v[216:219], v[40:43]
	v_mfma_f32_16x16x32_bf16 v[36:39], v[190:193], v[216:219], v[36:39]
	v_mfma_f32_16x16x32_bf16 v[24:27], v[182:185], v[224:227], v[24:27]
	v_mfma_f32_16x16x32_bf16 v[20:23], v[190:193], v[224:227], v[20:23]
	v_mfma_f32_16x16x32_bf16 v[8:11], v[182:185], v[232:235], v[8:11]
	v_mfma_f32_16x16x32_bf16 v[4:7], v[190:193], v[232:235], v[4:7]
	s_setprio 0
	s_barrier
	v_lshl_add_u64 v[132:133], v[132:133], 0, s[26:27]
	s_cmp_ge_i32 s12, s47
	v_lshl_add_u64 v[134:135], v[134:135], 0, s[26:27]
	s_cbranch_scc0 .LBB0_1340

; #define PG8_STAGE(bufoff, gbase, voff) do { _Pragma("unroll") for (int _i = 0; _i < 2; ++_i) \
;         __builtin_amdgcn_global_load_lds((const unsigned*)((const char*)(gbase) + (voff)[_i]), (PG8_LAS unsigned*)(lds + (bufoff) + ldsw + _i * 8192), 16, 0, 0); } while (0)
; #define PG8_LDA(dst, b, h) do { _Pragma("unroll") for (int m = 0; m < 4; ++m) _Pragma("unroll") for (int k = 0; k < 2; ++k) dst[m][k] = *(const PG8_LAS bf16x8*)(lds + PG8_SA(b, h) + aoff + m * 2048 + k * 1024); } while (0)
; #define PG8_LDB(dst, b, h) do { _Pragma("unroll") for (int n = 0; n < 2; ++n) _Pragma("unroll") for (int k = 0; k < 2; ++k) dst[n][k] = *(const PG8_LAS bf16x8*)(lds + PG8_SB(b, h) + boff + n * 2048 + k * 1024); } while (0)
; #define PG8_MMA(ai, bj, At, Bt) do { __builtin_amdgcn_s_setprio(1); _Pragma("unroll") for (int m = 0; m < 4; ++m) _Pragma("unroll") for (int n = 0; n < 2; ++n) _Pragma("unroll") for (int k = 0; k < 2; ++k) \
;         acc[ai][bj][m][n] = __builtin_amdgcn_mfma_f32_16x16x32_bf16(Bt[n][k], At[m][k], acc[ai][bj][m][n], 0, 0, 0); __builtin_amdgcn_s_setprio(0); } while (0)
; #define PG8_WAIT_V(n) asm volatile("s_waitcnt vmcnt(" #n ")" ::: "memory")
; #define PG8_WAIT_L(n) asm volatile("s_waitcnt lgkmcnt(" #n ")" ::: "memory")
; #define PG8_BAR __builtin_amdgcn_s_barrier()
; #define PG8_SCHED __builtin_amdgcn_sched_barrier(0)
; template <class Epi, class Sched, bool ALIGN_EPI = false, bool SP2 = false>
; __device__ __forceinline__ void gemm_phase(PG8_LAS unsigned char* lds, const Gemm g, const Sched& S, const Epi& E) {
;     ...
;             PG8_LDA(At, 0, 1); PG8_STAGE(PG8_SB(0, 0), b2, voffB); PG8_STAGE(PG8_SB(0, 1), b2 + hstep, voffB); PG8_STAGE(PG8_SA(0, 0), a2, voffA);
;             PG8_WAIT_V(8); PG8_WAIT_L(0); PG8_BAR; PG8_MMA(1, 0, At, B0); PG8_MMA(1, 1, At, B1); PG8_BAR; PG8_SCHED;
;             PG8_LDB(B0, 1, 0); PG8_LDB(B1, 1, 1); PG8_SCHED; PG8_LDA(At, 1, 0); PG8_STAGE(PG8_SA(0, 1), a2 + hstep, voffA);
;             PG8_WAIT_V(8); PG8_WAIT_L(0); PG8_BAR; PG8_MMA(0, 0, At, B0); PG8_MMA(0, 1, At, B1); PG8_BAR; PG8_SCHED;
.Lio_skipk0:
	s_setprio 0
	s_barrier
	s_add_i32 s11, s81, s41
	v_lshl_add_u64 v[240:241], v[214:215], 0, v[146:147]
	s_mov_b32 m0, s11
	ds_read_b128 v[198:201], v213 offset:16384
	ds_read_b128 v[202:205], v213 offset:17408
	ds_read_b128 v[206:209], v213 offset:18432
	ds_read_b128 v[220:223], v213 offset:19456
	ds_read_b128 v[224:227], v213 offset:20480
	ds_read_b128 v[228:231], v213 offset:21504
	ds_read_b128 v[232:235], v213 offset:22528
	ds_read_b128 v[236:239], v213 offset:23552
	global_load_lds_dwordx4 v[240:241], off
	v_lshl_add_u64 v[242:243], v[214:215], 0, v[150:151]
	s_add_i32 m0, s11, 0x2000
	v_lshl_add_u64 v[214:215], v[214:215], 0, s[18:19]
	s_add_i32 s11, s82, s41
	global_load_lds_dwordx4 v[242:243], off
	v_lshl_add_u64 v[244:245], v[214:215], 0, v[146:147]
	s_mov_b32 m0, s11
	v_lshl_add_u64 v[214:215], v[214:215], 0, v[150:151]
	global_load_lds_dwordx4 v[244:245], off
	s_add_i32 m0, s11, 0x2000
	v_lshl_add_u64 v[246:247], v[210:211], 0, v[144:145]
	global_load_lds_dwordx4 v[214:215], off
	s_mov_b32 m0, s47
	v_lshl_add_u64 v[248:249], v[210:211], 0, v[148:149]
	global_load_lds_dwordx4 v[246:247], off
	s_nop 0
	s_waitcnt vmcnt(7) lgkmcnt(0)
	s_setprio 1
	s_barrier
	v_mfma_f32_16x16x32_bf16 v[60:63], v[132:135], v[198:201], v[60:63]
	v_mfma_f32_16x16x32_bf16 v[56:59], v[174:177], v[198:201], v[56:59]
	v_mfma_f32_16x16x32_bf16 v[44:47], v[132:135], v[206:209], v[44:47]
	v_mfma_f32_16x16x32_bf16 v[40:43], v[174:177], v[206:209], v[40:43]
	v_mfma_f32_16x16x32_bf16 v[28:31], v[132:135], v[224:227], v[28:31]
	v_mfma_f32_16x16x32_bf16 v[24:27], v[174:177], v[224:227], v[24:27]
	v_mfma_f32_16x16x32_bf16 v[12:15], v[132:135], v[232:235], v[12:15]
	v_mfma_f32_16x16x32_bf16 v[8:11], v[174:177], v[232:235], v[8:11]
	v_mfma_f32_16x16x32_bf16 v[60:63], v[136:139], v[202:205], v[60:63]
	v_mfma_f32_16x16x32_bf16 v[56:59], v[178:181], v[202:205], v[56:59]
	v_mfma_f32_16x16x32_bf16 v[44:47], v[136:139], v[220:223], v[44:47]
	v_mfma_f32_16x16x32_bf16 v[40:43], v[178:181], v[220:223], v[40:43]
	v_mfma_f32_16x16x32_bf16 v[28:31], v[136:139], v[228:231], v[28:31]
	v_mfma_f32_16x16x32_bf16 v[24:27], v[178:181], v[228:231], v[24:27]
	v_mfma_f32_16x16x32_bf16 v[12:15], v[136:139], v[236:239], v[12:15]
	v_mfma_f32_16x16x32_bf16 v[8:11], v[178:181], v[236:239], v[8:11]
	s_cmp_eq_u32 s22, 12
	s_cbranch_scc1 .Lio_skipk1
	v_mfma_f32_16x16x32_bf16 v[52:55], v[182:185], v[198:201], v[52:55]
	v_mfma_f32_16x16x32_bf16 v[48:51], v[190:193], v[198:201], v[48:51]
	v_mfma_f32_16x16x32_bf16 v[36:39], v[182:185], v[206:209], v[36:39]
	v_mfma_f32_16x16x32_bf16 v[32:35], v[190:193], v[206:209], v[32:35]
	v_mfma_f32_16x16x32_bf16 v[20:23], v[182:185], v[224:227], v[20:23]
	v_mfma_f32_16x16x32_bf16 v[16:19], v[190:193], v[224:227], v[16:19]
	v_mfma_f32_16x16x32_bf16 v[4:7], v[182:185], v[232:235], v[4:7]
	v_mfma_f32_16x16x32_bf16 v[0:3], v[190:193], v[232:235], v[0:3]
	v_mfma_f32_16x16x32_bf16 v[52:55], v[186:189], v[202:205], v[52:55]
	v_mfma_f32_16x16x32_bf16 v[48:51], v[194:197], v[202:205], v[48:51]
	v_mfma_f32_16x16x32_bf16 v[36:39], v[186:189], v[220:223], v[36:39]
	v_mfma_f32_16x16x32_bf16 v[32:35], v[194:197], v[220:223], v[32:35]
	v_mfma_f32_16x16x32_bf16 v[20:23], v[186:189], v[228:231], v[20:23]
	v_mfma_f32_16x16x32_bf16 v[16:19], v[194:197], v[228:231], v[16:19]
	v_mfma_f32_16x16x32_bf16 v[4:7], v[186:189], v[236:239], v[4:7]
	v_mfma_f32_16x16x32_bf16 v[0:3], v[194:197], v[236:239], v[0:3]
.Lio_skipk1:
	s_setprio 0
	s_barrier
	s_add_i32 s11, 0, 0x18000
	v_add_u32_e32 v152, s11, v169
	s_add_i32 s13, 0, 0x1c000
	s_mov_b32 m0, s55
	ds_read_b128 v[132:135], v152
	global_load_lds_dwordx4 v[248:249], off
	ds_read_b128 v[136:139], v152 offset:1024
	ds_read_b128 v[174:177], v152 offset:2048
	ds_read_b128 v[178:181], v152 offset:3072
	v_add_u32_e32 v152, s13, v169
	ds_read_b128 v[182:185], v152
	ds_read_b128 v[186:189], v152 offset:1024
	ds_read_b128 v[190:193], v152 offset:2048
	ds_read_b128 v[194:197], v152 offset:3072
	v_lshl_add_u64 v[210:211], v[210:211], 0, s[18:19]
	s_mov_b32 m0, s57
	v_lshl_add_u64 v[250:251], v[210:211], 0, v[144:145]
	ds_read_b128 v[198:201], v213 offset:32768
	ds_read_b128 v[202:205], v213 offset:33792
	ds_read_b128 v[206:209], v213 offset:34816
	ds_read_b128 v[220:223], v213 offset:35840
	ds_read_b128 v[224:227], v213 offset:36864
	ds_read_b128 v[228:231], v213 offset:37888
	ds_read_b128 v[232:235], v213 offset:38912
	ds_read_b128 v[236:239], v213 offset:39936
	global_load_lds_dwordx4 v[250:251], off
	s_mov_b32 m0, s59
	v_lshl_add_u64 v[210:211], v[210:211], 0, v[148:149]
	global_load_lds_dwordx4 v[210:211], off
	s_waitcnt vmcnt(8) lgkmcnt(0)
	s_setprio 1
	s_barrier
	v_mfma_f32_16x16x32_bf16 v[124:127], v[132:135], v[198:201], v[124:127]
	v_mfma_f32_16x16x32_bf16 v[120:123], v[174:177], v[198:201], v[120:123]
	v_mfma_f32_16x16x32_bf16 v[108:111], v[132:135], v[206:209], v[108:111]
	v_mfma_f32_16x16x32_bf16 v[104:107], v[174:177], v[206:209], v[104:107]
	v_mfma_f32_16x16x32_bf16 v[92:95], v[132:135], v[224:227], v[92:95]
	v_mfma_f32_16x16x32_bf16 v[88:91], v[174:177], v[224:227], v[88:91]
	v_mfma_f32_16x16x32_bf16 v[76:79], v[132:135], v[232:235], v[76:79]
	v_mfma_f32_16x16x32_bf16 v[72:75], v[174:177], v[232:235], v[72:75]
	v_mfma_f32_16x16x32_bf16 v[124:127], v[136:139], v[202:205], v[124:127]
	v_mfma_f32_16x16x32_bf16 v[120:123], v[178:181], v[202:205], v[120:123]
	v_mfma_f32_16x16x32_bf16 v[108:111], v[136:139], v[220:223], v[108:111]
	v_mfma_f32_16x16x32_bf16 v[104:107], v[178:181], v[220:223], v[104:107]
	v_mfma_f32_16x16x32_bf16 v[92:95], v[136:139], v[228:231], v[92:95]
	v_mfma_f32_16x16x32_bf16 v[88:91], v[178:181], v[228:231], v[88:91]
	v_mfma_f32_16x16x32_bf16 v[76:79], v[136:139], v[236:239], v[76:79]
	v_mfma_f32_16x16x32_bf16 v[72:75], v[178:181], v[236:239], v[72:75]
	s_cmp_eq_u32 s22, 12
	s_cbranch_scc1 .Lio_skipk2
	v_mfma_f32_16x16x32_bf16 v[116:119], v[182:185], v[198:201], v[116:119]
	v_mfma_f32_16x16x32_bf16 v[112:115], v[190:193], v[198:201], v[112:115]
	v_mfma_f32_16x16x32_bf16 v[100:103], v[182:185], v[206:209], v[100:103]
	v_mfma_f32_16x16x32_bf16 v[96:99], v[190:193], v[206:209], v[96:99]
	v_mfma_f32_16x16x32_bf16 v[84:87], v[182:185], v[224:227], v[84:87]
	v_mfma_f32_16x16x32_bf16 v[80:83], v[190:193], v[224:227], v[80:83]
	v_mfma_f32_16x16x32_bf16 v[68:71], v[182:185], v[232:235], v[68:71]
	v_mfma_f32_16x16x32_bf16 v[64:67], v[190:193], v[232:235], v[64:67]
	v_mfma_f32_16x16x32_bf16 v[116:119], v[186:189], v[202:205], v[116:119]
	v_mfma_f32_16x16x32_bf16 v[112:115], v[194:197], v[202:205], v[112:115]
	v_mfma_f32_16x16x32_bf16 v[100:103], v[186:189], v[220:223], v[100:103]
	v_mfma_f32_16x16x32_bf16 v[96:99], v[194:197], v[220:223], v[96:99]
	v_mfma_f32_16x16x32_bf16 v[84:87], v[186:189], v[228:231], v[84:87]
	v_mfma_f32_16x16x32_bf16 v[80:83], v[194:197], v[228:231], v[80:83]
	v_mfma_f32_16x16x32_bf16 v[68:71], v[186:189], v[236:239], v[68:71]
	v_mfma_f32_16x16x32_bf16 v[64:67], v[194:197], v[236:239], v[64:67]

; #define PG8_STAGE(bufoff, gbase, voff) do { _Pragma("unroll") for (int _i = 0; _i < 2; ++_i) \
;         __builtin_amdgcn_global_load_lds((const unsigned*)((const char*)(gbase) + (voff)[_i]), (PG8_LAS unsigned*)(lds + (bufoff) + ldsw + _i * 8192), 16, 0, 0); } while (0)
; #define PG8_LDA(dst, b, h) do { _Pragma("unroll") for (int m = 0; m < 4; ++m) _Pragma("unroll") for (int k = 0; k < 2; ++k) dst[m][k] = *(const PG8_LAS bf16x8*)(lds + PG8_SA(b, h) + aoff + m * 2048 + k * 1024); } while (0)
; #define PG8_LDB(dst, b, h) do { _Pragma("unroll") for (int n = 0; n < 2; ++n) _Pragma("unroll") for (int k = 0; k < 2; ++k) dst[n][k] = *(const PG8_LAS bf16x8*)(lds + PG8_SB(b, h) + boff + n * 2048 + k * 1024); } while (0)
; #define PG8_MMA(ai, bj, At, Bt) do { __builtin_amdgcn_s_setprio(1); _Pragma("unroll") for (int m = 0; m < 4; ++m) _Pragma("unroll") for (int n = 0; n < 2; ++n) _Pragma("unroll") for (int k = 0; k < 2; ++k) \
;         acc[ai][bj][m][n] = __builtin_amdgcn_mfma_f32_16x16x32_bf16(Bt[n][k], At[m][k], acc[ai][bj][m][n], 0, 0, 0); __builtin_amdgcn_s_setprio(0); } while (0)
; #define PG8_WAIT_V(n) asm volatile("s_waitcnt vmcnt(" #n ")" ::: "memory")
; #define PG8_BAR __builtin_amdgcn_s_barrier()
; template <class Epi, class Sched, bool ALIGN_EPI = false, bool SP2 = false>
; __device__ __forceinline__ void gemm_phase(PG8_LAS unsigned char* lds, const Gemm g, const Sched& S, const Epi& E) {
;     ...
;         for (int t = 0; t < nt; t += 2) {
;             const bool last = (t == nt - 2);
;             const char* a1 = cA + (size_t)(t + 1) * kstep;
;             const char* a2 = last ? nA : cA + (size_t)(t + 2) * kstep; const char* b2 = last ? nB : cB + (size_t)(t + 2) * kstep;
;             const char* a3 = a2 + kstep; const char* b3 = b2 + kstep;
;             if (last && has_next) S.a_ready(nxt);
;             if constexpr (SP2) {
;             PG8_LDB(B0, 0, 0); PG8_LDB(B1, 0, 1); PG8_SCHED; PG8_LDA(At, 0, 0); PG8_STAGE(PG8_SA(1, 1), a1 + hstep, voffA);
;             PG8_WAIT_V(8); PG8_WAIT_L(0); PG8_BAR; PG8_MMA(0, 0, At, B0); PG8_MMA(0, 1, At, B1); PG8_BAR; PG8_SCHED;
;             PG8_LDA(At, 0, 1); PG8_STAGE(PG8_SB(0, 0), b2, voffB); PG8_STAGE(PG8_SB(0, 1), b2 + hstep, voffB); PG8_STAGE(PG8_SA(0, 0), a2, voffA);
;             PG8_WAIT_V(8); PG8_WAIT_L(0); PG8_BAR; PG8_MMA(1, 0, At, B0); PG8_MMA(1, 1, At, B1); PG8_BAR; PG8_SCHED;
.LBB0_1695:
	v_add_u32_e32 v188, s54, v199
	ds_read_b128 v[132:135], v201
	ds_read_b128 v[136:139], v201 offset:1024
	ds_read_b128 v[140:143], v201 offset:2048
	ds_read_b128 v[144:147], v201 offset:3072
	ds_read_b128 v[148:151], v188
	ds_read_b128 v[180:183], v188 offset:1024
	ds_read_b128 v[184:187], v188 offset:2048
	ds_read_b128 v[188:191], v188 offset:3072
	s_cmp_eq_u32 s48, s12
	v_lshl_add_u64 v[192:193], v[130:131], 0, s[22:23]
	s_cselect_b64 vcc, -1, 0
	s_add_i32 s12, s12, 2
	v_cndmask_b32_e32 v197, v193, v177, vcc
	v_cndmask_b32_e32 v196, v192, v176, vcc
	v_cndmask_b32_e32 v213, v129, v179, vcc
	v_cndmask_b32_e32 v212, v128, v178, vcc
	s_mov_b32 m0, s55
	v_lshl_add_u64 v[214:215], v[130:131], 0, v[172:173]
	ds_read_b128 v[192:195], v202
	ds_read_b128 v[204:207], v202 offset:1024
	ds_read_b128 v[208:211], v202 offset:2048
	ds_read_b128 v[216:219], v202 offset:3072
	ds_read_b128 v[220:223], v202 offset:4096
	ds_read_b128 v[224:227], v202 offset:5120
	ds_read_b128 v[228:231], v202 offset:6144
	ds_read_b128 v[232:235], v202 offset:7168
	global_load_lds_dwordx4 v[214:215], off
	s_mov_b32 m0, s56
	v_lshl_add_u64 v[214:215], v[130:131], 0, v[170:171]
	global_load_lds_dwordx4 v[214:215], off
	s_waitcnt vmcnt(8) lgkmcnt(0)
	s_setprio 1
	s_barrier
	v_mfma_f32_16x16x32_bf16 v[120:123], v[132:135], v[192:195], v[120:123]
	v_mfma_f32_16x16x32_bf16 v[124:127], v[140:143], v[192:195], v[124:127]
	v_mfma_f32_16x16x32_bf16 v[108:111], v[132:135], v[208:211], v[108:111]
	v_mfma_f32_16x16x32_bf16 v[104:107], v[140:143], v[208:211], v[104:107]
	v_mfma_f32_16x16x32_bf16 v[92:95], v[132:135], v[220:223], v[92:95]
	v_mfma_f32_16x16x32_bf16 v[88:91], v[140:143], v[220:223], v[88:91]
	v_mfma_f32_16x16x32_bf16 v[76:79], v[132:135], v[228:231], v[76:79]
	v_mfma_f32_16x16x32_bf16 v[72:75], v[140:143], v[228:231], v[72:75]
	v_mfma_f32_16x16x32_bf16 v[120:123], v[136:139], v[204:207], v[120:123]
	v_mfma_f32_16x16x32_bf16 v[124:127], v[144:147], v[204:207], v[124:127]
	v_mfma_f32_16x16x32_bf16 v[108:111], v[136:139], v[216:219], v[108:111]
	v_mfma_f32_16x16x32_bf16 v[104:107], v[144:147], v[216:219], v[104:107]
	v_mfma_f32_16x16x32_bf16 v[92:95], v[136:139], v[224:227], v[92:95]
	v_mfma_f32_16x16x32_bf16 v[88:91], v[144:147], v[224:227], v[88:91]
	v_mfma_f32_16x16x32_bf16 v[76:79], v[136:139], v[232:235], v[76:79]
	v_mfma_f32_16x16x32_bf16 v[72:75], v[144:147], v[232:235], v[72:75]
	v_mfma_f32_16x16x32_bf16 v[116:119], v[148:151], v[192:195], v[116:119]
	v_mfma_f32_16x16x32_bf16 v[112:115], v[184:187], v[192:195], v[112:115]
	v_mfma_f32_16x16x32_bf16 v[100:103], v[148:151], v[208:211], v[100:103]
	v_mfma_f32_16x16x32_bf16 v[96:99], v[184:187], v[208:211], v[96:99]
	v_mfma_f32_16x16x32_bf16 v[84:87], v[148:151], v[220:223], v[84:87]
	v_mfma_f32_16x16x32_bf16 v[80:83], v[184:187], v[220:223], v[80:83]
	v_mfma_f32_16x16x32_bf16 v[68:71], v[148:151], v[228:231], v[68:71]
	v_mfma_f32_16x16x32_bf16 v[64:67], v[184:187], v[228:231], v[64:67]
	v_mfma_f32_16x16x32_bf16 v[116:119], v[180:183], v[204:207], v[116:119]
	v_mfma_f32_16x16x32_bf16 v[112:115], v[188:191], v[204:207], v[112:115]
	v_mfma_f32_16x16x32_bf16 v[100:103], v[180:183], v[216:219], v[100:103]
	v_mfma_f32_16x16x32_bf16 v[96:99], v[188:191], v[216:219], v[96:99]
	v_mfma_f32_16x16x32_bf16 v[84:87], v[180:183], v[224:227], v[84:87]
	v_mfma_f32_16x16x32_bf16 v[80:83], v[188:191], v[224:227], v[80:83]
	v_mfma_f32_16x16x32_bf16 v[68:71], v[180:183], v[232:235], v[68:71]
	v_mfma_f32_16x16x32_bf16 v[64:67], v[188:191], v[232:235], v[64:67]
	s_setprio 0
	s_barrier
	s_mov_b32 m0, s57
	v_lshl_add_u64 v[214:215], v[212:213], 0, v[164:165]
	ds_read_b128 v[192:195], v202 offset:16384
	ds_read_b128 v[204:207], v202 offset:17408
	ds_read_b128 v[208:211], v202 offset:18432
	ds_read_b128 v[216:219], v202 offset:19456
	ds_read_b128 v[220:223], v202 offset:20480
	ds_read_b128 v[224:227], v202 offset:21504
	ds_read_b128 v[228:231], v202 offset:22528
	ds_read_b128 v[232:235], v202 offset:23552
	global_load_lds_dwordx4 v[214:215], off
	v_lshl_add_u64 v[236:237], v[212:213], 0, v[168:169]
	s_mov_b32 m0, s58
	v_lshl_add_u64 v[212:213], v[212:213], 0, s[14:15]
	s_add_i32 s13, s54, s30
	global_load_lds_dwordx4 v[236:237], off
	v_lshl_add_u64 v[238:239], v[212:213], 0, v[164:165]
	s_mov_b32 m0, s13
	v_lshl_add_u64 v[212:213], v[212:213], 0, v[168:169]
	global_load_lds_dwordx4 v[238:239], off
	s_add_i32 m0, s13, 0x2000
	v_lshl_add_u64 v[240:241], v[196:197], 0, v[162:163]
	global_load_lds_dwordx4 v[212:213], off
	s_mov_b32 m0, s31
	v_lshl_add_u64 v[242:243], v[196:197], 0, v[166:167]
	global_load_lds_dwordx4 v[240:241], off
	s_nop 0
	s_waitcnt vmcnt(7) lgkmcnt(0)
	s_setprio 1
	s_barrier
; #define PG8_STAGE(bufoff, gbase, voff) do { _Pragma("unroll") for (int _i = 0; _i < 2; ++_i) \
;         __builtin_amdgcn_global_load_lds((const unsigned*)((const char*)(gbase) + (voff)[_i]), (PG8_LAS unsigned*)(lds + (bufoff) + ldsw + _i * 8192), 16, 0, 0); } while (0)
; #define PG8_LDA(dst, b, h) do { _Pragma("unroll") for (int m = 0; m < 4; ++m) _Pragma("unroll") for (int k = 0; k < 2; ++k) dst[m][k] = *(const PG8_LAS bf16x8*)(lds + PG8_SA(b, h) + aoff + m * 2048 + k * 1024); } while (0)
; #define PG8_LDB(dst, b, h) do { _Pragma("unroll") for (int n = 0; n < 2; ++n) _Pragma("unroll") for (int k = 0; k < 2; ++k) dst[n][k] = *(const PG8_LAS bf16x8*)(lds + PG8_SB(b, h) + boff + n * 2048 + k * 1024); } while (0)
; #define PG8_MMA(ai, bj, At, Bt) do { __builtin_amdgcn_s_setprio(1); _Pragma("unroll") for (int m = 0; m < 4; ++m) _Pragma("unroll") for (int n = 0; n < 2; ++n) _Pragma("unroll") for (int k = 0; k < 2; ++k) \
;         acc[ai][bj][m][n] = __builtin_amdgcn_mfma_f32_16x16x32_bf16(Bt[n][k], At[m][k], acc[ai][bj][m][n], 0, 0, 0); __builtin_amdgcn_s_setprio(0); } while (0)
; #define PG8_WAIT_V(n) asm volatile("s_waitcnt vmcnt(" #n ")" ::: "memory")
; #define PG8_WAIT_L(n) asm volatile("s_waitcnt lgkmcnt(" #n ")" ::: "memory")
; #define PG8_BAR __builtin_amdgcn_s_barrier()
; #define PG8_SCHED __builtin_amdgcn_sched_barrier(0)
; template <class Epi, class Sched, bool ALIGN_EPI = false, bool SP2 = false>
; __device__ __forceinline__ void gemm_phase(PG8_LAS unsigned char* lds, const Gemm g, const Sched& S, const Epi& E) {
;     ...
;             PG8_WAIT_V(8); PG8_WAIT_L(0); PG8_BAR; PG8_MMA(1, 0, At, B0); PG8_MMA(1, 1, At, B1); PG8_BAR; PG8_SCHED;
;             PG8_LDB(B0, 1, 0); PG8_LDB(B1, 1, 1); PG8_SCHED; PG8_LDA(At, 1, 0); PG8_STAGE(PG8_SA(0, 1), a2 + hstep, voffA);
;             PG8_WAIT_V(8); PG8_WAIT_L(0); PG8_BAR; PG8_MMA(0, 0, At, B0); PG8_MMA(0, 1, At, B1); PG8_BAR; PG8_SCHED;
	v_mfma_f32_16x16x32_bf16 v[60:63], v[132:135], v[192:195], v[60:63]
	v_mfma_f32_16x16x32_bf16 v[56:59], v[140:143], v[192:195], v[56:59]
	v_mfma_f32_16x16x32_bf16 v[44:47], v[132:135], v[208:211], v[44:47]
	v_mfma_f32_16x16x32_bf16 v[40:43], v[140:143], v[208:211], v[40:43]
	v_mfma_f32_16x16x32_bf16 v[28:31], v[132:135], v[220:223], v[28:31]
	v_mfma_f32_16x16x32_bf16 v[24:27], v[140:143], v[220:223], v[24:27]
	v_mfma_f32_16x16x32_bf16 v[12:15], v[132:135], v[228:231], v[12:15]
	v_mfma_f32_16x16x32_bf16 v[8:11], v[140:143], v[228:231], v[8:11]
	v_mfma_f32_16x16x32_bf16 v[60:63], v[136:139], v[204:207], v[60:63]
	v_mfma_f32_16x16x32_bf16 v[56:59], v[144:147], v[204:207], v[56:59]
	v_mfma_f32_16x16x32_bf16 v[44:47], v[136:139], v[216:219], v[44:47]
	v_mfma_f32_16x16x32_bf16 v[40:43], v[144:147], v[216:219], v[40:43]
	v_mfma_f32_16x16x32_bf16 v[28:31], v[136:139], v[224:227], v[28:31]
	v_mfma_f32_16x16x32_bf16 v[24:27], v[144:147], v[224:227], v[24:27]
	v_mfma_f32_16x16x32_bf16 v[12:15], v[136:139], v[232:235], v[12:15]
	v_mfma_f32_16x16x32_bf16 v[8:11], v[144:147], v[232:235], v[8:11]
	v_mfma_f32_16x16x32_bf16 v[52:55], v[148:151], v[192:195], v[52:55]
	v_mfma_f32_16x16x32_bf16 v[48:51], v[184:187], v[192:195], v[48:51]
	v_mfma_f32_16x16x32_bf16 v[36:39], v[148:151], v[208:211], v[36:39]
	v_mfma_f32_16x16x32_bf16 v[32:35], v[184:187], v[208:211], v[32:35]
	v_mfma_f32_16x16x32_bf16 v[20:23], v[148:151], v[220:223], v[20:23]
	v_mfma_f32_16x16x32_bf16 v[16:19], v[184:187], v[220:223], v[16:19]
	v_mfma_f32_16x16x32_bf16 v[4:7], v[148:151], v[228:231], v[4:7]
	v_mfma_f32_16x16x32_bf16 v[0:3], v[184:187], v[228:231], v[0:3]
	v_mfma_f32_16x16x32_bf16 v[52:55], v[180:183], v[204:207], v[52:55]
	v_mfma_f32_16x16x32_bf16 v[48:51], v[188:191], v[204:207], v[48:51]
	v_mfma_f32_16x16x32_bf16 v[36:39], v[180:183], v[216:219], v[36:39]
	v_mfma_f32_16x16x32_bf16 v[32:35], v[188:191], v[216:219], v[32:35]
	v_mfma_f32_16x16x32_bf16 v[20:23], v[180:183], v[224:227], v[20:23]
	v_mfma_f32_16x16x32_bf16 v[16:19], v[188:191], v[224:227], v[16:19]
	v_mfma_f32_16x16x32_bf16 v[4:7], v[180:183], v[232:235], v[4:7]
	v_mfma_f32_16x16x32_bf16 v[0:3], v[188:191], v[232:235], v[0:3]
	s_setprio 0
	s_barrier
	s_add_i32 s13, 0, 0x18000
	s_add_i32 s29, 0, 0x1c000
	v_add_u32_e32 v144, s13, v199
	v_add_u32_e32 v188, s29, v199
	s_mov_b32 m0, s34
	ds_read_b128 v[132:135], v144
	global_load_lds_dwordx4 v[242:243], off
	ds_read_b128 v[136:139], v144 offset:1024
	ds_read_b128 v[140:143], v144 offset:2048
	ds_read_b128 v[144:147], v144 offset:3072
	ds_read_b128 v[148:151], v188
	ds_read_b128 v[180:183], v188 offset:1024
	ds_read_b128 v[184:187], v188 offset:2048
	ds_read_b128 v[188:191], v188 offset:3072
	v_lshl_add_u64 v[196:197], v[196:197], 0, s[14:15]
	s_mov_b32 m0, s35
	v_lshl_add_u64 v[244:245], v[196:197], 0, v[162:163]
	ds_read_b128 v[192:195], v202 offset:32768
	ds_read_b128 v[204:207], v202 offset:33792
	ds_read_b128 v[208:211], v202 offset:34816
	ds_read_b128 v[216:219], v202 offset:35840
	ds_read_b128 v[220:223], v202 offset:36864
	ds_read_b128 v[224:227], v202 offset:37888
	ds_read_b128 v[228:231], v202 offset:38912
	ds_read_b128 v[232:235], v202 offset:39936
	global_load_lds_dwordx4 v[244:245], off
	s_mov_b32 m0, s36
	v_lshl_add_u64 v[196:197], v[196:197], 0, v[166:167]
	global_load_lds_dwordx4 v[196:197], off
	s_waitcnt vmcnt(8) lgkmcnt(0)
	s_setprio 1
	s_barrier
	v_mfma_f32_16x16x32_bf16 v[120:123], v[132:135], v[192:195], v[120:123]
	v_mfma_f32_16x16x32_bf16 v[124:127], v[140:143], v[192:195], v[124:127]
	v_mfma_f32_16x16x32_bf16 v[108:111], v[132:135], v[208:211], v[108:111]
	v_mfma_f32_16x16x32_bf16 v[104:107], v[140:143], v[208:211], v[104:107]
	v_mfma_f32_16x16x32_bf16 v[92:95], v[132:135], v[220:223], v[92:95]
	v_mfma_f32_16x16x32_bf16 v[88:91], v[140:143], v[220:223], v[88:91]
	v_mfma_f32_16x16x32_bf16 v[76:79], v[132:135], v[228:231], v[76:79]
	v_mfma_f32_16x16x32_bf16 v[72:75], v[140:143], v[228:231], v[72:75]
	v_mfma_f32_16x16x32_bf16 v[120:123], v[136:139], v[204:207], v[120:123]
	v_mfma_f32_16x16x32_bf16 v[124:127], v[144:147], v[204:207], v[124:127]
	v_mfma_f32_16x16x32_bf16 v[108:111], v[136:139], v[216:219], v[108:111]
	v_mfma_f32_16x16x32_bf16 v[104:107], v[144:147], v[216:219], v[104:107]
	v_mfma_f32_16x16x32_bf16 v[92:95], v[136:139], v[224:227], v[92:95]
	v_mfma_f32_16x16x32_bf16 v[88:91], v[144:147], v[224:227], v[88:91]
	v_mfma_f32_16x16x32_bf16 v[76:79], v[136:139], v[232:235], v[76:79]
	v_mfma_f32_16x16x32_bf16 v[72:75], v[144:147], v[232:235], v[72:75]
	v_mfma_f32_16x16x32_bf16 v[116:119], v[148:151], v[192:195], v[116:119]
	v_mfma_f32_16x16x32_bf16 v[112:115], v[184:187], v[192:195], v[112:115]
	v_mfma_f32_16x16x32_bf16 v[100:103], v[148:151], v[208:211], v[100:103]
	v_mfma_f32_16x16x32_bf16 v[96:99], v[184:187], v[208:211], v[96:99]
	v_mfma_f32_16x16x32_bf16 v[84:87], v[148:151], v[220:223], v[84:87]
	v_mfma_f32_16x16x32_bf16 v[80:83], v[184:187], v[220:223], v[80:83]
	v_mfma_f32_16x16x32_bf16 v[68:71], v[148:151], v[228:231], v[68:71]
	v_mfma_f32_16x16x32_bf16 v[64:67], v[184:187], v[228:231], v[64:67]
	v_mfma_f32_16x16x32_bf16 v[116:119], v[180:183], v[204:207], v[116:119]
	v_mfma_f32_16x16x32_bf16 v[112:115], v[188:191], v[204:207], v[112:115]
	v_mfma_f32_16x16x32_bf16 v[100:103], v[180:183], v[216:219], v[100:103]
	v_mfma_f32_16x16x32_bf16 v[96:99], v[188:191], v[216:219], v[96:99]
	v_mfma_f32_16x16x32_bf16 v[84:87], v[180:183], v[224:227], v[84:87]
	v_mfma_f32_16x16x32_bf16 v[80:83], v[188:191], v[224:227], v[80:83]
	v_mfma_f32_16x16x32_bf16 v[68:71], v[180:183], v[232:235], v[68:71]
	v_mfma_f32_16x16x32_bf16 v[64:67], v[188:191], v[232:235], v[64:67]
	s_setprio 0
	s_barrier
; #define PG8_STAGE(bufoff, gbase, voff) do { _Pragma("unroll") for (int _i = 0; _i < 2; ++_i) \
;         __builtin_amdgcn_global_load_lds((const unsigned*)((const char*)(gbase) + (voff)[_i]), (PG8_LAS unsigned*)(lds + (bufoff) + ldsw + _i * 8192), 16, 0, 0); } while (0)
; #define PG8_LDA(dst, b, h) do { _Pragma("unroll") for (int m = 0; m < 4; ++m) _Pragma("unroll") for (int k = 0; k < 2; ++k) dst[m][k] = *(const PG8_LAS bf16x8*)(lds + PG8_SA(b, h) + aoff + m * 2048 + k * 1024); } while (0)
; #define PG8_MMA(ai, bj, At, Bt) do { __builtin_amdgcn_s_setprio(1); _Pragma("unroll") for (int m = 0; m < 4; ++m) _Pragma("unroll") for (int n = 0; n < 2; ++n) _Pragma("unroll") for (int k = 0; k < 2; ++k) \
;         acc[ai][bj][m][n] = __builtin_amdgcn_mfma_f32_16x16x32_bf16(Bt[n][k], At[m][k], acc[ai][bj][m][n], 0, 0, 0); __builtin_amdgcn_s_setprio(0); } while (0)
; #define PG8_WAIT_V(n) asm volatile("s_waitcnt vmcnt(" #n ")" ::: "memory")
; #define PG8_WAIT_L(n) asm volatile("s_waitcnt lgkmcnt(" #n ")" ::: "memory")
; #define PG8_BAR __builtin_amdgcn_s_barrier()
; #define PG8_SCHED __builtin_amdgcn_sched_barrier(0)
; template <class Epi, class Sched, bool ALIGN_EPI = false, bool SP2 = false>
; __device__ __forceinline__ void gemm_phase(PG8_LAS unsigned char* lds, const Gemm g, const Sched& S, const Epi& E) {
;     ...
;             PG8_LDA(At, 1, 1); PG8_STAGE(PG8_SB(1, 0), b3, voffB); PG8_STAGE(PG8_SB(1, 1), b3 + hstep, voffB); PG8_STAGE(PG8_SA(1, 0), a3, voffA);
;             PG8_WAIT_V(8); PG8_WAIT_L(0); PG8_BAR; PG8_MMA(1, 0, At, B0); PG8_MMA(1, 1, At, B1); PG8_BAR; PG8_SCHED;
	s_add_i32 s13, s13, s30
	v_lshl_add_u64 v[196:197], v[214:215], 0, s[22:23]
	s_mov_b32 m0, s13
	ds_read_b128 v[192:195], v202 offset:49152
	ds_read_b128 v[204:207], v202 offset:50176
	ds_read_b128 v[208:211], v202 offset:51200
	ds_read_b128 v[216:219], v202 offset:52224
	ds_read_b128 v[220:223], v202 offset:53248
	ds_read_b128 v[224:227], v202 offset:54272
	ds_read_b128 v[228:231], v202 offset:55296
	ds_read_b128 v[232:235], v202 offset:56320
	global_load_lds_dwordx4 v[196:197], off
	v_lshl_add_u64 v[196:197], v[236:237], 0, s[22:23]
	s_add_i32 m0, s13, 0x2000
	s_add_i32 s13, s29, s30
	global_load_lds_dwordx4 v[196:197], off
	s_mov_b32 m0, s13
	v_lshl_add_u64 v[196:197], v[238:239], 0, s[22:23]
	global_load_lds_dwordx4 v[196:197], off
	s_add_i32 m0, s13, 0x2000
	v_lshl_add_u64 v[196:197], v[212:213], 0, s[22:23]
	global_load_lds_dwordx4 v[196:197], off
	s_mov_b32 m0, s37
	v_lshl_add_u64 v[196:197], v[240:241], 0, s[22:23]
	global_load_lds_dwordx4 v[196:197], off
	s_mov_b32 m0, s41
	v_lshl_add_u64 v[196:197], v[242:243], 0, s[22:23]
	global_load_lds_dwordx4 v[196:197], off
	s_waitcnt vmcnt(8) lgkmcnt(0)
	s_setprio 1
	s_barrier
	v_mfma_f32_16x16x32_bf16 v[60:63], v[132:135], v[192:195], v[60:63]
	v_mfma_f32_16x16x32_bf16 v[56:59], v[140:143], v[192:195], v[56:59]
	v_mfma_f32_16x16x32_bf16 v[44:47], v[132:135], v[208:211], v[44:47]
	v_mfma_f32_16x16x32_bf16 v[40:43], v[140:143], v[208:211], v[40:43]
	v_mfma_f32_16x16x32_bf16 v[28:31], v[132:135], v[220:223], v[28:31]
	v_mfma_f32_16x16x32_bf16 v[24:27], v[140:143], v[220:223], v[24:27]
	v_mfma_f32_16x16x32_bf16 v[12:15], v[132:135], v[228:231], v[12:15]
	v_mfma_f32_16x16x32_bf16 v[8:11], v[140:143], v[228:231], v[8:11]
	v_mfma_f32_16x16x32_bf16 v[60:63], v[136:139], v[204:207], v[60:63]
	v_mfma_f32_16x16x32_bf16 v[56:59], v[144:147], v[204:207], v[56:59]
	v_mfma_f32_16x16x32_bf16 v[44:47], v[136:139], v[216:219], v[44:47]
	v_mfma_f32_16x16x32_bf16 v[40:43], v[144:147], v[216:219], v[40:43]
	v_mfma_f32_16x16x32_bf16 v[28:31], v[136:139], v[224:227], v[28:31]
	v_mfma_f32_16x16x32_bf16 v[24:27], v[144:147], v[224:227], v[24:27]
	v_mfma_f32_16x16x32_bf16 v[12:15], v[136:139], v[232:235], v[12:15]
	v_mfma_f32_16x16x32_bf16 v[8:11], v[144:147], v[232:235], v[8:11]
	v_mfma_f32_16x16x32_bf16 v[52:55], v[148:151], v[192:195], v[52:55]
	v_mfma_f32_16x16x32_bf16 v[48:51], v[184:187], v[192:195], v[48:51]
	v_mfma_f32_16x16x32_bf16 v[36:39], v[148:151], v[208:211], v[36:39]
	v_mfma_f32_16x16x32_bf16 v[32:35], v[184:187], v[208:211], v[32:35]
	v_mfma_f32_16x16x32_bf16 v[20:23], v[148:151], v[220:223], v[20:23]
	v_mfma_f32_16x16x32_bf16 v[16:19], v[184:187], v[220:223], v[16:19]
	v_mfma_f32_16x16x32_bf16 v[4:7], v[148:151], v[228:231], v[4:7]
	v_mfma_f32_16x16x32_bf16 v[0:3], v[184:187], v[228:231], v[0:3]
	v_mfma_f32_16x16x32_bf16 v[52:55], v[180:183], v[204:207], v[52:55]
	v_mfma_f32_16x16x32_bf16 v[48:51], v[188:191], v[204:207], v[48:51]
	v_mfma_f32_16x16x32_bf16 v[36:39], v[180:183], v[216:219], v[36:39]
	v_mfma_f32_16x16x32_bf16 v[32:35], v[188:191], v[216:219], v[32:35]
	v_mfma_f32_16x16x32_bf16 v[20:23], v[180:183], v[224:227], v[20:23]
	v_mfma_f32_16x16x32_bf16 v[16:19], v[188:191], v[224:227], v[16:19]
	v_mfma_f32_16x16x32_bf16 v[4:7], v[180:183], v[232:235], v[4:7]
	v_mfma_f32_16x16x32_bf16 v[0:3], v[188:191], v[232:235], v[0:3]
	s_setprio 0
	s_barrier
	v_lshl_add_u64 v[128:129], v[128:129], 0, s[26:27]
	s_cmp_ge_i32 s12, s47
	v_lshl_add_u64 v[130:131], v[130:131], 0, s[26:27]
	s_cbranch_scc0 .LBB0_1695

; #define PG8_STAGE(bufoff, gbase, voff) do { _Pragma("unroll") for (int _i = 0; _i < 2; ++_i) \
;         __builtin_amdgcn_global_load_lds((const unsigned*)((const char*)(gbase) + (voff)[_i]), (PG8_LAS unsigned*)(lds + (bufoff) + ldsw + _i * 8192), 16, 0, 0); } while (0)
; #define PG8_LDA(dst, b, h) do { _Pragma("unroll") for (int m = 0; m < 4; ++m) _Pragma("unroll") for (int k = 0; k < 2; ++k) dst[m][k] = *(const PG8_LAS bf16x8*)(lds + PG8_SA(b, h) + aoff + m * 2048 + k * 1024); } while (0)
; #define PG8_LDB(dst, b, h) do { _Pragma("unroll") for (int n = 0; n < 2; ++n) _Pragma("unroll") for (int k = 0; k < 2; ++k) dst[n][k] = *(const PG8_LAS bf16x8*)(lds + PG8_SB(b, h) + boff + n * 2048 + k * 1024); } while (0)
; #define PG8_MMA(ai, bj, At, Bt) do { __builtin_amdgcn_s_setprio(1); _Pragma("unroll") for (int m = 0; m < 4; ++m) _Pragma("unroll") for (int n = 0; n < 2; ++n) _Pragma("unroll") for (int k = 0; k < 2; ++k) \
;         acc[ai][bj][m][n] = __builtin_amdgcn_mfma_f32_16x16x32_bf16(Bt[n][k], At[m][k], acc[ai][bj][m][n], 0, 0, 0); __builtin_amdgcn_s_setprio(0); } while (0)
; #define PG8_WAIT_V(n) asm volatile("s_waitcnt vmcnt(" #n ")" ::: "memory")
; #define PG8_BAR __builtin_amdgcn_s_barrier()
; template <class Epi, class Sched, bool ALIGN_EPI = false, bool SP2 = false>
; __device__ __forceinline__ void gemm_phase(PG8_LAS unsigned char* lds, const Gemm g, const Sched& S, const Epi& E) {
;     ...
;         for (int t = 0; t < nt; t += 2) {
;             const bool last = (t == nt - 2);
;             const char* a1 = cA + (size_t)(t + 1) * kstep;
;             const char* a2 = last ? nA : cA + (size_t)(t + 2) * kstep; const char* b2 = last ? nB : cB + (size_t)(t + 2) * kstep;
;             const char* a3 = a2 + kstep; const char* b3 = b2 + kstep;
;             if (last && has_next) S.a_ready(nxt);
;             if constexpr (SP2) {
;             PG8_LDB(B0, 0, 0); PG8_LDB(B1, 0, 1); PG8_SCHED; PG8_LDA(At, 0, 0); PG8_STAGE(PG8_SA(1, 1), a1 + hstep, voffA);
;             PG8_WAIT_V(8); PG8_WAIT_L(0); PG8_BAR; PG8_MMA(0, 0, At, B0); PG8_MMA(0, 1, At, B1); PG8_BAR; PG8_SCHED;
;             PG8_LDA(At, 0, 1); PG8_STAGE(PG8_SB(0, 0), b2, voffB); PG8_STAGE(PG8_SB(0, 1), b2 + hstep, voffB); PG8_STAGE(PG8_SA(0, 0), a2, voffA);
;             PG8_WAIT_V(8); PG8_WAIT_L(0); PG8_BAR; PG8_MMA(1, 0, At, B0); PG8_MMA(1, 1, At, B1); PG8_BAR; PG8_SCHED;
.LBB0_1776:
	v_add_u32_e32 v166, s54, v169
	v_add_u32_e32 v168, s55, v169
	ds_read_b128 v[162:165], v166
	ds_read_b128 v[182:185], v166 offset:1024
	ds_read_b128 v[186:189], v166 offset:2048
	ds_read_b128 v[190:193], v166 offset:3072
	ds_read_b128 v[194:197], v168
	ds_read_b128 v[198:201], v168 offset:1024
	ds_read_b128 v[202:205], v168 offset:2048
	ds_read_b128 v[206:209], v168 offset:3072
	s_cmp_eq_u32 s53, s10
	v_lshl_add_u64 v[172:173], v[160:161], 0, s[22:23]
	s_cselect_b64 vcc, -1, 0
	s_add_i32 s10, s10, 2
	v_cndmask_b32_e32 v173, v173, v153, vcc
	v_cndmask_b32_e32 v172, v172, v152, vcc
	v_cndmask_b32_e32 v215, v159, v155, vcc
	v_cndmask_b32_e32 v214, v158, v154, vcc
	s_mov_b32 m0, s56
	v_lshl_add_u64 v[244:245], v[160:161], 0, v[148:149]
	ds_read_b128 v[210:213], v179
	ds_read_b128 v[216:219], v179 offset:1024
	ds_read_b128 v[220:223], v179 offset:2048
	ds_read_b128 v[224:227], v179 offset:3072
	ds_read_b128 v[228:231], v179 offset:4096
	ds_read_b128 v[232:235], v179 offset:5120
	ds_read_b128 v[236:239], v179 offset:6144
	ds_read_b128 v[240:243], v179 offset:7168
	global_load_lds_dwordx4 v[244:245], off
	s_mov_b32 m0, s57
	v_lshl_add_u64 v[244:245], v[160:161], 0, v[146:147]
	global_load_lds_dwordx4 v[244:245], off
	s_waitcnt vmcnt(8) lgkmcnt(0)
	s_setprio 1
	s_barrier
	v_mfma_f32_16x16x32_bf16 v[124:127], v[162:165], v[210:213], v[124:127]
	v_mfma_f32_16x16x32_bf16 v[116:119], v[186:189], v[210:213], v[116:119]
	v_mfma_f32_16x16x32_bf16 v[108:111], v[162:165], v[220:223], v[108:111]
	v_mfma_f32_16x16x32_bf16 v[100:103], v[186:189], v[220:223], v[100:103]
	v_mfma_f32_16x16x32_bf16 v[92:95], v[162:165], v[228:231], v[92:95]
	v_mfma_f32_16x16x32_bf16 v[84:87], v[186:189], v[228:231], v[84:87]
	v_mfma_f32_16x16x32_bf16 v[76:79], v[162:165], v[236:239], v[76:79]
	v_mfma_f32_16x16x32_bf16 v[68:71], v[186:189], v[236:239], v[68:71]
	v_mfma_f32_16x16x32_bf16 v[124:127], v[182:185], v[216:219], v[124:127]
	v_mfma_f32_16x16x32_bf16 v[116:119], v[190:193], v[216:219], v[116:119]
	v_mfma_f32_16x16x32_bf16 v[108:111], v[182:185], v[224:227], v[108:111]
	v_mfma_f32_16x16x32_bf16 v[100:103], v[190:193], v[224:227], v[100:103]
	v_mfma_f32_16x16x32_bf16 v[92:95], v[182:185], v[232:235], v[92:95]
	v_mfma_f32_16x16x32_bf16 v[84:87], v[190:193], v[232:235], v[84:87]
	v_mfma_f32_16x16x32_bf16 v[76:79], v[182:185], v[240:243], v[76:79]
	v_mfma_f32_16x16x32_bf16 v[68:71], v[190:193], v[240:243], v[68:71]
	v_mfma_f32_16x16x32_bf16 v[120:123], v[194:197], v[210:213], v[120:123]
	v_mfma_f32_16x16x32_bf16 v[112:115], v[202:205], v[210:213], v[112:115]
	v_mfma_f32_16x16x32_bf16 v[104:107], v[194:197], v[220:223], v[104:107]
	v_mfma_f32_16x16x32_bf16 v[96:99], v[202:205], v[220:223], v[96:99]
	v_mfma_f32_16x16x32_bf16 v[88:91], v[194:197], v[228:231], v[88:91]
	v_mfma_f32_16x16x32_bf16 v[80:83], v[202:205], v[228:231], v[80:83]
	v_mfma_f32_16x16x32_bf16 v[72:75], v[194:197], v[236:239], v[72:75]
	v_mfma_f32_16x16x32_bf16 v[64:67], v[202:205], v[236:239], v[64:67]
	v_mfma_f32_16x16x32_bf16 v[120:123], v[198:201], v[216:219], v[120:123]
	v_mfma_f32_16x16x32_bf16 v[112:115], v[206:209], v[216:219], v[112:115]
	v_mfma_f32_16x16x32_bf16 v[104:107], v[198:201], v[224:227], v[104:107]
	v_mfma_f32_16x16x32_bf16 v[96:99], v[206:209], v[224:227], v[96:99]
	v_mfma_f32_16x16x32_bf16 v[88:91], v[198:201], v[232:235], v[88:91]
	v_mfma_f32_16x16x32_bf16 v[80:83], v[206:209], v[232:235], v[80:83]
	v_mfma_f32_16x16x32_bf16 v[72:75], v[198:201], v[240:243], v[72:75]
	v_mfma_f32_16x16x32_bf16 v[64:67], v[206:209], v[240:243], v[64:67]
	s_setprio 0
	s_barrier
	s_mov_b32 m0, s60
	v_lshl_add_u64 v[244:245], v[214:215], 0, v[138:139]
	ds_read_b128 v[210:213], v179 offset:16384
	ds_read_b128 v[216:219], v179 offset:17408
	ds_read_b128 v[220:223], v179 offset:18432
	ds_read_b128 v[224:227], v179 offset:19456
	ds_read_b128 v[228:231], v179 offset:20480
	ds_read_b128 v[232:235], v179 offset:21504
	ds_read_b128 v[236:239], v179 offset:22528
	ds_read_b128 v[240:243], v179 offset:23552
	global_load_lds_dwordx4 v[244:245], off
	v_lshl_add_u64 v[246:247], v[214:215], 0, v[134:135]
	s_mov_b32 m0, s61
	v_lshl_add_u64 v[214:215], v[214:215], 0, s[14:15]
	global_load_lds_dwordx4 v[246:247], off
	v_lshl_add_u64 v[248:249], v[214:215], 0, v[138:139]
	s_mov_b32 m0, s62
	v_lshl_add_u64 v[214:215], v[214:215], 0, v[134:135]
	global_load_lds_dwordx4 v[248:249], off
	s_add_i32 m0, s62, 0x2000
	v_lshl_add_u64 v[250:251], v[172:173], 0, v[140:141]
	global_load_lds_dwordx4 v[214:215], off
	s_mov_b32 m0, s46
	v_lshl_add_u64 v[252:253], v[172:173], 0, v[136:137]
	global_load_lds_dwordx4 v[250:251], off
	s_nop 0
	s_waitcnt vmcnt(7) lgkmcnt(0)
	s_setprio 1
	s_barrier
; #define PG8_STAGE(bufoff, gbase, voff) do { _Pragma("unroll") for (int _i = 0; _i < 2; ++_i) \
;         __builtin_amdgcn_global_load_lds((const unsigned*)((const char*)(gbase) + (voff)[_i]), (PG8_LAS unsigned*)(lds + (bufoff) + ldsw + _i * 8192), 16, 0, 0); } while (0)
; #define PG8_LDA(dst, b, h) do { _Pragma("unroll") for (int m = 0; m < 4; ++m) _Pragma("unroll") for (int k = 0; k < 2; ++k) dst[m][k] = *(const PG8_LAS bf16x8*)(lds + PG8_SA(b, h) + aoff + m * 2048 + k * 1024); } while (0)
; #define PG8_LDB(dst, b, h) do { _Pragma("unroll") for (int n = 0; n < 2; ++n) _Pragma("unroll") for (int k = 0; k < 2; ++k) dst[n][k] = *(const PG8_LAS bf16x8*)(lds + PG8_SB(b, h) + boff + n * 2048 + k * 1024); } while (0)
; #define PG8_MMA(ai, bj, At, Bt) do { __builtin_amdgcn_s_setprio(1); _Pragma("unroll") for (int m = 0; m < 4; ++m) _Pragma("unroll") for (int n = 0; n < 2; ++n) _Pragma("unroll") for (int k = 0; k < 2; ++k) \
;         acc[ai][bj][m][n] = __builtin_amdgcn_mfma_f32_16x16x32_bf16(Bt[n][k], At[m][k], acc[ai][bj][m][n], 0, 0, 0); __builtin_amdgcn_s_setprio(0); } while (0)
; #define PG8_WAIT_V(n) asm volatile("s_waitcnt vmcnt(" #n ")" ::: "memory")
; #define PG8_WAIT_L(n) asm volatile("s_waitcnt lgkmcnt(" #n ")" ::: "memory")
; #define PG8_BAR __builtin_amdgcn_s_barrier()
; #define PG8_SCHED __builtin_amdgcn_sched_barrier(0)
; template <class Epi, class Sched, bool ALIGN_EPI = false, bool SP2 = false>
; __device__ __forceinline__ void gemm_phase(PG8_LAS unsigned char* lds, const Gemm g, const Sched& S, const Epi& E) {
;     ...
;             PG8_WAIT_V(8); PG8_WAIT_L(0); PG8_BAR; PG8_MMA(1, 0, At, B0); PG8_MMA(1, 1, At, B1); PG8_BAR; PG8_SCHED;
;             PG8_LDB(B0, 1, 0); PG8_LDB(B1, 1, 1); PG8_SCHED; PG8_LDA(At, 1, 0); PG8_STAGE(PG8_SA(0, 1), a2 + hstep, voffA);
;             PG8_WAIT_V(8); PG8_WAIT_L(0); PG8_BAR; PG8_MMA(0, 0, At, B0); PG8_MMA(0, 1, At, B1); PG8_BAR; PG8_SCHED;
	v_mfma_f32_16x16x32_bf16 v[60:63], v[162:165], v[210:213], v[60:63]
	v_mfma_f32_16x16x32_bf16 v[52:55], v[186:189], v[210:213], v[52:55]
	v_mfma_f32_16x16x32_bf16 v[44:47], v[162:165], v[220:223], v[44:47]
	v_mfma_f32_16x16x32_bf16 v[36:39], v[186:189], v[220:223], v[36:39]
	v_mfma_f32_16x16x32_bf16 v[28:31], v[162:165], v[228:231], v[28:31]
	v_mfma_f32_16x16x32_bf16 v[20:23], v[186:189], v[228:231], v[20:23]
	v_mfma_f32_16x16x32_bf16 v[12:15], v[162:165], v[236:239], v[12:15]
	v_mfma_f32_16x16x32_bf16 v[4:7], v[186:189], v[236:239], v[4:7]
	v_mfma_f32_16x16x32_bf16 v[60:63], v[182:185], v[216:219], v[60:63]
	v_mfma_f32_16x16x32_bf16 v[52:55], v[190:193], v[216:219], v[52:55]
	v_mfma_f32_16x16x32_bf16 v[44:47], v[182:185], v[224:227], v[44:47]
	v_mfma_f32_16x16x32_bf16 v[36:39], v[190:193], v[224:227], v[36:39]
	v_mfma_f32_16x16x32_bf16 v[28:31], v[182:185], v[232:235], v[28:31]
	v_mfma_f32_16x16x32_bf16 v[20:23], v[190:193], v[232:235], v[20:23]
	v_mfma_f32_16x16x32_bf16 v[12:15], v[182:185], v[240:243], v[12:15]
	v_mfma_f32_16x16x32_bf16 v[4:7], v[190:193], v[240:243], v[4:7]
	v_mfma_f32_16x16x32_bf16 v[56:59], v[194:197], v[210:213], v[56:59]
	v_mfma_f32_16x16x32_bf16 v[48:51], v[202:205], v[210:213], v[48:51]
	v_mfma_f32_16x16x32_bf16 v[40:43], v[194:197], v[220:223], v[40:43]
	v_mfma_f32_16x16x32_bf16 v[32:35], v[202:205], v[220:223], v[32:35]
	v_mfma_f32_16x16x32_bf16 v[24:27], v[194:197], v[228:231], v[24:27]
	v_mfma_f32_16x16x32_bf16 v[16:19], v[202:205], v[228:231], v[16:19]
	v_mfma_f32_16x16x32_bf16 v[8:11], v[194:197], v[236:239], v[8:11]
	v_mfma_f32_16x16x32_bf16 v[0:3], v[202:205], v[236:239], v[0:3]
	v_mfma_f32_16x16x32_bf16 v[56:59], v[198:201], v[216:219], v[56:59]
	v_mfma_f32_16x16x32_bf16 v[48:51], v[206:209], v[216:219], v[48:51]
	v_mfma_f32_16x16x32_bf16 v[40:43], v[198:201], v[224:227], v[40:43]
	v_mfma_f32_16x16x32_bf16 v[32:35], v[206:209], v[224:227], v[32:35]
	v_mfma_f32_16x16x32_bf16 v[24:27], v[198:201], v[232:235], v[24:27]
	v_mfma_f32_16x16x32_bf16 v[16:19], v[206:209], v[232:235], v[16:19]
	v_mfma_f32_16x16x32_bf16 v[8:11], v[198:201], v[240:243], v[8:11]
	v_mfma_f32_16x16x32_bf16 v[0:3], v[206:209], v[240:243], v[0:3]
	s_setprio 0
	s_barrier
	s_add_i32 s11, 0, 0x18000
	v_add_u32_e32 v166, s11, v169
	s_add_i32 s13, 0, 0x1c000
	s_mov_b32 m0, s47
	ds_read_b128 v[162:165], v166
	global_load_lds_dwordx4 v[252:253], off
	ds_read_b128 v[182:185], v166 offset:1024
	ds_read_b128 v[186:189], v166 offset:2048
	ds_read_b128 v[190:193], v166 offset:3072
	v_add_u32_e32 v166, s13, v169
	ds_read_b128 v[194:197], v166
	ds_read_b128 v[198:201], v166 offset:1024
	ds_read_b128 v[202:205], v166 offset:2048
	ds_read_b128 v[206:209], v166 offset:3072
	v_lshl_add_u64 v[172:173], v[172:173], 0, s[14:15]
	s_mov_b32 m0, s48
	v_lshl_add_u64 v[170:171], v[172:173], 0, v[140:141]
	ds_read_b128 v[210:213], v179 offset:32768
	ds_read_b128 v[216:219], v179 offset:33792
	ds_read_b128 v[220:223], v179 offset:34816
	ds_read_b128 v[224:227], v179 offset:35840
	ds_read_b128 v[228:231], v179 offset:36864
	ds_read_b128 v[232:235], v179 offset:37888
	ds_read_b128 v[236:239], v179 offset:38912
	ds_read_b128 v[240:243], v179 offset:39936
	global_load_lds_dwordx4 v[170:171], off
	s_mov_b32 m0, s49
	v_lshl_add_u64 v[170:171], v[172:173], 0, v[136:137]
	global_load_lds_dwordx4 v[170:171], off
	s_waitcnt vmcnt(8) lgkmcnt(0)
	s_setprio 1
	s_barrier
	v_mfma_f32_16x16x32_bf16 v[124:127], v[162:165], v[210:213], v[124:127]
	v_mfma_f32_16x16x32_bf16 v[116:119], v[186:189], v[210:213], v[116:119]
	v_mfma_f32_16x16x32_bf16 v[108:111], v[162:165], v[220:223], v[108:111]
	v_mfma_f32_16x16x32_bf16 v[100:103], v[186:189], v[220:223], v[100:103]
	v_mfma_f32_16x16x32_bf16 v[92:95], v[162:165], v[228:231], v[92:95]
	v_mfma_f32_16x16x32_bf16 v[84:87], v[186:189], v[228:231], v[84:87]
	v_mfma_f32_16x16x32_bf16 v[76:79], v[162:165], v[236:239], v[76:79]
	v_mfma_f32_16x16x32_bf16 v[68:71], v[186:189], v[236:239], v[68:71]
	v_mfma_f32_16x16x32_bf16 v[124:127], v[182:185], v[216:219], v[124:127]
	v_mfma_f32_16x16x32_bf16 v[116:119], v[190:193], v[216:219], v[116:119]
	v_mfma_f32_16x16x32_bf16 v[108:111], v[182:185], v[224:227], v[108:111]
	v_mfma_f32_16x16x32_bf16 v[100:103], v[190:193], v[224:227], v[100:103]
	v_mfma_f32_16x16x32_bf16 v[92:95], v[182:185], v[232:235], v[92:95]
	v_mfma_f32_16x16x32_bf16 v[84:87], v[190:193], v[232:235], v[84:87]
	v_mfma_f32_16x16x32_bf16 v[76:79], v[182:185], v[240:243], v[76:79]
	v_mfma_f32_16x16x32_bf16 v[68:71], v[190:193], v[240:243], v[68:71]
	v_mfma_f32_16x16x32_bf16 v[120:123], v[194:197], v[210:213], v[120:123]
	v_mfma_f32_16x16x32_bf16 v[112:115], v[202:205], v[210:213], v[112:115]
	v_mfma_f32_16x16x32_bf16 v[104:107], v[194:197], v[220:223], v[104:107]
	v_mfma_f32_16x16x32_bf16 v[96:99], v[202:205], v[220:223], v[96:99]
	v_mfma_f32_16x16x32_bf16 v[88:91], v[194:197], v[228:231], v[88:91]
	v_mfma_f32_16x16x32_bf16 v[80:83], v[202:205], v[228:231], v[80:83]
	v_mfma_f32_16x16x32_bf16 v[72:75], v[194:197], v[236:239], v[72:75]
	v_mfma_f32_16x16x32_bf16 v[64:67], v[202:205], v[236:239], v[64:67]
	v_mfma_f32_16x16x32_bf16 v[120:123], v[198:201], v[216:219], v[120:123]
	v_mfma_f32_16x16x32_bf16 v[112:115], v[206:209], v[216:219], v[112:115]
	v_mfma_f32_16x16x32_bf16 v[104:107], v[198:201], v[224:227], v[104:107]
	v_mfma_f32_16x16x32_bf16 v[96:99], v[206:209], v[224:227], v[96:99]
	v_mfma_f32_16x16x32_bf16 v[88:91], v[198:201], v[232:235], v[88:91]
	v_mfma_f32_16x16x32_bf16 v[80:83], v[206:209], v[232:235], v[80:83]
	v_mfma_f32_16x16x32_bf16 v[72:75], v[198:201], v[240:243], v[72:75]
	v_mfma_f32_16x16x32_bf16 v[64:67], v[206:209], v[240:243], v[64:67]
	s_setprio 0
	s_barrier
; #define PG8_STAGE(bufoff, gbase, voff) do { _Pragma("unroll") for (int _i = 0; _i < 2; ++_i) \
;         __builtin_amdgcn_global_load_lds((const unsigned*)((const char*)(gbase) + (voff)[_i]), (PG8_LAS unsigned*)(lds + (bufoff) + ldsw + _i * 8192), 16, 0, 0); } while (0)
; #define PG8_LDA(dst, b, h) do { _Pragma("unroll") for (int m = 0; m < 4; ++m) _Pragma("unroll") for (int k = 0; k < 2; ++k) dst[m][k] = *(const PG8_LAS bf16x8*)(lds + PG8_SA(b, h) + aoff + m * 2048 + k * 1024); } while (0)
; #define PG8_MMA(ai, bj, At, Bt) do { __builtin_amdgcn_s_setprio(1); _Pragma("unroll") for (int m = 0; m < 4; ++m) _Pragma("unroll") for (int n = 0; n < 2; ++n) _Pragma("unroll") for (int k = 0; k < 2; ++k) \
;         acc[ai][bj][m][n] = __builtin_amdgcn_mfma_f32_16x16x32_bf16(Bt[n][k], At[m][k], acc[ai][bj][m][n], 0, 0, 0); __builtin_amdgcn_s_setprio(0); } while (0)
; #define PG8_WAIT_V(n) asm volatile("s_waitcnt vmcnt(" #n ")" ::: "memory")
; #define PG8_WAIT_L(n) asm volatile("s_waitcnt lgkmcnt(" #n ")" ::: "memory")
; #define PG8_BAR __builtin_amdgcn_s_barrier()
; #define PG8_SCHED __builtin_amdgcn_sched_barrier(0)
; template <class Epi, class Sched, bool ALIGN_EPI = false, bool SP2 = false>
; __device__ __forceinline__ void gemm_phase(PG8_LAS unsigned char* lds, const Gemm g, const Sched& S, const Epi& E) {
;     ...
;             PG8_LDA(At, 1, 1); PG8_STAGE(PG8_SB(1, 0), b3, voffB); PG8_STAGE(PG8_SB(1, 1), b3 + hstep, voffB); PG8_STAGE(PG8_SA(1, 0), a3, voffA);
;             PG8_WAIT_V(8); PG8_WAIT_L(0); PG8_BAR; PG8_MMA(1, 0, At, B0); PG8_MMA(1, 1, At, B1); PG8_BAR; PG8_SCHED;
	s_add_i32 s11, s11, s29
	v_lshl_add_u64 v[170:171], v[244:245], 0, s[22:23]
	s_mov_b32 m0, s11
	ds_read_b128 v[210:213], v179 offset:49152
	ds_read_b128 v[216:219], v179 offset:50176
	ds_read_b128 v[220:223], v179 offset:51200
	ds_read_b128 v[224:227], v179 offset:52224
	ds_read_b128 v[228:231], v179 offset:53248
	ds_read_b128 v[232:235], v179 offset:54272
	ds_read_b128 v[236:239], v179 offset:55296
	ds_read_b128 v[240:243], v179 offset:56320
	global_load_lds_dwordx4 v[170:171], off
	v_lshl_add_u64 v[170:171], v[246:247], 0, s[22:23]
	s_add_i32 m0, s11, 0x2000
	s_add_i32 s11, s13, s29
	global_load_lds_dwordx4 v[170:171], off
	s_mov_b32 m0, s11
	v_lshl_add_u64 v[170:171], v[248:249], 0, s[22:23]
	global_load_lds_dwordx4 v[170:171], off
	s_add_i32 m0, s11, 0x2000
	v_lshl_add_u64 v[170:171], v[214:215], 0, s[22:23]
	global_load_lds_dwordx4 v[170:171], off
	s_mov_b32 m0, s50
	v_lshl_add_u64 v[170:171], v[250:251], 0, s[22:23]
	global_load_lds_dwordx4 v[170:171], off
	s_mov_b32 m0, s51
	v_lshl_add_u64 v[170:171], v[252:253], 0, s[22:23]
	global_load_lds_dwordx4 v[170:171], off
	s_waitcnt vmcnt(8) lgkmcnt(0)
	s_setprio 1
	s_barrier
	v_mfma_f32_16x16x32_bf16 v[60:63], v[162:165], v[210:213], v[60:63]
	v_mfma_f32_16x16x32_bf16 v[52:55], v[186:189], v[210:213], v[52:55]
	v_mfma_f32_16x16x32_bf16 v[44:47], v[162:165], v[220:223], v[44:47]
	v_mfma_f32_16x16x32_bf16 v[36:39], v[186:189], v[220:223], v[36:39]
	v_mfma_f32_16x16x32_bf16 v[28:31], v[162:165], v[228:231], v[28:31]
	v_mfma_f32_16x16x32_bf16 v[20:23], v[186:189], v[228:231], v[20:23]
	v_mfma_f32_16x16x32_bf16 v[12:15], v[162:165], v[236:239], v[12:15]
	v_mfma_f32_16x16x32_bf16 v[4:7], v[186:189], v[236:239], v[4:7]
	v_mfma_f32_16x16x32_bf16 v[60:63], v[182:185], v[216:219], v[60:63]
	v_mfma_f32_16x16x32_bf16 v[52:55], v[190:193], v[216:219], v[52:55]
	v_mfma_f32_16x16x32_bf16 v[44:47], v[182:185], v[224:227], v[44:47]
	v_mfma_f32_16x16x32_bf16 v[36:39], v[190:193], v[224:227], v[36:39]
	v_mfma_f32_16x16x32_bf16 v[28:31], v[182:185], v[232:235], v[28:31]
	v_mfma_f32_16x16x32_bf16 v[20:23], v[190:193], v[232:235], v[20:23]
	v_mfma_f32_16x16x32_bf16 v[12:15], v[182:185], v[240:243], v[12:15]
	v_mfma_f32_16x16x32_bf16 v[4:7], v[190:193], v[240:243], v[4:7]
	v_mfma_f32_16x16x32_bf16 v[56:59], v[194:197], v[210:213], v[56:59]
	v_mfma_f32_16x16x32_bf16 v[48:51], v[202:205], v[210:213], v[48:51]
	v_mfma_f32_16x16x32_bf16 v[40:43], v[194:197], v[220:223], v[40:43]
	v_mfma_f32_16x16x32_bf16 v[32:35], v[202:205], v[220:223], v[32:35]
	v_mfma_f32_16x16x32_bf16 v[24:27], v[194:197], v[228:231], v[24:27]
	v_mfma_f32_16x16x32_bf16 v[16:19], v[202:205], v[228:231], v[16:19]
	v_mfma_f32_16x16x32_bf16 v[8:11], v[194:197], v[236:239], v[8:11]
	v_mfma_f32_16x16x32_bf16 v[0:3], v[202:205], v[236:239], v[0:3]
	v_mfma_f32_16x16x32_bf16 v[56:59], v[198:201], v[216:219], v[56:59]
	v_mfma_f32_16x16x32_bf16 v[48:51], v[206:209], v[216:219], v[48:51]
	v_mfma_f32_16x16x32_bf16 v[40:43], v[198:201], v[224:227], v[40:43]
	v_mfma_f32_16x16x32_bf16 v[32:35], v[206:209], v[224:227], v[32:35]
	v_mfma_f32_16x16x32_bf16 v[24:27], v[198:201], v[232:235], v[24:27]
	v_mfma_f32_16x16x32_bf16 v[16:19], v[206:209], v[232:235], v[16:19]
	v_mfma_f32_16x16x32_bf16 v[8:11], v[198:201], v[240:243], v[8:11]
	v_mfma_f32_16x16x32_bf16 v[0:3], v[206:209], v[240:243], v[0:3]
	s_setprio 0
	s_barrier
	v_lshl_add_u64 v[158:159], v[158:159], 0, s[26:27]
	s_cmp_ge_i32 s10, s52
	v_lshl_add_u64 v[160:161], v[160:161], 0, s[26:27]
	s_cbranch_scc0 .LBB0_1776

; #define PG8_STAGE(bufoff, gbase, voff) do { _Pragma("unroll") for (int _i = 0; _i < 2; ++_i) \
;         __builtin_amdgcn_global_load_lds((const unsigned*)((const char*)(gbase) + (voff)[_i]), (PG8_LAS unsigned*)(lds + (bufoff) + ldsw + _i * 8192), 16, 0, 0); } while (0)
; #define PG8_LDA(dst, b, h) do { _Pragma("unroll") for (int m = 0; m < 4; ++m) _Pragma("unroll") for (int k = 0; k < 2; ++k) dst[m][k] = *(const PG8_LAS bf16x8*)(lds + PG8_SA(b, h) + aoff + m * 2048 + k * 1024); } while (0)
; #define PG8_LDB(dst, b, h) do { _Pragma("unroll") for (int n = 0; n < 2; ++n) _Pragma("unroll") for (int k = 0; k < 2; ++k) dst[n][k] = *(const PG8_LAS bf16x8*)(lds + PG8_SB(b, h) + boff + n * 2048 + k * 1024); } while (0)
; #define PG8_MMA(ai, bj, At, Bt) do { __builtin_amdgcn_s_setprio(1); _Pragma("unroll") for (int m = 0; m < 4; ++m) _Pragma("unroll") for (int n = 0; n < 2; ++n) _Pragma("unroll") for (int k = 0; k < 2; ++k) \
;         acc[ai][bj][m][n] = __builtin_amdgcn_mfma_f32_16x16x32_bf16(Bt[n][k], At[m][k], acc[ai][bj][m][n], 0, 0, 0); __builtin_amdgcn_s_setprio(0); } while (0)
; #define PG8_WAIT_V(n) asm volatile("s_waitcnt vmcnt(" #n ")" ::: "memory")
; #define PG8_BAR __builtin_amdgcn_s_barrier()
; template <class Epi, class Sched, bool ALIGN_EPI = false, bool SP2 = false>
; __device__ __forceinline__ void gemm_phase(PG8_LAS unsigned char* lds, const Gemm g, const Sched& S, const Epi& E) {
;     ...
;         for (int t = 0; t < nt; t += 2) {
;             const bool last = (t == nt - 2);
;             const char* a1 = cA + (size_t)(t + 1) * kstep;
;             const char* a2 = last ? nA : cA + (size_t)(t + 2) * kstep; const char* b2 = last ? nB : cB + (size_t)(t + 2) * kstep;
;             const char* a3 = a2 + kstep; const char* b3 = b2 + kstep;
;             if (last && has_next) S.a_ready(nxt);
;             if constexpr (SP2) {
;             PG8_LDB(B0, 0, 0); PG8_LDB(B1, 0, 1); PG8_SCHED; PG8_LDA(At, 0, 0); PG8_STAGE(PG8_SA(1, 1), a1 + hstep, voffA);
;             PG8_WAIT_V(8); PG8_WAIT_L(0); PG8_BAR; PG8_MMA(0, 0, At, B0); PG8_MMA(0, 1, At, B1); PG8_BAR; PG8_SCHED;
;             PG8_LDA(At, 0, 1); PG8_STAGE(PG8_SB(0, 0), b2, voffB); PG8_STAGE(PG8_SB(0, 1), b2 + hstep, voffB); PG8_STAGE(PG8_SA(0, 0), a2, voffA);
;             PG8_WAIT_V(8); PG8_WAIT_L(0); PG8_BAR; PG8_MMA(1, 0, At, B0); PG8_MMA(1, 1, At, B1); PG8_BAR; PG8_SCHED;
.LBB0_1924:
	v_add_u32_e32 v192, s50, v161
	ds_read_b128 v[164:167], v162
	ds_read_b128 v[168:171], v162 offset:1024
	ds_read_b128 v[172:175], v162 offset:2048
	ds_read_b128 v[176:179], v162 offset:3072
	ds_read_b128 v[180:183], v192
	ds_read_b128 v[184:187], v192 offset:1024
	ds_read_b128 v[188:191], v192 offset:2048
	ds_read_b128 v[192:195], v192 offset:3072
	s_cmp_eq_u32 s49, s10
	v_lshl_add_u64 v[196:197], v[158:159], 0, s[24:25]
	s_cselect_b64 vcc, -1, 0
	s_add_i32 s10, s10, 2
	v_cndmask_b32_e32 v213, v197, v151, vcc
	v_cndmask_b32_e32 v212, v196, v150, vcc
	v_cndmask_b32_e32 v215, v155, v153, vcc
	v_cndmask_b32_e32 v214, v154, v152, vcc
	s_mov_b32 m0, s51
	v_lshl_add_u64 v[232:233], v[158:159], 0, v[146:147]
	ds_read_b128 v[196:199], v163
	ds_read_b128 v[200:203], v163 offset:1024
	ds_read_b128 v[204:207], v163 offset:2048
	ds_read_b128 v[208:211], v163 offset:3072
	ds_read_b128 v[216:219], v163 offset:4096
	ds_read_b128 v[220:223], v163 offset:5120
	ds_read_b128 v[224:227], v163 offset:6144
	ds_read_b128 v[228:231], v163 offset:7168
	global_load_lds_dwordx4 v[232:233], off
	s_mov_b32 m0, s52
	v_lshl_add_u64 v[232:233], v[158:159], 0, v[144:145]
	global_load_lds_dwordx4 v[232:233], off
	s_waitcnt vmcnt(8) lgkmcnt(0)
	s_setprio 1
	s_barrier
	v_mfma_f32_16x16x32_bf16 v[124:127], v[164:167], v[196:199], v[124:127]
	v_mfma_f32_16x16x32_bf16 v[120:123], v[172:175], v[196:199], v[120:123]
	v_mfma_f32_16x16x32_bf16 v[108:111], v[164:167], v[204:207], v[108:111]
	v_mfma_f32_16x16x32_bf16 v[104:107], v[172:175], v[204:207], v[104:107]
	v_mfma_f32_16x16x32_bf16 v[92:95], v[164:167], v[216:219], v[92:95]
	v_mfma_f32_16x16x32_bf16 v[88:91], v[172:175], v[216:219], v[88:91]
	v_mfma_f32_16x16x32_bf16 v[76:79], v[164:167], v[224:227], v[76:79]
	v_mfma_f32_16x16x32_bf16 v[72:75], v[172:175], v[224:227], v[72:75]
	v_mfma_f32_16x16x32_bf16 v[124:127], v[168:171], v[200:203], v[124:127]
	v_mfma_f32_16x16x32_bf16 v[120:123], v[176:179], v[200:203], v[120:123]
	v_mfma_f32_16x16x32_bf16 v[108:111], v[168:171], v[208:211], v[108:111]
	v_mfma_f32_16x16x32_bf16 v[104:107], v[176:179], v[208:211], v[104:107]
	v_mfma_f32_16x16x32_bf16 v[92:95], v[168:171], v[220:223], v[92:95]
	v_mfma_f32_16x16x32_bf16 v[88:91], v[176:179], v[220:223], v[88:91]
	v_mfma_f32_16x16x32_bf16 v[76:79], v[168:171], v[228:231], v[76:79]
	v_mfma_f32_16x16x32_bf16 v[72:75], v[176:179], v[228:231], v[72:75]
	v_mfma_f32_16x16x32_bf16 v[116:119], v[180:183], v[196:199], v[116:119]
	v_mfma_f32_16x16x32_bf16 v[112:115], v[188:191], v[196:199], v[112:115]
	v_mfma_f32_16x16x32_bf16 v[100:103], v[180:183], v[204:207], v[100:103]
	v_mfma_f32_16x16x32_bf16 v[96:99], v[188:191], v[204:207], v[96:99]
	v_mfma_f32_16x16x32_bf16 v[84:87], v[180:183], v[216:219], v[84:87]
	v_mfma_f32_16x16x32_bf16 v[80:83], v[188:191], v[216:219], v[80:83]
	v_mfma_f32_16x16x32_bf16 v[68:71], v[180:183], v[224:227], v[68:71]
	v_mfma_f32_16x16x32_bf16 v[64:67], v[188:191], v[224:227], v[64:67]
	v_mfma_f32_16x16x32_bf16 v[116:119], v[184:187], v[200:203], v[116:119]
	v_mfma_f32_16x16x32_bf16 v[112:115], v[192:195], v[200:203], v[112:115]
	v_mfma_f32_16x16x32_bf16 v[100:103], v[184:187], v[208:211], v[100:103]
	v_mfma_f32_16x16x32_bf16 v[96:99], v[192:195], v[208:211], v[96:99]
	v_mfma_f32_16x16x32_bf16 v[84:87], v[184:187], v[220:223], v[84:87]
	v_mfma_f32_16x16x32_bf16 v[80:83], v[192:195], v[220:223], v[80:83]
	v_mfma_f32_16x16x32_bf16 v[68:71], v[184:187], v[228:231], v[68:71]
	v_mfma_f32_16x16x32_bf16 v[64:67], v[192:195], v[228:231], v[64:67]
	s_setprio 0
	s_barrier
	s_mov_b32 m0, s53
	v_lshl_add_u64 v[232:233], v[214:215], 0, v[138:139]
	ds_read_b128 v[196:199], v163 offset:16384
	ds_read_b128 v[200:203], v163 offset:17408
	ds_read_b128 v[204:207], v163 offset:18432
	ds_read_b128 v[208:211], v163 offset:19456
	ds_read_b128 v[216:219], v163 offset:20480
	ds_read_b128 v[220:223], v163 offset:21504
	ds_read_b128 v[224:227], v163 offset:22528
	ds_read_b128 v[228:231], v163 offset:23552
	global_load_lds_dwordx4 v[232:233], off
	v_lshl_add_u64 v[234:235], v[214:215], 0, v[134:135]
	s_mov_b32 m0, s54
	v_lshl_add_u64 v[214:215], v[214:215], 0, s[14:15]
	global_load_lds_dwordx4 v[234:235], off
	v_lshl_add_u64 v[236:237], v[214:215], 0, v[138:139]
	s_mov_b32 m0, s55
	v_lshl_add_u64 v[214:215], v[214:215], 0, v[134:135]
	global_load_lds_dwordx4 v[236:237], off
	s_mov_b32 m0, s56
	v_lshl_add_u64 v[238:239], v[212:213], 0, v[140:141]
	global_load_lds_dwordx4 v[214:215], off
	s_mov_b32 m0, s37
	v_lshl_add_u64 v[240:241], v[212:213], 0, v[136:137]
	global_load_lds_dwordx4 v[238:239], off
	s_nop 0
	s_waitcnt vmcnt(7) lgkmcnt(0)
	s_setprio 1
	s_barrier
; #define PG8_STAGE(bufoff, gbase, voff) do { _Pragma("unroll") for (int _i = 0; _i < 2; ++_i) \
;         __builtin_amdgcn_global_load_lds((const unsigned*)((const char*)(gbase) + (voff)[_i]), (PG8_LAS unsigned*)(lds + (bufoff) + ldsw + _i * 8192), 16, 0, 0); } while (0)
; #define PG8_LDA(dst, b, h) do { _Pragma("unroll") for (int m = 0; m < 4; ++m) _Pragma("unroll") for (int k = 0; k < 2; ++k) dst[m][k] = *(const PG8_LAS bf16x8*)(lds + PG8_SA(b, h) + aoff + m * 2048 + k * 1024); } while (0)
; #define PG8_LDB(dst, b, h) do { _Pragma("unroll") for (int n = 0; n < 2; ++n) _Pragma("unroll") for (int k = 0; k < 2; ++k) dst[n][k] = *(const PG8_LAS bf16x8*)(lds + PG8_SB(b, h) + boff + n * 2048 + k * 1024); } while (0)
; #define PG8_MMA(ai, bj, At, Bt) do { __builtin_amdgcn_s_setprio(1); _Pragma("unroll") for (int m = 0; m < 4; ++m) _Pragma("unroll") for (int n = 0; n < 2; ++n) _Pragma("unroll") for (int k = 0; k < 2; ++k) \
;         acc[ai][bj][m][n] = __builtin_amdgcn_mfma_f32_16x16x32_bf16(Bt[n][k], At[m][k], acc[ai][bj][m][n], 0, 0, 0); __builtin_amdgcn_s_setprio(0); } while (0)
; #define PG8_WAIT_V(n) asm volatile("s_waitcnt vmcnt(" #n ")" ::: "memory")
; #define PG8_WAIT_L(n) asm volatile("s_waitcnt lgkmcnt(" #n ")" ::: "memory")
; #define PG8_BAR __builtin_amdgcn_s_barrier()
; #define PG8_SCHED __builtin_amdgcn_sched_barrier(0)
; template <class Epi, class Sched, bool ALIGN_EPI = false, bool SP2 = false>
; __device__ __forceinline__ void gemm_phase(PG8_LAS unsigned char* lds, const Gemm g, const Sched& S, const Epi& E) {
;     ...
;             PG8_WAIT_V(8); PG8_WAIT_L(0); PG8_BAR; PG8_MMA(1, 0, At, B0); PG8_MMA(1, 1, At, B1); PG8_BAR; PG8_SCHED;
;             PG8_LDB(B0, 1, 0); PG8_LDB(B1, 1, 1); PG8_SCHED; PG8_LDA(At, 1, 0); PG8_STAGE(PG8_SA(0, 1), a2 + hstep, voffA);
;             PG8_WAIT_V(8); PG8_WAIT_L(0); PG8_BAR; PG8_MMA(0, 0, At, B0); PG8_MMA(0, 1, At, B1); PG8_BAR; PG8_SCHED;
	v_mfma_f32_16x16x32_bf16 v[60:63], v[164:167], v[196:199], v[60:63]
	v_mfma_f32_16x16x32_bf16 v[56:59], v[172:175], v[196:199], v[56:59]
	v_mfma_f32_16x16x32_bf16 v[44:47], v[164:167], v[204:207], v[44:47]
	v_mfma_f32_16x16x32_bf16 v[40:43], v[172:175], v[204:207], v[40:43]
	v_mfma_f32_16x16x32_bf16 v[28:31], v[164:167], v[216:219], v[28:31]
	v_mfma_f32_16x16x32_bf16 v[24:27], v[172:175], v[216:219], v[24:27]
	v_mfma_f32_16x16x32_bf16 v[12:15], v[164:167], v[224:227], v[12:15]
	v_mfma_f32_16x16x32_bf16 v[8:11], v[172:175], v[224:227], v[8:11]
	v_mfma_f32_16x16x32_bf16 v[60:63], v[168:171], v[200:203], v[60:63]
	v_mfma_f32_16x16x32_bf16 v[56:59], v[176:179], v[200:203], v[56:59]
	v_mfma_f32_16x16x32_bf16 v[44:47], v[168:171], v[208:211], v[44:47]
	v_mfma_f32_16x16x32_bf16 v[40:43], v[176:179], v[208:211], v[40:43]
	v_mfma_f32_16x16x32_bf16 v[28:31], v[168:171], v[220:223], v[28:31]
	v_mfma_f32_16x16x32_bf16 v[24:27], v[176:179], v[220:223], v[24:27]
	v_mfma_f32_16x16x32_bf16 v[12:15], v[168:171], v[228:231], v[12:15]
	v_mfma_f32_16x16x32_bf16 v[8:11], v[176:179], v[228:231], v[8:11]
	v_mfma_f32_16x16x32_bf16 v[52:55], v[180:183], v[196:199], v[52:55]
	v_mfma_f32_16x16x32_bf16 v[48:51], v[188:191], v[196:199], v[48:51]
	v_mfma_f32_16x16x32_bf16 v[36:39], v[180:183], v[204:207], v[36:39]
	v_mfma_f32_16x16x32_bf16 v[32:35], v[188:191], v[204:207], v[32:35]
	v_mfma_f32_16x16x32_bf16 v[20:23], v[180:183], v[216:219], v[20:23]
	v_mfma_f32_16x16x32_bf16 v[16:19], v[188:191], v[216:219], v[16:19]
	v_mfma_f32_16x16x32_bf16 v[4:7], v[180:183], v[224:227], v[4:7]
	v_mfma_f32_16x16x32_bf16 v[0:3], v[188:191], v[224:227], v[0:3]
	v_mfma_f32_16x16x32_bf16 v[52:55], v[184:187], v[200:203], v[52:55]
	v_mfma_f32_16x16x32_bf16 v[48:51], v[192:195], v[200:203], v[48:51]
	v_mfma_f32_16x16x32_bf16 v[36:39], v[184:187], v[208:211], v[36:39]
	v_mfma_f32_16x16x32_bf16 v[32:35], v[192:195], v[208:211], v[32:35]
	v_mfma_f32_16x16x32_bf16 v[20:23], v[184:187], v[220:223], v[20:23]
	v_mfma_f32_16x16x32_bf16 v[16:19], v[192:195], v[220:223], v[16:19]
	v_mfma_f32_16x16x32_bf16 v[4:7], v[184:187], v[228:231], v[4:7]
	v_mfma_f32_16x16x32_bf16 v[0:3], v[192:195], v[228:231], v[0:3]
	s_setprio 0
	s_barrier
	v_add_u32_e32 v176, s57, v161
	v_add_u32_e32 v192, s58, v161
	s_mov_b32 m0, s41
	ds_read_b128 v[164:167], v176
	global_load_lds_dwordx4 v[240:241], off
	ds_read_b128 v[168:171], v176 offset:1024
	ds_read_b128 v[172:175], v176 offset:2048
	ds_read_b128 v[176:179], v176 offset:3072
	ds_read_b128 v[180:183], v192
	ds_read_b128 v[184:187], v192 offset:1024
	ds_read_b128 v[188:191], v192 offset:2048
	ds_read_b128 v[192:195], v192 offset:3072
	v_lshl_add_u64 v[212:213], v[212:213], 0, s[14:15]
	s_mov_b32 m0, s44
	v_lshl_add_u64 v[242:243], v[212:213], 0, v[140:141]
	ds_read_b128 v[196:199], v163 offset:32768
	ds_read_b128 v[200:203], v163 offset:33792
	ds_read_b128 v[204:207], v163 offset:34816
	ds_read_b128 v[208:211], v163 offset:35840
	ds_read_b128 v[216:219], v163 offset:36864
	ds_read_b128 v[220:223], v163 offset:37888
	ds_read_b128 v[224:227], v163 offset:38912
	ds_read_b128 v[228:231], v163 offset:39936
	global_load_lds_dwordx4 v[242:243], off
	s_mov_b32 m0, s45
	v_lshl_add_u64 v[212:213], v[212:213], 0, v[136:137]
	global_load_lds_dwordx4 v[212:213], off
	s_waitcnt vmcnt(8) lgkmcnt(0)
	s_setprio 1
	s_barrier
	v_mfma_f32_16x16x32_bf16 v[124:127], v[164:167], v[196:199], v[124:127]
	v_mfma_f32_16x16x32_bf16 v[120:123], v[172:175], v[196:199], v[120:123]
	v_mfma_f32_16x16x32_bf16 v[108:111], v[164:167], v[204:207], v[108:111]
	v_mfma_f32_16x16x32_bf16 v[104:107], v[172:175], v[204:207], v[104:107]
	v_mfma_f32_16x16x32_bf16 v[92:95], v[164:167], v[216:219], v[92:95]
	v_mfma_f32_16x16x32_bf16 v[88:91], v[172:175], v[216:219], v[88:91]
	v_mfma_f32_16x16x32_bf16 v[76:79], v[164:167], v[224:227], v[76:79]
	v_mfma_f32_16x16x32_bf16 v[72:75], v[172:175], v[224:227], v[72:75]
	v_mfma_f32_16x16x32_bf16 v[124:127], v[168:171], v[200:203], v[124:127]
	v_mfma_f32_16x16x32_bf16 v[120:123], v[176:179], v[200:203], v[120:123]
	v_mfma_f32_16x16x32_bf16 v[108:111], v[168:171], v[208:211], v[108:111]
	v_mfma_f32_16x16x32_bf16 v[104:107], v[176:179], v[208:211], v[104:107]
	v_mfma_f32_16x16x32_bf16 v[92:95], v[168:171], v[220:223], v[92:95]
	v_mfma_f32_16x16x32_bf16 v[88:91], v[176:179], v[220:223], v[88:91]
	v_mfma_f32_16x16x32_bf16 v[76:79], v[168:171], v[228:231], v[76:79]
	v_mfma_f32_16x16x32_bf16 v[72:75], v[176:179], v[228:231], v[72:75]
	v_mfma_f32_16x16x32_bf16 v[116:119], v[180:183], v[196:199], v[116:119]
	v_mfma_f32_16x16x32_bf16 v[112:115], v[188:191], v[196:199], v[112:115]
	v_mfma_f32_16x16x32_bf16 v[100:103], v[180:183], v[204:207], v[100:103]
	v_mfma_f32_16x16x32_bf16 v[96:99], v[188:191], v[204:207], v[96:99]
	v_mfma_f32_16x16x32_bf16 v[84:87], v[180:183], v[216:219], v[84:87]
	v_mfma_f32_16x16x32_bf16 v[80:83], v[188:191], v[216:219], v[80:83]
	v_mfma_f32_16x16x32_bf16 v[68:71], v[180:183], v[224:227], v[68:71]
	v_mfma_f32_16x16x32_bf16 v[64:67], v[188:191], v[224:227], v[64:67]
	v_mfma_f32_16x16x32_bf16 v[116:119], v[184:187], v[200:203], v[116:119]
	v_mfma_f32_16x16x32_bf16 v[112:115], v[192:195], v[200:203], v[112:115]
	v_mfma_f32_16x16x32_bf16 v[100:103], v[184:187], v[208:211], v[100:103]
	v_mfma_f32_16x16x32_bf16 v[96:99], v[192:195], v[208:211], v[96:99]
	v_mfma_f32_16x16x32_bf16 v[84:87], v[184:187], v[220:223], v[84:87]
	v_mfma_f32_16x16x32_bf16 v[80:83], v[192:195], v[220:223], v[80:83]
	v_mfma_f32_16x16x32_bf16 v[68:71], v[184:187], v[228:231], v[68:71]
	v_mfma_f32_16x16x32_bf16 v[64:67], v[192:195], v[228:231], v[64:67]
	s_setprio 0
	s_barrier
; #define PG8_STAGE(bufoff, gbase, voff) do { _Pragma("unroll") for (int _i = 0; _i < 2; ++_i) \
;         __builtin_amdgcn_global_load_lds((const unsigned*)((const char*)(gbase) + (voff)[_i]), (PG8_LAS unsigned*)(lds + (bufoff) + ldsw + _i * 8192), 16, 0, 0); } while (0)
; #define PG8_LDA(dst, b, h) do { _Pragma("unroll") for (int m = 0; m < 4; ++m) _Pragma("unroll") for (int k = 0; k < 2; ++k) dst[m][k] = *(const PG8_LAS bf16x8*)(lds + PG8_SA(b, h) + aoff + m * 2048 + k * 1024); } while (0)
; #define PG8_MMA(ai, bj, At, Bt) do { __builtin_amdgcn_s_setprio(1); _Pragma("unroll") for (int m = 0; m < 4; ++m) _Pragma("unroll") for (int n = 0; n < 2; ++n) _Pragma("unroll") for (int k = 0; k < 2; ++k) \
;         acc[ai][bj][m][n] = __builtin_amdgcn_mfma_f32_16x16x32_bf16(Bt[n][k], At[m][k], acc[ai][bj][m][n], 0, 0, 0); __builtin_amdgcn_s_setprio(0); } while (0)
; #define PG8_WAIT_V(n) asm volatile("s_waitcnt vmcnt(" #n ")" ::: "memory")
; #define PG8_WAIT_L(n) asm volatile("s_waitcnt lgkmcnt(" #n ")" ::: "memory")
; #define PG8_BAR __builtin_amdgcn_s_barrier()
; #define PG8_SCHED __builtin_amdgcn_sched_barrier(0)
; template <class Epi, class Sched, bool ALIGN_EPI = false, bool SP2 = false>
; __device__ __forceinline__ void gemm_phase(PG8_LAS unsigned char* lds, const Gemm g, const Sched& S, const Epi& E) {
;     ...
;             PG8_LDA(At, 1, 1); PG8_STAGE(PG8_SB(1, 0), b3, voffB); PG8_STAGE(PG8_SB(1, 1), b3 + hstep, voffB); PG8_STAGE(PG8_SA(1, 0), a3, voffA);
;             PG8_WAIT_V(8); PG8_WAIT_L(0); PG8_BAR; PG8_MMA(1, 0, At, B0); PG8_MMA(1, 1, At, B1); PG8_BAR; PG8_SCHED;
	s_mov_b32 m0, s59
	v_lshl_add_u64 v[212:213], v[232:233], 0, s[24:25]
	ds_read_b128 v[196:199], v163 offset:49152
	ds_read_b128 v[200:203], v163 offset:50176
	ds_read_b128 v[204:207], v163 offset:51200
	ds_read_b128 v[208:211], v163 offset:52224
	ds_read_b128 v[216:219], v163 offset:53248
	ds_read_b128 v[220:223], v163 offset:54272
	ds_read_b128 v[224:227], v163 offset:55296
	ds_read_b128 v[228:231], v163 offset:56320
	global_load_lds_dwordx4 v[212:213], off
	s_mov_b32 m0, s60
	v_lshl_add_u64 v[212:213], v[234:235], 0, s[24:25]
	global_load_lds_dwordx4 v[212:213], off
	s_mov_b32 m0, s61
	v_lshl_add_u64 v[212:213], v[236:237], 0, s[24:25]
	global_load_lds_dwordx4 v[212:213], off
	s_mov_b32 m0, s62
	v_lshl_add_u64 v[212:213], v[214:215], 0, s[24:25]
	global_load_lds_dwordx4 v[212:213], off
	s_mov_b32 m0, s46
	v_lshl_add_u64 v[212:213], v[238:239], 0, s[24:25]
	global_load_lds_dwordx4 v[212:213], off
	s_mov_b32 m0, s47
	v_lshl_add_u64 v[212:213], v[240:241], 0, s[24:25]
	global_load_lds_dwordx4 v[212:213], off
	s_waitcnt vmcnt(8) lgkmcnt(0)
	s_setprio 1
	s_barrier
	v_mfma_f32_16x16x32_bf16 v[60:63], v[164:167], v[196:199], v[60:63]
	v_mfma_f32_16x16x32_bf16 v[56:59], v[172:175], v[196:199], v[56:59]
	v_mfma_f32_16x16x32_bf16 v[44:47], v[164:167], v[204:207], v[44:47]
	v_mfma_f32_16x16x32_bf16 v[40:43], v[172:175], v[204:207], v[40:43]
	v_mfma_f32_16x16x32_bf16 v[28:31], v[164:167], v[216:219], v[28:31]
	v_mfma_f32_16x16x32_bf16 v[24:27], v[172:175], v[216:219], v[24:27]
	v_mfma_f32_16x16x32_bf16 v[12:15], v[164:167], v[224:227], v[12:15]
	v_mfma_f32_16x16x32_bf16 v[8:11], v[172:175], v[224:227], v[8:11]
	v_mfma_f32_16x16x32_bf16 v[60:63], v[168:171], v[200:203], v[60:63]
	v_mfma_f32_16x16x32_bf16 v[56:59], v[176:179], v[200:203], v[56:59]
	v_mfma_f32_16x16x32_bf16 v[44:47], v[168:171], v[208:211], v[44:47]
	v_mfma_f32_16x16x32_bf16 v[40:43], v[176:179], v[208:211], v[40:43]
	v_mfma_f32_16x16x32_bf16 v[28:31], v[168:171], v[220:223], v[28:31]
	v_mfma_f32_16x16x32_bf16 v[24:27], v[176:179], v[220:223], v[24:27]
	v_mfma_f32_16x16x32_bf16 v[12:15], v[168:171], v[228:231], v[12:15]
	v_mfma_f32_16x16x32_bf16 v[8:11], v[176:179], v[228:231], v[8:11]
	v_mfma_f32_16x16x32_bf16 v[52:55], v[180:183], v[196:199], v[52:55]
	v_mfma_f32_16x16x32_bf16 v[48:51], v[188:191], v[196:199], v[48:51]
	v_mfma_f32_16x16x32_bf16 v[36:39], v[180:183], v[204:207], v[36:39]
	v_mfma_f32_16x16x32_bf16 v[32:35], v[188:191], v[204:207], v[32:35]
	v_mfma_f32_16x16x32_bf16 v[20:23], v[180:183], v[216:219], v[20:23]
	v_mfma_f32_16x16x32_bf16 v[16:19], v[188:191], v[216:219], v[16:19]
	v_mfma_f32_16x16x32_bf16 v[4:7], v[180:183], v[224:227], v[4:7]
	v_mfma_f32_16x16x32_bf16 v[0:3], v[188:191], v[224:227], v[0:3]
	v_mfma_f32_16x16x32_bf16 v[52:55], v[184:187], v[200:203], v[52:55]
	v_mfma_f32_16x16x32_bf16 v[48:51], v[192:195], v[200:203], v[48:51]
	v_mfma_f32_16x16x32_bf16 v[36:39], v[184:187], v[208:211], v[36:39]
	v_mfma_f32_16x16x32_bf16 v[32:35], v[192:195], v[208:211], v[32:35]
	v_mfma_f32_16x16x32_bf16 v[20:23], v[184:187], v[220:223], v[20:23]
	v_mfma_f32_16x16x32_bf16 v[16:19], v[192:195], v[220:223], v[16:19]
	v_mfma_f32_16x16x32_bf16 v[4:7], v[184:187], v[228:231], v[4:7]
	v_mfma_f32_16x16x32_bf16 v[0:3], v[192:195], v[228:231], v[0:3]
	s_setprio 0
	s_barrier
	v_lshl_add_u64 v[154:155], v[154:155], 0, s[28:29]
	s_cmp_ge_i32 s10, s48
	v_lshl_add_u64 v[158:159], v[158:159], 0, s[28:29]
	s_cbranch_scc0 .LBB0_1924

; #define PG8_STAGE(bufoff, gbase, voff) do { _Pragma("unroll") for (int _i = 0; _i < 2; ++_i) \
;         __builtin_amdgcn_global_load_lds((const unsigned*)((const char*)(gbase) + (voff)[_i]), (PG8_LAS unsigned*)(lds + (bufoff) + ldsw + _i * 8192), 16, 0, 0); } while (0)
; #define PG8_LDA(dst, b, h) do { _Pragma("unroll") for (int m = 0; m < 4; ++m) _Pragma("unroll") for (int k = 0; k < 2; ++k) dst[m][k] = *(const PG8_LAS bf16x8*)(lds + PG8_SA(b, h) + aoff + m * 2048 + k * 1024); } while (0)
; #define PG8_LDB(dst, b, h) do { _Pragma("unroll") for (int n = 0; n < 2; ++n) _Pragma("unroll") for (int k = 0; k < 2; ++k) dst[n][k] = *(const PG8_LAS bf16x8*)(lds + PG8_SB(b, h) + boff + n * 2048 + k * 1024); } while (0)
; #define PG8_MMA(ai, bj, At, Bt) do { __builtin_amdgcn_s_setprio(1); _Pragma("unroll") for (int m = 0; m < 4; ++m) _Pragma("unroll") for (int n = 0; n < 2; ++n) _Pragma("unroll") for (int k = 0; k < 2; ++k) \
;         acc[ai][bj][m][n] = __builtin_amdgcn_mfma_f32_16x16x32_bf16(Bt[n][k], At[m][k], acc[ai][bj][m][n], 0, 0, 0); __builtin_amdgcn_s_setprio(0); } while (0)
; #define PG8_WAIT_V(n) asm volatile("s_waitcnt vmcnt(" #n ")" ::: "memory")
; #define PG8_BAR __builtin_amdgcn_s_barrier()
; template <class Epi, class Sched, bool ALIGN_EPI = false, bool SP2 = false>
; __device__ __forceinline__ void gemm_phase(PG8_LAS unsigned char* lds, const Gemm g, const Sched& S, const Epi& E) {
;     ...
;         for (int t = 0; t < nt; t += 2) {
;             const bool last = (t == nt - 2);
;             const char* a1 = cA + (size_t)(t + 1) * kstep;
;             const char* a2 = last ? nA : cA + (size_t)(t + 2) * kstep; const char* b2 = last ? nB : cB + (size_t)(t + 2) * kstep;
;             const char* a3 = a2 + kstep; const char* b3 = b2 + kstep;
;             if (last && has_next) S.a_ready(nxt);
;             if constexpr (SP2) {
;             PG8_LDB(B0, 0, 0); PG8_LDB(B1, 0, 1); PG8_SCHED; PG8_LDA(At, 0, 0); PG8_STAGE(PG8_SA(1, 1), a1 + hstep, voffA);
;             PG8_WAIT_V(8); PG8_WAIT_L(0); PG8_BAR; PG8_MMA(0, 0, At, B0); PG8_MMA(0, 1, At, B1); PG8_BAR; PG8_SCHED;
;             PG8_LDA(At, 0, 1); PG8_STAGE(PG8_SB(0, 0), b2, voffB); PG8_STAGE(PG8_SB(0, 1), b2 + hstep, voffB); PG8_STAGE(PG8_SA(0, 0), a2, voffA);
;             PG8_WAIT_V(8); PG8_WAIT_L(0); PG8_BAR; PG8_MMA(1, 0, At, B0); PG8_MMA(1, 1, At, B1); PG8_BAR; PG8_SCHED;
.LBB0_1947:
	v_add_u32_e32 v178, s53, v216
	v_add_u32_e32 v194, s54, v216
	ds_read_b128 v[138:141], v178
	ds_read_b128 v[142:145], v178 offset:1024
	ds_read_b128 v[146:149], v178 offset:2048
	ds_read_b128 v[178:181], v178 offset:3072
	ds_read_b128 v[182:185], v194
	ds_read_b128 v[186:189], v194 offset:1024
	ds_read_b128 v[190:193], v194 offset:2048
	ds_read_b128 v[194:197], v194 offset:3072
	s_cmp_eq_u32 s47, s10
	v_lshl_add_u64 v[198:199], v[136:137], 0, s[20:21]
	s_cselect_b64 vcc, -1, 0
	s_add_i32 s10, s10, 2
	v_cndmask_b32_e32 v215, v199, v175, vcc
	v_cndmask_b32_e32 v214, v198, v174, vcc
	v_cndmask_b32_e32 v237, v135, v177, vcc
	v_cndmask_b32_e32 v236, v134, v176, vcc
	v_lshl_add_u64 v[238:239], v[136:137], 0, v[168:169]
	s_add_i32 m0, s34, 0xc000
	ds_read_b128 v[198:201], v218
	ds_read_b128 v[202:205], v218 offset:1024
	ds_read_b128 v[206:209], v218 offset:2048
	ds_read_b128 v[210:213], v218 offset:3072
	ds_read_b128 v[220:223], v218 offset:4096
	ds_read_b128 v[224:227], v218 offset:5120
	ds_read_b128 v[228:231], v218 offset:6144
	ds_read_b128 v[232:235], v218 offset:7168
	global_load_lds_dwordx4 v[238:239], off
	s_add_i32 m0, s34, 0xe000
	v_lshl_add_u64 v[238:239], v[136:137], 0, v[166:167]
	global_load_lds_dwordx4 v[238:239], off
	s_waitcnt vmcnt(8) lgkmcnt(0)
	s_setprio 1
	s_barrier
	v_mfma_f32_16x16x32_bf16 v[130:133], v[138:141], v[198:201], v[130:133]
	v_mfma_f32_16x16x32_bf16 v[126:129], v[146:149], v[198:201], v[126:129]
	v_mfma_f32_16x16x32_bf16 v[114:117], v[138:141], v[206:209], v[114:117]
	v_mfma_f32_16x16x32_bf16 v[110:113], v[146:149], v[206:209], v[110:113]
	v_mfma_f32_16x16x32_bf16 v[98:101], v[138:141], v[220:223], v[98:101]
	v_mfma_f32_16x16x32_bf16 v[94:97], v[146:149], v[220:223], v[94:97]
	v_mfma_f32_16x16x32_bf16 v[82:85], v[138:141], v[228:231], v[82:85]
	v_mfma_f32_16x16x32_bf16 v[78:81], v[146:149], v[228:231], v[78:81]
	v_mfma_f32_16x16x32_bf16 v[130:133], v[142:145], v[202:205], v[130:133]
	v_mfma_f32_16x16x32_bf16 v[126:129], v[178:181], v[202:205], v[126:129]
	v_mfma_f32_16x16x32_bf16 v[114:117], v[142:145], v[210:213], v[114:117]
	v_mfma_f32_16x16x32_bf16 v[110:113], v[178:181], v[210:213], v[110:113]
	v_mfma_f32_16x16x32_bf16 v[98:101], v[142:145], v[224:227], v[98:101]
	v_mfma_f32_16x16x32_bf16 v[94:97], v[178:181], v[224:227], v[94:97]
	v_mfma_f32_16x16x32_bf16 v[82:85], v[142:145], v[232:235], v[82:85]
	v_mfma_f32_16x16x32_bf16 v[78:81], v[178:181], v[232:235], v[78:81]
	v_mfma_f32_16x16x32_bf16 v[122:125], v[182:185], v[198:201], v[122:125]
	v_mfma_f32_16x16x32_bf16 v[118:121], v[190:193], v[198:201], v[118:121]
	v_mfma_f32_16x16x32_bf16 v[106:109], v[182:185], v[206:209], v[106:109]
	v_mfma_f32_16x16x32_bf16 v[102:105], v[190:193], v[206:209], v[102:105]
	v_mfma_f32_16x16x32_bf16 v[90:93], v[182:185], v[220:223], v[90:93]
	v_mfma_f32_16x16x32_bf16 v[86:89], v[190:193], v[220:223], v[86:89]
	v_mfma_f32_16x16x32_bf16 v[74:77], v[182:185], v[228:231], v[74:77]
	v_mfma_f32_16x16x32_bf16 v[70:73], v[190:193], v[228:231], v[70:73]
	v_mfma_f32_16x16x32_bf16 v[122:125], v[186:189], v[202:205], v[122:125]
	v_mfma_f32_16x16x32_bf16 v[118:121], v[194:197], v[202:205], v[118:121]
	v_mfma_f32_16x16x32_bf16 v[106:109], v[186:189], v[210:213], v[106:109]
	v_mfma_f32_16x16x32_bf16 v[102:105], v[194:197], v[210:213], v[102:105]
	v_mfma_f32_16x16x32_bf16 v[90:93], v[186:189], v[224:227], v[90:93]
	v_mfma_f32_16x16x32_bf16 v[86:89], v[194:197], v[224:227], v[86:89]
	v_mfma_f32_16x16x32_bf16 v[74:77], v[186:189], v[232:235], v[74:77]
	v_mfma_f32_16x16x32_bf16 v[70:73], v[194:197], v[232:235], v[70:73]
	s_setprio 0
	s_barrier
	s_add_i32 s11, s53, s29
	v_lshl_add_u64 v[238:239], v[236:237], 0, v[158:159]
	s_mov_b32 m0, s11
	ds_read_b128 v[198:201], v218 offset:16384
	ds_read_b128 v[202:205], v218 offset:17408
	ds_read_b128 v[206:209], v218 offset:18432
	ds_read_b128 v[210:213], v218 offset:19456
	ds_read_b128 v[220:223], v218 offset:20480
	ds_read_b128 v[224:227], v218 offset:21504
	ds_read_b128 v[228:231], v218 offset:22528
	ds_read_b128 v[232:235], v218 offset:23552
	global_load_lds_dwordx4 v[238:239], off
	v_lshl_add_u64 v[240:241], v[236:237], 0, v[162:163]
	s_add_i32 m0, s11, 0x2000
	v_lshl_add_u64 v[236:237], v[236:237], 0, s[12:13]
	s_add_i32 s11, s54, s29
	global_load_lds_dwordx4 v[240:241], off
	v_lshl_add_u64 v[242:243], v[236:237], 0, v[158:159]
	s_mov_b32 m0, s11
	v_lshl_add_u64 v[236:237], v[236:237], 0, v[162:163]
	global_load_lds_dwordx4 v[242:243], off
	s_add_i32 m0, s11, 0x2000
	v_lshl_add_u64 v[244:245], v[214:215], 0, v[154:155]
	global_load_lds_dwordx4 v[236:237], off
	s_mov_b32 m0, s34
	v_lshl_add_u64 v[246:247], v[214:215], 0, v[160:161]
	global_load_lds_dwordx4 v[244:245], off
	s_nop 0
	s_waitcnt vmcnt(7) lgkmcnt(0)
	s_setprio 1
	s_barrier
; #define PG8_STAGE(bufoff, gbase, voff) do { _Pragma("unroll") for (int _i = 0; _i < 2; ++_i) \
;         __builtin_amdgcn_global_load_lds((const unsigned*)((const char*)(gbase) + (voff)[_i]), (PG8_LAS unsigned*)(lds + (bufoff) + ldsw + _i * 8192), 16, 0, 0); } while (0)
; #define PG8_LDA(dst, b, h) do { _Pragma("unroll") for (int m = 0; m < 4; ++m) _Pragma("unroll") for (int k = 0; k < 2; ++k) dst[m][k] = *(const PG8_LAS bf16x8*)(lds + PG8_SA(b, h) + aoff + m * 2048 + k * 1024); } while (0)
; #define PG8_LDB(dst, b, h) do { _Pragma("unroll") for (int n = 0; n < 2; ++n) _Pragma("unroll") for (int k = 0; k < 2; ++k) dst[n][k] = *(const PG8_LAS bf16x8*)(lds + PG8_SB(b, h) + boff + n * 2048 + k * 1024); } while (0)
; #define PG8_MMA(ai, bj, At, Bt) do { __builtin_amdgcn_s_setprio(1); _Pragma("unroll") for (int m = 0; m < 4; ++m) _Pragma("unroll") for (int n = 0; n < 2; ++n) _Pragma("unroll") for (int k = 0; k < 2; ++k) \
;         acc[ai][bj][m][n] = __builtin_amdgcn_mfma_f32_16x16x32_bf16(Bt[n][k], At[m][k], acc[ai][bj][m][n], 0, 0, 0); __builtin_amdgcn_s_setprio(0); } while (0)
; #define PG8_WAIT_V(n) asm volatile("s_waitcnt vmcnt(" #n ")" ::: "memory")
; #define PG8_WAIT_L(n) asm volatile("s_waitcnt lgkmcnt(" #n ")" ::: "memory")
; #define PG8_BAR __builtin_amdgcn_s_barrier()
; #define PG8_SCHED __builtin_amdgcn_sched_barrier(0)
; template <class Epi, class Sched, bool ALIGN_EPI = false, bool SP2 = false>
; __device__ __forceinline__ void gemm_phase(PG8_LAS unsigned char* lds, const Gemm g, const Sched& S, const Epi& E) {
;     ...
;             PG8_WAIT_V(8); PG8_WAIT_L(0); PG8_BAR; PG8_MMA(1, 0, At, B0); PG8_MMA(1, 1, At, B1); PG8_BAR; PG8_SCHED;
;             PG8_LDB(B0, 1, 0); PG8_LDB(B1, 1, 1); PG8_SCHED; PG8_LDA(At, 1, 0); PG8_STAGE(PG8_SA(0, 1), a2 + hstep, voffA);
;             PG8_WAIT_V(8); PG8_WAIT_L(0); PG8_BAR; PG8_MMA(0, 0, At, B0); PG8_MMA(0, 1, At, B1); PG8_BAR; PG8_SCHED;
	v_mfma_f32_16x16x32_bf16 v[66:69], v[138:141], v[198:201], v[66:69]
	v_mfma_f32_16x16x32_bf16 v[62:65], v[146:149], v[198:201], v[62:65]
	v_mfma_f32_16x16x32_bf16 v[50:53], v[138:141], v[206:209], v[50:53]
	v_mfma_f32_16x16x32_bf16 v[46:49], v[146:149], v[206:209], v[46:49]
	v_mfma_f32_16x16x32_bf16 v[34:37], v[138:141], v[220:223], v[34:37]
	v_mfma_f32_16x16x32_bf16 v[30:33], v[146:149], v[220:223], v[30:33]
	v_mfma_f32_16x16x32_bf16 v[18:21], v[138:141], v[228:231], v[18:21]
	v_mfma_f32_16x16x32_bf16 v[14:17], v[146:149], v[228:231], v[14:17]
	v_mfma_f32_16x16x32_bf16 v[66:69], v[142:145], v[202:205], v[66:69]
	v_mfma_f32_16x16x32_bf16 v[62:65], v[178:181], v[202:205], v[62:65]
	v_mfma_f32_16x16x32_bf16 v[50:53], v[142:145], v[210:213], v[50:53]
	v_mfma_f32_16x16x32_bf16 v[46:49], v[178:181], v[210:213], v[46:49]
	v_mfma_f32_16x16x32_bf16 v[34:37], v[142:145], v[224:227], v[34:37]
	v_mfma_f32_16x16x32_bf16 v[30:33], v[178:181], v[224:227], v[30:33]
	v_mfma_f32_16x16x32_bf16 v[18:21], v[142:145], v[232:235], v[18:21]
	v_mfma_f32_16x16x32_bf16 v[14:17], v[178:181], v[232:235], v[14:17]
	v_mfma_f32_16x16x32_bf16 v[58:61], v[182:185], v[198:201], v[58:61]
	v_mfma_f32_16x16x32_bf16 v[54:57], v[190:193], v[198:201], v[54:57]
	v_mfma_f32_16x16x32_bf16 v[42:45], v[182:185], v[206:209], v[42:45]
	v_mfma_f32_16x16x32_bf16 v[38:41], v[190:193], v[206:209], v[38:41]
	v_mfma_f32_16x16x32_bf16 v[26:29], v[182:185], v[220:223], v[26:29]
	v_mfma_f32_16x16x32_bf16 v[22:25], v[190:193], v[220:223], v[22:25]
	v_mfma_f32_16x16x32_bf16 v[10:13], v[182:185], v[228:231], v[10:13]
	v_mfma_f32_16x16x32_bf16 v[6:9], v[190:193], v[228:231], v[6:9]
	v_mfma_f32_16x16x32_bf16 v[58:61], v[186:189], v[202:205], v[58:61]
	v_mfma_f32_16x16x32_bf16 v[54:57], v[194:197], v[202:205], v[54:57]
	v_mfma_f32_16x16x32_bf16 v[42:45], v[186:189], v[210:213], v[42:45]
	v_mfma_f32_16x16x32_bf16 v[38:41], v[194:197], v[210:213], v[38:41]
	v_mfma_f32_16x16x32_bf16 v[26:29], v[186:189], v[224:227], v[26:29]
	v_mfma_f32_16x16x32_bf16 v[22:25], v[194:197], v[224:227], v[22:25]
	v_mfma_f32_16x16x32_bf16 v[10:13], v[186:189], v[232:235], v[10:13]
	v_mfma_f32_16x16x32_bf16 v[6:9], v[194:197], v[232:235], v[6:9]
	s_setprio 0
	s_barrier
	s_add_i32 s11, 0, 0x18000
	s_add_i32 s31, 0, 0x1c000
	v_add_u32_e32 v178, s11, v216
	v_add_u32_e32 v194, s31, v216
	s_mov_b32 m0, s35
	ds_read_b128 v[138:141], v178
	global_load_lds_dwordx4 v[246:247], off
	ds_read_b128 v[142:145], v178 offset:1024
	ds_read_b128 v[146:149], v178 offset:2048
	ds_read_b128 v[178:181], v178 offset:3072
	ds_read_b128 v[182:185], v194
	ds_read_b128 v[186:189], v194 offset:1024
	ds_read_b128 v[190:193], v194 offset:2048
	ds_read_b128 v[194:197], v194 offset:3072
	v_lshl_add_u64 v[214:215], v[214:215], 0, s[12:13]
	s_mov_b32 m0, s36
	v_lshl_add_u64 v[248:249], v[214:215], 0, v[154:155]
	ds_read_b128 v[198:201], v218 offset:32768
	ds_read_b128 v[202:205], v218 offset:33792
	ds_read_b128 v[206:209], v218 offset:34816
	ds_read_b128 v[210:213], v218 offset:35840
	ds_read_b128 v[220:223], v218 offset:36864
	ds_read_b128 v[224:227], v218 offset:37888
	ds_read_b128 v[228:231], v218 offset:38912
	ds_read_b128 v[232:235], v218 offset:39936
	global_load_lds_dwordx4 v[248:249], off
	s_mov_b32 m0, s37
	v_lshl_add_u64 v[214:215], v[214:215], 0, v[160:161]
	global_load_lds_dwordx4 v[214:215], off
	s_waitcnt vmcnt(8) lgkmcnt(0)
	s_setprio 1
	s_barrier
	v_mfma_f32_16x16x32_bf16 v[130:133], v[138:141], v[198:201], v[130:133]
	v_mfma_f32_16x16x32_bf16 v[126:129], v[146:149], v[198:201], v[126:129]
	v_mfma_f32_16x16x32_bf16 v[114:117], v[138:141], v[206:209], v[114:117]
	v_mfma_f32_16x16x32_bf16 v[110:113], v[146:149], v[206:209], v[110:113]
	v_mfma_f32_16x16x32_bf16 v[98:101], v[138:141], v[220:223], v[98:101]
	v_mfma_f32_16x16x32_bf16 v[94:97], v[146:149], v[220:223], v[94:97]
	v_mfma_f32_16x16x32_bf16 v[82:85], v[138:141], v[228:231], v[82:85]
	v_mfma_f32_16x16x32_bf16 v[78:81], v[146:149], v[228:231], v[78:81]
	v_mfma_f32_16x16x32_bf16 v[130:133], v[142:145], v[202:205], v[130:133]
	v_mfma_f32_16x16x32_bf16 v[126:129], v[178:181], v[202:205], v[126:129]
	v_mfma_f32_16x16x32_bf16 v[114:117], v[142:145], v[210:213], v[114:117]
	v_mfma_f32_16x16x32_bf16 v[110:113], v[178:181], v[210:213], v[110:113]
	v_mfma_f32_16x16x32_bf16 v[98:101], v[142:145], v[224:227], v[98:101]
	v_mfma_f32_16x16x32_bf16 v[94:97], v[178:181], v[224:227], v[94:97]
	v_mfma_f32_16x16x32_bf16 v[82:85], v[142:145], v[232:235], v[82:85]
	v_mfma_f32_16x16x32_bf16 v[78:81], v[178:181], v[232:235], v[78:81]
	v_mfma_f32_16x16x32_bf16 v[122:125], v[182:185], v[198:201], v[122:125]
	v_mfma_f32_16x16x32_bf16 v[118:121], v[190:193], v[198:201], v[118:121]
	v_mfma_f32_16x16x32_bf16 v[106:109], v[182:185], v[206:209], v[106:109]
	v_mfma_f32_16x16x32_bf16 v[102:105], v[190:193], v[206:209], v[102:105]
	v_mfma_f32_16x16x32_bf16 v[90:93], v[182:185], v[220:223], v[90:93]
	v_mfma_f32_16x16x32_bf16 v[86:89], v[190:193], v[220:223], v[86:89]
	v_mfma_f32_16x16x32_bf16 v[74:77], v[182:185], v[228:231], v[74:77]
	v_mfma_f32_16x16x32_bf16 v[70:73], v[190:193], v[228:231], v[70:73]
	v_mfma_f32_16x16x32_bf16 v[122:125], v[186:189], v[202:205], v[122:125]
	v_mfma_f32_16x16x32_bf16 v[118:121], v[194:197], v[202:205], v[118:121]
	v_mfma_f32_16x16x32_bf16 v[106:109], v[186:189], v[210:213], v[106:109]
	v_mfma_f32_16x16x32_bf16 v[102:105], v[194:197], v[210:213], v[102:105]
	v_mfma_f32_16x16x32_bf16 v[90:93], v[186:189], v[224:227], v[90:93]
	v_mfma_f32_16x16x32_bf16 v[86:89], v[194:197], v[224:227], v[86:89]
	v_mfma_f32_16x16x32_bf16 v[74:77], v[186:189], v[232:235], v[74:77]
	v_mfma_f32_16x16x32_bf16 v[70:73], v[194:197], v[232:235], v[70:73]
	s_setprio 0
	s_barrier
; #define PG8_STAGE(bufoff, gbase, voff) do { _Pragma("unroll") for (int _i = 0; _i < 2; ++_i) \
;         __builtin_amdgcn_global_load_lds((const unsigned*)((const char*)(gbase) + (voff)[_i]), (PG8_LAS unsigned*)(lds + (bufoff) + ldsw + _i * 8192), 16, 0, 0); } while (0)
; #define PG8_LDA(dst, b, h) do { _Pragma("unroll") for (int m = 0; m < 4; ++m) _Pragma("unroll") for (int k = 0; k < 2; ++k) dst[m][k] = *(const PG8_LAS bf16x8*)(lds + PG8_SA(b, h) + aoff + m * 2048 + k * 1024); } while (0)
; #define PG8_MMA(ai, bj, At, Bt) do { __builtin_amdgcn_s_setprio(1); _Pragma("unroll") for (int m = 0; m < 4; ++m) _Pragma("unroll") for (int n = 0; n < 2; ++n) _Pragma("unroll") for (int k = 0; k < 2; ++k) \
;         acc[ai][bj][m][n] = __builtin_amdgcn_mfma_f32_16x16x32_bf16(Bt[n][k], At[m][k], acc[ai][bj][m][n], 0, 0, 0); __builtin_amdgcn_s_setprio(0); } while (0)
; #define PG8_WAIT_V(n) asm volatile("s_waitcnt vmcnt(" #n ")" ::: "memory")
; #define PG8_WAIT_L(n) asm volatile("s_waitcnt lgkmcnt(" #n ")" ::: "memory")
; #define PG8_BAR __builtin_amdgcn_s_barrier()
; #define PG8_SCHED __builtin_amdgcn_sched_barrier(0)
; template <class Epi, class Sched, bool ALIGN_EPI = false, bool SP2 = false>
; __device__ __forceinline__ void gemm_phase(PG8_LAS unsigned char* lds, const Gemm g, const Sched& S, const Epi& E) {
;     ...
;             PG8_LDA(At, 1, 1); PG8_STAGE(PG8_SB(1, 0), b3, voffB); PG8_STAGE(PG8_SB(1, 1), b3 + hstep, voffB); PG8_STAGE(PG8_SA(1, 0), a3, voffA);
;             PG8_WAIT_V(8); PG8_WAIT_L(0); PG8_BAR; PG8_MMA(1, 0, At, B0); PG8_MMA(1, 1, At, B1); PG8_BAR; PG8_SCHED;
	s_add_i32 s11, s11, s29
	v_lshl_add_u64 v[214:215], v[238:239], 0, s[20:21]
	s_mov_b32 m0, s11
	ds_read_b128 v[198:201], v218 offset:49152
	ds_read_b128 v[202:205], v218 offset:50176
	ds_read_b128 v[206:209], v218 offset:51200
	ds_read_b128 v[210:213], v218 offset:52224
	ds_read_b128 v[220:223], v218 offset:53248
	ds_read_b128 v[224:227], v218 offset:54272
	ds_read_b128 v[228:231], v218 offset:55296
	ds_read_b128 v[232:235], v218 offset:56320
	global_load_lds_dwordx4 v[214:215], off
	v_lshl_add_u64 v[214:215], v[240:241], 0, s[20:21]
	s_add_i32 m0, s11, 0x2000
	s_add_i32 s11, s31, s29
	global_load_lds_dwordx4 v[214:215], off
	s_mov_b32 m0, s11
	v_lshl_add_u64 v[214:215], v[242:243], 0, s[20:21]
	global_load_lds_dwordx4 v[214:215], off
	s_add_i32 m0, s11, 0x2000
	v_lshl_add_u64 v[214:215], v[236:237], 0, s[20:21]
	global_load_lds_dwordx4 v[214:215], off
	s_mov_b32 m0, s41
	v_lshl_add_u64 v[214:215], v[244:245], 0, s[20:21]
	global_load_lds_dwordx4 v[214:215], off
	s_mov_b32 m0, s44
	v_lshl_add_u64 v[214:215], v[246:247], 0, s[20:21]
	global_load_lds_dwordx4 v[214:215], off
	s_waitcnt vmcnt(8) lgkmcnt(0)
	s_setprio 1
	s_barrier
	v_mfma_f32_16x16x32_bf16 v[66:69], v[138:141], v[198:201], v[66:69]
	v_mfma_f32_16x16x32_bf16 v[62:65], v[146:149], v[198:201], v[62:65]
	v_mfma_f32_16x16x32_bf16 v[50:53], v[138:141], v[206:209], v[50:53]
	v_mfma_f32_16x16x32_bf16 v[46:49], v[146:149], v[206:209], v[46:49]
	v_mfma_f32_16x16x32_bf16 v[34:37], v[138:141], v[220:223], v[34:37]
	v_mfma_f32_16x16x32_bf16 v[30:33], v[146:149], v[220:223], v[30:33]
	v_mfma_f32_16x16x32_bf16 v[18:21], v[138:141], v[228:231], v[18:21]
	v_mfma_f32_16x16x32_bf16 v[14:17], v[146:149], v[228:231], v[14:17]
	v_mfma_f32_16x16x32_bf16 v[66:69], v[142:145], v[202:205], v[66:69]
	v_mfma_f32_16x16x32_bf16 v[62:65], v[178:181], v[202:205], v[62:65]
	v_mfma_f32_16x16x32_bf16 v[50:53], v[142:145], v[210:213], v[50:53]
	v_mfma_f32_16x16x32_bf16 v[46:49], v[178:181], v[210:213], v[46:49]
	v_mfma_f32_16x16x32_bf16 v[34:37], v[142:145], v[224:227], v[34:37]
	v_mfma_f32_16x16x32_bf16 v[30:33], v[178:181], v[224:227], v[30:33]
	v_mfma_f32_16x16x32_bf16 v[18:21], v[142:145], v[232:235], v[18:21]
	v_mfma_f32_16x16x32_bf16 v[14:17], v[178:181], v[232:235], v[14:17]
	v_mfma_f32_16x16x32_bf16 v[58:61], v[182:185], v[198:201], v[58:61]
	v_mfma_f32_16x16x32_bf16 v[54:57], v[190:193], v[198:201], v[54:57]
	v_mfma_f32_16x16x32_bf16 v[42:45], v[182:185], v[206:209], v[42:45]
	v_mfma_f32_16x16x32_bf16 v[38:41], v[190:193], v[206:209], v[38:41]
	v_mfma_f32_16x16x32_bf16 v[26:29], v[182:185], v[220:223], v[26:29]
	v_mfma_f32_16x16x32_bf16 v[22:25], v[190:193], v[220:223], v[22:25]
	v_mfma_f32_16x16x32_bf16 v[10:13], v[182:185], v[228:231], v[10:13]
	v_mfma_f32_16x16x32_bf16 v[6:9], v[190:193], v[228:231], v[6:9]
	v_mfma_f32_16x16x32_bf16 v[58:61], v[186:189], v[202:205], v[58:61]
	v_mfma_f32_16x16x32_bf16 v[54:57], v[194:197], v[202:205], v[54:57]
	v_mfma_f32_16x16x32_bf16 v[42:45], v[186:189], v[210:213], v[42:45]
	v_mfma_f32_16x16x32_bf16 v[38:41], v[194:197], v[210:213], v[38:41]
	v_mfma_f32_16x16x32_bf16 v[26:29], v[186:189], v[224:227], v[26:29]
	v_mfma_f32_16x16x32_bf16 v[22:25], v[194:197], v[224:227], v[22:25]
	v_mfma_f32_16x16x32_bf16 v[10:13], v[186:189], v[232:235], v[10:13]
	v_mfma_f32_16x16x32_bf16 v[6:9], v[194:197], v[232:235], v[6:9]
	s_setprio 0
	s_barrier
	v_lshl_add_u64 v[134:135], v[134:135], 0, s[26:27]
	s_cmp_ge_i32 s10, s46
	v_lshl_add_u64 v[136:137], v[136:137], 0, s[26:27]
	s_cbranch_scc0 .LBB0_1947
